# GEMM K-loops: redundant post-barrier lgkmcnt(0) removed, s_setprio moved off the barrier-to-MFMA path
# speedup vs baseline: 1.0294x; 1.0029x over previous
; #define PG8_STAGE(bufoff, gbase, voff) do { _Pragma("unroll") for (int _i = 0; _i < 2; ++_i) \
;         __builtin_amdgcn_global_load_lds((const unsigned*)((const char*)(gbase) + (voff)[_i]), (PG8_LAS unsigned*)(lds + (bufoff) + ldsw + _i * 8192), 16, 0, 0); } while (0)
; #define PG8_LDA(dst, b, h) do { _Pragma("unroll") for (int m = 0; m < 4; ++m) _Pragma("unroll") for (int k = 0; k < 2; ++k) dst[m][k] = *(const PG8_LAS bf16x8*)(lds + PG8_SA(b, h) + aoff + m * 2048 + k * 1024); } while (0)
; template <class Epi, class Sched, bool ALIGN_EPI = false, bool SP2 = false>
; __device__ __forceinline__ void gemm_phase(PG8_LAS unsigned char* lds, const Gemm g, const Sched& S, const Epi& E, const int tid) {
;     ...
;         const bool has_next = S.next(ui + 1, nxt);
;         const char* nA = has_next ? (const char*)g.A + (size_t)nxt.pm * tstep : cA; const char* nB = has_next ? (const char*)g.Bt + (size_t)nxt.pn * tstep : cB;
;         for (int t = 0; t < nt; t += 2) {
;             const bool last = (t == nt - 2);
;             const char* a1 = cA + (size_t)(t + 1) * kstep;
;             const char* a2 = last ? nA : cA + (size_t)(t + 2) * kstep; const char* b2 = last ? nB : cB + (size_t)(t + 2) * kstep;
;             const char* a3 = a2 + kstep; const char* b3 = b2 + kstep;
;             if (last && has_next) S.a_ready(nxt);
;             if constexpr (SP2) {
;             PG8_LDB(B0, 0, 0); PG8_LDB(B1, 0, 1); PG8_SCHED; PG8_LDA(At, 0, 0); PG8_STAGE(PG8_SA(1, 1), a1 + hstep, voffA);
;             PG8_WAIT_V(8); PG8_WAIT_L(0); PG8_BAR; PG8_MMA(0, 0, At, B0); PG8_MMA(0, 1, At, B1); PG8_BAR; PG8_SCHED;
;             PG8_LDA(At, 0, 1); PG8_STAGE(PG8_SB(0, 0), b2, voffB); PG8_STAGE(PG8_SB(0, 1), b2 + hstep, voffB); PG8_STAGE(PG8_SA(0, 0), a2, voffA);
;             PG8_WAIT_V(8); PG8_WAIT_L(0); PG8_BAR; PG8_MMA(1, 0, At, B0); PG8_MMA(1, 1, At, B1); PG8_BAR; PG8_SCHED;
;             PG8_LDB(B0, 1, 0); PG8_LDB(B1, 1, 1); PG8_SCHED; PG8_LDA(At, 1, 0); PG8_STAGE(PG8_SA(0, 1), a2 + hstep, voffA);
;             PG8_WAIT_V(8); PG8_WAIT_L(0); PG8_BAR; PG8_MMA(0, 0, At, B0); PG8_MMA(0, 1, At, B1); PG8_BAR; PG8_SCHED;
;             PG8_LDA(At, 1, 1); PG8_STAGE(PG8_SB(1, 0), b3, voffB); PG8_STAGE(PG8_SB(1, 1), b3 + hstep, voffB); PG8_STAGE(PG8_SA(1, 0), a3, voffA);
;             PG8_WAIT_V(8); PG8_WAIT_L(0); PG8_BAR; PG8_MMA(1, 0, At, B0); PG8_MMA(1, 1, At, B1); PG8_BAR; PG8_SCHED;
.LBB0_318:
	s_ashr_i32 s29, s28, 31
	s_lshl_b64 s[30:31], s[28:29], 20
	s_add_u32 s30, s48, s30
	s_addc_u32 s31, s49, s31
	s_and_b64 s[34:35], s[6:7], exec
	s_cselect_b32 s9, s31, s43
	s_cselect_b32 s29, s30, s42
	s_ashr_i32 s27, s26, 31
	s_lshl_b64 s[34:35], s[26:27], 20
	s_add_u32 s34, s50, s34
	s_addc_u32 s35, s51, s35
	s_and_b64 s[46:47], s[6:7], exec
	s_cselect_b32 s27, s35, s45
	s_cselect_b32 s37, s34, s44
	s_add_u32 s42, s42, 0x80080
	s_addc_u32 s43, s43, 0
	s_add_u32 s69, s44, 0x100
	s_addc_u32 s92, s45, 0
	s_mov_b32 s76, -2
	s_waitcnt vmcnt(0)
	s_add_u32 s44, s42, 0xfff80080
	s_addc_u32 s45, s43, -1
	s_add_i32 s77, 0, 0x10000
	s_cmp_eq_u32 s76, 28
	s_cselect_b32 s47, s9, s45
	s_cselect_b32 s46, s29, s44
	v_add_u32_e32 v136, s77, v178
	s_cselect_b32 s45, s27, s92
	s_cselect_b32 s44, s37, s69
	s_add_i32 s80, 0, 0x14000
	ds_read_b128 v[128:131], v136
	ds_read_b128 v[132:135], v136 offset:1024
	ds_read_b128 v[150:153], v136 offset:2048
	ds_read_b128 v[154:157], v136 offset:3072
	v_add_u32_e32 v136, s80, v178
	ds_read_b128 v[158:161], v136
	ds_read_b128 v[162:165], v136 offset:1024
	ds_read_b128 v[166:169], v136 offset:2048
	ds_read_b128 v[170:173], v136 offset:3072
	v_lshl_add_u64 v[136:137], s[42:43], 0, v[146:147]
	s_add_i32 m0, s53, 0xc000
	ds_read_b128 v[174:177], v179
	ds_read_b128 v[180:183], v179 offset:1024
	ds_read_b128 v[184:187], v179 offset:2048
	ds_read_b128 v[188:191], v179 offset:3072
	ds_read_b128 v[192:195], v179 offset:4096
	ds_read_b128 v[196:199], v179 offset:5120
	ds_read_b128 v[200:203], v179 offset:6144
	ds_read_b128 v[206:209], v179 offset:7168
	global_load_lds_dwordx4 v[136:137], off
	v_lshl_add_u64 v[136:137], s[42:43], 0, v[148:149]
	s_add_i32 m0, s53, 0xe000
	s_nop 0
	global_load_lds_dwordx4 v[136:137], off
	s_waitcnt vmcnt(24)
	s_waitcnt lgkmcnt(0)
	s_setprio 1
	s_barrier
	v_mfma_f32_16x16x32_bf16 v[124:127], v[128:131], v[174:177], 0
	v_mfma_f32_16x16x32_bf16 v[120:123], v[150:153], v[174:177], 0
	v_mfma_f32_16x16x32_bf16 v[108:111], v[128:131], v[184:187], 0
	v_mfma_f32_16x16x32_bf16 v[104:107], v[150:153], v[184:187], 0
	v_mfma_f32_16x16x32_bf16 v[92:95], v[128:131], v[192:195], 0
	v_mfma_f32_16x16x32_bf16 v[88:91], v[150:153], v[192:195], 0
	v_mfma_f32_16x16x32_bf16 v[76:79], v[128:131], v[200:203], 0
	v_mfma_f32_16x16x32_bf16 v[72:75], v[150:153], v[200:203], 0
	v_mfma_f32_16x16x32_bf16 v[124:127], v[132:135], v[180:183], v[124:127]
	v_mfma_f32_16x16x32_bf16 v[120:123], v[154:157], v[180:183], v[120:123]
	v_mfma_f32_16x16x32_bf16 v[108:111], v[132:135], v[188:191], v[108:111]
	v_mfma_f32_16x16x32_bf16 v[104:107], v[154:157], v[188:191], v[104:107]
	v_mfma_f32_16x16x32_bf16 v[92:95], v[132:135], v[196:199], v[92:95]
	v_mfma_f32_16x16x32_bf16 v[88:91], v[154:157], v[196:199], v[88:91]
	v_mfma_f32_16x16x32_bf16 v[76:79], v[132:135], v[206:209], v[76:79]
	v_mfma_f32_16x16x32_bf16 v[72:75], v[154:157], v[206:209], v[72:75]
	s_setprio 0
	s_setprio 1
	v_mfma_f32_16x16x32_bf16 v[116:119], v[158:161], v[174:177], 0
	v_mfma_f32_16x16x32_bf16 v[112:115], v[166:169], v[174:177], 0
	v_mfma_f32_16x16x32_bf16 v[100:103], v[158:161], v[184:187], 0
	v_mfma_f32_16x16x32_bf16 v[96:99], v[166:169], v[184:187], 0
	v_mfma_f32_16x16x32_bf16 v[84:87], v[158:161], v[192:195], 0
	v_mfma_f32_16x16x32_bf16 v[80:83], v[166:169], v[192:195], 0
	v_mfma_f32_16x16x32_bf16 v[68:71], v[158:161], v[200:203], 0
	v_mfma_f32_16x16x32_bf16 v[64:67], v[166:169], v[200:203], 0
	v_mfma_f32_16x16x32_bf16 v[116:119], v[162:165], v[180:183], v[116:119]
	v_mfma_f32_16x16x32_bf16 v[112:115], v[170:173], v[180:183], v[112:115]
	v_mfma_f32_16x16x32_bf16 v[100:103], v[162:165], v[188:191], v[100:103]
	v_mfma_f32_16x16x32_bf16 v[96:99], v[170:173], v[188:191], v[96:99]
	v_mfma_f32_16x16x32_bf16 v[84:87], v[162:165], v[196:199], v[84:87]
	v_mfma_f32_16x16x32_bf16 v[80:83], v[170:173], v[196:199], v[80:83]
	v_mfma_f32_16x16x32_bf16 v[68:71], v[162:165], v[206:209], v[68:71]
	v_mfma_f32_16x16x32_bf16 v[64:67], v[170:173], v[206:209], v[64:67]
	s_barrier
	s_setprio 0
	s_add_i32 s77, s77, s52
	v_lshl_add_u64 v[136:137], s[44:45], 0, v[140:141]
	s_mov_b32 m0, s77
	ds_read_b128 v[174:177], v179 offset:16384
	ds_read_b128 v[180:183], v179 offset:17408
	ds_read_b128 v[184:187], v179 offset:18432
	ds_read_b128 v[188:191], v179 offset:19456
	ds_read_b128 v[192:195], v179 offset:20480
	ds_read_b128 v[196:199], v179 offset:21504
	ds_read_b128 v[200:203], v179 offset:22528
	ds_read_b128 v[206:209], v179 offset:23552
	global_load_lds_dwordx4 v[136:137], off
	s_add_i32 m0, s77, 0x2000
	s_add_u32 s78, s44, 0x80000
	v_lshl_add_u64 v[210:211], s[44:45], 0, v[144:145]
	s_addc_u32 s79, s45, 0
	s_add_i32 s77, s80, s52
	global_load_lds_dwordx4 v[210:211], off
	v_lshl_add_u64 v[212:213], s[78:79], 0, v[140:141]
	s_mov_b32 m0, s77
	v_lshl_add_u64 v[214:215], s[46:47], 0, v[142:143]
	global_load_lds_dwordx4 v[212:213], off
	v_lshl_add_u64 v[212:213], s[78:79], 0, v[144:145]
	s_add_i32 m0, s77, 0x2000
	s_nop 0
	global_load_lds_dwordx4 v[212:213], off
	v_lshl_add_u64 v[212:213], s[46:47], 0, v[138:139]
	s_mov_b32 m0, s53
	s_nop 0
	global_load_lds_dwordx4 v[212:213], off
	s_mov_b32 m0, s54
	s_nop 0
	global_load_lds_dwordx4 v[214:215], off
	s_waitcnt vmcnt(8)
	s_waitcnt lgkmcnt(0)
	s_setprio 1
	s_barrier
; #define PG8_STAGE(bufoff, gbase, voff) do { _Pragma("unroll") for (int _i = 0; _i < 2; ++_i) \
;         __builtin_amdgcn_global_load_lds((const unsigned*)((const char*)(gbase) + (voff)[_i]), (PG8_LAS unsigned*)(lds + (bufoff) + ldsw + _i * 8192), 16, 0, 0); } while (0)
; #define PG8_LDA(dst, b, h) do { _Pragma("unroll") for (int m = 0; m < 4; ++m) _Pragma("unroll") for (int k = 0; k < 2; ++k) dst[m][k] = *(const PG8_LAS bf16x8*)(lds + PG8_SA(b, h) + aoff + m * 2048 + k * 1024); } while (0)
; #define PG8_LDB(dst, b, h) do { _Pragma("unroll") for (int n = 0; n < 2; ++n) _Pragma("unroll") for (int k = 0; k < 2; ++k) dst[n][k] = *(const PG8_LAS bf16x8*)(lds + PG8_SB(b, h) + boff + n * 2048 + k * 1024); } while (0)
; #define PG8_MMA(ai, bj, At, Bt) do { __builtin_amdgcn_s_setprio(1); _Pragma("unroll") for (int m = 0; m < 4; ++m) _Pragma("unroll") for (int n = 0; n < 2; ++n) _Pragma("unroll") for (int k = 0; k < 2; ++k) \
;         acc[ai][bj][m][n] = __builtin_amdgcn_mfma_f32_16x16x32_bf16(Bt[n][k], At[m][k], acc[ai][bj][m][n], 0, 0, 0); __builtin_amdgcn_s_setprio(0); } while (0)
; #define PG8_BAR __builtin_amdgcn_s_barrier()
; template <class Epi, class Sched, bool ALIGN_EPI = false, bool SP2 = false>
; __device__ __forceinline__ void gemm_phase(PG8_LAS unsigned char* lds, const Gemm g, const Sched& S, const Epi& E, const int tid) {
;     ...
;             PG8_LDB(B0, 0, 0); PG8_LDB(B1, 0, 1); PG8_SCHED; PG8_LDA(At, 0, 0); PG8_STAGE(PG8_SA(1, 1), a1 + hstep, voffA);
;             PG8_WAIT_V(8); PG8_WAIT_L(0); PG8_BAR; PG8_MMA(0, 0, At, B0); PG8_MMA(0, 1, At, B1); PG8_BAR; PG8_SCHED;
;             PG8_LDA(At, 0, 1); PG8_STAGE(PG8_SB(0, 0), b2, voffB); PG8_STAGE(PG8_SB(0, 1), b2 + hstep, voffB); PG8_STAGE(PG8_SA(0, 0), a2, voffA);
;             PG8_WAIT_V(8); PG8_WAIT_L(0); PG8_BAR; PG8_MMA(1, 0, At, B0); PG8_MMA(1, 1, At, B1); PG8_BAR; PG8_SCHED;
;             PG8_LDB(B0, 1, 0); PG8_LDB(B1, 1, 1); PG8_SCHED; PG8_LDA(At, 1, 0); PG8_STAGE(PG8_SA(0, 1), a2 + hstep, voffA);
;             PG8_WAIT_V(8); PG8_WAIT_L(0); PG8_BAR; PG8_MMA(0, 0, At, B0); PG8_MMA(0, 1, At, B1); PG8_BAR; PG8_SCHED;
;             PG8_LDA(At, 1, 1); PG8_STAGE(PG8_SB(1, 0), b3, voffB); PG8_STAGE(PG8_SB(1, 1), b3 + hstep, voffB); PG8_STAGE(PG8_SA(1, 0), a3, voffA);
;             PG8_WAIT_V(8); PG8_WAIT_L(0); PG8_BAR; PG8_MMA(1, 0, At, B0); PG8_MMA(1, 1, At, B1); PG8_BAR; PG8_SCHED;
	v_mfma_f32_16x16x32_bf16 v[60:63], v[128:131], v[174:177], 0
	v_mfma_f32_16x16x32_bf16 v[56:59], v[150:153], v[174:177], 0
	v_mfma_f32_16x16x32_bf16 v[44:47], v[128:131], v[184:187], 0
	v_mfma_f32_16x16x32_bf16 v[40:43], v[150:153], v[184:187], 0
	v_mfma_f32_16x16x32_bf16 v[28:31], v[128:131], v[192:195], 0
	v_mfma_f32_16x16x32_bf16 v[24:27], v[150:153], v[192:195], 0
	v_mfma_f32_16x16x32_bf16 v[12:15], v[128:131], v[200:203], 0
	v_mfma_f32_16x16x32_bf16 v[8:11], v[150:153], v[200:203], 0
	v_mfma_f32_16x16x32_bf16 v[60:63], v[132:135], v[180:183], v[60:63]
	v_mfma_f32_16x16x32_bf16 v[56:59], v[154:157], v[180:183], v[56:59]
	v_mfma_f32_16x16x32_bf16 v[44:47], v[132:135], v[188:191], v[44:47]
	v_mfma_f32_16x16x32_bf16 v[40:43], v[154:157], v[188:191], v[40:43]
	v_mfma_f32_16x16x32_bf16 v[28:31], v[132:135], v[196:199], v[28:31]
	v_mfma_f32_16x16x32_bf16 v[24:27], v[154:157], v[196:199], v[24:27]
	v_mfma_f32_16x16x32_bf16 v[12:15], v[132:135], v[206:209], v[12:15]
	v_mfma_f32_16x16x32_bf16 v[8:11], v[154:157], v[206:209], v[8:11]
	s_setprio 0
	s_setprio 1
	v_mfma_f32_16x16x32_bf16 v[52:55], v[158:161], v[174:177], 0
	v_mfma_f32_16x16x32_bf16 v[48:51], v[166:169], v[174:177], 0
	v_mfma_f32_16x16x32_bf16 v[36:39], v[158:161], v[184:187], 0
	v_mfma_f32_16x16x32_bf16 v[32:35], v[166:169], v[184:187], 0
	v_mfma_f32_16x16x32_bf16 v[20:23], v[158:161], v[192:195], 0
	v_mfma_f32_16x16x32_bf16 v[16:19], v[166:169], v[192:195], 0
	v_mfma_f32_16x16x32_bf16 v[4:7], v[158:161], v[200:203], 0
	v_mfma_f32_16x16x32_bf16 v[0:3], v[166:169], v[200:203], 0
	v_mfma_f32_16x16x32_bf16 v[52:55], v[162:165], v[180:183], v[52:55]
	v_mfma_f32_16x16x32_bf16 v[48:51], v[170:173], v[180:183], v[48:51]
	v_mfma_f32_16x16x32_bf16 v[36:39], v[162:165], v[188:191], v[36:39]
	v_mfma_f32_16x16x32_bf16 v[32:35], v[170:173], v[188:191], v[32:35]
	v_mfma_f32_16x16x32_bf16 v[20:23], v[162:165], v[196:199], v[20:23]
	v_mfma_f32_16x16x32_bf16 v[16:19], v[170:173], v[196:199], v[16:19]
	v_mfma_f32_16x16x32_bf16 v[4:7], v[162:165], v[206:209], v[4:7]
	v_mfma_f32_16x16x32_bf16 v[0:3], v[170:173], v[206:209], v[0:3]
	s_barrier
	s_setprio 0
	s_add_i32 s77, 0, 0x18000
	s_add_i32 s78, 0, 0x1c000
	v_add_u32_e32 v154, s77, v178
	v_add_u32_e32 v170, s78, v178
	ds_read_b128 v[128:131], v154
	ds_read_b128 v[132:135], v154 offset:1024
	ds_read_b128 v[150:153], v154 offset:2048
	ds_read_b128 v[154:157], v154 offset:3072
	ds_read_b128 v[158:161], v170
	ds_read_b128 v[162:165], v170 offset:1024
	ds_read_b128 v[166:169], v170 offset:2048
	ds_read_b128 v[170:173], v170 offset:3072
	s_add_u32 s46, s46, 0x80000
	s_addc_u32 s47, s47, 0
	s_mov_b32 m0, s55
	v_lshl_add_u64 v[216:217], s[46:47], 0, v[138:139]
	ds_read_b128 v[174:177], v179 offset:32768
	ds_read_b128 v[180:183], v179 offset:33792
	ds_read_b128 v[184:187], v179 offset:34816
	ds_read_b128 v[188:191], v179 offset:35840
	ds_read_b128 v[192:195], v179 offset:36864
	ds_read_b128 v[196:199], v179 offset:37888
	ds_read_b128 v[200:203], v179 offset:38912
	ds_read_b128 v[206:209], v179 offset:39936
	global_load_lds_dwordx4 v[216:217], off
	v_lshl_add_u64 v[216:217], s[46:47], 0, v[142:143]
	s_mov_b32 m0, s0
	s_nop 0
	global_load_lds_dwordx4 v[216:217], off
	s_waitcnt vmcnt(8)
	s_waitcnt lgkmcnt(0)
	s_setprio 1
	s_barrier
	v_mfma_f32_16x16x32_bf16 v[124:127], v[128:131], v[174:177], v[124:127]
	v_mfma_f32_16x16x32_bf16 v[120:123], v[150:153], v[174:177], v[120:123]
	v_mfma_f32_16x16x32_bf16 v[108:111], v[128:131], v[184:187], v[108:111]
	v_mfma_f32_16x16x32_bf16 v[104:107], v[150:153], v[184:187], v[104:107]
	v_mfma_f32_16x16x32_bf16 v[92:95], v[128:131], v[192:195], v[92:95]
	v_mfma_f32_16x16x32_bf16 v[88:91], v[150:153], v[192:195], v[88:91]
	v_mfma_f32_16x16x32_bf16 v[76:79], v[128:131], v[200:203], v[76:79]
	v_mfma_f32_16x16x32_bf16 v[72:75], v[150:153], v[200:203], v[72:75]
	v_mfma_f32_16x16x32_bf16 v[124:127], v[132:135], v[180:183], v[124:127]
	v_mfma_f32_16x16x32_bf16 v[120:123], v[154:157], v[180:183], v[120:123]
	v_mfma_f32_16x16x32_bf16 v[108:111], v[132:135], v[188:191], v[108:111]
	v_mfma_f32_16x16x32_bf16 v[104:107], v[154:157], v[188:191], v[104:107]
	v_mfma_f32_16x16x32_bf16 v[92:95], v[132:135], v[196:199], v[92:95]
	v_mfma_f32_16x16x32_bf16 v[88:91], v[154:157], v[196:199], v[88:91]
	v_mfma_f32_16x16x32_bf16 v[76:79], v[132:135], v[206:209], v[76:79]
	v_mfma_f32_16x16x32_bf16 v[72:75], v[154:157], v[206:209], v[72:75]
	s_setprio 0
	s_setprio 1
	v_mfma_f32_16x16x32_bf16 v[116:119], v[158:161], v[174:177], v[116:119]
	v_mfma_f32_16x16x32_bf16 v[112:115], v[166:169], v[174:177], v[112:115]
	v_mfma_f32_16x16x32_bf16 v[100:103], v[158:161], v[184:187], v[100:103]
	v_mfma_f32_16x16x32_bf16 v[96:99], v[166:169], v[184:187], v[96:99]
	v_mfma_f32_16x16x32_bf16 v[84:87], v[158:161], v[192:195], v[84:87]
	v_mfma_f32_16x16x32_bf16 v[80:83], v[166:169], v[192:195], v[80:83]
	v_mfma_f32_16x16x32_bf16 v[68:71], v[158:161], v[200:203], v[68:71]
	v_mfma_f32_16x16x32_bf16 v[64:67], v[166:169], v[200:203], v[64:67]
	v_mfma_f32_16x16x32_bf16 v[116:119], v[162:165], v[180:183], v[116:119]
	v_mfma_f32_16x16x32_bf16 v[112:115], v[170:173], v[180:183], v[112:115]
	v_mfma_f32_16x16x32_bf16 v[100:103], v[162:165], v[188:191], v[100:103]
	v_mfma_f32_16x16x32_bf16 v[96:99], v[170:173], v[188:191], v[96:99]
	v_mfma_f32_16x16x32_bf16 v[84:87], v[162:165], v[196:199], v[84:87]
	v_mfma_f32_16x16x32_bf16 v[80:83], v[170:173], v[196:199], v[80:83]
	v_mfma_f32_16x16x32_bf16 v[68:71], v[162:165], v[206:209], v[68:71]
	v_mfma_f32_16x16x32_bf16 v[64:67], v[170:173], v[206:209], v[64:67]
	s_barrier
; #define PG8_STAGE(bufoff, gbase, voff) do { _Pragma("unroll") for (int _i = 0; _i < 2; ++_i) \
;         __builtin_amdgcn_global_load_lds((const unsigned*)((const char*)(gbase) + (voff)[_i]), (PG8_LAS unsigned*)(lds + (bufoff) + ldsw + _i * 8192), 16, 0, 0); } while (0)
; #define PG8_LDA(dst, b, h) do { _Pragma("unroll") for (int m = 0; m < 4; ++m) _Pragma("unroll") for (int k = 0; k < 2; ++k) dst[m][k] = *(const PG8_LAS bf16x8*)(lds + PG8_SA(b, h) + aoff + m * 2048 + k * 1024); } while (0)
; #define PG8_WAIT_V(n) asm volatile("s_waitcnt vmcnt(" #n ")" ::: "memory")
; #define PG8_WAIT_L(n) asm volatile("s_waitcnt lgkmcnt(" #n ")" ::: "memory")
; #define PG8_BAR __builtin_amdgcn_s_barrier()
; template <class Epi, class Sched, bool ALIGN_EPI = false, bool SP2 = false>
; __device__ __forceinline__ void gemm_phase(PG8_LAS unsigned char* lds, const Gemm g, const Sched& S, const Epi& E, const int tid) {
;     ...
;         for (int t = 0; t < nt; t += 2) {
;             const bool last = (t == nt - 2);
;             const char* a1 = cA + (size_t)(t + 1) * kstep;
;             const char* a2 = last ? nA : cA + (size_t)(t + 2) * kstep; const char* b2 = last ? nB : cB + (size_t)(t + 2) * kstep;
;             const char* a3 = a2 + kstep; const char* b3 = b2 + kstep;
;             if (last && has_next) S.a_ready(nxt);
;             if constexpr (SP2) {
;             PG8_LDB(B0, 0, 0); PG8_LDB(B1, 0, 1); PG8_SCHED; PG8_LDA(At, 0, 0); PG8_STAGE(PG8_SA(1, 1), a1 + hstep, voffA);
;             PG8_WAIT_V(8); PG8_WAIT_L(0); PG8_BAR; PG8_MMA(0, 0, At, B0); PG8_MMA(0, 1, At, B1); PG8_BAR; PG8_SCHED;
;             PG8_LDA(At, 0, 1); PG8_STAGE(PG8_SB(0, 0), b2, voffB); PG8_STAGE(PG8_SB(0, 1), b2 + hstep, voffB); PG8_STAGE(PG8_SA(0, 0), a2, voffA);
;             PG8_WAIT_V(8); PG8_WAIT_L(0); PG8_BAR; PG8_MMA(1, 0, At, B0); PG8_MMA(1, 1, At, B1); PG8_BAR; PG8_SCHED;
;             PG8_LDB(B0, 1, 0); PG8_LDB(B1, 1, 1); PG8_SCHED; PG8_LDA(At, 1, 0); PG8_STAGE(PG8_SA(0, 1), a2 + hstep, voffA);
;             PG8_WAIT_V(8); PG8_WAIT_L(0); PG8_BAR; PG8_MMA(0, 0, At, B0); PG8_MMA(0, 1, At, B1); PG8_BAR; PG8_SCHED;
;             PG8_LDA(At, 1, 1); PG8_STAGE(PG8_SB(1, 0), b3, voffB); PG8_STAGE(PG8_SB(1, 1), b3 + hstep, voffB); PG8_STAGE(PG8_SA(1, 0), a3, voffA);
;             PG8_WAIT_V(8); PG8_WAIT_L(0); PG8_BAR; PG8_MMA(1, 0, At, B0); PG8_MMA(1, 1, At, B1); PG8_BAR; PG8_SCHED;
	s_setprio 0
	s_add_i32 s46, s77, s52
	v_lshl_add_u64 v[136:137], v[136:137], 0, s[70:71]
	s_mov_b32 m0, s46
	ds_read_b128 v[174:177], v179 offset:49152
	ds_read_b128 v[180:183], v179 offset:50176
	ds_read_b128 v[184:187], v179 offset:51200
	ds_read_b128 v[188:191], v179 offset:52224
	ds_read_b128 v[192:195], v179 offset:53248
	ds_read_b128 v[196:199], v179 offset:54272
	ds_read_b128 v[200:203], v179 offset:55296
	ds_read_b128 v[206:209], v179 offset:56320
	global_load_lds_dwordx4 v[136:137], off
	s_add_i32 m0, s46, 0x2000
	s_add_u32 s44, s44, 0x80080
	v_lshl_add_u64 v[136:137], v[210:211], 0, s[70:71]
	s_addc_u32 s45, s45, 0
	s_add_i32 s46, s78, s52
	global_load_lds_dwordx4 v[136:137], off
	v_lshl_add_u64 v[136:137], s[44:45], 0, v[140:141]
	s_mov_b32 m0, s46
	s_nop 0
	global_load_lds_dwordx4 v[136:137], off
	v_lshl_add_u64 v[136:137], s[44:45], 0, v[144:145]
	s_add_i32 m0, s46, 0x2000
	s_nop 0
	global_load_lds_dwordx4 v[136:137], off
	v_lshl_add_u64 v[136:137], v[212:213], 0, s[70:71]
	s_mov_b32 m0, s11
	s_nop 0
	global_load_lds_dwordx4 v[136:137], off
	v_lshl_add_u64 v[136:137], v[214:215], 0, s[70:71]
	s_mov_b32 m0, s64
	s_nop 0
	global_load_lds_dwordx4 v[136:137], off
	s_waitcnt vmcnt(8)
	s_waitcnt lgkmcnt(0)
	s_setprio 1
	s_barrier
	v_mfma_f32_16x16x32_bf16 v[60:63], v[128:131], v[174:177], v[60:63]
	v_mfma_f32_16x16x32_bf16 v[56:59], v[150:153], v[174:177], v[56:59]
	v_mfma_f32_16x16x32_bf16 v[44:47], v[128:131], v[184:187], v[44:47]
	v_mfma_f32_16x16x32_bf16 v[40:43], v[150:153], v[184:187], v[40:43]
	v_mfma_f32_16x16x32_bf16 v[28:31], v[128:131], v[192:195], v[28:31]
	v_mfma_f32_16x16x32_bf16 v[24:27], v[150:153], v[192:195], v[24:27]
	v_mfma_f32_16x16x32_bf16 v[12:15], v[128:131], v[200:203], v[12:15]
	v_mfma_f32_16x16x32_bf16 v[8:11], v[150:153], v[200:203], v[8:11]
	v_mfma_f32_16x16x32_bf16 v[60:63], v[132:135], v[180:183], v[60:63]
	v_mfma_f32_16x16x32_bf16 v[56:59], v[154:157], v[180:183], v[56:59]
	v_mfma_f32_16x16x32_bf16 v[44:47], v[132:135], v[188:191], v[44:47]
	v_mfma_f32_16x16x32_bf16 v[40:43], v[154:157], v[188:191], v[40:43]
	v_mfma_f32_16x16x32_bf16 v[28:31], v[132:135], v[196:199], v[28:31]
	v_mfma_f32_16x16x32_bf16 v[24:27], v[154:157], v[196:199], v[24:27]
	v_mfma_f32_16x16x32_bf16 v[12:15], v[132:135], v[206:209], v[12:15]
	v_mfma_f32_16x16x32_bf16 v[8:11], v[154:157], v[206:209], v[8:11]
	s_setprio 0
	s_setprio 1
	v_mfma_f32_16x16x32_bf16 v[52:55], v[158:161], v[174:177], v[52:55]
	v_mfma_f32_16x16x32_bf16 v[48:51], v[166:169], v[174:177], v[48:51]
	v_mfma_f32_16x16x32_bf16 v[36:39], v[158:161], v[184:187], v[36:39]
	v_mfma_f32_16x16x32_bf16 v[32:35], v[166:169], v[184:187], v[32:35]
	v_mfma_f32_16x16x32_bf16 v[20:23], v[158:161], v[192:195], v[20:23]
	v_mfma_f32_16x16x32_bf16 v[16:19], v[166:169], v[192:195], v[16:19]
	v_mfma_f32_16x16x32_bf16 v[4:7], v[158:161], v[200:203], v[4:7]
	v_mfma_f32_16x16x32_bf16 v[0:3], v[166:169], v[200:203], v[0:3]
	v_mfma_f32_16x16x32_bf16 v[52:55], v[162:165], v[180:183], v[52:55]
	v_mfma_f32_16x16x32_bf16 v[48:51], v[170:173], v[180:183], v[48:51]
	v_mfma_f32_16x16x32_bf16 v[36:39], v[162:165], v[188:191], v[36:39]
	v_mfma_f32_16x16x32_bf16 v[32:35], v[170:173], v[188:191], v[32:35]
	v_mfma_f32_16x16x32_bf16 v[20:23], v[162:165], v[196:199], v[20:23]
	v_mfma_f32_16x16x32_bf16 v[16:19], v[170:173], v[196:199], v[16:19]
	v_mfma_f32_16x16x32_bf16 v[4:7], v[162:165], v[206:209], v[4:7]
	v_mfma_f32_16x16x32_bf16 v[0:3], v[170:173], v[206:209], v[0:3]
	s_barrier
	s_setprio 0
	s_add_i32 s76, s76, 2
	s_add_u32 s42, s42, 0x100
	s_addc_u32 s43, s43, 0
	s_add_u32 s69, s69, 0x100
	s_addc_u32 s92, s92, 0
.LBB0_319:
	s_add_u32 s44, s42, 0xfff80080
	s_addc_u32 s45, s43, -1
	s_add_i32 s77, 0, 0x10000
	s_cmp_eq_u32 s76, 28
	s_cselect_b32 s47, s9, s45
	s_cselect_b32 s46, s29, s44
	v_add_u32_e32 v136, s77, v178
	s_cselect_b32 s45, s27, s92
	s_cselect_b32 s44, s37, s69
	s_add_i32 s80, 0, 0x14000
	ds_read_b128 v[128:131], v136
	ds_read_b128 v[132:135], v136 offset:1024
	ds_read_b128 v[150:153], v136 offset:2048
	ds_read_b128 v[154:157], v136 offset:3072
	v_add_u32_e32 v136, s80, v178
	ds_read_b128 v[158:161], v136
	ds_read_b128 v[162:165], v136 offset:1024
	ds_read_b128 v[166:169], v136 offset:2048
	ds_read_b128 v[170:173], v136 offset:3072
	v_lshl_add_u64 v[136:137], s[42:43], 0, v[146:147]
	s_add_i32 m0, s53, 0xc000
	ds_read_b128 v[174:177], v179
	ds_read_b128 v[180:183], v179 offset:1024
	ds_read_b128 v[184:187], v179 offset:2048
	ds_read_b128 v[188:191], v179 offset:3072
	ds_read_b128 v[192:195], v179 offset:4096
	ds_read_b128 v[196:199], v179 offset:5120
	ds_read_b128 v[200:203], v179 offset:6144
	ds_read_b128 v[206:209], v179 offset:7168
	global_load_lds_dwordx4 v[136:137], off
	v_lshl_add_u64 v[136:137], s[42:43], 0, v[148:149]
	s_add_i32 m0, s53, 0xe000
	s_nop 0
	global_load_lds_dwordx4 v[136:137], off
	s_waitcnt vmcnt(8)
	s_waitcnt lgkmcnt(0)
	s_setprio 1
	s_barrier
; #define PG8_STAGE(bufoff, gbase, voff) do { _Pragma("unroll") for (int _i = 0; _i < 2; ++_i) \
;         __builtin_amdgcn_global_load_lds((const unsigned*)((const char*)(gbase) + (voff)[_i]), (PG8_LAS unsigned*)(lds + (bufoff) + ldsw + _i * 8192), 16, 0, 0); } while (0)
; #define PG8_LDA(dst, b, h) do { _Pragma("unroll") for (int m = 0; m < 4; ++m) _Pragma("unroll") for (int k = 0; k < 2; ++k) dst[m][k] = *(const PG8_LAS bf16x8*)(lds + PG8_SA(b, h) + aoff + m * 2048 + k * 1024); } while (0)
; #define PG8_LDB(dst, b, h) do { _Pragma("unroll") for (int n = 0; n < 2; ++n) _Pragma("unroll") for (int k = 0; k < 2; ++k) dst[n][k] = *(const PG8_LAS bf16x8*)(lds + PG8_SB(b, h) + boff + n * 2048 + k * 1024); } while (0)
; #define PG8_MMA(ai, bj, At, Bt) do { __builtin_amdgcn_s_setprio(1); _Pragma("unroll") for (int m = 0; m < 4; ++m) _Pragma("unroll") for (int n = 0; n < 2; ++n) _Pragma("unroll") for (int k = 0; k < 2; ++k) \
;         acc[ai][bj][m][n] = __builtin_amdgcn_mfma_f32_16x16x32_bf16(Bt[n][k], At[m][k], acc[ai][bj][m][n], 0, 0, 0); __builtin_amdgcn_s_setprio(0); } while (0)
; #define PG8_BAR __builtin_amdgcn_s_barrier()
; template <class Epi, class Sched, bool ALIGN_EPI = false, bool SP2 = false>
; __device__ __forceinline__ void gemm_phase(PG8_LAS unsigned char* lds, const Gemm g, const Sched& S, const Epi& E, const int tid) {
;     ...
;             PG8_LDB(B0, 0, 0); PG8_LDB(B1, 0, 1); PG8_SCHED; PG8_LDA(At, 0, 0); PG8_STAGE(PG8_SA(1, 1), a1 + hstep, voffA);
;             PG8_WAIT_V(8); PG8_WAIT_L(0); PG8_BAR; PG8_MMA(0, 0, At, B0); PG8_MMA(0, 1, At, B1); PG8_BAR; PG8_SCHED;
;             PG8_LDA(At, 0, 1); PG8_STAGE(PG8_SB(0, 0), b2, voffB); PG8_STAGE(PG8_SB(0, 1), b2 + hstep, voffB); PG8_STAGE(PG8_SA(0, 0), a2, voffA);
;             PG8_WAIT_V(8); PG8_WAIT_L(0); PG8_BAR; PG8_MMA(1, 0, At, B0); PG8_MMA(1, 1, At, B1); PG8_BAR; PG8_SCHED;
;             PG8_LDB(B0, 1, 0); PG8_LDB(B1, 1, 1); PG8_SCHED; PG8_LDA(At, 1, 0); PG8_STAGE(PG8_SA(0, 1), a2 + hstep, voffA);
;             PG8_WAIT_V(8); PG8_WAIT_L(0); PG8_BAR; PG8_MMA(0, 0, At, B0); PG8_MMA(0, 1, At, B1); PG8_BAR; PG8_SCHED;
;             PG8_LDA(At, 1, 1); PG8_STAGE(PG8_SB(1, 0), b3, voffB); PG8_STAGE(PG8_SB(1, 1), b3 + hstep, voffB); PG8_STAGE(PG8_SA(1, 0), a3, voffA);
;             PG8_WAIT_V(8); PG8_WAIT_L(0); PG8_BAR; PG8_MMA(1, 0, At, B0); PG8_MMA(1, 1, At, B1); PG8_BAR; PG8_SCHED;
	v_mfma_f32_16x16x32_bf16 v[124:127], v[128:131], v[174:177], v[124:127]
	v_mfma_f32_16x16x32_bf16 v[120:123], v[150:153], v[174:177], v[120:123]
	v_mfma_f32_16x16x32_bf16 v[108:111], v[128:131], v[184:187], v[108:111]
	v_mfma_f32_16x16x32_bf16 v[104:107], v[150:153], v[184:187], v[104:107]
	v_mfma_f32_16x16x32_bf16 v[92:95], v[128:131], v[192:195], v[92:95]
	v_mfma_f32_16x16x32_bf16 v[88:91], v[150:153], v[192:195], v[88:91]
	v_mfma_f32_16x16x32_bf16 v[76:79], v[128:131], v[200:203], v[76:79]
	v_mfma_f32_16x16x32_bf16 v[72:75], v[150:153], v[200:203], v[72:75]
	v_mfma_f32_16x16x32_bf16 v[124:127], v[132:135], v[180:183], v[124:127]
	v_mfma_f32_16x16x32_bf16 v[120:123], v[154:157], v[180:183], v[120:123]
	v_mfma_f32_16x16x32_bf16 v[108:111], v[132:135], v[188:191], v[108:111]
	v_mfma_f32_16x16x32_bf16 v[104:107], v[154:157], v[188:191], v[104:107]
	v_mfma_f32_16x16x32_bf16 v[92:95], v[132:135], v[196:199], v[92:95]
	v_mfma_f32_16x16x32_bf16 v[88:91], v[154:157], v[196:199], v[88:91]
	v_mfma_f32_16x16x32_bf16 v[76:79], v[132:135], v[206:209], v[76:79]
	v_mfma_f32_16x16x32_bf16 v[72:75], v[154:157], v[206:209], v[72:75]
	s_setprio 0
	s_setprio 1
	v_mfma_f32_16x16x32_bf16 v[116:119], v[158:161], v[174:177], v[116:119]
	v_mfma_f32_16x16x32_bf16 v[112:115], v[166:169], v[174:177], v[112:115]
	v_mfma_f32_16x16x32_bf16 v[100:103], v[158:161], v[184:187], v[100:103]
	v_mfma_f32_16x16x32_bf16 v[96:99], v[166:169], v[184:187], v[96:99]
	v_mfma_f32_16x16x32_bf16 v[84:87], v[158:161], v[192:195], v[84:87]
	v_mfma_f32_16x16x32_bf16 v[80:83], v[166:169], v[192:195], v[80:83]
	v_mfma_f32_16x16x32_bf16 v[68:71], v[158:161], v[200:203], v[68:71]
	v_mfma_f32_16x16x32_bf16 v[64:67], v[166:169], v[200:203], v[64:67]
	v_mfma_f32_16x16x32_bf16 v[116:119], v[162:165], v[180:183], v[116:119]
	v_mfma_f32_16x16x32_bf16 v[112:115], v[170:173], v[180:183], v[112:115]
	v_mfma_f32_16x16x32_bf16 v[100:103], v[162:165], v[188:191], v[100:103]
	v_mfma_f32_16x16x32_bf16 v[96:99], v[170:173], v[188:191], v[96:99]
	v_mfma_f32_16x16x32_bf16 v[84:87], v[162:165], v[196:199], v[84:87]
	v_mfma_f32_16x16x32_bf16 v[80:83], v[170:173], v[196:199], v[80:83]
	v_mfma_f32_16x16x32_bf16 v[68:71], v[162:165], v[206:209], v[68:71]
	v_mfma_f32_16x16x32_bf16 v[64:67], v[170:173], v[206:209], v[64:67]
	s_barrier
	s_setprio 0
	s_add_i32 s77, s77, s52
	v_lshl_add_u64 v[136:137], s[44:45], 0, v[140:141]
	s_mov_b32 m0, s77
	ds_read_b128 v[174:177], v179 offset:16384
	ds_read_b128 v[180:183], v179 offset:17408
	ds_read_b128 v[184:187], v179 offset:18432
	ds_read_b128 v[188:191], v179 offset:19456
	ds_read_b128 v[192:195], v179 offset:20480
	ds_read_b128 v[196:199], v179 offset:21504
	ds_read_b128 v[200:203], v179 offset:22528
	ds_read_b128 v[206:209], v179 offset:23552
	global_load_lds_dwordx4 v[136:137], off
	s_add_i32 m0, s77, 0x2000
	s_add_u32 s78, s44, 0x80000
	v_lshl_add_u64 v[210:211], s[44:45], 0, v[144:145]
	s_addc_u32 s79, s45, 0
	s_add_i32 s77, s80, s52
	global_load_lds_dwordx4 v[210:211], off
	v_lshl_add_u64 v[212:213], s[78:79], 0, v[140:141]
	s_mov_b32 m0, s77
	v_lshl_add_u64 v[214:215], s[46:47], 0, v[142:143]
	global_load_lds_dwordx4 v[212:213], off
	v_lshl_add_u64 v[212:213], s[78:79], 0, v[144:145]
	s_add_i32 m0, s77, 0x2000
	s_nop 0
	global_load_lds_dwordx4 v[212:213], off
	v_lshl_add_u64 v[212:213], s[46:47], 0, v[138:139]
	s_mov_b32 m0, s53
	s_nop 0
	global_load_lds_dwordx4 v[212:213], off
	s_mov_b32 m0, s54
	s_nop 0
	global_load_lds_dwordx4 v[214:215], off
	s_waitcnt vmcnt(8)
	s_waitcnt lgkmcnt(0)
	s_setprio 1
	s_barrier
	v_mfma_f32_16x16x32_bf16 v[60:63], v[128:131], v[174:177], v[60:63]
	v_mfma_f32_16x16x32_bf16 v[56:59], v[150:153], v[174:177], v[56:59]
	v_mfma_f32_16x16x32_bf16 v[44:47], v[128:131], v[184:187], v[44:47]
	v_mfma_f32_16x16x32_bf16 v[40:43], v[150:153], v[184:187], v[40:43]
	v_mfma_f32_16x16x32_bf16 v[28:31], v[128:131], v[192:195], v[28:31]
	v_mfma_f32_16x16x32_bf16 v[24:27], v[150:153], v[192:195], v[24:27]
	v_mfma_f32_16x16x32_bf16 v[12:15], v[128:131], v[200:203], v[12:15]
	v_mfma_f32_16x16x32_bf16 v[8:11], v[150:153], v[200:203], v[8:11]
	v_mfma_f32_16x16x32_bf16 v[60:63], v[132:135], v[180:183], v[60:63]
	v_mfma_f32_16x16x32_bf16 v[56:59], v[154:157], v[180:183], v[56:59]
	v_mfma_f32_16x16x32_bf16 v[44:47], v[132:135], v[188:191], v[44:47]
	v_mfma_f32_16x16x32_bf16 v[40:43], v[154:157], v[188:191], v[40:43]
	v_mfma_f32_16x16x32_bf16 v[28:31], v[132:135], v[196:199], v[28:31]
	v_mfma_f32_16x16x32_bf16 v[24:27], v[154:157], v[196:199], v[24:27]
	v_mfma_f32_16x16x32_bf16 v[12:15], v[132:135], v[206:209], v[12:15]
	v_mfma_f32_16x16x32_bf16 v[8:11], v[154:157], v[206:209], v[8:11]
	s_setprio 0
	s_setprio 1
	v_mfma_f32_16x16x32_bf16 v[52:55], v[158:161], v[174:177], v[52:55]
	v_mfma_f32_16x16x32_bf16 v[48:51], v[166:169], v[174:177], v[48:51]
	v_mfma_f32_16x16x32_bf16 v[36:39], v[158:161], v[184:187], v[36:39]
	v_mfma_f32_16x16x32_bf16 v[32:35], v[166:169], v[184:187], v[32:35]
	v_mfma_f32_16x16x32_bf16 v[20:23], v[158:161], v[192:195], v[20:23]
	v_mfma_f32_16x16x32_bf16 v[16:19], v[166:169], v[192:195], v[16:19]
	v_mfma_f32_16x16x32_bf16 v[4:7], v[158:161], v[200:203], v[4:7]
	v_mfma_f32_16x16x32_bf16 v[0:3], v[166:169], v[200:203], v[0:3]
	v_mfma_f32_16x16x32_bf16 v[52:55], v[162:165], v[180:183], v[52:55]
	v_mfma_f32_16x16x32_bf16 v[48:51], v[170:173], v[180:183], v[48:51]
	v_mfma_f32_16x16x32_bf16 v[36:39], v[162:165], v[188:191], v[36:39]
	v_mfma_f32_16x16x32_bf16 v[32:35], v[170:173], v[188:191], v[32:35]
	v_mfma_f32_16x16x32_bf16 v[20:23], v[162:165], v[196:199], v[20:23]
	v_mfma_f32_16x16x32_bf16 v[16:19], v[170:173], v[196:199], v[16:19]
	v_mfma_f32_16x16x32_bf16 v[4:7], v[162:165], v[206:209], v[4:7]
	v_mfma_f32_16x16x32_bf16 v[0:3], v[170:173], v[206:209], v[0:3]
	s_barrier
; #define PG8_STAGE(bufoff, gbase, voff) do { _Pragma("unroll") for (int _i = 0; _i < 2; ++_i) \
;         __builtin_amdgcn_global_load_lds((const unsigned*)((const char*)(gbase) + (voff)[_i]), (PG8_LAS unsigned*)(lds + (bufoff) + ldsw + _i * 8192), 16, 0, 0); } while (0)
; #define PG8_LDA(dst, b, h) do { _Pragma("unroll") for (int m = 0; m < 4; ++m) _Pragma("unroll") for (int k = 0; k < 2; ++k) dst[m][k] = *(const PG8_LAS bf16x8*)(lds + PG8_SA(b, h) + aoff + m * 2048 + k * 1024); } while (0)
; #define PG8_LDB(dst, b, h) do { _Pragma("unroll") for (int n = 0; n < 2; ++n) _Pragma("unroll") for (int k = 0; k < 2; ++k) dst[n][k] = *(const PG8_LAS bf16x8*)(lds + PG8_SB(b, h) + boff + n * 2048 + k * 1024); } while (0)
; #define PG8_MMA(ai, bj, At, Bt) do { __builtin_amdgcn_s_setprio(1); _Pragma("unroll") for (int m = 0; m < 4; ++m) _Pragma("unroll") for (int n = 0; n < 2; ++n) _Pragma("unroll") for (int k = 0; k < 2; ++k) \
;         acc[ai][bj][m][n] = __builtin_amdgcn_mfma_f32_16x16x32_bf16(Bt[n][k], At[m][k], acc[ai][bj][m][n], 0, 0, 0); __builtin_amdgcn_s_setprio(0); } while (0)
; #define PG8_WAIT_V(n) asm volatile("s_waitcnt vmcnt(" #n ")" ::: "memory")
; #define PG8_WAIT_L(n) asm volatile("s_waitcnt lgkmcnt(" #n ")" ::: "memory")
; #define PG8_BAR __builtin_amdgcn_s_barrier()
; #define PG8_SCHED __builtin_amdgcn_sched_barrier(0)
; template <class Epi, class Sched, bool ALIGN_EPI = false, bool SP2 = false>
; __device__ __forceinline__ void gemm_phase(PG8_LAS unsigned char* lds, const Gemm g, const Sched& S, const Epi& E, const int tid) {
;     ...
;             PG8_LDB(B0, 1, 0); PG8_LDB(B1, 1, 1); PG8_SCHED; PG8_LDA(At, 1, 0); PG8_STAGE(PG8_SA(0, 1), a2 + hstep, voffA);
;             PG8_WAIT_V(8); PG8_WAIT_L(0); PG8_BAR; PG8_MMA(0, 0, At, B0); PG8_MMA(0, 1, At, B1); PG8_BAR; PG8_SCHED;
;             PG8_LDA(At, 1, 1); PG8_STAGE(PG8_SB(1, 0), b3, voffB); PG8_STAGE(PG8_SB(1, 1), b3 + hstep, voffB); PG8_STAGE(PG8_SA(1, 0), a3, voffA);
;             PG8_WAIT_V(8); PG8_WAIT_L(0); PG8_BAR; PG8_MMA(1, 0, At, B0); PG8_MMA(1, 1, At, B1); PG8_BAR; PG8_SCHED;
	s_setprio 0
	s_add_i32 s77, 0, 0x18000
	s_add_i32 s78, 0, 0x1c000
	v_add_u32_e32 v154, s77, v178
	v_add_u32_e32 v170, s78, v178
	ds_read_b128 v[128:131], v154
	ds_read_b128 v[132:135], v154 offset:1024
	ds_read_b128 v[150:153], v154 offset:2048
	ds_read_b128 v[154:157], v154 offset:3072
	ds_read_b128 v[158:161], v170
	ds_read_b128 v[162:165], v170 offset:1024
	ds_read_b128 v[166:169], v170 offset:2048
	ds_read_b128 v[170:173], v170 offset:3072
	s_add_u32 s46, s46, 0x80000
	s_addc_u32 s47, s47, 0
	s_mov_b32 m0, s55
	v_lshl_add_u64 v[216:217], s[46:47], 0, v[138:139]
	ds_read_b128 v[174:177], v179 offset:32768
	ds_read_b128 v[180:183], v179 offset:33792
	ds_read_b128 v[184:187], v179 offset:34816
	ds_read_b128 v[188:191], v179 offset:35840
	ds_read_b128 v[192:195], v179 offset:36864
	ds_read_b128 v[196:199], v179 offset:37888
	ds_read_b128 v[200:203], v179 offset:38912
	ds_read_b128 v[206:209], v179 offset:39936
	global_load_lds_dwordx4 v[216:217], off
	v_lshl_add_u64 v[216:217], s[46:47], 0, v[142:143]
	s_mov_b32 m0, s0
	s_nop 0
	global_load_lds_dwordx4 v[216:217], off
	s_waitcnt vmcnt(8)
	s_waitcnt lgkmcnt(0)
	s_setprio 1
	s_barrier
	v_mfma_f32_16x16x32_bf16 v[124:127], v[128:131], v[174:177], v[124:127]
	v_mfma_f32_16x16x32_bf16 v[120:123], v[150:153], v[174:177], v[120:123]
	v_mfma_f32_16x16x32_bf16 v[108:111], v[128:131], v[184:187], v[108:111]
	v_mfma_f32_16x16x32_bf16 v[104:107], v[150:153], v[184:187], v[104:107]
	v_mfma_f32_16x16x32_bf16 v[92:95], v[128:131], v[192:195], v[92:95]
	v_mfma_f32_16x16x32_bf16 v[88:91], v[150:153], v[192:195], v[88:91]
	v_mfma_f32_16x16x32_bf16 v[76:79], v[128:131], v[200:203], v[76:79]
	v_mfma_f32_16x16x32_bf16 v[72:75], v[150:153], v[200:203], v[72:75]
	v_mfma_f32_16x16x32_bf16 v[124:127], v[132:135], v[180:183], v[124:127]
	v_mfma_f32_16x16x32_bf16 v[120:123], v[154:157], v[180:183], v[120:123]
	v_mfma_f32_16x16x32_bf16 v[108:111], v[132:135], v[188:191], v[108:111]
	v_mfma_f32_16x16x32_bf16 v[104:107], v[154:157], v[188:191], v[104:107]
	v_mfma_f32_16x16x32_bf16 v[92:95], v[132:135], v[196:199], v[92:95]
	v_mfma_f32_16x16x32_bf16 v[88:91], v[154:157], v[196:199], v[88:91]
	v_mfma_f32_16x16x32_bf16 v[76:79], v[132:135], v[206:209], v[76:79]
	v_mfma_f32_16x16x32_bf16 v[72:75], v[154:157], v[206:209], v[72:75]
	s_setprio 0
	s_setprio 1
	v_mfma_f32_16x16x32_bf16 v[116:119], v[158:161], v[174:177], v[116:119]
	v_mfma_f32_16x16x32_bf16 v[112:115], v[166:169], v[174:177], v[112:115]
	v_mfma_f32_16x16x32_bf16 v[100:103], v[158:161], v[184:187], v[100:103]
	v_mfma_f32_16x16x32_bf16 v[96:99], v[166:169], v[184:187], v[96:99]
	v_mfma_f32_16x16x32_bf16 v[84:87], v[158:161], v[192:195], v[84:87]
	v_mfma_f32_16x16x32_bf16 v[80:83], v[166:169], v[192:195], v[80:83]
	v_mfma_f32_16x16x32_bf16 v[68:71], v[158:161], v[200:203], v[68:71]
	v_mfma_f32_16x16x32_bf16 v[64:67], v[166:169], v[200:203], v[64:67]
	v_mfma_f32_16x16x32_bf16 v[116:119], v[162:165], v[180:183], v[116:119]
	v_mfma_f32_16x16x32_bf16 v[112:115], v[170:173], v[180:183], v[112:115]
	v_mfma_f32_16x16x32_bf16 v[100:103], v[162:165], v[188:191], v[100:103]
	v_mfma_f32_16x16x32_bf16 v[96:99], v[170:173], v[188:191], v[96:99]
	v_mfma_f32_16x16x32_bf16 v[84:87], v[162:165], v[196:199], v[84:87]
	v_mfma_f32_16x16x32_bf16 v[80:83], v[170:173], v[196:199], v[80:83]
	v_mfma_f32_16x16x32_bf16 v[68:71], v[162:165], v[206:209], v[68:71]
	v_mfma_f32_16x16x32_bf16 v[64:67], v[170:173], v[206:209], v[64:67]
	s_barrier
; #define PG8_STAGE(bufoff, gbase, voff) do { _Pragma("unroll") for (int _i = 0; _i < 2; ++_i) \
;         __builtin_amdgcn_global_load_lds((const unsigned*)((const char*)(gbase) + (voff)[_i]), (PG8_LAS unsigned*)(lds + (bufoff) + ldsw + _i * 8192), 16, 0, 0); } while (0)
; #define PG8_WAIT_V(n) asm volatile("s_waitcnt vmcnt(" #n ")" ::: "memory")
; #define PG8_WAIT_L(n) asm volatile("s_waitcnt lgkmcnt(" #n ")" ::: "memory")
; template <class Epi, class Sched, bool ALIGN_EPI = false, bool SP2 = false>
; __device__ __forceinline__ void gemm_phase(PG8_LAS unsigned char* lds, const Gemm g, const Sched& S, const Epi& E, const int tid) {
;     ...
;             PG8_WAIT_V(8); PG8_WAIT_L(0); PG8_BAR; PG8_MMA(0, 0, At, B0); PG8_MMA(0, 1, At, B1); PG8_BAR; PG8_SCHED;
;             PG8_LDA(At, 1, 1); PG8_STAGE(PG8_SB(1, 0), b3, voffB); PG8_STAGE(PG8_SB(1, 1), b3 + hstep, voffB); PG8_STAGE(PG8_SA(1, 0), a3, voffA);
;             PG8_WAIT_V(8); PG8_WAIT_L(0); PG8_BAR; PG8_MMA(1, 0, At, B0); PG8_MMA(1, 1, At, B1); PG8_BAR; PG8_SCHED;
;             } else {
;             PG8_LDB(B0, 0, 0); PG8_SCHED; PG8_LDA(At, 0, 0); PG8_STAGE(PG8_SA(1, 1), a1 + hstep, voffA);
;             PG8_WAIT_L(8); PG8_BAR; PG8_WAIT_L(0); PG8_MMA(0, 0, At, B0); PG8_BAR; PG8_SCHED;
;             PG8_LDB(B1, 0, 1); PG8_STAGE(PG8_SB(0, 0), b2, voffB);
;             PG8_BAR; PG8_WAIT_L(0); PG8_MMA(0, 1, At, B1); PG8_BAR;
;             PG8_LDA(At, 0, 1); PG8_STAGE(PG8_SA(0, 0), a2, voffA);
;             PG8_BAR; PG8_WAIT_L(0); PG8_MMA(1, 0, At, B0); PG8_BAR; PG8_SCHED;
;             PG8_STAGE(PG8_SB(0, 1), b2 + hstep, voffB);
;             PG8_WAIT_V(6); PG8_BAR; PG8_MMA(1, 1, At, B1); PG8_BAR;
;             PG8_LDB(B0, 1, 0); PG8_SCHED; PG8_LDA(At, 1, 0); PG8_STAGE(PG8_SA(0, 1), a2 + hstep, voffA);
;             PG8_WAIT_L(8); PG8_BAR; PG8_WAIT_L(0); PG8_MMA(0, 0, At, B0); PG8_BAR; PG8_SCHED;
;             PG8_LDB(B1, 1, 1); PG8_STAGE(PG8_SB(1, 0), b3, voffB);
;             PG8_BAR; PG8_WAIT_L(0); PG8_MMA(0, 1, At, B1); PG8_BAR;
;             PG8_LDA(At, 1, 1); PG8_STAGE(PG8_SA(1, 0), a3, voffA);
;             PG8_BAR; PG8_WAIT_L(0); PG8_MMA(1, 0, At, B0); PG8_BAR; PG8_SCHED;
;             PG8_STAGE(PG8_SB(1, 1), b3 + hstep, voffB);
;             PG8_WAIT_V(6); PG8_BAR; PG8_MMA(1, 1, At, B1); PG8_BAR;
;             }
;         }
;         if constexpr (ALIGN_EPI) { if (wr == 0) PG8_BAR; }
	s_setprio 0
	s_add_i32 s46, s77, s52
	v_lshl_add_u64 v[136:137], v[136:137], 0, s[70:71]
	s_mov_b32 m0, s46
	ds_read_b128 v[174:177], v179 offset:49152
	ds_read_b128 v[180:183], v179 offset:50176
	ds_read_b128 v[184:187], v179 offset:51200
	ds_read_b128 v[188:191], v179 offset:52224
	ds_read_b128 v[192:195], v179 offset:53248
	ds_read_b128 v[196:199], v179 offset:54272
	ds_read_b128 v[200:203], v179 offset:55296
	ds_read_b128 v[206:209], v179 offset:56320
	global_load_lds_dwordx4 v[136:137], off
	s_add_i32 m0, s46, 0x2000
	s_add_u32 s44, s44, 0x80080
	v_lshl_add_u64 v[136:137], v[210:211], 0, s[70:71]
	s_addc_u32 s45, s45, 0
	s_add_i32 s46, s78, s52
	global_load_lds_dwordx4 v[136:137], off
	v_lshl_add_u64 v[136:137], s[44:45], 0, v[140:141]
	s_mov_b32 m0, s46
	s_nop 0
	global_load_lds_dwordx4 v[136:137], off
	v_lshl_add_u64 v[136:137], s[44:45], 0, v[144:145]
	s_add_i32 m0, s46, 0x2000
	s_nop 0
	global_load_lds_dwordx4 v[136:137], off
	v_lshl_add_u64 v[136:137], v[212:213], 0, s[70:71]
	s_mov_b32 m0, s11
	s_nop 0
	global_load_lds_dwordx4 v[136:137], off
	v_lshl_add_u64 v[136:137], v[214:215], 0, s[70:71]
	s_mov_b32 m0, s64
	s_nop 0
	global_load_lds_dwordx4 v[136:137], off
	s_waitcnt vmcnt(8)
	s_waitcnt lgkmcnt(0)
	s_setprio 1
	s_barrier
	v_mfma_f32_16x16x32_bf16 v[60:63], v[128:131], v[174:177], v[60:63]
	v_mfma_f32_16x16x32_bf16 v[56:59], v[150:153], v[174:177], v[56:59]
	v_mfma_f32_16x16x32_bf16 v[44:47], v[128:131], v[184:187], v[44:47]
	v_mfma_f32_16x16x32_bf16 v[40:43], v[150:153], v[184:187], v[40:43]
	v_mfma_f32_16x16x32_bf16 v[28:31], v[128:131], v[192:195], v[28:31]
	v_mfma_f32_16x16x32_bf16 v[24:27], v[150:153], v[192:195], v[24:27]
	v_mfma_f32_16x16x32_bf16 v[12:15], v[128:131], v[200:203], v[12:15]
	v_mfma_f32_16x16x32_bf16 v[8:11], v[150:153], v[200:203], v[8:11]
	v_mfma_f32_16x16x32_bf16 v[60:63], v[132:135], v[180:183], v[60:63]
	v_mfma_f32_16x16x32_bf16 v[56:59], v[154:157], v[180:183], v[56:59]
	v_mfma_f32_16x16x32_bf16 v[44:47], v[132:135], v[188:191], v[44:47]
	v_mfma_f32_16x16x32_bf16 v[40:43], v[154:157], v[188:191], v[40:43]
	v_mfma_f32_16x16x32_bf16 v[28:31], v[132:135], v[196:199], v[28:31]
	v_mfma_f32_16x16x32_bf16 v[24:27], v[154:157], v[196:199], v[24:27]
	v_mfma_f32_16x16x32_bf16 v[12:15], v[132:135], v[206:209], v[12:15]
	v_mfma_f32_16x16x32_bf16 v[8:11], v[154:157], v[206:209], v[8:11]
	s_setprio 0
	s_setprio 1
	v_mfma_f32_16x16x32_bf16 v[52:55], v[158:161], v[174:177], v[52:55]
	v_mfma_f32_16x16x32_bf16 v[48:51], v[166:169], v[174:177], v[48:51]
	v_mfma_f32_16x16x32_bf16 v[36:39], v[158:161], v[184:187], v[36:39]
	v_mfma_f32_16x16x32_bf16 v[32:35], v[166:169], v[184:187], v[32:35]
	v_mfma_f32_16x16x32_bf16 v[20:23], v[158:161], v[192:195], v[20:23]
	v_mfma_f32_16x16x32_bf16 v[16:19], v[166:169], v[192:195], v[16:19]
	v_mfma_f32_16x16x32_bf16 v[4:7], v[158:161], v[200:203], v[4:7]
	v_mfma_f32_16x16x32_bf16 v[0:3], v[166:169], v[200:203], v[0:3]
	v_mfma_f32_16x16x32_bf16 v[52:55], v[162:165], v[180:183], v[52:55]
	v_mfma_f32_16x16x32_bf16 v[48:51], v[170:173], v[180:183], v[48:51]
	v_mfma_f32_16x16x32_bf16 v[36:39], v[162:165], v[188:191], v[36:39]
	v_mfma_f32_16x16x32_bf16 v[32:35], v[170:173], v[188:191], v[32:35]
	v_mfma_f32_16x16x32_bf16 v[20:23], v[162:165], v[196:199], v[20:23]
	v_mfma_f32_16x16x32_bf16 v[16:19], v[170:173], v[196:199], v[16:19]
	v_mfma_f32_16x16x32_bf16 v[4:7], v[162:165], v[206:209], v[4:7]
	v_mfma_f32_16x16x32_bf16 v[0:3], v[170:173], v[206:209], v[0:3]
	s_barrier
	s_setprio 0
	s_add_i32 s76, s76, 2
	s_add_u32 s42, s42, 0x100
	s_addc_u32 s43, s43, 0
	s_add_u32 s69, s69, 0x100
	s_addc_u32 s92, s92, 0
	s_cmp_gt_u32 s76, 29
	s_cbranch_scc0 .LBB0_319
	s_and_b64 vcc, exec, s[24:25]
	s_cbranch_vccz .LBB0_322
	s_barrier

; #define PG8_STAGE(bufoff, gbase, voff) do { _Pragma("unroll") for (int _i = 0; _i < 2; ++_i) \
;         __builtin_amdgcn_global_load_lds((const unsigned*)((const char*)(gbase) + (voff)[_i]), (PG8_LAS unsigned*)(lds + (bufoff) + ldsw + _i * 8192), 16, 0, 0); } while (0)
; #define PG8_LDA(dst, b, h) do { _Pragma("unroll") for (int m = 0; m < 4; ++m) _Pragma("unroll") for (int k = 0; k < 2; ++k) dst[m][k] = *(const PG8_LAS bf16x8*)(lds + PG8_SA(b, h) + aoff + m * 2048 + k * 1024); } while (0)
; #define PG8_LDB(dst, b, h) do { _Pragma("unroll") for (int n = 0; n < 2; ++n) _Pragma("unroll") for (int k = 0; k < 2; ++k) dst[n][k] = *(const PG8_LAS bf16x8*)(lds + PG8_SB(b, h) + boff + n * 2048 + k * 1024); } while (0)
; #define PG8_MMA(ai, bj, At, Bt) do { __builtin_amdgcn_s_setprio(1); _Pragma("unroll") for (int m = 0; m < 4; ++m) _Pragma("unroll") for (int n = 0; n < 2; ++n) _Pragma("unroll") for (int k = 0; k < 2; ++k) \
;         acc[ai][bj][m][n] = __builtin_amdgcn_mfma_f32_16x16x32_bf16(Bt[n][k], At[m][k], acc[ai][bj][m][n], 0, 0, 0); __builtin_amdgcn_s_setprio(0); } while (0)
; #define PG8_BAR __builtin_amdgcn_s_barrier()
; template <class Epi, class Sched, bool ALIGN_EPI = false, bool SP2 = false>
; __device__ __forceinline__ void gemm_phase(PG8_LAS unsigned char* lds, const Gemm g, const Sched& S, const Epi& E, const int tid) {
;     ...
;             PG8_LDB(B0, 0, 0); PG8_LDB(B1, 0, 1); PG8_SCHED; PG8_LDA(At, 0, 0); PG8_STAGE(PG8_SA(1, 1), a1 + hstep, voffA);
;             PG8_WAIT_V(8); PG8_WAIT_L(0); PG8_BAR; PG8_MMA(0, 0, At, B0); PG8_MMA(0, 1, At, B1); PG8_BAR; PG8_SCHED;
;             PG8_LDA(At, 0, 1); PG8_STAGE(PG8_SB(0, 0), b2, voffB); PG8_STAGE(PG8_SB(0, 1), b2 + hstep, voffB); PG8_STAGE(PG8_SA(0, 0), a2, voffA);
;             PG8_WAIT_V(8); PG8_WAIT_L(0); PG8_BAR; PG8_MMA(1, 0, At, B0); PG8_MMA(1, 1, At, B1); PG8_BAR; PG8_SCHED;
;             PG8_LDB(B0, 1, 0); PG8_LDB(B1, 1, 1); PG8_SCHED; PG8_LDA(At, 1, 0); PG8_STAGE(PG8_SA(0, 1), a2 + hstep, voffA);
;             PG8_WAIT_V(8); PG8_WAIT_L(0); PG8_BAR; PG8_MMA(0, 0, At, B0); PG8_MMA(0, 1, At, B1); PG8_BAR; PG8_SCHED;
;             PG8_LDA(At, 1, 1); PG8_STAGE(PG8_SB(1, 0), b3, voffB); PG8_STAGE(PG8_SB(1, 1), b3 + hstep, voffB); PG8_STAGE(PG8_SA(1, 0), a3, voffA);
;             PG8_WAIT_V(8); PG8_WAIT_L(0); PG8_BAR; PG8_MMA(1, 0, At, B0); PG8_MMA(1, 1, At, B1); PG8_BAR; PG8_SCHED;
.LBB0_583:
	s_add_u32 s30, s34, 0xfffc0080
	s_addc_u32 s31, s35, -1
	s_add_i32 s69, 0, 0x10000
	s_cmp_eq_u32 s68, 12
	s_cselect_b32 s37, s21, s31
	s_cselect_b32 s36, s40, s30
	s_cselect_b32 s31, s19, s65
	s_cselect_b32 s30, s62, s64
	s_add_i32 s75, 0, 0x14000
	v_add_u32_e32 v140, s69, v216
	v_add_u32_e32 v156, s75, v216
	ds_read_b128 v[128:131], v140
	ds_read_b128 v[132:135], v140 offset:1024
	ds_read_b128 v[136:139], v140 offset:2048
	ds_read_b128 v[140:143], v140 offset:3072
	ds_read_b128 v[144:147], v156
	ds_read_b128 v[148:151], v156 offset:1024
	ds_read_b128 v[152:155], v156 offset:2048
	ds_read_b128 v[156:159], v156 offset:3072
	v_lshl_add_u64 v[202:203], s[34:35], 0, v[198:199]
	s_add_i32 m0, s46, 0xc000
	ds_read_b128 v[160:163], v217
	ds_read_b128 v[164:167], v217 offset:1024
	ds_read_b128 v[168:171], v217 offset:2048
	ds_read_b128 v[172:175], v217 offset:3072
	ds_read_b128 v[176:179], v217 offset:4096
	ds_read_b128 v[180:183], v217 offset:5120
	ds_read_b128 v[184:187], v217 offset:6144
	ds_read_b128 v[188:191], v217 offset:7168
	global_load_lds_dwordx4 v[202:203], off
	v_lshl_add_u64 v[202:203], s[34:35], 0, v[200:201]
	s_add_i32 m0, s46, 0xe000
	s_nop 0
	global_load_lds_dwordx4 v[202:203], off
	s_waitcnt vmcnt(8)
	s_waitcnt lgkmcnt(0)
	s_setprio 1
	s_barrier
	v_mfma_f32_16x16x32_bf16 v[120:123], v[128:131], v[160:163], v[120:123]
	v_mfma_f32_16x16x32_bf16 v[124:127], v[136:139], v[160:163], v[124:127]
	v_mfma_f32_16x16x32_bf16 v[104:107], v[128:131], v[168:171], v[104:107]
	v_mfma_f32_16x16x32_bf16 v[108:111], v[136:139], v[168:171], v[108:111]
	v_mfma_f32_16x16x32_bf16 v[88:91], v[128:131], v[176:179], v[88:91]
	v_mfma_f32_16x16x32_bf16 v[92:95], v[136:139], v[176:179], v[92:95]
	v_mfma_f32_16x16x32_bf16 v[72:75], v[128:131], v[184:187], v[72:75]
	v_mfma_f32_16x16x32_bf16 v[76:79], v[136:139], v[184:187], v[76:79]
	v_mfma_f32_16x16x32_bf16 v[120:123], v[132:135], v[164:167], v[120:123]
	v_mfma_f32_16x16x32_bf16 v[124:127], v[140:143], v[164:167], v[124:127]
	v_mfma_f32_16x16x32_bf16 v[104:107], v[132:135], v[172:175], v[104:107]
	v_mfma_f32_16x16x32_bf16 v[108:111], v[140:143], v[172:175], v[108:111]
	v_mfma_f32_16x16x32_bf16 v[88:91], v[132:135], v[180:183], v[88:91]
	v_mfma_f32_16x16x32_bf16 v[92:95], v[140:143], v[180:183], v[92:95]
	v_mfma_f32_16x16x32_bf16 v[72:75], v[132:135], v[188:191], v[72:75]
	v_mfma_f32_16x16x32_bf16 v[76:79], v[140:143], v[188:191], v[76:79]
	s_setprio 0
	s_setprio 1
	v_mfma_f32_16x16x32_bf16 v[112:115], v[144:147], v[160:163], v[112:115]
	v_mfma_f32_16x16x32_bf16 v[116:119], v[152:155], v[160:163], v[116:119]
	v_mfma_f32_16x16x32_bf16 v[96:99], v[144:147], v[168:171], v[96:99]
	v_mfma_f32_16x16x32_bf16 v[100:103], v[152:155], v[168:171], v[100:103]
	v_mfma_f32_16x16x32_bf16 v[80:83], v[144:147], v[176:179], v[80:83]
	v_mfma_f32_16x16x32_bf16 v[84:87], v[152:155], v[176:179], v[84:87]
	v_mfma_f32_16x16x32_bf16 v[60:63], v[144:147], v[184:187], v[60:63]
	v_mfma_f32_16x16x32_bf16 v[68:71], v[152:155], v[184:187], v[68:71]
	v_mfma_f32_16x16x32_bf16 v[112:115], v[148:151], v[164:167], v[112:115]
	v_mfma_f32_16x16x32_bf16 v[116:119], v[156:159], v[164:167], v[116:119]
	v_mfma_f32_16x16x32_bf16 v[96:99], v[148:151], v[172:175], v[96:99]
	v_mfma_f32_16x16x32_bf16 v[100:103], v[156:159], v[172:175], v[100:103]
	v_mfma_f32_16x16x32_bf16 v[80:83], v[148:151], v[180:183], v[80:83]
	v_mfma_f32_16x16x32_bf16 v[84:87], v[156:159], v[180:183], v[84:87]
	v_mfma_f32_16x16x32_bf16 v[60:63], v[148:151], v[188:191], v[60:63]
	v_mfma_f32_16x16x32_bf16 v[68:71], v[156:159], v[188:191], v[68:71]
	s_barrier
	s_setprio 0
	s_add_i32 s69, s69, s43
	v_lshl_add_u64 v[202:203], s[30:31], 0, v[204:205]
	s_mov_b32 m0, s69
	ds_read_b128 v[160:163], v217 offset:16384
	ds_read_b128 v[164:167], v217 offset:17408
	ds_read_b128 v[168:171], v217 offset:18432
	ds_read_b128 v[172:175], v217 offset:19456
	ds_read_b128 v[176:179], v217 offset:20480
	ds_read_b128 v[180:183], v217 offset:21504
	ds_read_b128 v[184:187], v217 offset:22528
	ds_read_b128 v[188:191], v217 offset:23552
	global_load_lds_dwordx4 v[202:203], off
	s_add_i32 m0, s69, 0x2000
	s_add_u32 s76, s30, 0x40000
	v_lshl_add_u64 v[206:207], s[30:31], 0, v[196:197]
	s_addc_u32 s77, s31, 0
	s_add_i32 s69, s75, s43
	global_load_lds_dwordx4 v[206:207], off
	v_lshl_add_u64 v[208:209], s[76:77], 0, v[204:205]
	s_mov_b32 m0, s69
	v_lshl_add_u64 v[210:211], s[36:37], 0, v[194:195]
	global_load_lds_dwordx4 v[208:209], off
	v_lshl_add_u64 v[208:209], s[76:77], 0, v[196:197]
	s_add_i32 m0, s69, 0x2000
	s_nop 0
	global_load_lds_dwordx4 v[208:209], off
	v_lshl_add_u64 v[208:209], s[36:37], 0, v[192:193]
	s_mov_b32 m0, s46
	s_nop 0
	global_load_lds_dwordx4 v[208:209], off
	s_mov_b32 m0, s47
	s_nop 0
	global_load_lds_dwordx4 v[210:211], off
	s_waitcnt vmcnt(8)
	s_waitcnt lgkmcnt(0)
	s_setprio 1
	s_barrier
; #define PG8_STAGE(bufoff, gbase, voff) do { _Pragma("unroll") for (int _i = 0; _i < 2; ++_i) \
;         __builtin_amdgcn_global_load_lds((const unsigned*)((const char*)(gbase) + (voff)[_i]), (PG8_LAS unsigned*)(lds + (bufoff) + ldsw + _i * 8192), 16, 0, 0); } while (0)
; #define PG8_LDA(dst, b, h) do { _Pragma("unroll") for (int m = 0; m < 4; ++m) _Pragma("unroll") for (int k = 0; k < 2; ++k) dst[m][k] = *(const PG8_LAS bf16x8*)(lds + PG8_SA(b, h) + aoff + m * 2048 + k * 1024); } while (0)
; #define PG8_LDB(dst, b, h) do { _Pragma("unroll") for (int n = 0; n < 2; ++n) _Pragma("unroll") for (int k = 0; k < 2; ++k) dst[n][k] = *(const PG8_LAS bf16x8*)(lds + PG8_SB(b, h) + boff + n * 2048 + k * 1024); } while (0)
; #define PG8_MMA(ai, bj, At, Bt) do { __builtin_amdgcn_s_setprio(1); _Pragma("unroll") for (int m = 0; m < 4; ++m) _Pragma("unroll") for (int n = 0; n < 2; ++n) _Pragma("unroll") for (int k = 0; k < 2; ++k) \
;         acc[ai][bj][m][n] = __builtin_amdgcn_mfma_f32_16x16x32_bf16(Bt[n][k], At[m][k], acc[ai][bj][m][n], 0, 0, 0); __builtin_amdgcn_s_setprio(0); } while (0)
; #define PG8_BAR __builtin_amdgcn_s_barrier()
; template <class Epi, class Sched, bool ALIGN_EPI = false, bool SP2 = false>
; __device__ __forceinline__ void gemm_phase(PG8_LAS unsigned char* lds, const Gemm g, const Sched& S, const Epi& E, const int tid) {
;     ...
;             PG8_LDB(B0, 0, 0); PG8_LDB(B1, 0, 1); PG8_SCHED; PG8_LDA(At, 0, 0); PG8_STAGE(PG8_SA(1, 1), a1 + hstep, voffA);
;             PG8_WAIT_V(8); PG8_WAIT_L(0); PG8_BAR; PG8_MMA(0, 0, At, B0); PG8_MMA(0, 1, At, B1); PG8_BAR; PG8_SCHED;
;             PG8_LDA(At, 0, 1); PG8_STAGE(PG8_SB(0, 0), b2, voffB); PG8_STAGE(PG8_SB(0, 1), b2 + hstep, voffB); PG8_STAGE(PG8_SA(0, 0), a2, voffA);
;             PG8_WAIT_V(8); PG8_WAIT_L(0); PG8_BAR; PG8_MMA(1, 0, At, B0); PG8_MMA(1, 1, At, B1); PG8_BAR; PG8_SCHED;
;             PG8_LDB(B0, 1, 0); PG8_LDB(B1, 1, 1); PG8_SCHED; PG8_LDA(At, 1, 0); PG8_STAGE(PG8_SA(0, 1), a2 + hstep, voffA);
;             PG8_WAIT_V(8); PG8_WAIT_L(0); PG8_BAR; PG8_MMA(0, 0, At, B0); PG8_MMA(0, 1, At, B1); PG8_BAR; PG8_SCHED;
;             PG8_LDA(At, 1, 1); PG8_STAGE(PG8_SB(1, 0), b3, voffB); PG8_STAGE(PG8_SB(1, 1), b3 + hstep, voffB); PG8_STAGE(PG8_SA(1, 0), a3, voffA);
;             PG8_WAIT_V(8); PG8_WAIT_L(0); PG8_BAR; PG8_MMA(1, 0, At, B0); PG8_MMA(1, 1, At, B1); PG8_BAR; PG8_SCHED;
	v_mfma_f32_16x16x32_bf16 v[48:51], v[128:131], v[160:163], v[48:51]
	v_mfma_f32_16x16x32_bf16 v[56:59], v[136:139], v[160:163], v[56:59]
	v_mfma_f32_16x16x32_bf16 v[20:23], v[128:131], v[168:171], v[20:23]
	v_mfma_f32_16x16x32_bf16 v[64:67], v[136:139], v[168:171], v[64:67]
	v_mfma_f32_16x16x32_bf16 v[28:31], v[128:131], v[176:179], v[28:31]
	v_mfma_f32_16x16x32_bf16 v[36:39], v[136:139], v[176:179], v[36:39]
	v_mfma_f32_16x16x32_bf16 v[8:11], v[128:131], v[184:187], v[8:11]
	v_mfma_f32_16x16x32_bf16 v[12:15], v[136:139], v[184:187], v[12:15]
	v_mfma_f32_16x16x32_bf16 v[48:51], v[132:135], v[164:167], v[48:51]
	v_mfma_f32_16x16x32_bf16 v[56:59], v[140:143], v[164:167], v[56:59]
	v_mfma_f32_16x16x32_bf16 v[20:23], v[132:135], v[172:175], v[20:23]
	v_mfma_f32_16x16x32_bf16 v[64:67], v[140:143], v[172:175], v[64:67]
	v_mfma_f32_16x16x32_bf16 v[28:31], v[132:135], v[180:183], v[28:31]
	v_mfma_f32_16x16x32_bf16 v[36:39], v[140:143], v[180:183], v[36:39]
	v_mfma_f32_16x16x32_bf16 v[8:11], v[132:135], v[188:191], v[8:11]
	v_mfma_f32_16x16x32_bf16 v[12:15], v[140:143], v[188:191], v[12:15]
	s_setprio 0
	s_setprio 1
	v_mfma_f32_16x16x32_bf16 v[32:35], v[144:147], v[160:163], v[32:35]
	v_mfma_f32_16x16x32_bf16 v[40:43], v[152:155], v[160:163], v[40:43]
	v_mfma_f32_16x16x32_bf16 v[44:47], v[144:147], v[168:171], v[44:47]
	v_mfma_f32_16x16x32_bf16 v[52:55], v[152:155], v[168:171], v[52:55]
	v_mfma_f32_16x16x32_bf16 v[16:19], v[144:147], v[176:179], v[16:19]
	v_mfma_f32_16x16x32_bf16 v[24:27], v[152:155], v[176:179], v[24:27]
	v_mfma_f32_16x16x32_bf16 v[0:3], v[144:147], v[184:187], v[0:3]
	v_mfma_f32_16x16x32_bf16 v[4:7], v[152:155], v[184:187], v[4:7]
	v_mfma_f32_16x16x32_bf16 v[32:35], v[148:151], v[164:167], v[32:35]
	v_mfma_f32_16x16x32_bf16 v[40:43], v[156:159], v[164:167], v[40:43]
	v_mfma_f32_16x16x32_bf16 v[44:47], v[148:151], v[172:175], v[44:47]
	v_mfma_f32_16x16x32_bf16 v[52:55], v[156:159], v[172:175], v[52:55]
	v_mfma_f32_16x16x32_bf16 v[16:19], v[148:151], v[180:183], v[16:19]
	v_mfma_f32_16x16x32_bf16 v[24:27], v[156:159], v[180:183], v[24:27]
	v_mfma_f32_16x16x32_bf16 v[0:3], v[148:151], v[188:191], v[0:3]
	v_mfma_f32_16x16x32_bf16 v[4:7], v[156:159], v[188:191], v[4:7]
	s_barrier
	s_setprio 0
	s_add_i32 s69, 0, 0x18000
	s_add_i32 s75, 0, 0x1c000
	v_add_u32_e32 v140, s69, v216
	v_add_u32_e32 v156, s75, v216
	ds_read_b128 v[128:131], v140
	ds_read_b128 v[132:135], v140 offset:1024
	ds_read_b128 v[136:139], v140 offset:2048
	ds_read_b128 v[140:143], v140 offset:3072
	ds_read_b128 v[144:147], v156
	ds_read_b128 v[148:151], v156 offset:1024
	ds_read_b128 v[152:155], v156 offset:2048
	ds_read_b128 v[156:159], v156 offset:3072
	s_add_u32 s36, s36, 0x40000
	s_addc_u32 s37, s37, 0
	s_mov_b32 m0, s48
	v_lshl_add_u64 v[212:213], s[36:37], 0, v[192:193]
	ds_read_b128 v[160:163], v217 offset:32768
	ds_read_b128 v[164:167], v217 offset:33792
	ds_read_b128 v[168:171], v217 offset:34816
	ds_read_b128 v[172:175], v217 offset:35840
	ds_read_b128 v[176:179], v217 offset:36864
	ds_read_b128 v[180:183], v217 offset:37888
	ds_read_b128 v[184:187], v217 offset:38912
	ds_read_b128 v[188:191], v217 offset:39936
	global_load_lds_dwordx4 v[212:213], off
	v_lshl_add_u64 v[212:213], s[36:37], 0, v[194:195]
	s_mov_b32 m0, s49
	s_nop 0
	global_load_lds_dwordx4 v[212:213], off
	s_waitcnt vmcnt(8)
	s_waitcnt lgkmcnt(0)
	s_setprio 1
	s_barrier
	v_mfma_f32_16x16x32_bf16 v[120:123], v[128:131], v[160:163], v[120:123]
	v_mfma_f32_16x16x32_bf16 v[124:127], v[136:139], v[160:163], v[124:127]
	v_mfma_f32_16x16x32_bf16 v[104:107], v[128:131], v[168:171], v[104:107]
	v_mfma_f32_16x16x32_bf16 v[108:111], v[136:139], v[168:171], v[108:111]
	v_mfma_f32_16x16x32_bf16 v[88:91], v[128:131], v[176:179], v[88:91]
	v_mfma_f32_16x16x32_bf16 v[92:95], v[136:139], v[176:179], v[92:95]
	v_mfma_f32_16x16x32_bf16 v[72:75], v[128:131], v[184:187], v[72:75]
	v_mfma_f32_16x16x32_bf16 v[76:79], v[136:139], v[184:187], v[76:79]
	v_mfma_f32_16x16x32_bf16 v[120:123], v[132:135], v[164:167], v[120:123]
	v_mfma_f32_16x16x32_bf16 v[124:127], v[140:143], v[164:167], v[124:127]
	v_mfma_f32_16x16x32_bf16 v[104:107], v[132:135], v[172:175], v[104:107]
	v_mfma_f32_16x16x32_bf16 v[108:111], v[140:143], v[172:175], v[108:111]
	v_mfma_f32_16x16x32_bf16 v[88:91], v[132:135], v[180:183], v[88:91]
	v_mfma_f32_16x16x32_bf16 v[92:95], v[140:143], v[180:183], v[92:95]
	v_mfma_f32_16x16x32_bf16 v[72:75], v[132:135], v[188:191], v[72:75]
	v_mfma_f32_16x16x32_bf16 v[76:79], v[140:143], v[188:191], v[76:79]
	s_setprio 0
	s_setprio 1
	v_mfma_f32_16x16x32_bf16 v[112:115], v[144:147], v[160:163], v[112:115]
	v_mfma_f32_16x16x32_bf16 v[116:119], v[152:155], v[160:163], v[116:119]
	v_mfma_f32_16x16x32_bf16 v[96:99], v[144:147], v[168:171], v[96:99]
	v_mfma_f32_16x16x32_bf16 v[100:103], v[152:155], v[168:171], v[100:103]
	v_mfma_f32_16x16x32_bf16 v[80:83], v[144:147], v[176:179], v[80:83]
	v_mfma_f32_16x16x32_bf16 v[84:87], v[152:155], v[176:179], v[84:87]
	v_mfma_f32_16x16x32_bf16 v[60:63], v[144:147], v[184:187], v[60:63]
	v_mfma_f32_16x16x32_bf16 v[68:71], v[152:155], v[184:187], v[68:71]
	v_mfma_f32_16x16x32_bf16 v[112:115], v[148:151], v[164:167], v[112:115]
	v_mfma_f32_16x16x32_bf16 v[116:119], v[156:159], v[164:167], v[116:119]
	v_mfma_f32_16x16x32_bf16 v[96:99], v[148:151], v[172:175], v[96:99]
	v_mfma_f32_16x16x32_bf16 v[100:103], v[156:159], v[172:175], v[100:103]
	v_mfma_f32_16x16x32_bf16 v[80:83], v[148:151], v[180:183], v[80:83]
	v_mfma_f32_16x16x32_bf16 v[84:87], v[156:159], v[180:183], v[84:87]
	v_mfma_f32_16x16x32_bf16 v[60:63], v[148:151], v[188:191], v[60:63]
	v_mfma_f32_16x16x32_bf16 v[68:71], v[156:159], v[188:191], v[68:71]
	s_barrier
; #define PG8_STAGE(bufoff, gbase, voff) do { _Pragma("unroll") for (int _i = 0; _i < 2; ++_i) \
;         __builtin_amdgcn_global_load_lds((const unsigned*)((const char*)(gbase) + (voff)[_i]), (PG8_LAS unsigned*)(lds + (bufoff) + ldsw + _i * 8192), 16, 0, 0); } while (0)
; #define PG8_BAR __builtin_amdgcn_s_barrier()
; template <class Epi, class Sched, bool ALIGN_EPI = false, bool SP2 = false>
; __device__ __forceinline__ void gemm_phase(PG8_LAS unsigned char* lds, const Gemm g, const Sched& S, const Epi& E, const int tid) {
;     ...
;             PG8_LDB(B0, 1, 0); PG8_LDB(B1, 1, 1); PG8_SCHED; PG8_LDA(At, 1, 0); PG8_STAGE(PG8_SA(0, 1), a2 + hstep, voffA);
;             PG8_WAIT_V(8); PG8_WAIT_L(0); PG8_BAR; PG8_MMA(0, 0, At, B0); PG8_MMA(0, 1, At, B1); PG8_BAR; PG8_SCHED;
;             PG8_LDA(At, 1, 1); PG8_STAGE(PG8_SB(1, 0), b3, voffB); PG8_STAGE(PG8_SB(1, 1), b3 + hstep, voffB); PG8_STAGE(PG8_SA(1, 0), a3, voffA);
;             PG8_WAIT_V(8); PG8_WAIT_L(0); PG8_BAR; PG8_MMA(1, 0, At, B0); PG8_MMA(1, 1, At, B1); PG8_BAR; PG8_SCHED;
;             } else {
;             PG8_LDB(B0, 0, 0); PG8_SCHED; PG8_LDA(At, 0, 0); PG8_STAGE(PG8_SA(1, 1), a1 + hstep, voffA);
;             PG8_WAIT_L(8); PG8_BAR; PG8_WAIT_L(0); PG8_MMA(0, 0, At, B0); PG8_BAR; PG8_SCHED;
;             PG8_LDB(B1, 0, 1); PG8_STAGE(PG8_SB(0, 0), b2, voffB);
;             PG8_BAR; PG8_WAIT_L(0); PG8_MMA(0, 1, At, B1); PG8_BAR;
;             PG8_LDA(At, 0, 1); PG8_STAGE(PG8_SA(0, 0), a2, voffA);
;             PG8_BAR; PG8_WAIT_L(0); PG8_MMA(1, 0, At, B0); PG8_BAR; PG8_SCHED;
;             PG8_STAGE(PG8_SB(0, 1), b2 + hstep, voffB);
;             PG8_WAIT_V(6); PG8_BAR; PG8_MMA(1, 1, At, B1); PG8_BAR;
;             PG8_LDB(B0, 1, 0); PG8_SCHED; PG8_LDA(At, 1, 0); PG8_STAGE(PG8_SA(0, 1), a2 + hstep, voffA);
;             PG8_WAIT_L(8); PG8_BAR; PG8_WAIT_L(0); PG8_MMA(0, 0, At, B0); PG8_BAR; PG8_SCHED;
;             PG8_LDB(B1, 1, 1); PG8_STAGE(PG8_SB(1, 0), b3, voffB);
;             PG8_BAR; PG8_WAIT_L(0); PG8_MMA(0, 1, At, B1); PG8_BAR;
;             PG8_LDA(At, 1, 1); PG8_STAGE(PG8_SA(1, 0), a3, voffA);
;             PG8_BAR; PG8_WAIT_L(0); PG8_MMA(1, 0, At, B0); PG8_BAR; PG8_SCHED;
;             PG8_STAGE(PG8_SB(1, 1), b3 + hstep, voffB);
;             PG8_WAIT_V(6); PG8_BAR; PG8_MMA(1, 1, At, B1); PG8_BAR;
;             }
;         }
;         if constexpr (ALIGN_EPI) { if (wr == 0) PG8_BAR; }
	s_setprio 0
	s_add_i32 s36, s69, s43
	v_lshl_add_u64 v[202:203], v[202:203], 0, s[70:71]
	s_mov_b32 m0, s36
	ds_read_b128 v[160:163], v217 offset:49152
	ds_read_b128 v[164:167], v217 offset:50176
	ds_read_b128 v[168:171], v217 offset:51200
	ds_read_b128 v[172:175], v217 offset:52224
	ds_read_b128 v[176:179], v217 offset:53248
	ds_read_b128 v[180:183], v217 offset:54272
	ds_read_b128 v[184:187], v217 offset:55296
	ds_read_b128 v[188:191], v217 offset:56320
	global_load_lds_dwordx4 v[202:203], off
	s_add_i32 m0, s36, 0x2000
	s_add_u32 s30, s30, 0x40080
	v_lshl_add_u64 v[202:203], v[206:207], 0, s[70:71]
	s_addc_u32 s31, s31, 0
	s_add_i32 s36, s75, s43
	global_load_lds_dwordx4 v[202:203], off
	v_lshl_add_u64 v[202:203], s[30:31], 0, v[204:205]
	s_mov_b32 m0, s36
	s_nop 0
	global_load_lds_dwordx4 v[202:203], off
	v_lshl_add_u64 v[202:203], s[30:31], 0, v[196:197]
	s_add_i32 m0, s36, 0x2000
	s_nop 0
	global_load_lds_dwordx4 v[202:203], off
	v_lshl_add_u64 v[202:203], v[208:209], 0, s[70:71]
	s_mov_b32 m0, s51
	s_nop 0
	global_load_lds_dwordx4 v[202:203], off
	v_lshl_add_u64 v[202:203], v[210:211], 0, s[70:71]
	s_mov_b32 m0, s52
	s_nop 0
	global_load_lds_dwordx4 v[202:203], off
	s_waitcnt vmcnt(8)
	s_waitcnt lgkmcnt(0)
	s_setprio 1
	s_barrier
	v_mfma_f32_16x16x32_bf16 v[48:51], v[128:131], v[160:163], v[48:51]
	v_mfma_f32_16x16x32_bf16 v[56:59], v[136:139], v[160:163], v[56:59]
	v_mfma_f32_16x16x32_bf16 v[20:23], v[128:131], v[168:171], v[20:23]
	v_mfma_f32_16x16x32_bf16 v[64:67], v[136:139], v[168:171], v[64:67]
	v_mfma_f32_16x16x32_bf16 v[28:31], v[128:131], v[176:179], v[28:31]
	v_mfma_f32_16x16x32_bf16 v[36:39], v[136:139], v[176:179], v[36:39]
	v_mfma_f32_16x16x32_bf16 v[8:11], v[128:131], v[184:187], v[8:11]
	v_mfma_f32_16x16x32_bf16 v[12:15], v[136:139], v[184:187], v[12:15]
	v_mfma_f32_16x16x32_bf16 v[48:51], v[132:135], v[164:167], v[48:51]
	v_mfma_f32_16x16x32_bf16 v[56:59], v[140:143], v[164:167], v[56:59]
	v_mfma_f32_16x16x32_bf16 v[20:23], v[132:135], v[172:175], v[20:23]
	v_mfma_f32_16x16x32_bf16 v[64:67], v[140:143], v[172:175], v[64:67]
	v_mfma_f32_16x16x32_bf16 v[28:31], v[132:135], v[180:183], v[28:31]
	v_mfma_f32_16x16x32_bf16 v[36:39], v[140:143], v[180:183], v[36:39]
	v_mfma_f32_16x16x32_bf16 v[8:11], v[132:135], v[188:191], v[8:11]
	v_mfma_f32_16x16x32_bf16 v[12:15], v[140:143], v[188:191], v[12:15]
	s_setprio 0
	s_setprio 1
	v_mfma_f32_16x16x32_bf16 v[32:35], v[144:147], v[160:163], v[32:35]
	v_mfma_f32_16x16x32_bf16 v[40:43], v[152:155], v[160:163], v[40:43]
	v_mfma_f32_16x16x32_bf16 v[44:47], v[144:147], v[168:171], v[44:47]
	v_mfma_f32_16x16x32_bf16 v[52:55], v[152:155], v[168:171], v[52:55]
	v_mfma_f32_16x16x32_bf16 v[16:19], v[144:147], v[176:179], v[16:19]
	v_mfma_f32_16x16x32_bf16 v[24:27], v[152:155], v[176:179], v[24:27]
	v_mfma_f32_16x16x32_bf16 v[0:3], v[144:147], v[184:187], v[0:3]
	v_mfma_f32_16x16x32_bf16 v[4:7], v[152:155], v[184:187], v[4:7]
	v_mfma_f32_16x16x32_bf16 v[32:35], v[148:151], v[164:167], v[32:35]
	v_mfma_f32_16x16x32_bf16 v[40:43], v[156:159], v[164:167], v[40:43]
	v_mfma_f32_16x16x32_bf16 v[44:47], v[148:151], v[172:175], v[44:47]
	v_mfma_f32_16x16x32_bf16 v[52:55], v[156:159], v[172:175], v[52:55]
	v_mfma_f32_16x16x32_bf16 v[16:19], v[148:151], v[180:183], v[16:19]
	v_mfma_f32_16x16x32_bf16 v[24:27], v[156:159], v[180:183], v[24:27]
	v_mfma_f32_16x16x32_bf16 v[0:3], v[148:151], v[188:191], v[0:3]
	v_mfma_f32_16x16x32_bf16 v[4:7], v[156:159], v[188:191], v[4:7]
	s_barrier
	s_setprio 0
	s_add_i32 s68, s68, 2
	s_add_u32 s34, s34, 0x100
	s_addc_u32 s35, s35, 0
	s_add_u32 s64, s64, 0x100
	s_addc_u32 s65, s65, 0
	s_cmp_gt_u32 s68, 13
	s_cbranch_scc0 .LBB0_583
	s_and_b64 vcc, exec, s[16:17]
	s_cbranch_vccz .LBB0_586
	s_barrier

; #define PG8_STAGE(bufoff, gbase, voff) do { _Pragma("unroll") for (int _i = 0; _i < 2; ++_i) \
;         __builtin_amdgcn_global_load_lds((const unsigned*)((const char*)(gbase) + (voff)[_i]), (PG8_LAS unsigned*)(lds + (bufoff) + ldsw + _i * 8192), 16, 0, 0); } while (0)
; #define PG8_LDA(dst, b, h) do { _Pragma("unroll") for (int m = 0; m < 4; ++m) _Pragma("unroll") for (int k = 0; k < 2; ++k) dst[m][k] = *(const PG8_LAS bf16x8*)(lds + PG8_SA(b, h) + aoff + m * 2048 + k * 1024); } while (0)
; template <class Epi, class Sched, bool ALIGN_EPI = false, bool SP2 = false>
; __device__ __forceinline__ void gemm_phase(PG8_LAS unsigned char* lds, const Gemm g, const Sched& S, const Epi& E, const int tid) {
;     ...
;         const bool has_next = S.next(ui + 1, nxt);
;         const char* nA = has_next ? (const char*)g.A + (size_t)nxt.pm * tstep : cA; const char* nB = has_next ? (const char*)g.Bt + (size_t)nxt.pn * tstep : cB;
;         for (int t = 0; t < nt; t += 2) {
;             const bool last = (t == nt - 2);
;             const char* a1 = cA + (size_t)(t + 1) * kstep;
;             const char* a2 = last ? nA : cA + (size_t)(t + 2) * kstep; const char* b2 = last ? nB : cB + (size_t)(t + 2) * kstep;
;             const char* a3 = a2 + kstep; const char* b3 = b2 + kstep;
;             if (last && has_next) S.a_ready(nxt);
;             if constexpr (SP2) {
;             PG8_LDB(B0, 0, 0); PG8_LDB(B1, 0, 1); PG8_SCHED; PG8_LDA(At, 0, 0); PG8_STAGE(PG8_SA(1, 1), a1 + hstep, voffA);
;             PG8_WAIT_V(8); PG8_WAIT_L(0); PG8_BAR; PG8_MMA(0, 0, At, B0); PG8_MMA(0, 1, At, B1); PG8_BAR; PG8_SCHED;
;             PG8_LDA(At, 0, 1); PG8_STAGE(PG8_SB(0, 0), b2, voffB); PG8_STAGE(PG8_SB(0, 1), b2 + hstep, voffB); PG8_STAGE(PG8_SA(0, 0), a2, voffA);
;             PG8_WAIT_V(8); PG8_WAIT_L(0); PG8_BAR; PG8_MMA(1, 0, At, B0); PG8_MMA(1, 1, At, B1); PG8_BAR; PG8_SCHED;
;             PG8_LDB(B0, 1, 0); PG8_LDB(B1, 1, 1); PG8_SCHED; PG8_LDA(At, 1, 0); PG8_STAGE(PG8_SA(0, 1), a2 + hstep, voffA);
;             PG8_WAIT_V(8); PG8_WAIT_L(0); PG8_BAR; PG8_MMA(0, 0, At, B0); PG8_MMA(0, 1, At, B1); PG8_BAR; PG8_SCHED;
;             PG8_LDA(At, 1, 1); PG8_STAGE(PG8_SB(1, 0), b3, voffB); PG8_STAGE(PG8_SB(1, 1), b3 + hstep, voffB); PG8_STAGE(PG8_SA(1, 0), a3, voffA);
;             PG8_WAIT_V(8); PG8_WAIT_L(0); PG8_BAR; PG8_MMA(1, 0, At, B0); PG8_MMA(1, 1, At, B1); PG8_BAR; PG8_SCHED;
.LBB0_660:
	s_ashr_i32 s19, s18, 31
	s_lshl_b64 s[20:21], s[18:19], 20
	s_add_u32 s20, s10, s20
	s_addc_u32 s21, s11, s21
	s_and_b64 s[22:23], s[4:5], exec
	s_cselect_b32 s19, s21, s27
	s_cselect_b32 s50, s20, s26
	s_ashr_i32 s17, s16, 31
	s_lshl_b64 s[22:23], s[16:17], 20
	s_add_u32 s22, s33, s22
	s_addc_u32 s23, s34, s23
	s_and_b64 s[30:31], s[4:5], exec
	s_cselect_b32 s17, s23, s29
	s_cselect_b32 s51, s22, s28
	s_add_u32 s26, s26, 0x80080
	s_addc_u32 s27, s27, 0
	s_add_u32 s52, s28, 0x100
	s_addc_u32 s53, s29, 0
	s_mov_b32 s54, -2
	s_add_u32 s28, s26, 0xfff80080
	s_addc_u32 s29, s27, -1
	s_add_i32 s55, 0, 0x10000
	s_cmp_eq_u32 s54, 28
	s_cselect_b32 s31, s19, s29
	s_cselect_b32 s30, s50, s28
	v_add_u32_e32 v138, s55, v139
	s_cselect_b32 s29, s17, s53
	s_cselect_b32 s28, s51, s52
	s_add_i32 s62, 0, 0x14000
	ds_read_b128 v[144:147], v138
	ds_read_b128 v[148:151], v138 offset:1024
	ds_read_b128 v[152:155], v138 offset:2048
	ds_read_b128 v[156:159], v138 offset:3072
	v_add_u32_e32 v138, s62, v139
	ds_read_b128 v[160:163], v138
	ds_read_b128 v[164:167], v138 offset:1024
	ds_read_b128 v[168:171], v138 offset:2048
	ds_read_b128 v[172:175], v138 offset:3072
	v_lshl_add_u64 v[140:141], s[26:27], 0, v[134:135]
	s_add_i32 m0, s37, 0xc000
	ds_read_b128 v[176:179], v143
	ds_read_b128 v[180:183], v143 offset:1024
	ds_read_b128 v[184:187], v143 offset:2048
	ds_read_b128 v[188:191], v143 offset:3072
	ds_read_b128 v[192:195], v143 offset:4096
	ds_read_b128 v[196:199], v143 offset:5120
	ds_read_b128 v[200:203], v143 offset:6144
	ds_read_b128 v[206:209], v143 offset:7168
	global_load_lds_dwordx4 v[140:141], off
	v_lshl_add_u64 v[140:141], s[26:27], 0, v[136:137]
	s_add_i32 m0, s37, 0xe000
	s_nop 0
	global_load_lds_dwordx4 v[140:141], off
	s_waitcnt vmcnt(24)
	s_waitcnt lgkmcnt(0)
	s_setprio 1
	s_barrier
	v_mfma_f32_16x16x32_bf16 v[124:127], v[144:147], v[176:179], 0
	v_mfma_f32_16x16x32_bf16 v[120:123], v[152:155], v[176:179], 0
	v_mfma_f32_16x16x32_bf16 v[108:111], v[144:147], v[184:187], 0
	v_mfma_f32_16x16x32_bf16 v[104:107], v[152:155], v[184:187], 0
	v_mfma_f32_16x16x32_bf16 v[92:95], v[144:147], v[192:195], 0
	v_mfma_f32_16x16x32_bf16 v[88:91], v[152:155], v[192:195], 0
	v_mfma_f32_16x16x32_bf16 v[76:79], v[144:147], v[200:203], 0
	v_mfma_f32_16x16x32_bf16 v[72:75], v[152:155], v[200:203], 0
	v_mfma_f32_16x16x32_bf16 v[124:127], v[148:151], v[180:183], v[124:127]
	v_mfma_f32_16x16x32_bf16 v[120:123], v[156:159], v[180:183], v[120:123]
	v_mfma_f32_16x16x32_bf16 v[108:111], v[148:151], v[188:191], v[108:111]
	v_mfma_f32_16x16x32_bf16 v[104:107], v[156:159], v[188:191], v[104:107]
	v_mfma_f32_16x16x32_bf16 v[92:95], v[148:151], v[196:199], v[92:95]
	v_mfma_f32_16x16x32_bf16 v[88:91], v[156:159], v[196:199], v[88:91]
	v_mfma_f32_16x16x32_bf16 v[76:79], v[148:151], v[206:209], v[76:79]
	v_mfma_f32_16x16x32_bf16 v[72:75], v[156:159], v[206:209], v[72:75]
	s_setprio 0
	s_setprio 1
	v_mfma_f32_16x16x32_bf16 v[116:119], v[160:163], v[176:179], 0
	v_mfma_f32_16x16x32_bf16 v[112:115], v[168:171], v[176:179], 0
	v_mfma_f32_16x16x32_bf16 v[100:103], v[160:163], v[184:187], 0
	v_mfma_f32_16x16x32_bf16 v[96:99], v[168:171], v[184:187], 0
	v_mfma_f32_16x16x32_bf16 v[84:87], v[160:163], v[192:195], 0
	v_mfma_f32_16x16x32_bf16 v[80:83], v[168:171], v[192:195], 0
	v_mfma_f32_16x16x32_bf16 v[68:71], v[160:163], v[200:203], 0
	v_mfma_f32_16x16x32_bf16 v[64:67], v[168:171], v[200:203], 0
	v_mfma_f32_16x16x32_bf16 v[116:119], v[164:167], v[180:183], v[116:119]
	v_mfma_f32_16x16x32_bf16 v[112:115], v[172:175], v[180:183], v[112:115]
	v_mfma_f32_16x16x32_bf16 v[100:103], v[164:167], v[188:191], v[100:103]
	v_mfma_f32_16x16x32_bf16 v[96:99], v[172:175], v[188:191], v[96:99]
	v_mfma_f32_16x16x32_bf16 v[84:87], v[164:167], v[196:199], v[84:87]
	v_mfma_f32_16x16x32_bf16 v[80:83], v[172:175], v[196:199], v[80:83]
	v_mfma_f32_16x16x32_bf16 v[68:71], v[164:167], v[206:209], v[68:71]
	v_mfma_f32_16x16x32_bf16 v[64:67], v[172:175], v[206:209], v[64:67]
	s_barrier
	s_setprio 0
	s_add_i32 s55, s55, s35
	v_lshl_add_u64 v[140:141], s[28:29], 0, v[204:205]
	s_mov_b32 m0, s55
	ds_read_b128 v[176:179], v143 offset:16384
	ds_read_b128 v[180:183], v143 offset:17408
	ds_read_b128 v[184:187], v143 offset:18432
	ds_read_b128 v[188:191], v143 offset:19456
	ds_read_b128 v[192:195], v143 offset:20480
	ds_read_b128 v[196:199], v143 offset:21504
	ds_read_b128 v[200:203], v143 offset:22528
	ds_read_b128 v[206:209], v143 offset:23552
	global_load_lds_dwordx4 v[140:141], off
	s_add_i32 m0, s55, 0x2000
	s_add_u32 s64, s28, 0x80000
	v_lshl_add_u64 v[210:211], s[28:29], 0, v[128:129]
	s_addc_u32 s65, s29, 0
	s_add_i32 s55, s62, s35
	global_load_lds_dwordx4 v[210:211], off
	v_lshl_add_u64 v[212:213], s[64:65], 0, v[204:205]
	s_mov_b32 m0, s55
	v_lshl_add_u64 v[214:215], s[30:31], 0, v[130:131]
	global_load_lds_dwordx4 v[212:213], off
	v_lshl_add_u64 v[212:213], s[64:65], 0, v[128:129]
	s_add_i32 m0, s55, 0x2000
	s_nop 0
	global_load_lds_dwordx4 v[212:213], off
	v_lshl_add_u64 v[212:213], s[30:31], 0, v[132:133]
	s_mov_b32 m0, s37
	s_nop 0
	global_load_lds_dwordx4 v[212:213], off
	s_mov_b32 m0, s38
	s_nop 0
	global_load_lds_dwordx4 v[214:215], off
	s_waitcnt vmcnt(8)
	s_waitcnt lgkmcnt(0)
	s_setprio 1
	s_barrier
; #define PG8_STAGE(bufoff, gbase, voff) do { _Pragma("unroll") for (int _i = 0; _i < 2; ++_i) \
;         __builtin_amdgcn_global_load_lds((const unsigned*)((const char*)(gbase) + (voff)[_i]), (PG8_LAS unsigned*)(lds + (bufoff) + ldsw + _i * 8192), 16, 0, 0); } while (0)
; #define PG8_LDA(dst, b, h) do { _Pragma("unroll") for (int m = 0; m < 4; ++m) _Pragma("unroll") for (int k = 0; k < 2; ++k) dst[m][k] = *(const PG8_LAS bf16x8*)(lds + PG8_SA(b, h) + aoff + m * 2048 + k * 1024); } while (0)
; #define PG8_LDB(dst, b, h) do { _Pragma("unroll") for (int n = 0; n < 2; ++n) _Pragma("unroll") for (int k = 0; k < 2; ++k) dst[n][k] = *(const PG8_LAS bf16x8*)(lds + PG8_SB(b, h) + boff + n * 2048 + k * 1024); } while (0)
; #define PG8_MMA(ai, bj, At, Bt) do { __builtin_amdgcn_s_setprio(1); _Pragma("unroll") for (int m = 0; m < 4; ++m) _Pragma("unroll") for (int n = 0; n < 2; ++n) _Pragma("unroll") for (int k = 0; k < 2; ++k) \
;         acc[ai][bj][m][n] = __builtin_amdgcn_mfma_f32_16x16x32_bf16(Bt[n][k], At[m][k], acc[ai][bj][m][n], 0, 0, 0); __builtin_amdgcn_s_setprio(0); } while (0)
; #define PG8_BAR __builtin_amdgcn_s_barrier()
; template <class Epi, class Sched, bool ALIGN_EPI = false, bool SP2 = false>
; __device__ __forceinline__ void gemm_phase(PG8_LAS unsigned char* lds, const Gemm g, const Sched& S, const Epi& E, const int tid) {
;     ...
;             PG8_LDB(B0, 0, 0); PG8_LDB(B1, 0, 1); PG8_SCHED; PG8_LDA(At, 0, 0); PG8_STAGE(PG8_SA(1, 1), a1 + hstep, voffA);
;             PG8_WAIT_V(8); PG8_WAIT_L(0); PG8_BAR; PG8_MMA(0, 0, At, B0); PG8_MMA(0, 1, At, B1); PG8_BAR; PG8_SCHED;
;             PG8_LDA(At, 0, 1); PG8_STAGE(PG8_SB(0, 0), b2, voffB); PG8_STAGE(PG8_SB(0, 1), b2 + hstep, voffB); PG8_STAGE(PG8_SA(0, 0), a2, voffA);
;             PG8_WAIT_V(8); PG8_WAIT_L(0); PG8_BAR; PG8_MMA(1, 0, At, B0); PG8_MMA(1, 1, At, B1); PG8_BAR; PG8_SCHED;
;             PG8_LDB(B0, 1, 0); PG8_LDB(B1, 1, 1); PG8_SCHED; PG8_LDA(At, 1, 0); PG8_STAGE(PG8_SA(0, 1), a2 + hstep, voffA);
;             PG8_WAIT_V(8); PG8_WAIT_L(0); PG8_BAR; PG8_MMA(0, 0, At, B0); PG8_MMA(0, 1, At, B1); PG8_BAR; PG8_SCHED;
;             PG8_LDA(At, 1, 1); PG8_STAGE(PG8_SB(1, 0), b3, voffB); PG8_STAGE(PG8_SB(1, 1), b3 + hstep, voffB); PG8_STAGE(PG8_SA(1, 0), a3, voffA);
;             PG8_WAIT_V(8); PG8_WAIT_L(0); PG8_BAR; PG8_MMA(1, 0, At, B0); PG8_MMA(1, 1, At, B1); PG8_BAR; PG8_SCHED;
	v_mfma_f32_16x16x32_bf16 v[60:63], v[144:147], v[176:179], 0
	v_mfma_f32_16x16x32_bf16 v[56:59], v[152:155], v[176:179], 0
	v_mfma_f32_16x16x32_bf16 v[48:51], v[144:147], v[184:187], 0
	v_mfma_f32_16x16x32_bf16 v[40:43], v[152:155], v[184:187], 0
	v_mfma_f32_16x16x32_bf16 v[32:35], v[144:147], v[192:195], 0
	v_mfma_f32_16x16x32_bf16 v[24:27], v[152:155], v[192:195], 0
	v_mfma_f32_16x16x32_bf16 v[16:19], v[144:147], v[200:203], 0
	v_mfma_f32_16x16x32_bf16 v[8:11], v[152:155], v[200:203], 0
	v_mfma_f32_16x16x32_bf16 v[60:63], v[148:151], v[180:183], v[60:63]
	v_mfma_f32_16x16x32_bf16 v[56:59], v[156:159], v[180:183], v[56:59]
	v_mfma_f32_16x16x32_bf16 v[48:51], v[148:151], v[188:191], v[48:51]
	v_mfma_f32_16x16x32_bf16 v[40:43], v[156:159], v[188:191], v[40:43]
	v_mfma_f32_16x16x32_bf16 v[32:35], v[148:151], v[196:199], v[32:35]
	v_mfma_f32_16x16x32_bf16 v[24:27], v[156:159], v[196:199], v[24:27]
	v_mfma_f32_16x16x32_bf16 v[16:19], v[148:151], v[206:209], v[16:19]
	v_mfma_f32_16x16x32_bf16 v[8:11], v[156:159], v[206:209], v[8:11]
	s_setprio 0
	s_setprio 1
	v_mfma_f32_16x16x32_bf16 v[52:55], v[160:163], v[176:179], 0
	v_mfma_f32_16x16x32_bf16 v[44:47], v[168:171], v[176:179], 0
	v_mfma_f32_16x16x32_bf16 v[36:39], v[160:163], v[184:187], 0
	v_mfma_f32_16x16x32_bf16 v[28:31], v[168:171], v[184:187], 0
	v_mfma_f32_16x16x32_bf16 v[20:23], v[160:163], v[192:195], 0
	v_mfma_f32_16x16x32_bf16 v[12:15], v[168:171], v[192:195], 0
	v_mfma_f32_16x16x32_bf16 v[4:7], v[160:163], v[200:203], 0
	v_mfma_f32_16x16x32_bf16 v[0:3], v[168:171], v[200:203], 0
	v_mfma_f32_16x16x32_bf16 v[52:55], v[164:167], v[180:183], v[52:55]
	v_mfma_f32_16x16x32_bf16 v[44:47], v[172:175], v[180:183], v[44:47]
	v_mfma_f32_16x16x32_bf16 v[36:39], v[164:167], v[188:191], v[36:39]
	v_mfma_f32_16x16x32_bf16 v[28:31], v[172:175], v[188:191], v[28:31]
	v_mfma_f32_16x16x32_bf16 v[20:23], v[164:167], v[196:199], v[20:23]
	v_mfma_f32_16x16x32_bf16 v[12:15], v[172:175], v[196:199], v[12:15]
	v_mfma_f32_16x16x32_bf16 v[4:7], v[164:167], v[206:209], v[4:7]
	v_mfma_f32_16x16x32_bf16 v[0:3], v[172:175], v[206:209], v[0:3]
	s_barrier
	s_setprio 0
	s_add_i32 s55, 0, 0x18000
	v_add_u32_e32 v138, s55, v139
	s_add_i32 s62, 0, 0x1c000
	ds_read_b128 v[144:147], v138
	ds_read_b128 v[148:151], v138 offset:1024
	ds_read_b128 v[152:155], v138 offset:2048
	ds_read_b128 v[156:159], v138 offset:3072
	v_add_u32_e32 v138, s62, v139
	ds_read_b128 v[160:163], v138
	ds_read_b128 v[164:167], v138 offset:1024
	ds_read_b128 v[168:171], v138 offset:2048
	ds_read_b128 v[172:175], v138 offset:3072
	s_add_u32 s30, s30, 0x80000
	s_addc_u32 s31, s31, 0
	s_mov_b32 m0, s40
	v_lshl_add_u64 v[216:217], s[30:31], 0, v[132:133]
	ds_read_b128 v[176:179], v143 offset:32768
	ds_read_b128 v[180:183], v143 offset:33792
	ds_read_b128 v[184:187], v143 offset:34816
	ds_read_b128 v[188:191], v143 offset:35840
	ds_read_b128 v[192:195], v143 offset:36864
	ds_read_b128 v[196:199], v143 offset:37888
	ds_read_b128 v[200:203], v143 offset:38912
	ds_read_b128 v[206:209], v143 offset:39936
	global_load_lds_dwordx4 v[216:217], off
	v_lshl_add_u64 v[216:217], s[30:31], 0, v[130:131]
	s_mov_b32 m0, s42
	s_nop 0
	global_load_lds_dwordx4 v[216:217], off
	s_waitcnt vmcnt(8)
	s_waitcnt lgkmcnt(0)
	s_setprio 1
	s_barrier
	v_mfma_f32_16x16x32_bf16 v[124:127], v[144:147], v[176:179], v[124:127]
	v_mfma_f32_16x16x32_bf16 v[120:123], v[152:155], v[176:179], v[120:123]
	v_mfma_f32_16x16x32_bf16 v[108:111], v[144:147], v[184:187], v[108:111]
	v_mfma_f32_16x16x32_bf16 v[104:107], v[152:155], v[184:187], v[104:107]
	v_mfma_f32_16x16x32_bf16 v[92:95], v[144:147], v[192:195], v[92:95]
	v_mfma_f32_16x16x32_bf16 v[88:91], v[152:155], v[192:195], v[88:91]
	v_mfma_f32_16x16x32_bf16 v[76:79], v[144:147], v[200:203], v[76:79]
	v_mfma_f32_16x16x32_bf16 v[72:75], v[152:155], v[200:203], v[72:75]
	v_mfma_f32_16x16x32_bf16 v[124:127], v[148:151], v[180:183], v[124:127]
	v_mfma_f32_16x16x32_bf16 v[120:123], v[156:159], v[180:183], v[120:123]
	v_mfma_f32_16x16x32_bf16 v[108:111], v[148:151], v[188:191], v[108:111]
	v_mfma_f32_16x16x32_bf16 v[104:107], v[156:159], v[188:191], v[104:107]
	v_mfma_f32_16x16x32_bf16 v[92:95], v[148:151], v[196:199], v[92:95]
	v_mfma_f32_16x16x32_bf16 v[88:91], v[156:159], v[196:199], v[88:91]
	v_mfma_f32_16x16x32_bf16 v[76:79], v[148:151], v[206:209], v[76:79]
	v_mfma_f32_16x16x32_bf16 v[72:75], v[156:159], v[206:209], v[72:75]
	s_setprio 0
	s_setprio 1
	v_mfma_f32_16x16x32_bf16 v[116:119], v[160:163], v[176:179], v[116:119]
	v_mfma_f32_16x16x32_bf16 v[112:115], v[168:171], v[176:179], v[112:115]
	v_mfma_f32_16x16x32_bf16 v[100:103], v[160:163], v[184:187], v[100:103]
	v_mfma_f32_16x16x32_bf16 v[96:99], v[168:171], v[184:187], v[96:99]
	v_mfma_f32_16x16x32_bf16 v[84:87], v[160:163], v[192:195], v[84:87]
	v_mfma_f32_16x16x32_bf16 v[80:83], v[168:171], v[192:195], v[80:83]
	v_mfma_f32_16x16x32_bf16 v[68:71], v[160:163], v[200:203], v[68:71]
	v_mfma_f32_16x16x32_bf16 v[64:67], v[168:171], v[200:203], v[64:67]
	v_mfma_f32_16x16x32_bf16 v[116:119], v[164:167], v[180:183], v[116:119]
	v_mfma_f32_16x16x32_bf16 v[112:115], v[172:175], v[180:183], v[112:115]
	v_mfma_f32_16x16x32_bf16 v[100:103], v[164:167], v[188:191], v[100:103]
	v_mfma_f32_16x16x32_bf16 v[96:99], v[172:175], v[188:191], v[96:99]
	v_mfma_f32_16x16x32_bf16 v[84:87], v[164:167], v[196:199], v[84:87]
	v_mfma_f32_16x16x32_bf16 v[80:83], v[172:175], v[196:199], v[80:83]
	v_mfma_f32_16x16x32_bf16 v[68:71], v[164:167], v[206:209], v[68:71]
	v_mfma_f32_16x16x32_bf16 v[64:67], v[172:175], v[206:209], v[64:67]
	s_barrier
; #define PG8_STAGE(bufoff, gbase, voff) do { _Pragma("unroll") for (int _i = 0; _i < 2; ++_i) \
;         __builtin_amdgcn_global_load_lds((const unsigned*)((const char*)(gbase) + (voff)[_i]), (PG8_LAS unsigned*)(lds + (bufoff) + ldsw + _i * 8192), 16, 0, 0); } while (0)
; #define PG8_LDA(dst, b, h) do { _Pragma("unroll") for (int m = 0; m < 4; ++m) _Pragma("unroll") for (int k = 0; k < 2; ++k) dst[m][k] = *(const PG8_LAS bf16x8*)(lds + PG8_SA(b, h) + aoff + m * 2048 + k * 1024); } while (0)
; #define PG8_WAIT_V(n) asm volatile("s_waitcnt vmcnt(" #n ")" ::: "memory")
; #define PG8_WAIT_L(n) asm volatile("s_waitcnt lgkmcnt(" #n ")" ::: "memory")
; #define PG8_BAR __builtin_amdgcn_s_barrier()
; template <class Epi, class Sched, bool ALIGN_EPI = false, bool SP2 = false>
; __device__ __forceinline__ void gemm_phase(PG8_LAS unsigned char* lds, const Gemm g, const Sched& S, const Epi& E, const int tid) {
;     ...
;         for (int t = 0; t < nt; t += 2) {
;             const bool last = (t == nt - 2);
;             const char* a1 = cA + (size_t)(t + 1) * kstep;
;             const char* a2 = last ? nA : cA + (size_t)(t + 2) * kstep; const char* b2 = last ? nB : cB + (size_t)(t + 2) * kstep;
;             const char* a3 = a2 + kstep; const char* b3 = b2 + kstep;
;             if (last && has_next) S.a_ready(nxt);
;             if constexpr (SP2) {
;             PG8_LDB(B0, 0, 0); PG8_LDB(B1, 0, 1); PG8_SCHED; PG8_LDA(At, 0, 0); PG8_STAGE(PG8_SA(1, 1), a1 + hstep, voffA);
;             PG8_WAIT_V(8); PG8_WAIT_L(0); PG8_BAR; PG8_MMA(0, 0, At, B0); PG8_MMA(0, 1, At, B1); PG8_BAR; PG8_SCHED;
;             PG8_LDA(At, 0, 1); PG8_STAGE(PG8_SB(0, 0), b2, voffB); PG8_STAGE(PG8_SB(0, 1), b2 + hstep, voffB); PG8_STAGE(PG8_SA(0, 0), a2, voffA);
;             PG8_WAIT_V(8); PG8_WAIT_L(0); PG8_BAR; PG8_MMA(1, 0, At, B0); PG8_MMA(1, 1, At, B1); PG8_BAR; PG8_SCHED;
;             PG8_LDB(B0, 1, 0); PG8_LDB(B1, 1, 1); PG8_SCHED; PG8_LDA(At, 1, 0); PG8_STAGE(PG8_SA(0, 1), a2 + hstep, voffA);
;             PG8_WAIT_V(8); PG8_WAIT_L(0); PG8_BAR; PG8_MMA(0, 0, At, B0); PG8_MMA(0, 1, At, B1); PG8_BAR; PG8_SCHED;
;             PG8_LDA(At, 1, 1); PG8_STAGE(PG8_SB(1, 0), b3, voffB); PG8_STAGE(PG8_SB(1, 1), b3 + hstep, voffB); PG8_STAGE(PG8_SA(1, 0), a3, voffA);
;             PG8_WAIT_V(8); PG8_WAIT_L(0); PG8_BAR; PG8_MMA(1, 0, At, B0); PG8_MMA(1, 1, At, B1); PG8_BAR; PG8_SCHED;
	s_setprio 0
	s_add_i32 s30, s55, s35
	v_lshl_add_u64 v[140:141], v[140:141], 0, s[70:71]
	s_mov_b32 m0, s30
	ds_read_b128 v[176:179], v143 offset:49152
	ds_read_b128 v[180:183], v143 offset:50176
	ds_read_b128 v[184:187], v143 offset:51200
	ds_read_b128 v[188:191], v143 offset:52224
	ds_read_b128 v[192:195], v143 offset:53248
	ds_read_b128 v[196:199], v143 offset:54272
	ds_read_b128 v[200:203], v143 offset:55296
	ds_read_b128 v[206:209], v143 offset:56320
	global_load_lds_dwordx4 v[140:141], off
	s_add_i32 m0, s30, 0x2000
	s_add_u32 s28, s28, 0x80080
	v_lshl_add_u64 v[140:141], v[210:211], 0, s[70:71]
	s_addc_u32 s29, s29, 0
	s_add_i32 s30, s62, s35
	global_load_lds_dwordx4 v[140:141], off
	v_lshl_add_u64 v[140:141], s[28:29], 0, v[204:205]
	s_mov_b32 m0, s30
	s_nop 0
	global_load_lds_dwordx4 v[140:141], off
	v_lshl_add_u64 v[140:141], s[28:29], 0, v[128:129]
	s_add_i32 m0, s30, 0x2000
	s_nop 0
	global_load_lds_dwordx4 v[140:141], off
	v_lshl_add_u64 v[140:141], v[212:213], 0, s[70:71]
	s_mov_b32 m0, s46
	s_nop 0
	global_load_lds_dwordx4 v[140:141], off
	v_lshl_add_u64 v[140:141], v[214:215], 0, s[70:71]
	s_mov_b32 m0, s47
	s_nop 0
	global_load_lds_dwordx4 v[140:141], off
	s_waitcnt vmcnt(8)
	s_waitcnt lgkmcnt(0)
	s_setprio 1
	s_barrier
	v_mfma_f32_16x16x32_bf16 v[60:63], v[144:147], v[176:179], v[60:63]
	v_mfma_f32_16x16x32_bf16 v[56:59], v[152:155], v[176:179], v[56:59]
	v_mfma_f32_16x16x32_bf16 v[48:51], v[144:147], v[184:187], v[48:51]
	v_mfma_f32_16x16x32_bf16 v[40:43], v[152:155], v[184:187], v[40:43]
	v_mfma_f32_16x16x32_bf16 v[32:35], v[144:147], v[192:195], v[32:35]
	v_mfma_f32_16x16x32_bf16 v[24:27], v[152:155], v[192:195], v[24:27]
	v_mfma_f32_16x16x32_bf16 v[16:19], v[144:147], v[200:203], v[16:19]
	v_mfma_f32_16x16x32_bf16 v[8:11], v[152:155], v[200:203], v[8:11]
	v_mfma_f32_16x16x32_bf16 v[60:63], v[148:151], v[180:183], v[60:63]
	v_mfma_f32_16x16x32_bf16 v[56:59], v[156:159], v[180:183], v[56:59]
	v_mfma_f32_16x16x32_bf16 v[48:51], v[148:151], v[188:191], v[48:51]
	v_mfma_f32_16x16x32_bf16 v[40:43], v[156:159], v[188:191], v[40:43]
	v_mfma_f32_16x16x32_bf16 v[32:35], v[148:151], v[196:199], v[32:35]
	v_mfma_f32_16x16x32_bf16 v[24:27], v[156:159], v[196:199], v[24:27]
	v_mfma_f32_16x16x32_bf16 v[16:19], v[148:151], v[206:209], v[16:19]
	v_mfma_f32_16x16x32_bf16 v[8:11], v[156:159], v[206:209], v[8:11]
	s_setprio 0
	s_setprio 1
	v_mfma_f32_16x16x32_bf16 v[52:55], v[160:163], v[176:179], v[52:55]
	v_mfma_f32_16x16x32_bf16 v[44:47], v[168:171], v[176:179], v[44:47]
	v_mfma_f32_16x16x32_bf16 v[36:39], v[160:163], v[184:187], v[36:39]
	v_mfma_f32_16x16x32_bf16 v[28:31], v[168:171], v[184:187], v[28:31]
	v_mfma_f32_16x16x32_bf16 v[20:23], v[160:163], v[192:195], v[20:23]
	v_mfma_f32_16x16x32_bf16 v[12:15], v[168:171], v[192:195], v[12:15]
	v_mfma_f32_16x16x32_bf16 v[4:7], v[160:163], v[200:203], v[4:7]
	v_mfma_f32_16x16x32_bf16 v[0:3], v[168:171], v[200:203], v[0:3]
	v_mfma_f32_16x16x32_bf16 v[52:55], v[164:167], v[180:183], v[52:55]
	v_mfma_f32_16x16x32_bf16 v[44:47], v[172:175], v[180:183], v[44:47]
	v_mfma_f32_16x16x32_bf16 v[36:39], v[164:167], v[188:191], v[36:39]
	v_mfma_f32_16x16x32_bf16 v[28:31], v[172:175], v[188:191], v[28:31]
	v_mfma_f32_16x16x32_bf16 v[20:23], v[164:167], v[196:199], v[20:23]
	v_mfma_f32_16x16x32_bf16 v[12:15], v[172:175], v[196:199], v[12:15]
	v_mfma_f32_16x16x32_bf16 v[4:7], v[164:167], v[206:209], v[4:7]
	v_mfma_f32_16x16x32_bf16 v[0:3], v[172:175], v[206:209], v[0:3]
	s_barrier
	s_setprio 0
	s_add_i32 s54, s54, 2
	s_add_u32 s26, s26, 0x100
	s_addc_u32 s27, s27, 0
	s_add_u32 s52, s52, 0x100
	s_addc_u32 s53, s53, 0
.LBB0_661:
	s_add_u32 s28, s26, 0xfff80080
	s_addc_u32 s29, s27, -1
	s_add_i32 s55, 0, 0x10000
	s_cmp_eq_u32 s54, 28
	s_cselect_b32 s31, s19, s29
	s_cselect_b32 s30, s50, s28
	v_add_u32_e32 v138, s55, v139
	s_cselect_b32 s29, s17, s53
	s_cselect_b32 s28, s51, s52
	s_add_i32 s62, 0, 0x14000
	ds_read_b128 v[144:147], v138
	ds_read_b128 v[148:151], v138 offset:1024
	ds_read_b128 v[152:155], v138 offset:2048
	ds_read_b128 v[156:159], v138 offset:3072
	v_add_u32_e32 v138, s62, v139
	ds_read_b128 v[160:163], v138
	ds_read_b128 v[164:167], v138 offset:1024
	ds_read_b128 v[168:171], v138 offset:2048
	ds_read_b128 v[172:175], v138 offset:3072
	v_lshl_add_u64 v[140:141], s[26:27], 0, v[134:135]
	s_add_i32 m0, s37, 0xc000
	ds_read_b128 v[176:179], v143
	ds_read_b128 v[180:183], v143 offset:1024
	ds_read_b128 v[184:187], v143 offset:2048
	ds_read_b128 v[188:191], v143 offset:3072
	ds_read_b128 v[192:195], v143 offset:4096
	ds_read_b128 v[196:199], v143 offset:5120
	ds_read_b128 v[200:203], v143 offset:6144
	ds_read_b128 v[206:209], v143 offset:7168
	global_load_lds_dwordx4 v[140:141], off
	v_lshl_add_u64 v[140:141], s[26:27], 0, v[136:137]
	s_add_i32 m0, s37, 0xe000
	s_nop 0
	global_load_lds_dwordx4 v[140:141], off
	s_waitcnt vmcnt(8)
	s_waitcnt lgkmcnt(0)
	s_setprio 1
	s_barrier
; #define PG8_STAGE(bufoff, gbase, voff) do { _Pragma("unroll") for (int _i = 0; _i < 2; ++_i) \
;         __builtin_amdgcn_global_load_lds((const unsigned*)((const char*)(gbase) + (voff)[_i]), (PG8_LAS unsigned*)(lds + (bufoff) + ldsw + _i * 8192), 16, 0, 0); } while (0)
; #define PG8_LDA(dst, b, h) do { _Pragma("unroll") for (int m = 0; m < 4; ++m) _Pragma("unroll") for (int k = 0; k < 2; ++k) dst[m][k] = *(const PG8_LAS bf16x8*)(lds + PG8_SA(b, h) + aoff + m * 2048 + k * 1024); } while (0)
; #define PG8_LDB(dst, b, h) do { _Pragma("unroll") for (int n = 0; n < 2; ++n) _Pragma("unroll") for (int k = 0; k < 2; ++k) dst[n][k] = *(const PG8_LAS bf16x8*)(lds + PG8_SB(b, h) + boff + n * 2048 + k * 1024); } while (0)
; #define PG8_MMA(ai, bj, At, Bt) do { __builtin_amdgcn_s_setprio(1); _Pragma("unroll") for (int m = 0; m < 4; ++m) _Pragma("unroll") for (int n = 0; n < 2; ++n) _Pragma("unroll") for (int k = 0; k < 2; ++k) \
;         acc[ai][bj][m][n] = __builtin_amdgcn_mfma_f32_16x16x32_bf16(Bt[n][k], At[m][k], acc[ai][bj][m][n], 0, 0, 0); __builtin_amdgcn_s_setprio(0); } while (0)
; #define PG8_BAR __builtin_amdgcn_s_barrier()
; template <class Epi, class Sched, bool ALIGN_EPI = false, bool SP2 = false>
; __device__ __forceinline__ void gemm_phase(PG8_LAS unsigned char* lds, const Gemm g, const Sched& S, const Epi& E, const int tid) {
;     ...
;             PG8_LDB(B0, 0, 0); PG8_LDB(B1, 0, 1); PG8_SCHED; PG8_LDA(At, 0, 0); PG8_STAGE(PG8_SA(1, 1), a1 + hstep, voffA);
;             PG8_WAIT_V(8); PG8_WAIT_L(0); PG8_BAR; PG8_MMA(0, 0, At, B0); PG8_MMA(0, 1, At, B1); PG8_BAR; PG8_SCHED;
;             PG8_LDA(At, 0, 1); PG8_STAGE(PG8_SB(0, 0), b2, voffB); PG8_STAGE(PG8_SB(0, 1), b2 + hstep, voffB); PG8_STAGE(PG8_SA(0, 0), a2, voffA);
;             PG8_WAIT_V(8); PG8_WAIT_L(0); PG8_BAR; PG8_MMA(1, 0, At, B0); PG8_MMA(1, 1, At, B1); PG8_BAR; PG8_SCHED;
;             PG8_LDB(B0, 1, 0); PG8_LDB(B1, 1, 1); PG8_SCHED; PG8_LDA(At, 1, 0); PG8_STAGE(PG8_SA(0, 1), a2 + hstep, voffA);
;             PG8_WAIT_V(8); PG8_WAIT_L(0); PG8_BAR; PG8_MMA(0, 0, At, B0); PG8_MMA(0, 1, At, B1); PG8_BAR; PG8_SCHED;
;             PG8_LDA(At, 1, 1); PG8_STAGE(PG8_SB(1, 0), b3, voffB); PG8_STAGE(PG8_SB(1, 1), b3 + hstep, voffB); PG8_STAGE(PG8_SA(1, 0), a3, voffA);
;             PG8_WAIT_V(8); PG8_WAIT_L(0); PG8_BAR; PG8_MMA(1, 0, At, B0); PG8_MMA(1, 1, At, B1); PG8_BAR; PG8_SCHED;
	v_mfma_f32_16x16x32_bf16 v[124:127], v[144:147], v[176:179], v[124:127]
	v_mfma_f32_16x16x32_bf16 v[120:123], v[152:155], v[176:179], v[120:123]
	v_mfma_f32_16x16x32_bf16 v[108:111], v[144:147], v[184:187], v[108:111]
	v_mfma_f32_16x16x32_bf16 v[104:107], v[152:155], v[184:187], v[104:107]
	v_mfma_f32_16x16x32_bf16 v[92:95], v[144:147], v[192:195], v[92:95]
	v_mfma_f32_16x16x32_bf16 v[88:91], v[152:155], v[192:195], v[88:91]
	v_mfma_f32_16x16x32_bf16 v[76:79], v[144:147], v[200:203], v[76:79]
	v_mfma_f32_16x16x32_bf16 v[72:75], v[152:155], v[200:203], v[72:75]
	v_mfma_f32_16x16x32_bf16 v[124:127], v[148:151], v[180:183], v[124:127]
	v_mfma_f32_16x16x32_bf16 v[120:123], v[156:159], v[180:183], v[120:123]
	v_mfma_f32_16x16x32_bf16 v[108:111], v[148:151], v[188:191], v[108:111]
	v_mfma_f32_16x16x32_bf16 v[104:107], v[156:159], v[188:191], v[104:107]
	v_mfma_f32_16x16x32_bf16 v[92:95], v[148:151], v[196:199], v[92:95]
	v_mfma_f32_16x16x32_bf16 v[88:91], v[156:159], v[196:199], v[88:91]
	v_mfma_f32_16x16x32_bf16 v[76:79], v[148:151], v[206:209], v[76:79]
	v_mfma_f32_16x16x32_bf16 v[72:75], v[156:159], v[206:209], v[72:75]
	s_setprio 0
	s_setprio 1
	v_mfma_f32_16x16x32_bf16 v[116:119], v[160:163], v[176:179], v[116:119]
	v_mfma_f32_16x16x32_bf16 v[112:115], v[168:171], v[176:179], v[112:115]
	v_mfma_f32_16x16x32_bf16 v[100:103], v[160:163], v[184:187], v[100:103]
	v_mfma_f32_16x16x32_bf16 v[96:99], v[168:171], v[184:187], v[96:99]
	v_mfma_f32_16x16x32_bf16 v[84:87], v[160:163], v[192:195], v[84:87]
	v_mfma_f32_16x16x32_bf16 v[80:83], v[168:171], v[192:195], v[80:83]
	v_mfma_f32_16x16x32_bf16 v[68:71], v[160:163], v[200:203], v[68:71]
	v_mfma_f32_16x16x32_bf16 v[64:67], v[168:171], v[200:203], v[64:67]
	v_mfma_f32_16x16x32_bf16 v[116:119], v[164:167], v[180:183], v[116:119]
	v_mfma_f32_16x16x32_bf16 v[112:115], v[172:175], v[180:183], v[112:115]
	v_mfma_f32_16x16x32_bf16 v[100:103], v[164:167], v[188:191], v[100:103]
	v_mfma_f32_16x16x32_bf16 v[96:99], v[172:175], v[188:191], v[96:99]
	v_mfma_f32_16x16x32_bf16 v[84:87], v[164:167], v[196:199], v[84:87]
	v_mfma_f32_16x16x32_bf16 v[80:83], v[172:175], v[196:199], v[80:83]
	v_mfma_f32_16x16x32_bf16 v[68:71], v[164:167], v[206:209], v[68:71]
	v_mfma_f32_16x16x32_bf16 v[64:67], v[172:175], v[206:209], v[64:67]
	s_barrier
	s_setprio 0
	s_add_i32 s55, s55, s35
	v_lshl_add_u64 v[140:141], s[28:29], 0, v[204:205]
	s_mov_b32 m0, s55
	ds_read_b128 v[176:179], v143 offset:16384
	ds_read_b128 v[180:183], v143 offset:17408
	ds_read_b128 v[184:187], v143 offset:18432
	ds_read_b128 v[188:191], v143 offset:19456
	ds_read_b128 v[192:195], v143 offset:20480
	ds_read_b128 v[196:199], v143 offset:21504
	ds_read_b128 v[200:203], v143 offset:22528
	ds_read_b128 v[206:209], v143 offset:23552
	global_load_lds_dwordx4 v[140:141], off
	s_add_i32 m0, s55, 0x2000
	s_add_u32 s64, s28, 0x80000
	v_lshl_add_u64 v[210:211], s[28:29], 0, v[128:129]
	s_addc_u32 s65, s29, 0
	s_add_i32 s55, s62, s35
	global_load_lds_dwordx4 v[210:211], off
	v_lshl_add_u64 v[212:213], s[64:65], 0, v[204:205]
	s_mov_b32 m0, s55
	v_lshl_add_u64 v[214:215], s[30:31], 0, v[130:131]
	global_load_lds_dwordx4 v[212:213], off
	v_lshl_add_u64 v[212:213], s[64:65], 0, v[128:129]
	s_add_i32 m0, s55, 0x2000
	s_nop 0
	global_load_lds_dwordx4 v[212:213], off
	v_lshl_add_u64 v[212:213], s[30:31], 0, v[132:133]
	s_mov_b32 m0, s37
	s_nop 0
	global_load_lds_dwordx4 v[212:213], off
	s_mov_b32 m0, s38
	s_nop 0
	global_load_lds_dwordx4 v[214:215], off
	s_waitcnt vmcnt(8)
	s_waitcnt lgkmcnt(0)
	s_setprio 1
	s_barrier
	v_mfma_f32_16x16x32_bf16 v[60:63], v[144:147], v[176:179], v[60:63]
	v_mfma_f32_16x16x32_bf16 v[56:59], v[152:155], v[176:179], v[56:59]
	v_mfma_f32_16x16x32_bf16 v[48:51], v[144:147], v[184:187], v[48:51]
	v_mfma_f32_16x16x32_bf16 v[40:43], v[152:155], v[184:187], v[40:43]
	v_mfma_f32_16x16x32_bf16 v[32:35], v[144:147], v[192:195], v[32:35]
	v_mfma_f32_16x16x32_bf16 v[24:27], v[152:155], v[192:195], v[24:27]
	v_mfma_f32_16x16x32_bf16 v[16:19], v[144:147], v[200:203], v[16:19]
	v_mfma_f32_16x16x32_bf16 v[8:11], v[152:155], v[200:203], v[8:11]
	v_mfma_f32_16x16x32_bf16 v[60:63], v[148:151], v[180:183], v[60:63]
	v_mfma_f32_16x16x32_bf16 v[56:59], v[156:159], v[180:183], v[56:59]
	v_mfma_f32_16x16x32_bf16 v[48:51], v[148:151], v[188:191], v[48:51]
	v_mfma_f32_16x16x32_bf16 v[40:43], v[156:159], v[188:191], v[40:43]
	v_mfma_f32_16x16x32_bf16 v[32:35], v[148:151], v[196:199], v[32:35]
	v_mfma_f32_16x16x32_bf16 v[24:27], v[156:159], v[196:199], v[24:27]
	v_mfma_f32_16x16x32_bf16 v[16:19], v[148:151], v[206:209], v[16:19]
	v_mfma_f32_16x16x32_bf16 v[8:11], v[156:159], v[206:209], v[8:11]
	s_setprio 0
	s_setprio 1
	v_mfma_f32_16x16x32_bf16 v[52:55], v[160:163], v[176:179], v[52:55]
	v_mfma_f32_16x16x32_bf16 v[44:47], v[168:171], v[176:179], v[44:47]
	v_mfma_f32_16x16x32_bf16 v[36:39], v[160:163], v[184:187], v[36:39]
	v_mfma_f32_16x16x32_bf16 v[28:31], v[168:171], v[184:187], v[28:31]
	v_mfma_f32_16x16x32_bf16 v[20:23], v[160:163], v[192:195], v[20:23]
	v_mfma_f32_16x16x32_bf16 v[12:15], v[168:171], v[192:195], v[12:15]
	v_mfma_f32_16x16x32_bf16 v[4:7], v[160:163], v[200:203], v[4:7]
	v_mfma_f32_16x16x32_bf16 v[0:3], v[168:171], v[200:203], v[0:3]
	v_mfma_f32_16x16x32_bf16 v[52:55], v[164:167], v[180:183], v[52:55]
	v_mfma_f32_16x16x32_bf16 v[44:47], v[172:175], v[180:183], v[44:47]
	v_mfma_f32_16x16x32_bf16 v[36:39], v[164:167], v[188:191], v[36:39]
	v_mfma_f32_16x16x32_bf16 v[28:31], v[172:175], v[188:191], v[28:31]
	v_mfma_f32_16x16x32_bf16 v[20:23], v[164:167], v[196:199], v[20:23]
	v_mfma_f32_16x16x32_bf16 v[12:15], v[172:175], v[196:199], v[12:15]
	v_mfma_f32_16x16x32_bf16 v[4:7], v[164:167], v[206:209], v[4:7]
	v_mfma_f32_16x16x32_bf16 v[0:3], v[172:175], v[206:209], v[0:3]
	s_barrier
; #define PG8_STAGE(bufoff, gbase, voff) do { _Pragma("unroll") for (int _i = 0; _i < 2; ++_i) \
;         __builtin_amdgcn_global_load_lds((const unsigned*)((const char*)(gbase) + (voff)[_i]), (PG8_LAS unsigned*)(lds + (bufoff) + ldsw + _i * 8192), 16, 0, 0); } while (0)
; #define PG8_LDA(dst, b, h) do { _Pragma("unroll") for (int m = 0; m < 4; ++m) _Pragma("unroll") for (int k = 0; k < 2; ++k) dst[m][k] = *(const PG8_LAS bf16x8*)(lds + PG8_SA(b, h) + aoff + m * 2048 + k * 1024); } while (0)
; #define PG8_LDB(dst, b, h) do { _Pragma("unroll") for (int n = 0; n < 2; ++n) _Pragma("unroll") for (int k = 0; k < 2; ++k) dst[n][k] = *(const PG8_LAS bf16x8*)(lds + PG8_SB(b, h) + boff + n * 2048 + k * 1024); } while (0)
; #define PG8_MMA(ai, bj, At, Bt) do { __builtin_amdgcn_s_setprio(1); _Pragma("unroll") for (int m = 0; m < 4; ++m) _Pragma("unroll") for (int n = 0; n < 2; ++n) _Pragma("unroll") for (int k = 0; k < 2; ++k) \
;         acc[ai][bj][m][n] = __builtin_amdgcn_mfma_f32_16x16x32_bf16(Bt[n][k], At[m][k], acc[ai][bj][m][n], 0, 0, 0); __builtin_amdgcn_s_setprio(0); } while (0)
; #define PG8_WAIT_V(n) asm volatile("s_waitcnt vmcnt(" #n ")" ::: "memory")
; #define PG8_WAIT_L(n) asm volatile("s_waitcnt lgkmcnt(" #n ")" ::: "memory")
; #define PG8_BAR __builtin_amdgcn_s_barrier()
; #define PG8_SCHED __builtin_amdgcn_sched_barrier(0)
; template <class Epi, class Sched, bool ALIGN_EPI = false, bool SP2 = false>
; __device__ __forceinline__ void gemm_phase(PG8_LAS unsigned char* lds, const Gemm g, const Sched& S, const Epi& E, const int tid) {
;     ...
;             PG8_LDB(B0, 1, 0); PG8_LDB(B1, 1, 1); PG8_SCHED; PG8_LDA(At, 1, 0); PG8_STAGE(PG8_SA(0, 1), a2 + hstep, voffA);
;             PG8_WAIT_V(8); PG8_WAIT_L(0); PG8_BAR; PG8_MMA(0, 0, At, B0); PG8_MMA(0, 1, At, B1); PG8_BAR; PG8_SCHED;
;             PG8_LDA(At, 1, 1); PG8_STAGE(PG8_SB(1, 0), b3, voffB); PG8_STAGE(PG8_SB(1, 1), b3 + hstep, voffB); PG8_STAGE(PG8_SA(1, 0), a3, voffA);
;             PG8_WAIT_V(8); PG8_WAIT_L(0); PG8_BAR; PG8_MMA(1, 0, At, B0); PG8_MMA(1, 1, At, B1); PG8_BAR; PG8_SCHED;
	s_setprio 0
	s_add_i32 s55, 0, 0x18000
	v_add_u32_e32 v138, s55, v139
	s_add_i32 s62, 0, 0x1c000
	ds_read_b128 v[144:147], v138
	ds_read_b128 v[148:151], v138 offset:1024
	ds_read_b128 v[152:155], v138 offset:2048
	ds_read_b128 v[156:159], v138 offset:3072
	v_add_u32_e32 v138, s62, v139
	ds_read_b128 v[160:163], v138
	ds_read_b128 v[164:167], v138 offset:1024
	ds_read_b128 v[168:171], v138 offset:2048
	ds_read_b128 v[172:175], v138 offset:3072
	s_add_u32 s30, s30, 0x80000
	s_addc_u32 s31, s31, 0
	s_mov_b32 m0, s40
	v_lshl_add_u64 v[216:217], s[30:31], 0, v[132:133]
	ds_read_b128 v[176:179], v143 offset:32768
	ds_read_b128 v[180:183], v143 offset:33792
	ds_read_b128 v[184:187], v143 offset:34816
	ds_read_b128 v[188:191], v143 offset:35840
	ds_read_b128 v[192:195], v143 offset:36864
	ds_read_b128 v[196:199], v143 offset:37888
	ds_read_b128 v[200:203], v143 offset:38912
	ds_read_b128 v[206:209], v143 offset:39936
	global_load_lds_dwordx4 v[216:217], off
	v_lshl_add_u64 v[216:217], s[30:31], 0, v[130:131]
	s_mov_b32 m0, s42
	s_nop 0
	global_load_lds_dwordx4 v[216:217], off
	s_waitcnt vmcnt(8)
	s_waitcnt lgkmcnt(0)
	s_setprio 1
	s_barrier
	v_mfma_f32_16x16x32_bf16 v[124:127], v[144:147], v[176:179], v[124:127]
	v_mfma_f32_16x16x32_bf16 v[120:123], v[152:155], v[176:179], v[120:123]
	v_mfma_f32_16x16x32_bf16 v[108:111], v[144:147], v[184:187], v[108:111]
	v_mfma_f32_16x16x32_bf16 v[104:107], v[152:155], v[184:187], v[104:107]
	v_mfma_f32_16x16x32_bf16 v[92:95], v[144:147], v[192:195], v[92:95]
	v_mfma_f32_16x16x32_bf16 v[88:91], v[152:155], v[192:195], v[88:91]
	v_mfma_f32_16x16x32_bf16 v[76:79], v[144:147], v[200:203], v[76:79]
	v_mfma_f32_16x16x32_bf16 v[72:75], v[152:155], v[200:203], v[72:75]
	v_mfma_f32_16x16x32_bf16 v[124:127], v[148:151], v[180:183], v[124:127]
	v_mfma_f32_16x16x32_bf16 v[120:123], v[156:159], v[180:183], v[120:123]
	v_mfma_f32_16x16x32_bf16 v[108:111], v[148:151], v[188:191], v[108:111]
	v_mfma_f32_16x16x32_bf16 v[104:107], v[156:159], v[188:191], v[104:107]
	v_mfma_f32_16x16x32_bf16 v[92:95], v[148:151], v[196:199], v[92:95]
	v_mfma_f32_16x16x32_bf16 v[88:91], v[156:159], v[196:199], v[88:91]
	v_mfma_f32_16x16x32_bf16 v[76:79], v[148:151], v[206:209], v[76:79]
	v_mfma_f32_16x16x32_bf16 v[72:75], v[156:159], v[206:209], v[72:75]
	s_setprio 0
	s_setprio 1
	v_mfma_f32_16x16x32_bf16 v[116:119], v[160:163], v[176:179], v[116:119]
	v_mfma_f32_16x16x32_bf16 v[112:115], v[168:171], v[176:179], v[112:115]
	v_mfma_f32_16x16x32_bf16 v[100:103], v[160:163], v[184:187], v[100:103]
	v_mfma_f32_16x16x32_bf16 v[96:99], v[168:171], v[184:187], v[96:99]
	v_mfma_f32_16x16x32_bf16 v[84:87], v[160:163], v[192:195], v[84:87]
	v_mfma_f32_16x16x32_bf16 v[80:83], v[168:171], v[192:195], v[80:83]
	v_mfma_f32_16x16x32_bf16 v[68:71], v[160:163], v[200:203], v[68:71]
	v_mfma_f32_16x16x32_bf16 v[64:67], v[168:171], v[200:203], v[64:67]
	v_mfma_f32_16x16x32_bf16 v[116:119], v[164:167], v[180:183], v[116:119]
	v_mfma_f32_16x16x32_bf16 v[112:115], v[172:175], v[180:183], v[112:115]
	v_mfma_f32_16x16x32_bf16 v[100:103], v[164:167], v[188:191], v[100:103]
	v_mfma_f32_16x16x32_bf16 v[96:99], v[172:175], v[188:191], v[96:99]
	v_mfma_f32_16x16x32_bf16 v[84:87], v[164:167], v[196:199], v[84:87]
	v_mfma_f32_16x16x32_bf16 v[80:83], v[172:175], v[196:199], v[80:83]
	v_mfma_f32_16x16x32_bf16 v[68:71], v[164:167], v[206:209], v[68:71]
	v_mfma_f32_16x16x32_bf16 v[64:67], v[172:175], v[206:209], v[64:67]
	s_barrier
; #define PG8_STAGE(bufoff, gbase, voff) do { _Pragma("unroll") for (int _i = 0; _i < 2; ++_i) \
;         __builtin_amdgcn_global_load_lds((const unsigned*)((const char*)(gbase) + (voff)[_i]), (PG8_LAS unsigned*)(lds + (bufoff) + ldsw + _i * 8192), 16, 0, 0); } while (0)
; #define PG8_BAR __builtin_amdgcn_s_barrier()
; template <class Epi, class Sched, bool ALIGN_EPI = false, bool SP2 = false>
; __device__ __forceinline__ void gemm_phase(PG8_LAS unsigned char* lds, const Gemm g, const Sched& S, const Epi& E, const int tid) {
;     ...
;             PG8_LDB(B0, 1, 0); PG8_LDB(B1, 1, 1); PG8_SCHED; PG8_LDA(At, 1, 0); PG8_STAGE(PG8_SA(0, 1), a2 + hstep, voffA);
;             PG8_WAIT_V(8); PG8_WAIT_L(0); PG8_BAR; PG8_MMA(0, 0, At, B0); PG8_MMA(0, 1, At, B1); PG8_BAR; PG8_SCHED;
;             PG8_LDA(At, 1, 1); PG8_STAGE(PG8_SB(1, 0), b3, voffB); PG8_STAGE(PG8_SB(1, 1), b3 + hstep, voffB); PG8_STAGE(PG8_SA(1, 0), a3, voffA);
;             PG8_WAIT_V(8); PG8_WAIT_L(0); PG8_BAR; PG8_MMA(1, 0, At, B0); PG8_MMA(1, 1, At, B1); PG8_BAR; PG8_SCHED;
;             } else {
;             PG8_LDB(B0, 0, 0); PG8_SCHED; PG8_LDA(At, 0, 0); PG8_STAGE(PG8_SA(1, 1), a1 + hstep, voffA);
;             PG8_WAIT_L(8); PG8_BAR; PG8_WAIT_L(0); PG8_MMA(0, 0, At, B0); PG8_BAR; PG8_SCHED;
;             PG8_LDB(B1, 0, 1); PG8_STAGE(PG8_SB(0, 0), b2, voffB);
;             PG8_BAR; PG8_WAIT_L(0); PG8_MMA(0, 1, At, B1); PG8_BAR;
;             PG8_LDA(At, 0, 1); PG8_STAGE(PG8_SA(0, 0), a2, voffA);
;             PG8_BAR; PG8_WAIT_L(0); PG8_MMA(1, 0, At, B0); PG8_BAR; PG8_SCHED;
;             PG8_STAGE(PG8_SB(0, 1), b2 + hstep, voffB);
;             PG8_WAIT_V(6); PG8_BAR; PG8_MMA(1, 1, At, B1); PG8_BAR;
;             PG8_LDB(B0, 1, 0); PG8_SCHED; PG8_LDA(At, 1, 0); PG8_STAGE(PG8_SA(0, 1), a2 + hstep, voffA);
;             PG8_WAIT_L(8); PG8_BAR; PG8_WAIT_L(0); PG8_MMA(0, 0, At, B0); PG8_BAR; PG8_SCHED;
;             PG8_LDB(B1, 1, 1); PG8_STAGE(PG8_SB(1, 0), b3, voffB);
;             PG8_BAR; PG8_WAIT_L(0); PG8_MMA(0, 1, At, B1); PG8_BAR;
;             PG8_LDA(At, 1, 1); PG8_STAGE(PG8_SA(1, 0), a3, voffA);
;             PG8_BAR; PG8_WAIT_L(0); PG8_MMA(1, 0, At, B0); PG8_BAR; PG8_SCHED;
;             PG8_STAGE(PG8_SB(1, 1), b3 + hstep, voffB);
;             PG8_WAIT_V(6); PG8_BAR; PG8_MMA(1, 1, At, B1); PG8_BAR;
;             }
;         }
;         if constexpr (ALIGN_EPI) { if (wr == 0) PG8_BAR; }
	s_setprio 0
	s_add_i32 s30, s55, s35
	v_lshl_add_u64 v[140:141], v[140:141], 0, s[70:71]
	s_mov_b32 m0, s30
	ds_read_b128 v[176:179], v143 offset:49152
	ds_read_b128 v[180:183], v143 offset:50176
	ds_read_b128 v[184:187], v143 offset:51200
	ds_read_b128 v[188:191], v143 offset:52224
	ds_read_b128 v[192:195], v143 offset:53248
	ds_read_b128 v[196:199], v143 offset:54272
	ds_read_b128 v[200:203], v143 offset:55296
	ds_read_b128 v[206:209], v143 offset:56320
	global_load_lds_dwordx4 v[140:141], off
	s_add_i32 m0, s30, 0x2000
	s_add_u32 s28, s28, 0x80080
	v_lshl_add_u64 v[140:141], v[210:211], 0, s[70:71]
	s_addc_u32 s29, s29, 0
	s_add_i32 s30, s62, s35
	global_load_lds_dwordx4 v[140:141], off
	v_lshl_add_u64 v[140:141], s[28:29], 0, v[204:205]
	s_mov_b32 m0, s30
	s_nop 0
	global_load_lds_dwordx4 v[140:141], off
	v_lshl_add_u64 v[140:141], s[28:29], 0, v[128:129]
	s_add_i32 m0, s30, 0x2000
	s_nop 0
	global_load_lds_dwordx4 v[140:141], off
	v_lshl_add_u64 v[140:141], v[212:213], 0, s[70:71]
	s_mov_b32 m0, s46
	s_nop 0
	global_load_lds_dwordx4 v[140:141], off
	v_lshl_add_u64 v[140:141], v[214:215], 0, s[70:71]
	s_mov_b32 m0, s47
	s_nop 0
	global_load_lds_dwordx4 v[140:141], off
	s_waitcnt vmcnt(8)
	s_waitcnt lgkmcnt(0)
	s_setprio 1
	s_barrier
	v_mfma_f32_16x16x32_bf16 v[60:63], v[144:147], v[176:179], v[60:63]
	v_mfma_f32_16x16x32_bf16 v[56:59], v[152:155], v[176:179], v[56:59]
	v_mfma_f32_16x16x32_bf16 v[48:51], v[144:147], v[184:187], v[48:51]
	v_mfma_f32_16x16x32_bf16 v[40:43], v[152:155], v[184:187], v[40:43]
	v_mfma_f32_16x16x32_bf16 v[32:35], v[144:147], v[192:195], v[32:35]
	v_mfma_f32_16x16x32_bf16 v[24:27], v[152:155], v[192:195], v[24:27]
	v_mfma_f32_16x16x32_bf16 v[16:19], v[144:147], v[200:203], v[16:19]
	v_mfma_f32_16x16x32_bf16 v[8:11], v[152:155], v[200:203], v[8:11]
	v_mfma_f32_16x16x32_bf16 v[60:63], v[148:151], v[180:183], v[60:63]
	v_mfma_f32_16x16x32_bf16 v[56:59], v[156:159], v[180:183], v[56:59]
	v_mfma_f32_16x16x32_bf16 v[48:51], v[148:151], v[188:191], v[48:51]
	v_mfma_f32_16x16x32_bf16 v[40:43], v[156:159], v[188:191], v[40:43]
	v_mfma_f32_16x16x32_bf16 v[32:35], v[148:151], v[196:199], v[32:35]
	v_mfma_f32_16x16x32_bf16 v[24:27], v[156:159], v[196:199], v[24:27]
	v_mfma_f32_16x16x32_bf16 v[16:19], v[148:151], v[206:209], v[16:19]
	v_mfma_f32_16x16x32_bf16 v[8:11], v[156:159], v[206:209], v[8:11]
	s_setprio 0
	s_setprio 1
	v_mfma_f32_16x16x32_bf16 v[52:55], v[160:163], v[176:179], v[52:55]
	v_mfma_f32_16x16x32_bf16 v[44:47], v[168:171], v[176:179], v[44:47]
	v_mfma_f32_16x16x32_bf16 v[36:39], v[160:163], v[184:187], v[36:39]
	v_mfma_f32_16x16x32_bf16 v[28:31], v[168:171], v[184:187], v[28:31]
	v_mfma_f32_16x16x32_bf16 v[20:23], v[160:163], v[192:195], v[20:23]
	v_mfma_f32_16x16x32_bf16 v[12:15], v[168:171], v[192:195], v[12:15]
	v_mfma_f32_16x16x32_bf16 v[4:7], v[160:163], v[200:203], v[4:7]
	v_mfma_f32_16x16x32_bf16 v[0:3], v[168:171], v[200:203], v[0:3]
	v_mfma_f32_16x16x32_bf16 v[52:55], v[164:167], v[180:183], v[52:55]
	v_mfma_f32_16x16x32_bf16 v[44:47], v[172:175], v[180:183], v[44:47]
	v_mfma_f32_16x16x32_bf16 v[36:39], v[164:167], v[188:191], v[36:39]
	v_mfma_f32_16x16x32_bf16 v[28:31], v[172:175], v[188:191], v[28:31]
	v_mfma_f32_16x16x32_bf16 v[20:23], v[164:167], v[196:199], v[20:23]
	v_mfma_f32_16x16x32_bf16 v[12:15], v[172:175], v[196:199], v[12:15]
	v_mfma_f32_16x16x32_bf16 v[4:7], v[164:167], v[206:209], v[4:7]
	v_mfma_f32_16x16x32_bf16 v[0:3], v[172:175], v[206:209], v[0:3]
	s_barrier
	s_setprio 0
	s_add_i32 s54, s54, 2
	s_add_u32 s26, s26, 0x100
	s_addc_u32 s27, s27, 0
	s_add_u32 s52, s52, 0x100
	s_addc_u32 s53, s53, 0
	s_cmp_gt_u32 s54, 29
	s_cbranch_scc0 .LBB0_661
	s_and_b64 vcc, exec, s[14:15]
	s_cbranch_vccz .LBB0_664
	s_barrier

; #define PG8_STAGE(bufoff, gbase, voff) do { _Pragma("unroll") for (int _i = 0; _i < 2; ++_i) \
;         __builtin_amdgcn_global_load_lds((const unsigned*)((const char*)(gbase) + (voff)[_i]), (PG8_LAS unsigned*)(lds + (bufoff) + ldsw + _i * 8192), 16, 0, 0); } while (0)
; #define PG8_LDA(dst, b, h) do { _Pragma("unroll") for (int m = 0; m < 4; ++m) _Pragma("unroll") for (int k = 0; k < 2; ++k) dst[m][k] = *(const PG8_LAS bf16x8*)(lds + PG8_SA(b, h) + aoff + m * 2048 + k * 1024); } while (0)
; template <class Epi, class Sched, bool ALIGN_EPI = false, bool SP2 = false>
; __device__ __forceinline__ void gemm_phase(PG8_LAS unsigned char* lds, const Gemm g, const Sched& S, const Epi& E, const int tid) {
;     ...
;         const bool has_next = S.next(ui + 1, nxt);
;         const char* nA = has_next ? (const char*)g.A + (size_t)nxt.pm * tstep : cA; const char* nB = has_next ? (const char*)g.Bt + (size_t)nxt.pn * tstep : cB;
;         for (int t = 0; t < nt; t += 2) {
;             const bool last = (t == nt - 2);
;             const char* a1 = cA + (size_t)(t + 1) * kstep;
;             const char* a2 = last ? nA : cA + (size_t)(t + 2) * kstep; const char* b2 = last ? nB : cB + (size_t)(t + 2) * kstep;
;             const char* a3 = a2 + kstep; const char* b3 = b2 + kstep;
;             if (last && has_next) S.a_ready(nxt);
;             if constexpr (SP2) {
;             PG8_LDB(B0, 0, 0); PG8_LDB(B1, 0, 1); PG8_SCHED; PG8_LDA(At, 0, 0); PG8_STAGE(PG8_SA(1, 1), a1 + hstep, voffA);
;             PG8_WAIT_V(8); PG8_WAIT_L(0); PG8_BAR; PG8_MMA(0, 0, At, B0); PG8_MMA(0, 1, At, B1); PG8_BAR; PG8_SCHED;
;             PG8_LDA(At, 0, 1); PG8_STAGE(PG8_SB(0, 0), b2, voffB); PG8_STAGE(PG8_SB(0, 1), b2 + hstep, voffB); PG8_STAGE(PG8_SA(0, 0), a2, voffA);
;             PG8_WAIT_V(8); PG8_WAIT_L(0); PG8_BAR; PG8_MMA(1, 0, At, B0); PG8_MMA(1, 1, At, B1); PG8_BAR; PG8_SCHED;
;             PG8_LDB(B0, 1, 0); PG8_LDB(B1, 1, 1); PG8_SCHED; PG8_LDA(At, 1, 0); PG8_STAGE(PG8_SA(0, 1), a2 + hstep, voffA);
;             PG8_WAIT_V(8); PG8_WAIT_L(0); PG8_BAR; PG8_MMA(0, 0, At, B0); PG8_MMA(0, 1, At, B1); PG8_BAR; PG8_SCHED;
;             PG8_LDA(At, 1, 1); PG8_STAGE(PG8_SB(1, 0), b3, voffB); PG8_STAGE(PG8_SB(1, 1), b3 + hstep, voffB); PG8_STAGE(PG8_SA(1, 0), a3, voffA);
;             PG8_WAIT_V(8); PG8_WAIT_L(0); PG8_BAR; PG8_MMA(1, 0, At, B0); PG8_MMA(1, 1, At, B1); PG8_BAR; PG8_SCHED;
.LBB0_679:
	s_ashr_i32 s29, s28, 31
	s_lshl_b64 s[30:31], s[28:29], 20
	s_add_u32 s30, s50, s30
	s_addc_u32 s31, s51, s31
	s_and_b64 s[34:35], s[6:7], exec
	s_cselect_b32 s29, s31, s45
	s_cselect_b32 s43, s30, s44
	s_ashr_i32 s27, s26, 31
	s_lshl_b64 s[34:35], s[26:27], 20
	s_add_u32 s34, s52, s34
	s_addc_u32 s35, s53, s35
	s_and_b64 s[48:49], s[6:7], exec
	s_cselect_b32 s27, s35, s47
	s_cselect_b32 s69, s34, s46
	s_add_u32 s44, s44, 0x80080
	s_addc_u32 s45, s45, 0
	s_add_u32 vcc_lo, s46, 0x100
	s_addc_u32 vcc_hi, s47, 0
	s_mov_b32 s76, -2
	s_waitcnt vmcnt(0)
	s_add_u32 s46, s44, 0xfff80080
	s_addc_u32 s47, s45, -1
	s_add_i32 s77, 0, 0x10000
	s_cmp_eq_u32 s76, 28
	s_cselect_b32 s49, s29, s47
	s_cselect_b32 s48, s43, s46
	s_cselect_b32 s47, s27, vcc_hi
	s_cselect_b32 s46, s69, vcc_lo
	s_add_i32 s80, 0, 0x14000
	v_add_u32_e32 v152, s77, v166
	v_add_u32_e32 v164, s80, v166
	ds_read_b128 v[128:131], v152
	ds_read_b128 v[144:147], v152 offset:1024
	ds_read_b128 v[148:151], v152 offset:2048
	ds_read_b128 v[152:155], v152 offset:3072
	ds_read_b128 v[156:159], v164
	ds_read_b128 v[160:163], v164 offset:1024
	ds_read_b128 v[168:171], v164 offset:2048
	ds_read_b128 v[172:175], v164 offset:3072
	v_lshl_add_u64 v[164:165], s[44:45], 0, v[140:141]
	s_add_i32 m0, s37, 0xc000
	ds_read_b128 v[176:179], v167
	ds_read_b128 v[180:183], v167 offset:1024
	ds_read_b128 v[184:187], v167 offset:2048
	ds_read_b128 v[188:191], v167 offset:3072
	ds_read_b128 v[192:195], v167 offset:4096
	ds_read_b128 v[196:199], v167 offset:5120
	ds_read_b128 v[200:203], v167 offset:6144
	ds_read_b128 v[214:217], v167 offset:7168
	global_load_lds_dwordx4 v[164:165], off
	v_lshl_add_u64 v[164:165], s[44:45], 0, v[142:143]
	s_add_i32 m0, s37, 0xe000
	s_nop 0
	global_load_lds_dwordx4 v[164:165], off
	s_waitcnt vmcnt(24)
	s_waitcnt lgkmcnt(0)
	s_setprio 1
	s_barrier
	v_mfma_f32_16x16x32_bf16 v[124:127], v[128:131], v[176:179], 0
	v_mfma_f32_16x16x32_bf16 v[120:123], v[148:151], v[176:179], 0
	v_mfma_f32_16x16x32_bf16 v[108:111], v[128:131], v[184:187], 0
	v_mfma_f32_16x16x32_bf16 v[104:107], v[148:151], v[184:187], 0
	v_mfma_f32_16x16x32_bf16 v[92:95], v[128:131], v[192:195], 0
	v_mfma_f32_16x16x32_bf16 v[88:91], v[148:151], v[192:195], 0
	v_mfma_f32_16x16x32_bf16 v[76:79], v[128:131], v[200:203], 0
	v_mfma_f32_16x16x32_bf16 v[72:75], v[148:151], v[200:203], 0
	v_mfma_f32_16x16x32_bf16 v[124:127], v[144:147], v[180:183], v[124:127]
	v_mfma_f32_16x16x32_bf16 v[120:123], v[152:155], v[180:183], v[120:123]
	v_mfma_f32_16x16x32_bf16 v[108:111], v[144:147], v[188:191], v[108:111]
	v_mfma_f32_16x16x32_bf16 v[104:107], v[152:155], v[188:191], v[104:107]
	v_mfma_f32_16x16x32_bf16 v[92:95], v[144:147], v[196:199], v[92:95]
	v_mfma_f32_16x16x32_bf16 v[88:91], v[152:155], v[196:199], v[88:91]
	v_mfma_f32_16x16x32_bf16 v[76:79], v[144:147], v[214:217], v[76:79]
	v_mfma_f32_16x16x32_bf16 v[72:75], v[152:155], v[214:217], v[72:75]
	s_setprio 0
	s_setprio 1
	v_mfma_f32_16x16x32_bf16 v[116:119], v[156:159], v[176:179], 0
	v_mfma_f32_16x16x32_bf16 v[112:115], v[168:171], v[176:179], 0
	v_mfma_f32_16x16x32_bf16 v[100:103], v[156:159], v[184:187], 0
	v_mfma_f32_16x16x32_bf16 v[96:99], v[168:171], v[184:187], 0
	v_mfma_f32_16x16x32_bf16 v[84:87], v[156:159], v[192:195], 0
	v_mfma_f32_16x16x32_bf16 v[80:83], v[168:171], v[192:195], 0
	v_mfma_f32_16x16x32_bf16 v[68:71], v[156:159], v[200:203], 0
	v_mfma_f32_16x16x32_bf16 v[64:67], v[168:171], v[200:203], 0
	v_mfma_f32_16x16x32_bf16 v[116:119], v[160:163], v[180:183], v[116:119]
	v_mfma_f32_16x16x32_bf16 v[112:115], v[172:175], v[180:183], v[112:115]
	v_mfma_f32_16x16x32_bf16 v[100:103], v[160:163], v[188:191], v[100:103]
	v_mfma_f32_16x16x32_bf16 v[96:99], v[172:175], v[188:191], v[96:99]
	v_mfma_f32_16x16x32_bf16 v[84:87], v[160:163], v[196:199], v[84:87]
	v_mfma_f32_16x16x32_bf16 v[80:83], v[172:175], v[196:199], v[80:83]
	v_mfma_f32_16x16x32_bf16 v[68:71], v[160:163], v[214:217], v[68:71]
	v_mfma_f32_16x16x32_bf16 v[64:67], v[172:175], v[214:217], v[64:67]
	s_barrier
	s_setprio 0
	s_add_i32 s77, s77, s54
	v_lshl_add_u64 v[164:165], s[46:47], 0, v[134:135]
	s_mov_b32 m0, s77
	ds_read_b128 v[176:179], v167 offset:16384
	ds_read_b128 v[180:183], v167 offset:17408
	ds_read_b128 v[184:187], v167 offset:18432
	ds_read_b128 v[188:191], v167 offset:19456
	ds_read_b128 v[192:195], v167 offset:20480
	ds_read_b128 v[196:199], v167 offset:21504
	ds_read_b128 v[200:203], v167 offset:22528
	ds_read_b128 v[214:217], v167 offset:23552
	global_load_lds_dwordx4 v[164:165], off
	s_add_i32 m0, s77, 0x2000
	s_add_u32 s78, s46, 0x80000
	v_lshl_add_u64 v[206:207], s[46:47], 0, v[138:139]
	s_addc_u32 s79, s47, 0
	s_add_i32 s77, s80, s54
	global_load_lds_dwordx4 v[206:207], off
	v_lshl_add_u64 v[208:209], s[78:79], 0, v[134:135]
	s_mov_b32 m0, s77
	v_lshl_add_u64 v[210:211], s[48:49], 0, v[136:137]
	global_load_lds_dwordx4 v[208:209], off
	v_lshl_add_u64 v[208:209], s[78:79], 0, v[138:139]
	s_add_i32 m0, s77, 0x2000
	s_nop 0
	global_load_lds_dwordx4 v[208:209], off
	v_lshl_add_u64 v[208:209], s[48:49], 0, v[132:133]
	s_mov_b32 m0, s37
	s_nop 0
	global_load_lds_dwordx4 v[208:209], off
	s_mov_b32 m0, s55
	s_nop 0
	global_load_lds_dwordx4 v[210:211], off
	s_waitcnt vmcnt(8)
	s_waitcnt lgkmcnt(0)
	s_setprio 1
	s_barrier
; #define PG8_STAGE(bufoff, gbase, voff) do { _Pragma("unroll") for (int _i = 0; _i < 2; ++_i) \
;         __builtin_amdgcn_global_load_lds((const unsigned*)((const char*)(gbase) + (voff)[_i]), (PG8_LAS unsigned*)(lds + (bufoff) + ldsw + _i * 8192), 16, 0, 0); } while (0)
; #define PG8_LDA(dst, b, h) do { _Pragma("unroll") for (int m = 0; m < 4; ++m) _Pragma("unroll") for (int k = 0; k < 2; ++k) dst[m][k] = *(const PG8_LAS bf16x8*)(lds + PG8_SA(b, h) + aoff + m * 2048 + k * 1024); } while (0)
; #define PG8_LDB(dst, b, h) do { _Pragma("unroll") for (int n = 0; n < 2; ++n) _Pragma("unroll") for (int k = 0; k < 2; ++k) dst[n][k] = *(const PG8_LAS bf16x8*)(lds + PG8_SB(b, h) + boff + n * 2048 + k * 1024); } while (0)
; #define PG8_MMA(ai, bj, At, Bt) do { __builtin_amdgcn_s_setprio(1); _Pragma("unroll") for (int m = 0; m < 4; ++m) _Pragma("unroll") for (int n = 0; n < 2; ++n) _Pragma("unroll") for (int k = 0; k < 2; ++k) \
;         acc[ai][bj][m][n] = __builtin_amdgcn_mfma_f32_16x16x32_bf16(Bt[n][k], At[m][k], acc[ai][bj][m][n], 0, 0, 0); __builtin_amdgcn_s_setprio(0); } while (0)
; #define PG8_BAR __builtin_amdgcn_s_barrier()
; template <class Epi, class Sched, bool ALIGN_EPI = false, bool SP2 = false>
; __device__ __forceinline__ void gemm_phase(PG8_LAS unsigned char* lds, const Gemm g, const Sched& S, const Epi& E, const int tid) {
;     ...
;             PG8_LDB(B0, 0, 0); PG8_LDB(B1, 0, 1); PG8_SCHED; PG8_LDA(At, 0, 0); PG8_STAGE(PG8_SA(1, 1), a1 + hstep, voffA);
;             PG8_WAIT_V(8); PG8_WAIT_L(0); PG8_BAR; PG8_MMA(0, 0, At, B0); PG8_MMA(0, 1, At, B1); PG8_BAR; PG8_SCHED;
;             PG8_LDA(At, 0, 1); PG8_STAGE(PG8_SB(0, 0), b2, voffB); PG8_STAGE(PG8_SB(0, 1), b2 + hstep, voffB); PG8_STAGE(PG8_SA(0, 0), a2, voffA);
;             PG8_WAIT_V(8); PG8_WAIT_L(0); PG8_BAR; PG8_MMA(1, 0, At, B0); PG8_MMA(1, 1, At, B1); PG8_BAR; PG8_SCHED;
;             PG8_LDB(B0, 1, 0); PG8_LDB(B1, 1, 1); PG8_SCHED; PG8_LDA(At, 1, 0); PG8_STAGE(PG8_SA(0, 1), a2 + hstep, voffA);
;             PG8_WAIT_V(8); PG8_WAIT_L(0); PG8_BAR; PG8_MMA(0, 0, At, B0); PG8_MMA(0, 1, At, B1); PG8_BAR; PG8_SCHED;
;             PG8_LDA(At, 1, 1); PG8_STAGE(PG8_SB(1, 0), b3, voffB); PG8_STAGE(PG8_SB(1, 1), b3 + hstep, voffB); PG8_STAGE(PG8_SA(1, 0), a3, voffA);
;             PG8_WAIT_V(8); PG8_WAIT_L(0); PG8_BAR; PG8_MMA(1, 0, At, B0); PG8_MMA(1, 1, At, B1); PG8_BAR; PG8_SCHED;
	v_mfma_f32_16x16x32_bf16 v[60:63], v[128:131], v[176:179], 0
	v_mfma_f32_16x16x32_bf16 v[56:59], v[148:151], v[176:179], 0
	v_mfma_f32_16x16x32_bf16 v[44:47], v[128:131], v[184:187], 0
	v_mfma_f32_16x16x32_bf16 v[40:43], v[148:151], v[184:187], 0
	v_mfma_f32_16x16x32_bf16 v[28:31], v[128:131], v[192:195], 0
	v_mfma_f32_16x16x32_bf16 v[24:27], v[148:151], v[192:195], 0
	v_mfma_f32_16x16x32_bf16 v[12:15], v[128:131], v[200:203], 0
	v_mfma_f32_16x16x32_bf16 v[8:11], v[148:151], v[200:203], 0
	v_mfma_f32_16x16x32_bf16 v[60:63], v[144:147], v[180:183], v[60:63]
	v_mfma_f32_16x16x32_bf16 v[56:59], v[152:155], v[180:183], v[56:59]
	v_mfma_f32_16x16x32_bf16 v[44:47], v[144:147], v[188:191], v[44:47]
	v_mfma_f32_16x16x32_bf16 v[40:43], v[152:155], v[188:191], v[40:43]
	v_mfma_f32_16x16x32_bf16 v[28:31], v[144:147], v[196:199], v[28:31]
	v_mfma_f32_16x16x32_bf16 v[24:27], v[152:155], v[196:199], v[24:27]
	v_mfma_f32_16x16x32_bf16 v[12:15], v[144:147], v[214:217], v[12:15]
	v_mfma_f32_16x16x32_bf16 v[8:11], v[152:155], v[214:217], v[8:11]
	s_setprio 0
	s_setprio 1
	v_mfma_f32_16x16x32_bf16 v[52:55], v[156:159], v[176:179], 0
	v_mfma_f32_16x16x32_bf16 v[48:51], v[168:171], v[176:179], 0
	v_mfma_f32_16x16x32_bf16 v[36:39], v[156:159], v[184:187], 0
	v_mfma_f32_16x16x32_bf16 v[32:35], v[168:171], v[184:187], 0
	v_mfma_f32_16x16x32_bf16 v[20:23], v[156:159], v[192:195], 0
	v_mfma_f32_16x16x32_bf16 v[16:19], v[168:171], v[192:195], 0
	v_mfma_f32_16x16x32_bf16 v[4:7], v[156:159], v[200:203], 0
	v_mfma_f32_16x16x32_bf16 v[0:3], v[168:171], v[200:203], 0
	v_mfma_f32_16x16x32_bf16 v[52:55], v[160:163], v[180:183], v[52:55]
	v_mfma_f32_16x16x32_bf16 v[48:51], v[172:175], v[180:183], v[48:51]
	v_mfma_f32_16x16x32_bf16 v[36:39], v[160:163], v[188:191], v[36:39]
	v_mfma_f32_16x16x32_bf16 v[32:35], v[172:175], v[188:191], v[32:35]
	v_mfma_f32_16x16x32_bf16 v[20:23], v[160:163], v[196:199], v[20:23]
	v_mfma_f32_16x16x32_bf16 v[16:19], v[172:175], v[196:199], v[16:19]
	v_mfma_f32_16x16x32_bf16 v[4:7], v[160:163], v[214:217], v[4:7]
	v_mfma_f32_16x16x32_bf16 v[0:3], v[172:175], v[214:217], v[0:3]
	s_barrier
	s_setprio 0
	s_add_i32 s77, 0, 0x18000
	s_add_i32 s78, 0, 0x1c000
	v_add_u32_e32 v152, s77, v166
	v_add_u32_e32 v172, s78, v166
	ds_read_b128 v[128:131], v152
	ds_read_b128 v[144:147], v152 offset:1024
	ds_read_b128 v[148:151], v152 offset:2048
	ds_read_b128 v[152:155], v152 offset:3072
	ds_read_b128 v[156:159], v172
	ds_read_b128 v[160:163], v172 offset:1024
	ds_read_b128 v[168:171], v172 offset:2048
	ds_read_b128 v[172:175], v172 offset:3072
	s_add_u32 s48, s48, 0x80000
	s_addc_u32 s49, s49, 0
	s_mov_b32 m0, s0
	v_lshl_add_u64 v[212:213], s[48:49], 0, v[132:133]
	ds_read_b128 v[176:179], v167 offset:32768
	ds_read_b128 v[180:183], v167 offset:33792
	ds_read_b128 v[184:187], v167 offset:34816
	ds_read_b128 v[188:191], v167 offset:35840
	ds_read_b128 v[192:195], v167 offset:36864
	ds_read_b128 v[196:199], v167 offset:37888
	ds_read_b128 v[200:203], v167 offset:38912
	ds_read_b128 v[214:217], v167 offset:39936
	global_load_lds_dwordx4 v[212:213], off
	v_lshl_add_u64 v[212:213], s[48:49], 0, v[136:137]
	s_mov_b32 m0, s33
	s_nop 0
	global_load_lds_dwordx4 v[212:213], off
	s_waitcnt vmcnt(8)
	s_waitcnt lgkmcnt(0)
	s_setprio 1
	s_barrier
	v_mfma_f32_16x16x32_bf16 v[124:127], v[128:131], v[176:179], v[124:127]
	v_mfma_f32_16x16x32_bf16 v[120:123], v[148:151], v[176:179], v[120:123]
	v_mfma_f32_16x16x32_bf16 v[108:111], v[128:131], v[184:187], v[108:111]
	v_mfma_f32_16x16x32_bf16 v[104:107], v[148:151], v[184:187], v[104:107]
	v_mfma_f32_16x16x32_bf16 v[92:95], v[128:131], v[192:195], v[92:95]
	v_mfma_f32_16x16x32_bf16 v[88:91], v[148:151], v[192:195], v[88:91]
	v_mfma_f32_16x16x32_bf16 v[76:79], v[128:131], v[200:203], v[76:79]
	v_mfma_f32_16x16x32_bf16 v[72:75], v[148:151], v[200:203], v[72:75]
	v_mfma_f32_16x16x32_bf16 v[124:127], v[144:147], v[180:183], v[124:127]
	v_mfma_f32_16x16x32_bf16 v[120:123], v[152:155], v[180:183], v[120:123]
	v_mfma_f32_16x16x32_bf16 v[108:111], v[144:147], v[188:191], v[108:111]
	v_mfma_f32_16x16x32_bf16 v[104:107], v[152:155], v[188:191], v[104:107]
	v_mfma_f32_16x16x32_bf16 v[92:95], v[144:147], v[196:199], v[92:95]
	v_mfma_f32_16x16x32_bf16 v[88:91], v[152:155], v[196:199], v[88:91]
	v_mfma_f32_16x16x32_bf16 v[76:79], v[144:147], v[214:217], v[76:79]
	v_mfma_f32_16x16x32_bf16 v[72:75], v[152:155], v[214:217], v[72:75]
	s_setprio 0
	s_setprio 1
	v_mfma_f32_16x16x32_bf16 v[116:119], v[156:159], v[176:179], v[116:119]
	v_mfma_f32_16x16x32_bf16 v[112:115], v[168:171], v[176:179], v[112:115]
	v_mfma_f32_16x16x32_bf16 v[100:103], v[156:159], v[184:187], v[100:103]
	v_mfma_f32_16x16x32_bf16 v[96:99], v[168:171], v[184:187], v[96:99]
	v_mfma_f32_16x16x32_bf16 v[84:87], v[156:159], v[192:195], v[84:87]
	v_mfma_f32_16x16x32_bf16 v[80:83], v[168:171], v[192:195], v[80:83]
	v_mfma_f32_16x16x32_bf16 v[68:71], v[156:159], v[200:203], v[68:71]
	v_mfma_f32_16x16x32_bf16 v[64:67], v[168:171], v[200:203], v[64:67]
	v_mfma_f32_16x16x32_bf16 v[116:119], v[160:163], v[180:183], v[116:119]
	v_mfma_f32_16x16x32_bf16 v[112:115], v[172:175], v[180:183], v[112:115]
	v_mfma_f32_16x16x32_bf16 v[100:103], v[160:163], v[188:191], v[100:103]
	v_mfma_f32_16x16x32_bf16 v[96:99], v[172:175], v[188:191], v[96:99]
	v_mfma_f32_16x16x32_bf16 v[84:87], v[160:163], v[196:199], v[84:87]
	v_mfma_f32_16x16x32_bf16 v[80:83], v[172:175], v[196:199], v[80:83]
	v_mfma_f32_16x16x32_bf16 v[68:71], v[160:163], v[214:217], v[68:71]
	v_mfma_f32_16x16x32_bf16 v[64:67], v[172:175], v[214:217], v[64:67]
	s_barrier
; #define PG8_STAGE(bufoff, gbase, voff) do { _Pragma("unroll") for (int _i = 0; _i < 2; ++_i) \
;         __builtin_amdgcn_global_load_lds((const unsigned*)((const char*)(gbase) + (voff)[_i]), (PG8_LAS unsigned*)(lds + (bufoff) + ldsw + _i * 8192), 16, 0, 0); } while (0)
; #define PG8_LDA(dst, b, h) do { _Pragma("unroll") for (int m = 0; m < 4; ++m) _Pragma("unroll") for (int k = 0; k < 2; ++k) dst[m][k] = *(const PG8_LAS bf16x8*)(lds + PG8_SA(b, h) + aoff + m * 2048 + k * 1024); } while (0)
; #define PG8_WAIT_V(n) asm volatile("s_waitcnt vmcnt(" #n ")" ::: "memory")
; #define PG8_WAIT_L(n) asm volatile("s_waitcnt lgkmcnt(" #n ")" ::: "memory")
; #define PG8_BAR __builtin_amdgcn_s_barrier()
; template <class Epi, class Sched, bool ALIGN_EPI = false, bool SP2 = false>
; __device__ __forceinline__ void gemm_phase(PG8_LAS unsigned char* lds, const Gemm g, const Sched& S, const Epi& E, const int tid) {
;     ...
;         for (int t = 0; t < nt; t += 2) {
;             const bool last = (t == nt - 2);
;             const char* a1 = cA + (size_t)(t + 1) * kstep;
;             const char* a2 = last ? nA : cA + (size_t)(t + 2) * kstep; const char* b2 = last ? nB : cB + (size_t)(t + 2) * kstep;
;             const char* a3 = a2 + kstep; const char* b3 = b2 + kstep;
;             if (last && has_next) S.a_ready(nxt);
;             if constexpr (SP2) {
;             PG8_LDB(B0, 0, 0); PG8_LDB(B1, 0, 1); PG8_SCHED; PG8_LDA(At, 0, 0); PG8_STAGE(PG8_SA(1, 1), a1 + hstep, voffA);
;             PG8_WAIT_V(8); PG8_WAIT_L(0); PG8_BAR; PG8_MMA(0, 0, At, B0); PG8_MMA(0, 1, At, B1); PG8_BAR; PG8_SCHED;
;             PG8_LDA(At, 0, 1); PG8_STAGE(PG8_SB(0, 0), b2, voffB); PG8_STAGE(PG8_SB(0, 1), b2 + hstep, voffB); PG8_STAGE(PG8_SA(0, 0), a2, voffA);
;             PG8_WAIT_V(8); PG8_WAIT_L(0); PG8_BAR; PG8_MMA(1, 0, At, B0); PG8_MMA(1, 1, At, B1); PG8_BAR; PG8_SCHED;
;             PG8_LDB(B0, 1, 0); PG8_LDB(B1, 1, 1); PG8_SCHED; PG8_LDA(At, 1, 0); PG8_STAGE(PG8_SA(0, 1), a2 + hstep, voffA);
;             PG8_WAIT_V(8); PG8_WAIT_L(0); PG8_BAR; PG8_MMA(0, 0, At, B0); PG8_MMA(0, 1, At, B1); PG8_BAR; PG8_SCHED;
;             PG8_LDA(At, 1, 1); PG8_STAGE(PG8_SB(1, 0), b3, voffB); PG8_STAGE(PG8_SB(1, 1), b3 + hstep, voffB); PG8_STAGE(PG8_SA(1, 0), a3, voffA);
;             PG8_WAIT_V(8); PG8_WAIT_L(0); PG8_BAR; PG8_MMA(1, 0, At, B0); PG8_MMA(1, 1, At, B1); PG8_BAR; PG8_SCHED;
	s_setprio 0
	s_add_i32 s48, s77, s54
	v_lshl_add_u64 v[164:165], v[164:165], 0, s[70:71]
	s_mov_b32 m0, s48
	ds_read_b128 v[176:179], v167 offset:49152
	ds_read_b128 v[180:183], v167 offset:50176
	ds_read_b128 v[184:187], v167 offset:51200
	ds_read_b128 v[188:191], v167 offset:52224
	ds_read_b128 v[192:195], v167 offset:53248
	ds_read_b128 v[196:199], v167 offset:54272
	ds_read_b128 v[200:203], v167 offset:55296
	ds_read_b128 v[214:217], v167 offset:56320
	global_load_lds_dwordx4 v[164:165], off
	s_add_i32 m0, s48, 0x2000
	s_add_u32 s46, s46, 0x80080
	v_lshl_add_u64 v[164:165], v[206:207], 0, s[70:71]
	s_addc_u32 s47, s47, 0
	s_add_i32 s48, s78, s54
	global_load_lds_dwordx4 v[164:165], off
	v_lshl_add_u64 v[164:165], s[46:47], 0, v[134:135]
	s_mov_b32 m0, s48
	s_nop 0
	global_load_lds_dwordx4 v[164:165], off
	v_lshl_add_u64 v[164:165], s[46:47], 0, v[138:139]
	s_add_i32 m0, s48, 0x2000
	s_nop 0
	global_load_lds_dwordx4 v[164:165], off
	v_lshl_add_u64 v[164:165], v[208:209], 0, s[70:71]
	s_mov_b32 m0, s10
	s_nop 0
	global_load_lds_dwordx4 v[164:165], off
	v_lshl_add_u64 v[164:165], v[210:211], 0, s[70:71]
	s_mov_b32 m0, s11
	s_nop 0
	global_load_lds_dwordx4 v[164:165], off
	s_waitcnt vmcnt(8)
	s_waitcnt lgkmcnt(0)
	s_setprio 1
	s_barrier
	v_mfma_f32_16x16x32_bf16 v[60:63], v[128:131], v[176:179], v[60:63]
	v_mfma_f32_16x16x32_bf16 v[56:59], v[148:151], v[176:179], v[56:59]
	v_mfma_f32_16x16x32_bf16 v[44:47], v[128:131], v[184:187], v[44:47]
	v_mfma_f32_16x16x32_bf16 v[40:43], v[148:151], v[184:187], v[40:43]
	v_mfma_f32_16x16x32_bf16 v[28:31], v[128:131], v[192:195], v[28:31]
	v_mfma_f32_16x16x32_bf16 v[24:27], v[148:151], v[192:195], v[24:27]
	v_mfma_f32_16x16x32_bf16 v[12:15], v[128:131], v[200:203], v[12:15]
	v_mfma_f32_16x16x32_bf16 v[8:11], v[148:151], v[200:203], v[8:11]
	v_mfma_f32_16x16x32_bf16 v[60:63], v[144:147], v[180:183], v[60:63]
	v_mfma_f32_16x16x32_bf16 v[56:59], v[152:155], v[180:183], v[56:59]
	v_mfma_f32_16x16x32_bf16 v[44:47], v[144:147], v[188:191], v[44:47]
	v_mfma_f32_16x16x32_bf16 v[40:43], v[152:155], v[188:191], v[40:43]
	v_mfma_f32_16x16x32_bf16 v[28:31], v[144:147], v[196:199], v[28:31]
	v_mfma_f32_16x16x32_bf16 v[24:27], v[152:155], v[196:199], v[24:27]
	v_mfma_f32_16x16x32_bf16 v[12:15], v[144:147], v[214:217], v[12:15]
	v_mfma_f32_16x16x32_bf16 v[8:11], v[152:155], v[214:217], v[8:11]
	s_setprio 0
	s_setprio 1
	v_mfma_f32_16x16x32_bf16 v[52:55], v[156:159], v[176:179], v[52:55]
	v_mfma_f32_16x16x32_bf16 v[48:51], v[168:171], v[176:179], v[48:51]
	v_mfma_f32_16x16x32_bf16 v[36:39], v[156:159], v[184:187], v[36:39]
	v_mfma_f32_16x16x32_bf16 v[32:35], v[168:171], v[184:187], v[32:35]
	v_mfma_f32_16x16x32_bf16 v[20:23], v[156:159], v[192:195], v[20:23]
	v_mfma_f32_16x16x32_bf16 v[16:19], v[168:171], v[192:195], v[16:19]
	v_mfma_f32_16x16x32_bf16 v[4:7], v[156:159], v[200:203], v[4:7]
	v_mfma_f32_16x16x32_bf16 v[0:3], v[168:171], v[200:203], v[0:3]
	v_mfma_f32_16x16x32_bf16 v[52:55], v[160:163], v[180:183], v[52:55]
	v_mfma_f32_16x16x32_bf16 v[48:51], v[172:175], v[180:183], v[48:51]
	v_mfma_f32_16x16x32_bf16 v[36:39], v[160:163], v[188:191], v[36:39]
	v_mfma_f32_16x16x32_bf16 v[32:35], v[172:175], v[188:191], v[32:35]
	v_mfma_f32_16x16x32_bf16 v[20:23], v[160:163], v[196:199], v[20:23]
	v_mfma_f32_16x16x32_bf16 v[16:19], v[172:175], v[196:199], v[16:19]
	v_mfma_f32_16x16x32_bf16 v[4:7], v[160:163], v[214:217], v[4:7]
	v_mfma_f32_16x16x32_bf16 v[0:3], v[172:175], v[214:217], v[0:3]
	s_barrier
	s_setprio 0
	s_add_i32 s76, s76, 2
	s_add_u32 s44, s44, 0x100
	s_addc_u32 s45, s45, 0
	s_add_u32 vcc_lo, vcc_lo, 0x100
	s_addc_u32 vcc_hi, vcc_hi, 0
.LBB0_680:
	s_add_u32 s46, s44, 0xfff80080
	s_addc_u32 s47, s45, -1
	s_add_i32 s77, 0, 0x10000
	s_cmp_eq_u32 s76, 28
	s_cselect_b32 s49, s29, s47
	s_cselect_b32 s48, s43, s46
	s_cselect_b32 s47, s27, vcc_hi
	s_cselect_b32 s46, s69, vcc_lo
	s_add_i32 s80, 0, 0x14000
	v_add_u32_e32 v152, s77, v166
	v_add_u32_e32 v164, s80, v166
	ds_read_b128 v[128:131], v152
	ds_read_b128 v[144:147], v152 offset:1024
	ds_read_b128 v[148:151], v152 offset:2048
	ds_read_b128 v[152:155], v152 offset:3072
	ds_read_b128 v[156:159], v164
	ds_read_b128 v[160:163], v164 offset:1024
	ds_read_b128 v[168:171], v164 offset:2048
	ds_read_b128 v[172:175], v164 offset:3072
	v_lshl_add_u64 v[164:165], s[44:45], 0, v[140:141]
	s_add_i32 m0, s37, 0xc000
	ds_read_b128 v[176:179], v167
	ds_read_b128 v[180:183], v167 offset:1024
	ds_read_b128 v[184:187], v167 offset:2048
	ds_read_b128 v[188:191], v167 offset:3072
	ds_read_b128 v[192:195], v167 offset:4096
	ds_read_b128 v[196:199], v167 offset:5120
	ds_read_b128 v[200:203], v167 offset:6144
	ds_read_b128 v[214:217], v167 offset:7168
	global_load_lds_dwordx4 v[164:165], off
	v_lshl_add_u64 v[164:165], s[44:45], 0, v[142:143]
	s_add_i32 m0, s37, 0xe000
	s_nop 0
	global_load_lds_dwordx4 v[164:165], off
	s_waitcnt vmcnt(8)
	s_waitcnt lgkmcnt(0)
	s_setprio 1
	s_barrier
; #define PG8_STAGE(bufoff, gbase, voff) do { _Pragma("unroll") for (int _i = 0; _i < 2; ++_i) \
;         __builtin_amdgcn_global_load_lds((const unsigned*)((const char*)(gbase) + (voff)[_i]), (PG8_LAS unsigned*)(lds + (bufoff) + ldsw + _i * 8192), 16, 0, 0); } while (0)
; #define PG8_LDA(dst, b, h) do { _Pragma("unroll") for (int m = 0; m < 4; ++m) _Pragma("unroll") for (int k = 0; k < 2; ++k) dst[m][k] = *(const PG8_LAS bf16x8*)(lds + PG8_SA(b, h) + aoff + m * 2048 + k * 1024); } while (0)
; #define PG8_LDB(dst, b, h) do { _Pragma("unroll") for (int n = 0; n < 2; ++n) _Pragma("unroll") for (int k = 0; k < 2; ++k) dst[n][k] = *(const PG8_LAS bf16x8*)(lds + PG8_SB(b, h) + boff + n * 2048 + k * 1024); } while (0)
; #define PG8_MMA(ai, bj, At, Bt) do { __builtin_amdgcn_s_setprio(1); _Pragma("unroll") for (int m = 0; m < 4; ++m) _Pragma("unroll") for (int n = 0; n < 2; ++n) _Pragma("unroll") for (int k = 0; k < 2; ++k) \
;         acc[ai][bj][m][n] = __builtin_amdgcn_mfma_f32_16x16x32_bf16(Bt[n][k], At[m][k], acc[ai][bj][m][n], 0, 0, 0); __builtin_amdgcn_s_setprio(0); } while (0)
; #define PG8_BAR __builtin_amdgcn_s_barrier()
; template <class Epi, class Sched, bool ALIGN_EPI = false, bool SP2 = false>
; __device__ __forceinline__ void gemm_phase(PG8_LAS unsigned char* lds, const Gemm g, const Sched& S, const Epi& E, const int tid) {
;     ...
;             PG8_LDB(B0, 0, 0); PG8_LDB(B1, 0, 1); PG8_SCHED; PG8_LDA(At, 0, 0); PG8_STAGE(PG8_SA(1, 1), a1 + hstep, voffA);
;             PG8_WAIT_V(8); PG8_WAIT_L(0); PG8_BAR; PG8_MMA(0, 0, At, B0); PG8_MMA(0, 1, At, B1); PG8_BAR; PG8_SCHED;
;             PG8_LDA(At, 0, 1); PG8_STAGE(PG8_SB(0, 0), b2, voffB); PG8_STAGE(PG8_SB(0, 1), b2 + hstep, voffB); PG8_STAGE(PG8_SA(0, 0), a2, voffA);
;             PG8_WAIT_V(8); PG8_WAIT_L(0); PG8_BAR; PG8_MMA(1, 0, At, B0); PG8_MMA(1, 1, At, B1); PG8_BAR; PG8_SCHED;
;             PG8_LDB(B0, 1, 0); PG8_LDB(B1, 1, 1); PG8_SCHED; PG8_LDA(At, 1, 0); PG8_STAGE(PG8_SA(0, 1), a2 + hstep, voffA);
;             PG8_WAIT_V(8); PG8_WAIT_L(0); PG8_BAR; PG8_MMA(0, 0, At, B0); PG8_MMA(0, 1, At, B1); PG8_BAR; PG8_SCHED;
;             PG8_LDA(At, 1, 1); PG8_STAGE(PG8_SB(1, 0), b3, voffB); PG8_STAGE(PG8_SB(1, 1), b3 + hstep, voffB); PG8_STAGE(PG8_SA(1, 0), a3, voffA);
;             PG8_WAIT_V(8); PG8_WAIT_L(0); PG8_BAR; PG8_MMA(1, 0, At, B0); PG8_MMA(1, 1, At, B1); PG8_BAR; PG8_SCHED;
	v_mfma_f32_16x16x32_bf16 v[124:127], v[128:131], v[176:179], v[124:127]
	v_mfma_f32_16x16x32_bf16 v[120:123], v[148:151], v[176:179], v[120:123]
	v_mfma_f32_16x16x32_bf16 v[108:111], v[128:131], v[184:187], v[108:111]
	v_mfma_f32_16x16x32_bf16 v[104:107], v[148:151], v[184:187], v[104:107]
	v_mfma_f32_16x16x32_bf16 v[92:95], v[128:131], v[192:195], v[92:95]
	v_mfma_f32_16x16x32_bf16 v[88:91], v[148:151], v[192:195], v[88:91]
	v_mfma_f32_16x16x32_bf16 v[76:79], v[128:131], v[200:203], v[76:79]
	v_mfma_f32_16x16x32_bf16 v[72:75], v[148:151], v[200:203], v[72:75]
	v_mfma_f32_16x16x32_bf16 v[124:127], v[144:147], v[180:183], v[124:127]
	v_mfma_f32_16x16x32_bf16 v[120:123], v[152:155], v[180:183], v[120:123]
	v_mfma_f32_16x16x32_bf16 v[108:111], v[144:147], v[188:191], v[108:111]
	v_mfma_f32_16x16x32_bf16 v[104:107], v[152:155], v[188:191], v[104:107]
	v_mfma_f32_16x16x32_bf16 v[92:95], v[144:147], v[196:199], v[92:95]
	v_mfma_f32_16x16x32_bf16 v[88:91], v[152:155], v[196:199], v[88:91]
	v_mfma_f32_16x16x32_bf16 v[76:79], v[144:147], v[214:217], v[76:79]
	v_mfma_f32_16x16x32_bf16 v[72:75], v[152:155], v[214:217], v[72:75]
	s_setprio 0
	s_setprio 1
	v_mfma_f32_16x16x32_bf16 v[116:119], v[156:159], v[176:179], v[116:119]
	v_mfma_f32_16x16x32_bf16 v[112:115], v[168:171], v[176:179], v[112:115]
	v_mfma_f32_16x16x32_bf16 v[100:103], v[156:159], v[184:187], v[100:103]
	v_mfma_f32_16x16x32_bf16 v[96:99], v[168:171], v[184:187], v[96:99]
	v_mfma_f32_16x16x32_bf16 v[84:87], v[156:159], v[192:195], v[84:87]
	v_mfma_f32_16x16x32_bf16 v[80:83], v[168:171], v[192:195], v[80:83]
	v_mfma_f32_16x16x32_bf16 v[68:71], v[156:159], v[200:203], v[68:71]
	v_mfma_f32_16x16x32_bf16 v[64:67], v[168:171], v[200:203], v[64:67]
	v_mfma_f32_16x16x32_bf16 v[116:119], v[160:163], v[180:183], v[116:119]
	v_mfma_f32_16x16x32_bf16 v[112:115], v[172:175], v[180:183], v[112:115]
	v_mfma_f32_16x16x32_bf16 v[100:103], v[160:163], v[188:191], v[100:103]
	v_mfma_f32_16x16x32_bf16 v[96:99], v[172:175], v[188:191], v[96:99]
	v_mfma_f32_16x16x32_bf16 v[84:87], v[160:163], v[196:199], v[84:87]
	v_mfma_f32_16x16x32_bf16 v[80:83], v[172:175], v[196:199], v[80:83]
	v_mfma_f32_16x16x32_bf16 v[68:71], v[160:163], v[214:217], v[68:71]
	v_mfma_f32_16x16x32_bf16 v[64:67], v[172:175], v[214:217], v[64:67]
	s_barrier
	s_setprio 0
	s_add_i32 s77, s77, s54
	v_lshl_add_u64 v[164:165], s[46:47], 0, v[134:135]
	s_mov_b32 m0, s77
	ds_read_b128 v[176:179], v167 offset:16384
	ds_read_b128 v[180:183], v167 offset:17408
	ds_read_b128 v[184:187], v167 offset:18432
	ds_read_b128 v[188:191], v167 offset:19456
	ds_read_b128 v[192:195], v167 offset:20480
	ds_read_b128 v[196:199], v167 offset:21504
	ds_read_b128 v[200:203], v167 offset:22528
	ds_read_b128 v[214:217], v167 offset:23552
	global_load_lds_dwordx4 v[164:165], off
	s_add_i32 m0, s77, 0x2000
	s_add_u32 s78, s46, 0x80000
	v_lshl_add_u64 v[206:207], s[46:47], 0, v[138:139]
	s_addc_u32 s79, s47, 0
	s_add_i32 s77, s80, s54
	global_load_lds_dwordx4 v[206:207], off
	v_lshl_add_u64 v[208:209], s[78:79], 0, v[134:135]
	s_mov_b32 m0, s77
	v_lshl_add_u64 v[210:211], s[48:49], 0, v[136:137]
	global_load_lds_dwordx4 v[208:209], off
	v_lshl_add_u64 v[208:209], s[78:79], 0, v[138:139]
	s_add_i32 m0, s77, 0x2000
	s_nop 0
	global_load_lds_dwordx4 v[208:209], off
	v_lshl_add_u64 v[208:209], s[48:49], 0, v[132:133]
	s_mov_b32 m0, s37
	s_nop 0
	global_load_lds_dwordx4 v[208:209], off
	s_mov_b32 m0, s55
	s_nop 0
	global_load_lds_dwordx4 v[210:211], off
	s_waitcnt vmcnt(8)
	s_waitcnt lgkmcnt(0)
	s_setprio 1
	s_barrier
	v_mfma_f32_16x16x32_bf16 v[60:63], v[128:131], v[176:179], v[60:63]
	v_mfma_f32_16x16x32_bf16 v[56:59], v[148:151], v[176:179], v[56:59]
	v_mfma_f32_16x16x32_bf16 v[44:47], v[128:131], v[184:187], v[44:47]
	v_mfma_f32_16x16x32_bf16 v[40:43], v[148:151], v[184:187], v[40:43]
	v_mfma_f32_16x16x32_bf16 v[28:31], v[128:131], v[192:195], v[28:31]
	v_mfma_f32_16x16x32_bf16 v[24:27], v[148:151], v[192:195], v[24:27]
	v_mfma_f32_16x16x32_bf16 v[12:15], v[128:131], v[200:203], v[12:15]
	v_mfma_f32_16x16x32_bf16 v[8:11], v[148:151], v[200:203], v[8:11]
	v_mfma_f32_16x16x32_bf16 v[60:63], v[144:147], v[180:183], v[60:63]
	v_mfma_f32_16x16x32_bf16 v[56:59], v[152:155], v[180:183], v[56:59]
	v_mfma_f32_16x16x32_bf16 v[44:47], v[144:147], v[188:191], v[44:47]
	v_mfma_f32_16x16x32_bf16 v[40:43], v[152:155], v[188:191], v[40:43]
	v_mfma_f32_16x16x32_bf16 v[28:31], v[144:147], v[196:199], v[28:31]
	v_mfma_f32_16x16x32_bf16 v[24:27], v[152:155], v[196:199], v[24:27]
	v_mfma_f32_16x16x32_bf16 v[12:15], v[144:147], v[214:217], v[12:15]
	v_mfma_f32_16x16x32_bf16 v[8:11], v[152:155], v[214:217], v[8:11]
	s_setprio 0
	s_setprio 1
	v_mfma_f32_16x16x32_bf16 v[52:55], v[156:159], v[176:179], v[52:55]
	v_mfma_f32_16x16x32_bf16 v[48:51], v[168:171], v[176:179], v[48:51]
	v_mfma_f32_16x16x32_bf16 v[36:39], v[156:159], v[184:187], v[36:39]
	v_mfma_f32_16x16x32_bf16 v[32:35], v[168:171], v[184:187], v[32:35]
	v_mfma_f32_16x16x32_bf16 v[20:23], v[156:159], v[192:195], v[20:23]
	v_mfma_f32_16x16x32_bf16 v[16:19], v[168:171], v[192:195], v[16:19]
	v_mfma_f32_16x16x32_bf16 v[4:7], v[156:159], v[200:203], v[4:7]
	v_mfma_f32_16x16x32_bf16 v[0:3], v[168:171], v[200:203], v[0:3]
	v_mfma_f32_16x16x32_bf16 v[52:55], v[160:163], v[180:183], v[52:55]
	v_mfma_f32_16x16x32_bf16 v[48:51], v[172:175], v[180:183], v[48:51]
	v_mfma_f32_16x16x32_bf16 v[36:39], v[160:163], v[188:191], v[36:39]
	v_mfma_f32_16x16x32_bf16 v[32:35], v[172:175], v[188:191], v[32:35]
	v_mfma_f32_16x16x32_bf16 v[20:23], v[160:163], v[196:199], v[20:23]
	v_mfma_f32_16x16x32_bf16 v[16:19], v[172:175], v[196:199], v[16:19]
	v_mfma_f32_16x16x32_bf16 v[4:7], v[160:163], v[214:217], v[4:7]
	v_mfma_f32_16x16x32_bf16 v[0:3], v[172:175], v[214:217], v[0:3]
	s_barrier
; #define PG8_STAGE(bufoff, gbase, voff) do { _Pragma("unroll") for (int _i = 0; _i < 2; ++_i) \
;         __builtin_amdgcn_global_load_lds((const unsigned*)((const char*)(gbase) + (voff)[_i]), (PG8_LAS unsigned*)(lds + (bufoff) + ldsw + _i * 8192), 16, 0, 0); } while (0)
; #define PG8_LDA(dst, b, h) do { _Pragma("unroll") for (int m = 0; m < 4; ++m) _Pragma("unroll") for (int k = 0; k < 2; ++k) dst[m][k] = *(const PG8_LAS bf16x8*)(lds + PG8_SA(b, h) + aoff + m * 2048 + k * 1024); } while (0)
; #define PG8_LDB(dst, b, h) do { _Pragma("unroll") for (int n = 0; n < 2; ++n) _Pragma("unroll") for (int k = 0; k < 2; ++k) dst[n][k] = *(const PG8_LAS bf16x8*)(lds + PG8_SB(b, h) + boff + n * 2048 + k * 1024); } while (0)
; #define PG8_MMA(ai, bj, At, Bt) do { __builtin_amdgcn_s_setprio(1); _Pragma("unroll") for (int m = 0; m < 4; ++m) _Pragma("unroll") for (int n = 0; n < 2; ++n) _Pragma("unroll") for (int k = 0; k < 2; ++k) \
;         acc[ai][bj][m][n] = __builtin_amdgcn_mfma_f32_16x16x32_bf16(Bt[n][k], At[m][k], acc[ai][bj][m][n], 0, 0, 0); __builtin_amdgcn_s_setprio(0); } while (0)
; #define PG8_WAIT_V(n) asm volatile("s_waitcnt vmcnt(" #n ")" ::: "memory")
; #define PG8_WAIT_L(n) asm volatile("s_waitcnt lgkmcnt(" #n ")" ::: "memory")
; #define PG8_BAR __builtin_amdgcn_s_barrier()
; #define PG8_SCHED __builtin_amdgcn_sched_barrier(0)
; template <class Epi, class Sched, bool ALIGN_EPI = false, bool SP2 = false>
; __device__ __forceinline__ void gemm_phase(PG8_LAS unsigned char* lds, const Gemm g, const Sched& S, const Epi& E, const int tid) {
;     ...
;             PG8_LDB(B0, 1, 0); PG8_LDB(B1, 1, 1); PG8_SCHED; PG8_LDA(At, 1, 0); PG8_STAGE(PG8_SA(0, 1), a2 + hstep, voffA);
;             PG8_WAIT_V(8); PG8_WAIT_L(0); PG8_BAR; PG8_MMA(0, 0, At, B0); PG8_MMA(0, 1, At, B1); PG8_BAR; PG8_SCHED;
;             PG8_LDA(At, 1, 1); PG8_STAGE(PG8_SB(1, 0), b3, voffB); PG8_STAGE(PG8_SB(1, 1), b3 + hstep, voffB); PG8_STAGE(PG8_SA(1, 0), a3, voffA);
;             PG8_WAIT_V(8); PG8_WAIT_L(0); PG8_BAR; PG8_MMA(1, 0, At, B0); PG8_MMA(1, 1, At, B1); PG8_BAR; PG8_SCHED;
	s_setprio 0
	s_add_i32 s77, 0, 0x18000
	s_add_i32 s78, 0, 0x1c000
	v_add_u32_e32 v152, s77, v166
	v_add_u32_e32 v172, s78, v166
	ds_read_b128 v[128:131], v152
	ds_read_b128 v[144:147], v152 offset:1024
	ds_read_b128 v[148:151], v152 offset:2048
	ds_read_b128 v[152:155], v152 offset:3072
	ds_read_b128 v[156:159], v172
	ds_read_b128 v[160:163], v172 offset:1024
	ds_read_b128 v[168:171], v172 offset:2048
	ds_read_b128 v[172:175], v172 offset:3072
	s_add_u32 s48, s48, 0x80000
	s_addc_u32 s49, s49, 0
	s_mov_b32 m0, s0
	v_lshl_add_u64 v[212:213], s[48:49], 0, v[132:133]
	ds_read_b128 v[176:179], v167 offset:32768
	ds_read_b128 v[180:183], v167 offset:33792
	ds_read_b128 v[184:187], v167 offset:34816
	ds_read_b128 v[188:191], v167 offset:35840
	ds_read_b128 v[192:195], v167 offset:36864
	ds_read_b128 v[196:199], v167 offset:37888
	ds_read_b128 v[200:203], v167 offset:38912
	ds_read_b128 v[214:217], v167 offset:39936
	global_load_lds_dwordx4 v[212:213], off
	v_lshl_add_u64 v[212:213], s[48:49], 0, v[136:137]
	s_mov_b32 m0, s33
	s_nop 0
	global_load_lds_dwordx4 v[212:213], off
	s_waitcnt vmcnt(8)
	s_waitcnt lgkmcnt(0)
	s_setprio 1
	s_barrier
	v_mfma_f32_16x16x32_bf16 v[124:127], v[128:131], v[176:179], v[124:127]
	v_mfma_f32_16x16x32_bf16 v[120:123], v[148:151], v[176:179], v[120:123]
	v_mfma_f32_16x16x32_bf16 v[108:111], v[128:131], v[184:187], v[108:111]
	v_mfma_f32_16x16x32_bf16 v[104:107], v[148:151], v[184:187], v[104:107]
	v_mfma_f32_16x16x32_bf16 v[92:95], v[128:131], v[192:195], v[92:95]
	v_mfma_f32_16x16x32_bf16 v[88:91], v[148:151], v[192:195], v[88:91]
	v_mfma_f32_16x16x32_bf16 v[76:79], v[128:131], v[200:203], v[76:79]
	v_mfma_f32_16x16x32_bf16 v[72:75], v[148:151], v[200:203], v[72:75]
	v_mfma_f32_16x16x32_bf16 v[124:127], v[144:147], v[180:183], v[124:127]
	v_mfma_f32_16x16x32_bf16 v[120:123], v[152:155], v[180:183], v[120:123]
	v_mfma_f32_16x16x32_bf16 v[108:111], v[144:147], v[188:191], v[108:111]
	v_mfma_f32_16x16x32_bf16 v[104:107], v[152:155], v[188:191], v[104:107]
	v_mfma_f32_16x16x32_bf16 v[92:95], v[144:147], v[196:199], v[92:95]
	v_mfma_f32_16x16x32_bf16 v[88:91], v[152:155], v[196:199], v[88:91]
	v_mfma_f32_16x16x32_bf16 v[76:79], v[144:147], v[214:217], v[76:79]
	v_mfma_f32_16x16x32_bf16 v[72:75], v[152:155], v[214:217], v[72:75]
	s_setprio 0
	s_setprio 1
	v_mfma_f32_16x16x32_bf16 v[116:119], v[156:159], v[176:179], v[116:119]
	v_mfma_f32_16x16x32_bf16 v[112:115], v[168:171], v[176:179], v[112:115]
	v_mfma_f32_16x16x32_bf16 v[100:103], v[156:159], v[184:187], v[100:103]
	v_mfma_f32_16x16x32_bf16 v[96:99], v[168:171], v[184:187], v[96:99]
	v_mfma_f32_16x16x32_bf16 v[84:87], v[156:159], v[192:195], v[84:87]
	v_mfma_f32_16x16x32_bf16 v[80:83], v[168:171], v[192:195], v[80:83]
	v_mfma_f32_16x16x32_bf16 v[68:71], v[156:159], v[200:203], v[68:71]
	v_mfma_f32_16x16x32_bf16 v[64:67], v[168:171], v[200:203], v[64:67]
	v_mfma_f32_16x16x32_bf16 v[116:119], v[160:163], v[180:183], v[116:119]
	v_mfma_f32_16x16x32_bf16 v[112:115], v[172:175], v[180:183], v[112:115]
	v_mfma_f32_16x16x32_bf16 v[100:103], v[160:163], v[188:191], v[100:103]
	v_mfma_f32_16x16x32_bf16 v[96:99], v[172:175], v[188:191], v[96:99]
	v_mfma_f32_16x16x32_bf16 v[84:87], v[160:163], v[196:199], v[84:87]
	v_mfma_f32_16x16x32_bf16 v[80:83], v[172:175], v[196:199], v[80:83]
	v_mfma_f32_16x16x32_bf16 v[68:71], v[160:163], v[214:217], v[68:71]
	v_mfma_f32_16x16x32_bf16 v[64:67], v[172:175], v[214:217], v[64:67]
	s_barrier
; #define PG8_STAGE(bufoff, gbase, voff) do { _Pragma("unroll") for (int _i = 0; _i < 2; ++_i) \
;         __builtin_amdgcn_global_load_lds((const unsigned*)((const char*)(gbase) + (voff)[_i]), (PG8_LAS unsigned*)(lds + (bufoff) + ldsw + _i * 8192), 16, 0, 0); } while (0)
; #define PG8_LDA(dst, b, h) do { _Pragma("unroll") for (int m = 0; m < 4; ++m) _Pragma("unroll") for (int k = 0; k < 2; ++k) dst[m][k] = *(const PG8_LAS bf16x8*)(lds + PG8_SA(b, h) + aoff + m * 2048 + k * 1024); } while (0)
; #define PG8_BAR __builtin_amdgcn_s_barrier()
; template <class Epi, class Sched, bool ALIGN_EPI = false, bool SP2 = false>
; __device__ __forceinline__ void gemm_phase(PG8_LAS unsigned char* lds, const Gemm g, const Sched& S, const Epi& E, const int tid) {
;     ...
;             PG8_LDA(At, 1, 1); PG8_STAGE(PG8_SB(1, 0), b3, voffB); PG8_STAGE(PG8_SB(1, 1), b3 + hstep, voffB); PG8_STAGE(PG8_SA(1, 0), a3, voffA);
;             PG8_WAIT_V(8); PG8_WAIT_L(0); PG8_BAR; PG8_MMA(1, 0, At, B0); PG8_MMA(1, 1, At, B1); PG8_BAR; PG8_SCHED;
;             } else {
;             PG8_LDB(B0, 0, 0); PG8_SCHED; PG8_LDA(At, 0, 0); PG8_STAGE(PG8_SA(1, 1), a1 + hstep, voffA);
;             PG8_WAIT_L(8); PG8_BAR; PG8_WAIT_L(0); PG8_MMA(0, 0, At, B0); PG8_BAR; PG8_SCHED;
;             PG8_LDB(B1, 0, 1); PG8_STAGE(PG8_SB(0, 0), b2, voffB);
;             PG8_BAR; PG8_WAIT_L(0); PG8_MMA(0, 1, At, B1); PG8_BAR;
;             PG8_LDA(At, 0, 1); PG8_STAGE(PG8_SA(0, 0), a2, voffA);
;             PG8_BAR; PG8_WAIT_L(0); PG8_MMA(1, 0, At, B0); PG8_BAR; PG8_SCHED;
;             PG8_STAGE(PG8_SB(0, 1), b2 + hstep, voffB);
;             PG8_WAIT_V(6); PG8_BAR; PG8_MMA(1, 1, At, B1); PG8_BAR;
;             PG8_LDB(B0, 1, 0); PG8_SCHED; PG8_LDA(At, 1, 0); PG8_STAGE(PG8_SA(0, 1), a2 + hstep, voffA);
;             PG8_WAIT_L(8); PG8_BAR; PG8_WAIT_L(0); PG8_MMA(0, 0, At, B0); PG8_BAR; PG8_SCHED;
;             PG8_LDB(B1, 1, 1); PG8_STAGE(PG8_SB(1, 0), b3, voffB);
;             PG8_BAR; PG8_WAIT_L(0); PG8_MMA(0, 1, At, B1); PG8_BAR;
;             PG8_LDA(At, 1, 1); PG8_STAGE(PG8_SA(1, 0), a3, voffA);
;             PG8_BAR; PG8_WAIT_L(0); PG8_MMA(1, 0, At, B0); PG8_BAR; PG8_SCHED;
;             PG8_STAGE(PG8_SB(1, 1), b3 + hstep, voffB);
;             PG8_WAIT_V(6); PG8_BAR; PG8_MMA(1, 1, At, B1); PG8_BAR;
;             }
;         }
;         if constexpr (ALIGN_EPI) { if (wr == 0) PG8_BAR; }
	s_setprio 0
	s_add_i32 s48, s77, s54
	v_lshl_add_u64 v[164:165], v[164:165], 0, s[70:71]
	s_mov_b32 m0, s48
	ds_read_b128 v[176:179], v167 offset:49152
	ds_read_b128 v[180:183], v167 offset:50176
	ds_read_b128 v[184:187], v167 offset:51200
	ds_read_b128 v[188:191], v167 offset:52224
	ds_read_b128 v[192:195], v167 offset:53248
	ds_read_b128 v[196:199], v167 offset:54272
	ds_read_b128 v[200:203], v167 offset:55296
	ds_read_b128 v[214:217], v167 offset:56320
	global_load_lds_dwordx4 v[164:165], off
	s_add_i32 m0, s48, 0x2000
	s_add_u32 s46, s46, 0x80080
	v_lshl_add_u64 v[164:165], v[206:207], 0, s[70:71]
	s_addc_u32 s47, s47, 0
	s_add_i32 s48, s78, s54
	global_load_lds_dwordx4 v[164:165], off
	v_lshl_add_u64 v[164:165], s[46:47], 0, v[134:135]
	s_mov_b32 m0, s48
	s_nop 0
	global_load_lds_dwordx4 v[164:165], off
	v_lshl_add_u64 v[164:165], s[46:47], 0, v[138:139]
	s_add_i32 m0, s48, 0x2000
	s_nop 0
	global_load_lds_dwordx4 v[164:165], off
	v_lshl_add_u64 v[164:165], v[208:209], 0, s[70:71]
	s_mov_b32 m0, s10
	s_nop 0
	global_load_lds_dwordx4 v[164:165], off
	v_lshl_add_u64 v[164:165], v[210:211], 0, s[70:71]
	s_mov_b32 m0, s11
	s_nop 0
	global_load_lds_dwordx4 v[164:165], off
	s_waitcnt vmcnt(8)
	s_waitcnt lgkmcnt(0)
	s_setprio 1
	s_barrier
	v_mfma_f32_16x16x32_bf16 v[60:63], v[128:131], v[176:179], v[60:63]
	v_mfma_f32_16x16x32_bf16 v[56:59], v[148:151], v[176:179], v[56:59]
	v_mfma_f32_16x16x32_bf16 v[44:47], v[128:131], v[184:187], v[44:47]
	v_mfma_f32_16x16x32_bf16 v[40:43], v[148:151], v[184:187], v[40:43]
	v_mfma_f32_16x16x32_bf16 v[28:31], v[128:131], v[192:195], v[28:31]
	v_mfma_f32_16x16x32_bf16 v[24:27], v[148:151], v[192:195], v[24:27]
	v_mfma_f32_16x16x32_bf16 v[12:15], v[128:131], v[200:203], v[12:15]
	v_mfma_f32_16x16x32_bf16 v[8:11], v[148:151], v[200:203], v[8:11]
	v_mfma_f32_16x16x32_bf16 v[60:63], v[144:147], v[180:183], v[60:63]
	v_mfma_f32_16x16x32_bf16 v[56:59], v[152:155], v[180:183], v[56:59]
	v_mfma_f32_16x16x32_bf16 v[44:47], v[144:147], v[188:191], v[44:47]
	v_mfma_f32_16x16x32_bf16 v[40:43], v[152:155], v[188:191], v[40:43]
	v_mfma_f32_16x16x32_bf16 v[28:31], v[144:147], v[196:199], v[28:31]
	v_mfma_f32_16x16x32_bf16 v[24:27], v[152:155], v[196:199], v[24:27]
	v_mfma_f32_16x16x32_bf16 v[12:15], v[144:147], v[214:217], v[12:15]
	v_mfma_f32_16x16x32_bf16 v[8:11], v[152:155], v[214:217], v[8:11]
	s_setprio 0
	s_setprio 1
	v_mfma_f32_16x16x32_bf16 v[52:55], v[156:159], v[176:179], v[52:55]
	v_mfma_f32_16x16x32_bf16 v[48:51], v[168:171], v[176:179], v[48:51]
	v_mfma_f32_16x16x32_bf16 v[36:39], v[156:159], v[184:187], v[36:39]
	v_mfma_f32_16x16x32_bf16 v[32:35], v[168:171], v[184:187], v[32:35]
	v_mfma_f32_16x16x32_bf16 v[20:23], v[156:159], v[192:195], v[20:23]
	v_mfma_f32_16x16x32_bf16 v[16:19], v[168:171], v[192:195], v[16:19]
	v_mfma_f32_16x16x32_bf16 v[4:7], v[156:159], v[200:203], v[4:7]
	v_mfma_f32_16x16x32_bf16 v[0:3], v[168:171], v[200:203], v[0:3]
	v_mfma_f32_16x16x32_bf16 v[52:55], v[160:163], v[180:183], v[52:55]
	v_mfma_f32_16x16x32_bf16 v[48:51], v[172:175], v[180:183], v[48:51]
	v_mfma_f32_16x16x32_bf16 v[36:39], v[160:163], v[188:191], v[36:39]
	v_mfma_f32_16x16x32_bf16 v[32:35], v[172:175], v[188:191], v[32:35]
	v_mfma_f32_16x16x32_bf16 v[20:23], v[160:163], v[196:199], v[20:23]
	v_mfma_f32_16x16x32_bf16 v[16:19], v[172:175], v[196:199], v[16:19]
	v_mfma_f32_16x16x32_bf16 v[4:7], v[160:163], v[214:217], v[4:7]
	v_mfma_f32_16x16x32_bf16 v[0:3], v[172:175], v[214:217], v[0:3]
	s_barrier
	s_setprio 0
	s_add_i32 s76, s76, 2
	s_add_u32 s44, s44, 0x100
	s_addc_u32 s45, s45, 0
	s_add_u32 vcc_lo, vcc_lo, 0x100
	s_addc_u32 vcc_hi, vcc_hi, 0
	s_cmp_gt_u32 s76, 29
	s_cbranch_scc0 .LBB0_680
	s_and_b64 vcc, exec, s[22:23]
	s_cbranch_vccz .LBB0_683
	s_barrier

; #define PG8_STAGE(bufoff, gbase, voff) do { _Pragma("unroll") for (int _i = 0; _i < 2; ++_i) \
;         __builtin_amdgcn_global_load_lds((const unsigned*)((const char*)(gbase) + (voff)[_i]), (PG8_LAS unsigned*)(lds + (bufoff) + ldsw + _i * 8192), 16, 0, 0); } while (0)
; #define PG8_LDA(dst, b, h) do { _Pragma("unroll") for (int m = 0; m < 4; ++m) _Pragma("unroll") for (int k = 0; k < 2; ++k) dst[m][k] = *(const PG8_LAS bf16x8*)(lds + PG8_SA(b, h) + aoff + m * 2048 + k * 1024); } while (0)
; #define PG8_LDB(dst, b, h) do { _Pragma("unroll") for (int n = 0; n < 2; ++n) _Pragma("unroll") for (int k = 0; k < 2; ++k) dst[n][k] = *(const PG8_LAS bf16x8*)(lds + PG8_SB(b, h) + boff + n * 2048 + k * 1024); } while (0)
; #define PG8_MMA(ai, bj, At, Bt) do { __builtin_amdgcn_s_setprio(1); _Pragma("unroll") for (int m = 0; m < 4; ++m) _Pragma("unroll") for (int n = 0; n < 2; ++n) _Pragma("unroll") for (int k = 0; k < 2; ++k) \
;         acc[ai][bj][m][n] = __builtin_amdgcn_mfma_f32_16x16x32_bf16(Bt[n][k], At[m][k], acc[ai][bj][m][n], 0, 0, 0); __builtin_amdgcn_s_setprio(0); } while (0)
; #define PG8_WAIT_V(n) asm volatile("s_waitcnt vmcnt(" #n ")" ::: "memory")
; #define PG8_BAR __builtin_amdgcn_s_barrier()
; template <class Epi, class Sched, bool ALIGN_EPI = false, bool SP2 = false>
; __device__ __forceinline__ void gemm_phase(PG8_LAS unsigned char* lds, const Gemm g, const Sched& S, const Epi& E, const int tid) {
;     ...
;         for (int t = 0; t < nt; t += 2) {
;             const bool last = (t == nt - 2);
;             const char* a1 = cA + (size_t)(t + 1) * kstep;
;             const char* a2 = last ? nA : cA + (size_t)(t + 2) * kstep; const char* b2 = last ? nB : cB + (size_t)(t + 2) * kstep;
;             const char* a3 = a2 + kstep; const char* b3 = b2 + kstep;
;             if (last && has_next) S.a_ready(nxt);
;             if constexpr (SP2) {
;             PG8_LDB(B0, 0, 0); PG8_LDB(B1, 0, 1); PG8_SCHED; PG8_LDA(At, 0, 0); PG8_STAGE(PG8_SA(1, 1), a1 + hstep, voffA);
;             PG8_WAIT_V(8); PG8_WAIT_L(0); PG8_BAR; PG8_MMA(0, 0, At, B0); PG8_MMA(0, 1, At, B1); PG8_BAR; PG8_SCHED;
;             PG8_LDA(At, 0, 1); PG8_STAGE(PG8_SB(0, 0), b2, voffB); PG8_STAGE(PG8_SB(0, 1), b2 + hstep, voffB); PG8_STAGE(PG8_SA(0, 0), a2, voffA);
;             PG8_WAIT_V(8); PG8_WAIT_L(0); PG8_BAR; PG8_MMA(1, 0, At, B0); PG8_MMA(1, 1, At, B1); PG8_BAR; PG8_SCHED;
.LBB0_897:
	s_add_u32 s30, s34, 0xfff80080
	s_addc_u32 s31, s35, -1
	s_add_i32 s69, 0, 0x10000
	s_cmp_eq_u32 s68, 28
	s_cselect_b32 s37, s21, s31
	s_cselect_b32 s36, s40, s30
	s_cselect_b32 s31, s19, s65
	s_cselect_b32 s30, s62, s64
	s_add_i32 s75, 0, 0x14000
	v_add_u32_e32 v140, s69, v216
	v_add_u32_e32 v156, s75, v216
	ds_read_b128 v[128:131], v140
	ds_read_b128 v[132:135], v140 offset:1024
	ds_read_b128 v[136:139], v140 offset:2048
	ds_read_b128 v[140:143], v140 offset:3072
	ds_read_b128 v[144:147], v156
	ds_read_b128 v[148:151], v156 offset:1024
	ds_read_b128 v[152:155], v156 offset:2048
	ds_read_b128 v[156:159], v156 offset:3072
	v_lshl_add_u64 v[202:203], s[34:35], 0, v[198:199]
	s_add_i32 m0, s46, 0xc000
	ds_read_b128 v[160:163], v217
	ds_read_b128 v[164:167], v217 offset:1024
	ds_read_b128 v[168:171], v217 offset:2048
	ds_read_b128 v[172:175], v217 offset:3072
	ds_read_b128 v[176:179], v217 offset:4096
	ds_read_b128 v[180:183], v217 offset:5120
	ds_read_b128 v[184:187], v217 offset:6144
	ds_read_b128 v[188:191], v217 offset:7168
	global_load_lds_dwordx4 v[202:203], off
	v_lshl_add_u64 v[202:203], s[34:35], 0, v[200:201]
	s_add_i32 m0, s46, 0xe000
	s_nop 0
	global_load_lds_dwordx4 v[202:203], off
	s_waitcnt vmcnt(8)
	s_waitcnt lgkmcnt(0)
	s_setprio 1
	s_barrier
	v_mfma_f32_16x16x32_bf16 v[120:123], v[128:131], v[160:163], v[120:123]
	v_mfma_f32_16x16x32_bf16 v[124:127], v[136:139], v[160:163], v[124:127]
	v_mfma_f32_16x16x32_bf16 v[104:107], v[128:131], v[168:171], v[104:107]
	v_mfma_f32_16x16x32_bf16 v[108:111], v[136:139], v[168:171], v[108:111]
	v_mfma_f32_16x16x32_bf16 v[88:91], v[128:131], v[176:179], v[88:91]
	v_mfma_f32_16x16x32_bf16 v[92:95], v[136:139], v[176:179], v[92:95]
	v_mfma_f32_16x16x32_bf16 v[72:75], v[128:131], v[184:187], v[72:75]
	v_mfma_f32_16x16x32_bf16 v[76:79], v[136:139], v[184:187], v[76:79]
	v_mfma_f32_16x16x32_bf16 v[120:123], v[132:135], v[164:167], v[120:123]
	v_mfma_f32_16x16x32_bf16 v[124:127], v[140:143], v[164:167], v[124:127]
	v_mfma_f32_16x16x32_bf16 v[104:107], v[132:135], v[172:175], v[104:107]
	v_mfma_f32_16x16x32_bf16 v[108:111], v[140:143], v[172:175], v[108:111]
	v_mfma_f32_16x16x32_bf16 v[88:91], v[132:135], v[180:183], v[88:91]
	v_mfma_f32_16x16x32_bf16 v[92:95], v[140:143], v[180:183], v[92:95]
	v_mfma_f32_16x16x32_bf16 v[72:75], v[132:135], v[188:191], v[72:75]
	v_mfma_f32_16x16x32_bf16 v[76:79], v[140:143], v[188:191], v[76:79]
	s_setprio 0
	s_setprio 1
	v_mfma_f32_16x16x32_bf16 v[112:115], v[144:147], v[160:163], v[112:115]
	v_mfma_f32_16x16x32_bf16 v[116:119], v[152:155], v[160:163], v[116:119]
	v_mfma_f32_16x16x32_bf16 v[96:99], v[144:147], v[168:171], v[96:99]
	v_mfma_f32_16x16x32_bf16 v[100:103], v[152:155], v[168:171], v[100:103]
	v_mfma_f32_16x16x32_bf16 v[80:83], v[144:147], v[176:179], v[80:83]
	v_mfma_f32_16x16x32_bf16 v[84:87], v[152:155], v[176:179], v[84:87]
	v_mfma_f32_16x16x32_bf16 v[60:63], v[144:147], v[184:187], v[60:63]
	v_mfma_f32_16x16x32_bf16 v[68:71], v[152:155], v[184:187], v[68:71]
	v_mfma_f32_16x16x32_bf16 v[112:115], v[148:151], v[164:167], v[112:115]
	v_mfma_f32_16x16x32_bf16 v[116:119], v[156:159], v[164:167], v[116:119]
	v_mfma_f32_16x16x32_bf16 v[96:99], v[148:151], v[172:175], v[96:99]
	v_mfma_f32_16x16x32_bf16 v[100:103], v[156:159], v[172:175], v[100:103]
	v_mfma_f32_16x16x32_bf16 v[80:83], v[148:151], v[180:183], v[80:83]
	v_mfma_f32_16x16x32_bf16 v[84:87], v[156:159], v[180:183], v[84:87]
	v_mfma_f32_16x16x32_bf16 v[60:63], v[148:151], v[188:191], v[60:63]
	v_mfma_f32_16x16x32_bf16 v[68:71], v[156:159], v[188:191], v[68:71]
	s_barrier
	s_setprio 0
	s_add_i32 s69, s69, s43
	v_lshl_add_u64 v[202:203], s[30:31], 0, v[204:205]
	s_mov_b32 m0, s69
	ds_read_b128 v[160:163], v217 offset:16384
	ds_read_b128 v[164:167], v217 offset:17408
	ds_read_b128 v[168:171], v217 offset:18432
	ds_read_b128 v[172:175], v217 offset:19456
	ds_read_b128 v[176:179], v217 offset:20480
	ds_read_b128 v[180:183], v217 offset:21504
	ds_read_b128 v[184:187], v217 offset:22528
	ds_read_b128 v[188:191], v217 offset:23552
	global_load_lds_dwordx4 v[202:203], off
	s_add_i32 m0, s69, 0x2000
	s_add_u32 s76, s30, 0x80000
	v_lshl_add_u64 v[206:207], s[30:31], 0, v[196:197]
	s_addc_u32 s77, s31, 0
	s_add_i32 s69, s75, s43
	global_load_lds_dwordx4 v[206:207], off
	v_lshl_add_u64 v[208:209], s[76:77], 0, v[204:205]
	s_mov_b32 m0, s69
	v_lshl_add_u64 v[210:211], s[36:37], 0, v[194:195]
	global_load_lds_dwordx4 v[208:209], off
	v_lshl_add_u64 v[208:209], s[76:77], 0, v[196:197]
	s_add_i32 m0, s69, 0x2000
	s_nop 0
	global_load_lds_dwordx4 v[208:209], off
	v_lshl_add_u64 v[208:209], s[36:37], 0, v[192:193]
	s_mov_b32 m0, s46
	s_nop 0
	global_load_lds_dwordx4 v[208:209], off
	s_mov_b32 m0, s47
	s_nop 0
	global_load_lds_dwordx4 v[210:211], off
	s_waitcnt vmcnt(8)
	s_waitcnt lgkmcnt(0)
	s_setprio 1
	s_barrier
; #define PG8_STAGE(bufoff, gbase, voff) do { _Pragma("unroll") for (int _i = 0; _i < 2; ++_i) \
;         __builtin_amdgcn_global_load_lds((const unsigned*)((const char*)(gbase) + (voff)[_i]), (PG8_LAS unsigned*)(lds + (bufoff) + ldsw + _i * 8192), 16, 0, 0); } while (0)
; #define PG8_LDA(dst, b, h) do { _Pragma("unroll") for (int m = 0; m < 4; ++m) _Pragma("unroll") for (int k = 0; k < 2; ++k) dst[m][k] = *(const PG8_LAS bf16x8*)(lds + PG8_SA(b, h) + aoff + m * 2048 + k * 1024); } while (0)
; #define PG8_LDB(dst, b, h) do { _Pragma("unroll") for (int n = 0; n < 2; ++n) _Pragma("unroll") for (int k = 0; k < 2; ++k) dst[n][k] = *(const PG8_LAS bf16x8*)(lds + PG8_SB(b, h) + boff + n * 2048 + k * 1024); } while (0)
; #define PG8_MMA(ai, bj, At, Bt) do { __builtin_amdgcn_s_setprio(1); _Pragma("unroll") for (int m = 0; m < 4; ++m) _Pragma("unroll") for (int n = 0; n < 2; ++n) _Pragma("unroll") for (int k = 0; k < 2; ++k) \
;         acc[ai][bj][m][n] = __builtin_amdgcn_mfma_f32_16x16x32_bf16(Bt[n][k], At[m][k], acc[ai][bj][m][n], 0, 0, 0); __builtin_amdgcn_s_setprio(0); } while (0)
; #define PG8_WAIT_V(n) asm volatile("s_waitcnt vmcnt(" #n ")" ::: "memory")
; #define PG8_WAIT_L(n) asm volatile("s_waitcnt lgkmcnt(" #n ")" ::: "memory")
; #define PG8_BAR __builtin_amdgcn_s_barrier()
; #define PG8_SCHED __builtin_amdgcn_sched_barrier(0)
; template <class Epi, class Sched, bool ALIGN_EPI = false, bool SP2 = false>
; __device__ __forceinline__ void gemm_phase(PG8_LAS unsigned char* lds, const Gemm g, const Sched& S, const Epi& E, const int tid) {
;     ...
;             PG8_LDA(At, 0, 1); PG8_STAGE(PG8_SB(0, 0), b2, voffB); PG8_STAGE(PG8_SB(0, 1), b2 + hstep, voffB); PG8_STAGE(PG8_SA(0, 0), a2, voffA);
;             PG8_WAIT_V(8); PG8_WAIT_L(0); PG8_BAR; PG8_MMA(1, 0, At, B0); PG8_MMA(1, 1, At, B1); PG8_BAR; PG8_SCHED;
;             PG8_LDB(B0, 1, 0); PG8_LDB(B1, 1, 1); PG8_SCHED; PG8_LDA(At, 1, 0); PG8_STAGE(PG8_SA(0, 1), a2 + hstep, voffA);
;             PG8_WAIT_V(8); PG8_WAIT_L(0); PG8_BAR; PG8_MMA(0, 0, At, B0); PG8_MMA(0, 1, At, B1); PG8_BAR; PG8_SCHED;
	v_mfma_f32_16x16x32_bf16 v[48:51], v[128:131], v[160:163], v[48:51]
	v_mfma_f32_16x16x32_bf16 v[56:59], v[136:139], v[160:163], v[56:59]
	v_mfma_f32_16x16x32_bf16 v[20:23], v[128:131], v[168:171], v[20:23]
	v_mfma_f32_16x16x32_bf16 v[64:67], v[136:139], v[168:171], v[64:67]
	v_mfma_f32_16x16x32_bf16 v[28:31], v[128:131], v[176:179], v[28:31]
	v_mfma_f32_16x16x32_bf16 v[36:39], v[136:139], v[176:179], v[36:39]
	v_mfma_f32_16x16x32_bf16 v[8:11], v[128:131], v[184:187], v[8:11]
	v_mfma_f32_16x16x32_bf16 v[12:15], v[136:139], v[184:187], v[12:15]
	v_mfma_f32_16x16x32_bf16 v[48:51], v[132:135], v[164:167], v[48:51]
	v_mfma_f32_16x16x32_bf16 v[56:59], v[140:143], v[164:167], v[56:59]
	v_mfma_f32_16x16x32_bf16 v[20:23], v[132:135], v[172:175], v[20:23]
	v_mfma_f32_16x16x32_bf16 v[64:67], v[140:143], v[172:175], v[64:67]
	v_mfma_f32_16x16x32_bf16 v[28:31], v[132:135], v[180:183], v[28:31]
	v_mfma_f32_16x16x32_bf16 v[36:39], v[140:143], v[180:183], v[36:39]
	v_mfma_f32_16x16x32_bf16 v[8:11], v[132:135], v[188:191], v[8:11]
	v_mfma_f32_16x16x32_bf16 v[12:15], v[140:143], v[188:191], v[12:15]
	s_setprio 0
	s_setprio 1
	v_mfma_f32_16x16x32_bf16 v[32:35], v[144:147], v[160:163], v[32:35]
	v_mfma_f32_16x16x32_bf16 v[40:43], v[152:155], v[160:163], v[40:43]
	v_mfma_f32_16x16x32_bf16 v[44:47], v[144:147], v[168:171], v[44:47]
	v_mfma_f32_16x16x32_bf16 v[52:55], v[152:155], v[168:171], v[52:55]
	v_mfma_f32_16x16x32_bf16 v[16:19], v[144:147], v[176:179], v[16:19]
	v_mfma_f32_16x16x32_bf16 v[24:27], v[152:155], v[176:179], v[24:27]
	v_mfma_f32_16x16x32_bf16 v[0:3], v[144:147], v[184:187], v[0:3]
	v_mfma_f32_16x16x32_bf16 v[4:7], v[152:155], v[184:187], v[4:7]
	v_mfma_f32_16x16x32_bf16 v[32:35], v[148:151], v[164:167], v[32:35]
	v_mfma_f32_16x16x32_bf16 v[40:43], v[156:159], v[164:167], v[40:43]
	v_mfma_f32_16x16x32_bf16 v[44:47], v[148:151], v[172:175], v[44:47]
	v_mfma_f32_16x16x32_bf16 v[52:55], v[156:159], v[172:175], v[52:55]
	v_mfma_f32_16x16x32_bf16 v[16:19], v[148:151], v[180:183], v[16:19]
	v_mfma_f32_16x16x32_bf16 v[24:27], v[156:159], v[180:183], v[24:27]
	v_mfma_f32_16x16x32_bf16 v[0:3], v[148:151], v[188:191], v[0:3]
	v_mfma_f32_16x16x32_bf16 v[4:7], v[156:159], v[188:191], v[4:7]
	s_barrier
	s_setprio 0
	s_add_i32 s69, 0, 0x18000
	s_add_i32 s75, 0, 0x1c000
	v_add_u32_e32 v140, s69, v216
	v_add_u32_e32 v156, s75, v216
	ds_read_b128 v[128:131], v140
	ds_read_b128 v[132:135], v140 offset:1024
	ds_read_b128 v[136:139], v140 offset:2048
	ds_read_b128 v[140:143], v140 offset:3072
	ds_read_b128 v[144:147], v156
	ds_read_b128 v[148:151], v156 offset:1024
	ds_read_b128 v[152:155], v156 offset:2048
	ds_read_b128 v[156:159], v156 offset:3072
	s_add_u32 s36, s36, 0x80000
	s_addc_u32 s37, s37, 0
	s_mov_b32 m0, s48
	v_lshl_add_u64 v[212:213], s[36:37], 0, v[192:193]
	ds_read_b128 v[160:163], v217 offset:32768
	ds_read_b128 v[164:167], v217 offset:33792
	ds_read_b128 v[168:171], v217 offset:34816
	ds_read_b128 v[172:175], v217 offset:35840
	ds_read_b128 v[176:179], v217 offset:36864
	ds_read_b128 v[180:183], v217 offset:37888
	ds_read_b128 v[184:187], v217 offset:38912
	ds_read_b128 v[188:191], v217 offset:39936
	global_load_lds_dwordx4 v[212:213], off
	v_lshl_add_u64 v[212:213], s[36:37], 0, v[194:195]
	s_mov_b32 m0, s49
	s_nop 0
	global_load_lds_dwordx4 v[212:213], off
	s_waitcnt vmcnt(8)
	s_waitcnt lgkmcnt(0)
	s_setprio 1
	s_barrier
	v_mfma_f32_16x16x32_bf16 v[120:123], v[128:131], v[160:163], v[120:123]
	v_mfma_f32_16x16x32_bf16 v[124:127], v[136:139], v[160:163], v[124:127]
	v_mfma_f32_16x16x32_bf16 v[104:107], v[128:131], v[168:171], v[104:107]
	v_mfma_f32_16x16x32_bf16 v[108:111], v[136:139], v[168:171], v[108:111]
	v_mfma_f32_16x16x32_bf16 v[88:91], v[128:131], v[176:179], v[88:91]
	v_mfma_f32_16x16x32_bf16 v[92:95], v[136:139], v[176:179], v[92:95]
	v_mfma_f32_16x16x32_bf16 v[72:75], v[128:131], v[184:187], v[72:75]
	v_mfma_f32_16x16x32_bf16 v[76:79], v[136:139], v[184:187], v[76:79]
	v_mfma_f32_16x16x32_bf16 v[120:123], v[132:135], v[164:167], v[120:123]
	v_mfma_f32_16x16x32_bf16 v[124:127], v[140:143], v[164:167], v[124:127]
	v_mfma_f32_16x16x32_bf16 v[104:107], v[132:135], v[172:175], v[104:107]
	v_mfma_f32_16x16x32_bf16 v[108:111], v[140:143], v[172:175], v[108:111]
	v_mfma_f32_16x16x32_bf16 v[88:91], v[132:135], v[180:183], v[88:91]
	v_mfma_f32_16x16x32_bf16 v[92:95], v[140:143], v[180:183], v[92:95]
	v_mfma_f32_16x16x32_bf16 v[72:75], v[132:135], v[188:191], v[72:75]
	v_mfma_f32_16x16x32_bf16 v[76:79], v[140:143], v[188:191], v[76:79]
	s_setprio 0
	s_setprio 1
	v_mfma_f32_16x16x32_bf16 v[112:115], v[144:147], v[160:163], v[112:115]
	v_mfma_f32_16x16x32_bf16 v[116:119], v[152:155], v[160:163], v[116:119]
	v_mfma_f32_16x16x32_bf16 v[96:99], v[144:147], v[168:171], v[96:99]
	v_mfma_f32_16x16x32_bf16 v[100:103], v[152:155], v[168:171], v[100:103]
	v_mfma_f32_16x16x32_bf16 v[80:83], v[144:147], v[176:179], v[80:83]
	v_mfma_f32_16x16x32_bf16 v[84:87], v[152:155], v[176:179], v[84:87]
	v_mfma_f32_16x16x32_bf16 v[60:63], v[144:147], v[184:187], v[60:63]
	v_mfma_f32_16x16x32_bf16 v[68:71], v[152:155], v[184:187], v[68:71]
	v_mfma_f32_16x16x32_bf16 v[112:115], v[148:151], v[164:167], v[112:115]
	v_mfma_f32_16x16x32_bf16 v[116:119], v[156:159], v[164:167], v[116:119]
	v_mfma_f32_16x16x32_bf16 v[96:99], v[148:151], v[172:175], v[96:99]
	v_mfma_f32_16x16x32_bf16 v[100:103], v[156:159], v[172:175], v[100:103]
	v_mfma_f32_16x16x32_bf16 v[80:83], v[148:151], v[180:183], v[80:83]
	v_mfma_f32_16x16x32_bf16 v[84:87], v[156:159], v[180:183], v[84:87]
	v_mfma_f32_16x16x32_bf16 v[60:63], v[148:151], v[188:191], v[60:63]
	v_mfma_f32_16x16x32_bf16 v[68:71], v[156:159], v[188:191], v[68:71]
	s_barrier
; #define PG8_STAGE(bufoff, gbase, voff) do { _Pragma("unroll") for (int _i = 0; _i < 2; ++_i) \
;         __builtin_amdgcn_global_load_lds((const unsigned*)((const char*)(gbase) + (voff)[_i]), (PG8_LAS unsigned*)(lds + (bufoff) + ldsw + _i * 8192), 16, 0, 0); } while (0)
; #define PG8_LDA(dst, b, h) do { _Pragma("unroll") for (int m = 0; m < 4; ++m) _Pragma("unroll") for (int k = 0; k < 2; ++k) dst[m][k] = *(const PG8_LAS bf16x8*)(lds + PG8_SA(b, h) + aoff + m * 2048 + k * 1024); } while (0)
; #define PG8_BAR __builtin_amdgcn_s_barrier()
; template <class Epi, class Sched, bool ALIGN_EPI = false, bool SP2 = false>
; __device__ __forceinline__ void gemm_phase(PG8_LAS unsigned char* lds, const Gemm g, const Sched& S, const Epi& E, const int tid) {
;     ...
;             PG8_LDA(At, 1, 1); PG8_STAGE(PG8_SB(1, 0), b3, voffB); PG8_STAGE(PG8_SB(1, 1), b3 + hstep, voffB); PG8_STAGE(PG8_SA(1, 0), a3, voffA);
;             PG8_WAIT_V(8); PG8_WAIT_L(0); PG8_BAR; PG8_MMA(1, 0, At, B0); PG8_MMA(1, 1, At, B1); PG8_BAR; PG8_SCHED;
;             } else {
;             PG8_LDB(B0, 0, 0); PG8_SCHED; PG8_LDA(At, 0, 0); PG8_STAGE(PG8_SA(1, 1), a1 + hstep, voffA);
;             PG8_WAIT_L(8); PG8_BAR; PG8_WAIT_L(0); PG8_MMA(0, 0, At, B0); PG8_BAR; PG8_SCHED;
;             PG8_LDB(B1, 0, 1); PG8_STAGE(PG8_SB(0, 0), b2, voffB);
;             PG8_BAR; PG8_WAIT_L(0); PG8_MMA(0, 1, At, B1); PG8_BAR;
;             PG8_LDA(At, 0, 1); PG8_STAGE(PG8_SA(0, 0), a2, voffA);
;             PG8_BAR; PG8_WAIT_L(0); PG8_MMA(1, 0, At, B0); PG8_BAR; PG8_SCHED;
;             PG8_STAGE(PG8_SB(0, 1), b2 + hstep, voffB);
;             PG8_WAIT_V(6); PG8_BAR; PG8_MMA(1, 1, At, B1); PG8_BAR;
;             PG8_LDB(B0, 1, 0); PG8_SCHED; PG8_LDA(At, 1, 0); PG8_STAGE(PG8_SA(0, 1), a2 + hstep, voffA);
;             PG8_WAIT_L(8); PG8_BAR; PG8_WAIT_L(0); PG8_MMA(0, 0, At, B0); PG8_BAR; PG8_SCHED;
;             PG8_LDB(B1, 1, 1); PG8_STAGE(PG8_SB(1, 0), b3, voffB);
;             PG8_BAR; PG8_WAIT_L(0); PG8_MMA(0, 1, At, B1); PG8_BAR;
;             PG8_LDA(At, 1, 1); PG8_STAGE(PG8_SA(1, 0), a3, voffA);
;             PG8_BAR; PG8_WAIT_L(0); PG8_MMA(1, 0, At, B0); PG8_BAR; PG8_SCHED;
;             PG8_STAGE(PG8_SB(1, 1), b3 + hstep, voffB);
;             PG8_WAIT_V(6); PG8_BAR; PG8_MMA(1, 1, At, B1); PG8_BAR;
;             }
;         }
;         if constexpr (ALIGN_EPI) { if (wr == 0) PG8_BAR; }
	s_setprio 0
	s_add_i32 s36, s69, s43
	v_lshl_add_u64 v[202:203], v[202:203], 0, s[70:71]
	s_mov_b32 m0, s36
	ds_read_b128 v[160:163], v217 offset:49152
	ds_read_b128 v[164:167], v217 offset:50176
	ds_read_b128 v[168:171], v217 offset:51200
	ds_read_b128 v[172:175], v217 offset:52224
	ds_read_b128 v[176:179], v217 offset:53248
	ds_read_b128 v[180:183], v217 offset:54272
	ds_read_b128 v[184:187], v217 offset:55296
	ds_read_b128 v[188:191], v217 offset:56320
	global_load_lds_dwordx4 v[202:203], off
	s_add_i32 m0, s36, 0x2000
	s_add_u32 s30, s30, 0x80080
	v_lshl_add_u64 v[202:203], v[206:207], 0, s[70:71]
	s_addc_u32 s31, s31, 0
	s_add_i32 s36, s75, s43
	global_load_lds_dwordx4 v[202:203], off
	v_lshl_add_u64 v[202:203], s[30:31], 0, v[204:205]
	s_mov_b32 m0, s36
	s_nop 0
	global_load_lds_dwordx4 v[202:203], off
	v_lshl_add_u64 v[202:203], s[30:31], 0, v[196:197]
	s_add_i32 m0, s36, 0x2000
	s_nop 0
	global_load_lds_dwordx4 v[202:203], off
	v_lshl_add_u64 v[202:203], v[208:209], 0, s[70:71]
	s_mov_b32 m0, s51
	s_nop 0
	global_load_lds_dwordx4 v[202:203], off
	v_lshl_add_u64 v[202:203], v[210:211], 0, s[70:71]
	s_mov_b32 m0, s52
	s_nop 0
	global_load_lds_dwordx4 v[202:203], off
	s_waitcnt vmcnt(8)
	s_waitcnt lgkmcnt(0)
	s_setprio 1
	s_barrier
	v_mfma_f32_16x16x32_bf16 v[48:51], v[128:131], v[160:163], v[48:51]
	v_mfma_f32_16x16x32_bf16 v[56:59], v[136:139], v[160:163], v[56:59]
	v_mfma_f32_16x16x32_bf16 v[20:23], v[128:131], v[168:171], v[20:23]
	v_mfma_f32_16x16x32_bf16 v[64:67], v[136:139], v[168:171], v[64:67]
	v_mfma_f32_16x16x32_bf16 v[28:31], v[128:131], v[176:179], v[28:31]
	v_mfma_f32_16x16x32_bf16 v[36:39], v[136:139], v[176:179], v[36:39]
	v_mfma_f32_16x16x32_bf16 v[8:11], v[128:131], v[184:187], v[8:11]
	v_mfma_f32_16x16x32_bf16 v[12:15], v[136:139], v[184:187], v[12:15]
	v_mfma_f32_16x16x32_bf16 v[48:51], v[132:135], v[164:167], v[48:51]
	v_mfma_f32_16x16x32_bf16 v[56:59], v[140:143], v[164:167], v[56:59]
	v_mfma_f32_16x16x32_bf16 v[20:23], v[132:135], v[172:175], v[20:23]
	v_mfma_f32_16x16x32_bf16 v[64:67], v[140:143], v[172:175], v[64:67]
	v_mfma_f32_16x16x32_bf16 v[28:31], v[132:135], v[180:183], v[28:31]
	v_mfma_f32_16x16x32_bf16 v[36:39], v[140:143], v[180:183], v[36:39]
	v_mfma_f32_16x16x32_bf16 v[8:11], v[132:135], v[188:191], v[8:11]
	v_mfma_f32_16x16x32_bf16 v[12:15], v[140:143], v[188:191], v[12:15]
	s_setprio 0
	s_setprio 1
	v_mfma_f32_16x16x32_bf16 v[32:35], v[144:147], v[160:163], v[32:35]
	v_mfma_f32_16x16x32_bf16 v[40:43], v[152:155], v[160:163], v[40:43]
	v_mfma_f32_16x16x32_bf16 v[44:47], v[144:147], v[168:171], v[44:47]
	v_mfma_f32_16x16x32_bf16 v[52:55], v[152:155], v[168:171], v[52:55]
	v_mfma_f32_16x16x32_bf16 v[16:19], v[144:147], v[176:179], v[16:19]
	v_mfma_f32_16x16x32_bf16 v[24:27], v[152:155], v[176:179], v[24:27]
	v_mfma_f32_16x16x32_bf16 v[0:3], v[144:147], v[184:187], v[0:3]
	v_mfma_f32_16x16x32_bf16 v[4:7], v[152:155], v[184:187], v[4:7]
	v_mfma_f32_16x16x32_bf16 v[32:35], v[148:151], v[164:167], v[32:35]
	v_mfma_f32_16x16x32_bf16 v[40:43], v[156:159], v[164:167], v[40:43]
	v_mfma_f32_16x16x32_bf16 v[44:47], v[148:151], v[172:175], v[44:47]
	v_mfma_f32_16x16x32_bf16 v[52:55], v[156:159], v[172:175], v[52:55]
	v_mfma_f32_16x16x32_bf16 v[16:19], v[148:151], v[180:183], v[16:19]
	v_mfma_f32_16x16x32_bf16 v[24:27], v[156:159], v[180:183], v[24:27]
	v_mfma_f32_16x16x32_bf16 v[0:3], v[148:151], v[188:191], v[0:3]
	v_mfma_f32_16x16x32_bf16 v[4:7], v[156:159], v[188:191], v[4:7]
	s_barrier
	s_setprio 0
	s_add_i32 s68, s68, 2
	s_add_u32 s34, s34, 0x100
	s_addc_u32 s35, s35, 0
	s_add_u32 s64, s64, 0x100
	s_addc_u32 s65, s65, 0
	s_cmp_gt_u32 s68, 29
	s_cbranch_scc0 .LBB0_897
	s_and_b64 vcc, exec, s[16:17]
	s_cbranch_vccz .LBB0_900
	s_barrier

; #define PG8_STAGE(bufoff, gbase, voff) do { _Pragma("unroll") for (int _i = 0; _i < 2; ++_i) \
;         __builtin_amdgcn_global_load_lds((const unsigned*)((const char*)(gbase) + (voff)[_i]), (PG8_LAS unsigned*)(lds + (bufoff) + ldsw + _i * 8192), 16, 0, 0); } while (0)
; #define PG8_LDA(dst, b, h) do { _Pragma("unroll") for (int m = 0; m < 4; ++m) _Pragma("unroll") for (int k = 0; k < 2; ++k) dst[m][k] = *(const PG8_LAS bf16x8*)(lds + PG8_SA(b, h) + aoff + m * 2048 + k * 1024); } while (0)
; #define PG8_LDB(dst, b, h) do { _Pragma("unroll") for (int n = 0; n < 2; ++n) _Pragma("unroll") for (int k = 0; k < 2; ++k) dst[n][k] = *(const PG8_LAS bf16x8*)(lds + PG8_SB(b, h) + boff + n * 2048 + k * 1024); } while (0)
; #define PG8_WAIT_V(n) asm volatile("s_waitcnt vmcnt(" #n ")" ::: "memory")
; #define PG8_WAIT_L(n) asm volatile("s_waitcnt lgkmcnt(" #n ")" ::: "memory")
; #define PG8_BAR __builtin_amdgcn_s_barrier()
; #define PG8_SCHED __builtin_amdgcn_sched_barrier(0)
; template <class Epi, class Sched, bool ALIGN_EPI = false, bool SP2 = false>
; __device__ __forceinline__ void gemm_phase(PG8_LAS unsigned char* lds, const Gemm g, const Sched& S, const Epi& E, const int tid) {
;     ...
;         const bool has_next = S.next(ui + 1, nxt);
;         const char* nA = has_next ? (const char*)g.A + (size_t)nxt.pm * tstep : cA; const char* nB = has_next ? (const char*)g.Bt + (size_t)nxt.pn * tstep : cB;
;         for (int t = 0; t < nt; t += 2) {
;             const bool last = (t == nt - 2);
;             const char* a1 = cA + (size_t)(t + 1) * kstep;
;             const char* a2 = last ? nA : cA + (size_t)(t + 2) * kstep; const char* b2 = last ? nB : cB + (size_t)(t + 2) * kstep;
;             const char* a3 = a2 + kstep; const char* b3 = b2 + kstep;
;             if (last && has_next) S.a_ready(nxt);
;             if constexpr (SP2) {
;             PG8_LDB(B0, 0, 0); PG8_LDB(B1, 0, 1); PG8_SCHED; PG8_LDA(At, 0, 0); PG8_STAGE(PG8_SA(1, 1), a1 + hstep, voffA);
;             PG8_WAIT_V(8); PG8_WAIT_L(0); PG8_BAR; PG8_MMA(0, 0, At, B0); PG8_MMA(0, 1, At, B1); PG8_BAR; PG8_SCHED;
;             PG8_LDA(At, 0, 1); PG8_STAGE(PG8_SB(0, 0), b2, voffB); PG8_STAGE(PG8_SB(0, 1), b2 + hstep, voffB); PG8_STAGE(PG8_SA(0, 0), a2, voffA);
;             PG8_WAIT_V(8); PG8_WAIT_L(0); PG8_BAR; PG8_MMA(1, 0, At, B0); PG8_MMA(1, 1, At, B1); PG8_BAR; PG8_SCHED;
.LBB0_1087:
	s_ashr_i32 s19, s18, 31
	s_lshl_b64 s[20:21], s[18:19], 20
	s_add_u32 s20, s11, s20
	s_addc_u32 s21, s33, s21
	s_and_b64 s[22:23], s[4:5], exec
	s_cselect_b32 s19, s21, s27
	s_cselect_b32 s50, s20, s26
	s_ashr_i32 s17, s16, 31
	s_lshl_b64 s[22:23], s[16:17], 20
	s_add_u32 s22, s34, s22
	s_addc_u32 s23, s35, s23
	s_and_b64 s[30:31], s[4:5], exec
	s_cselect_b32 s17, s23, s29
	s_cselect_b32 s51, s22, s28
	s_add_u32 s26, s26, 0x80080
	s_addc_u32 s27, s27, 0
	s_add_u32 s52, s28, 0x100
	s_addc_u32 s53, s29, 0
	s_mov_b32 s54, -2
	s_add_u32 s28, s26, 0xfff80080
	s_addc_u32 s29, s27, -1
	s_add_i32 s55, 0, 0x10000
	s_cmp_eq_u32 s54, 28
	s_cselect_b32 s31, s19, s29
	s_cselect_b32 s30, s50, s28
	v_add_u32_e32 v138, s55, v139
	s_cselect_b32 s29, s17, s53
	s_cselect_b32 s28, s51, s52
	s_add_i32 s62, 0, 0x14000
	ds_read_b128 v[144:147], v138
	ds_read_b128 v[148:151], v138 offset:1024
	ds_read_b128 v[152:155], v138 offset:2048
	ds_read_b128 v[156:159], v138 offset:3072
	v_add_u32_e32 v138, s62, v139
	ds_read_b128 v[160:163], v138
	ds_read_b128 v[164:167], v138 offset:1024
	ds_read_b128 v[168:171], v138 offset:2048
	ds_read_b128 v[172:175], v138 offset:3072
	v_lshl_add_u64 v[140:141], s[26:27], 0, v[134:135]
	s_add_i32 m0, s37, 0xc000
	ds_read_b128 v[176:179], v143
	ds_read_b128 v[180:183], v143 offset:1024
	ds_read_b128 v[184:187], v143 offset:2048
	ds_read_b128 v[188:191], v143 offset:3072
	ds_read_b128 v[192:195], v143 offset:4096
	ds_read_b128 v[196:199], v143 offset:5120
	ds_read_b128 v[200:203], v143 offset:6144
	ds_read_b128 v[206:209], v143 offset:7168
	global_load_lds_dwordx4 v[140:141], off
	v_lshl_add_u64 v[140:141], s[26:27], 0, v[136:137]
	s_add_i32 m0, s37, 0xe000
	s_nop 0
	global_load_lds_dwordx4 v[140:141], off
	s_waitcnt vmcnt(24)
	s_waitcnt lgkmcnt(0)
	s_setprio 1
	s_barrier
	v_mfma_f32_16x16x32_bf16 v[124:127], v[144:147], v[176:179], 0
	v_mfma_f32_16x16x32_bf16 v[120:123], v[152:155], v[176:179], 0
	v_mfma_f32_16x16x32_bf16 v[108:111], v[144:147], v[184:187], 0
	v_mfma_f32_16x16x32_bf16 v[104:107], v[152:155], v[184:187], 0
	v_mfma_f32_16x16x32_bf16 v[92:95], v[144:147], v[192:195], 0
	v_mfma_f32_16x16x32_bf16 v[88:91], v[152:155], v[192:195], 0
	v_mfma_f32_16x16x32_bf16 v[76:79], v[144:147], v[200:203], 0
	v_mfma_f32_16x16x32_bf16 v[72:75], v[152:155], v[200:203], 0
	v_mfma_f32_16x16x32_bf16 v[124:127], v[148:151], v[180:183], v[124:127]
	v_mfma_f32_16x16x32_bf16 v[120:123], v[156:159], v[180:183], v[120:123]
	v_mfma_f32_16x16x32_bf16 v[108:111], v[148:151], v[188:191], v[108:111]
	v_mfma_f32_16x16x32_bf16 v[104:107], v[156:159], v[188:191], v[104:107]
	v_mfma_f32_16x16x32_bf16 v[92:95], v[148:151], v[196:199], v[92:95]
	v_mfma_f32_16x16x32_bf16 v[88:91], v[156:159], v[196:199], v[88:91]
	v_mfma_f32_16x16x32_bf16 v[76:79], v[148:151], v[206:209], v[76:79]
	v_mfma_f32_16x16x32_bf16 v[72:75], v[156:159], v[206:209], v[72:75]
	s_setprio 0
	s_setprio 1
	v_mfma_f32_16x16x32_bf16 v[116:119], v[160:163], v[176:179], 0
	v_mfma_f32_16x16x32_bf16 v[112:115], v[168:171], v[176:179], 0
	v_mfma_f32_16x16x32_bf16 v[100:103], v[160:163], v[184:187], 0
	v_mfma_f32_16x16x32_bf16 v[96:99], v[168:171], v[184:187], 0
	v_mfma_f32_16x16x32_bf16 v[84:87], v[160:163], v[192:195], 0
	v_mfma_f32_16x16x32_bf16 v[80:83], v[168:171], v[192:195], 0
	v_mfma_f32_16x16x32_bf16 v[68:71], v[160:163], v[200:203], 0
	v_mfma_f32_16x16x32_bf16 v[64:67], v[168:171], v[200:203], 0
	v_mfma_f32_16x16x32_bf16 v[116:119], v[164:167], v[180:183], v[116:119]
	v_mfma_f32_16x16x32_bf16 v[112:115], v[172:175], v[180:183], v[112:115]
	v_mfma_f32_16x16x32_bf16 v[100:103], v[164:167], v[188:191], v[100:103]
	v_mfma_f32_16x16x32_bf16 v[96:99], v[172:175], v[188:191], v[96:99]
	v_mfma_f32_16x16x32_bf16 v[84:87], v[164:167], v[196:199], v[84:87]
	v_mfma_f32_16x16x32_bf16 v[80:83], v[172:175], v[196:199], v[80:83]
	v_mfma_f32_16x16x32_bf16 v[68:71], v[164:167], v[206:209], v[68:71]
	v_mfma_f32_16x16x32_bf16 v[64:67], v[172:175], v[206:209], v[64:67]
	s_barrier
	s_setprio 0
	s_add_i32 s55, s55, s36
	v_lshl_add_u64 v[140:141], s[28:29], 0, v[204:205]
	s_mov_b32 m0, s55
	ds_read_b128 v[176:179], v143 offset:16384
	ds_read_b128 v[180:183], v143 offset:17408
	ds_read_b128 v[184:187], v143 offset:18432
	ds_read_b128 v[188:191], v143 offset:19456
	ds_read_b128 v[192:195], v143 offset:20480
	ds_read_b128 v[196:199], v143 offset:21504
	ds_read_b128 v[200:203], v143 offset:22528
	ds_read_b128 v[206:209], v143 offset:23552
	global_load_lds_dwordx4 v[140:141], off
	s_add_i32 m0, s55, 0x2000
	s_add_u32 s64, s28, 0x80000
	v_lshl_add_u64 v[210:211], s[28:29], 0, v[132:133]
	s_addc_u32 s65, s29, 0
	s_add_i32 s55, s62, s36
	global_load_lds_dwordx4 v[210:211], off
	v_lshl_add_u64 v[212:213], s[64:65], 0, v[204:205]
	s_mov_b32 m0, s55
	v_lshl_add_u64 v[214:215], s[30:31], 0, v[130:131]
	global_load_lds_dwordx4 v[212:213], off
	v_lshl_add_u64 v[212:213], s[64:65], 0, v[132:133]
	s_add_i32 m0, s55, 0x2000
	s_nop 0
	global_load_lds_dwordx4 v[212:213], off
	v_lshl_add_u64 v[212:213], s[30:31], 0, v[128:129]
	s_mov_b32 m0, s37
	s_nop 0
	global_load_lds_dwordx4 v[212:213], off
	s_mov_b32 m0, s38
	s_nop 0
	global_load_lds_dwordx4 v[214:215], off
	s_waitcnt vmcnt(8)
	s_waitcnt lgkmcnt(0)
	s_setprio 1
	s_barrier
; #define PG8_STAGE(bufoff, gbase, voff) do { _Pragma("unroll") for (int _i = 0; _i < 2; ++_i) \
;         __builtin_amdgcn_global_load_lds((const unsigned*)((const char*)(gbase) + (voff)[_i]), (PG8_LAS unsigned*)(lds + (bufoff) + ldsw + _i * 8192), 16, 0, 0); } while (0)
; #define PG8_LDA(dst, b, h) do { _Pragma("unroll") for (int m = 0; m < 4; ++m) _Pragma("unroll") for (int k = 0; k < 2; ++k) dst[m][k] = *(const PG8_LAS bf16x8*)(lds + PG8_SA(b, h) + aoff + m * 2048 + k * 1024); } while (0)
; #define PG8_LDB(dst, b, h) do { _Pragma("unroll") for (int n = 0; n < 2; ++n) _Pragma("unroll") for (int k = 0; k < 2; ++k) dst[n][k] = *(const PG8_LAS bf16x8*)(lds + PG8_SB(b, h) + boff + n * 2048 + k * 1024); } while (0)
; #define PG8_MMA(ai, bj, At, Bt) do { __builtin_amdgcn_s_setprio(1); _Pragma("unroll") for (int m = 0; m < 4; ++m) _Pragma("unroll") for (int n = 0; n < 2; ++n) _Pragma("unroll") for (int k = 0; k < 2; ++k) \
;         acc[ai][bj][m][n] = __builtin_amdgcn_mfma_f32_16x16x32_bf16(Bt[n][k], At[m][k], acc[ai][bj][m][n], 0, 0, 0); __builtin_amdgcn_s_setprio(0); } while (0)
; #define PG8_WAIT_V(n) asm volatile("s_waitcnt vmcnt(" #n ")" ::: "memory")
; #define PG8_WAIT_L(n) asm volatile("s_waitcnt lgkmcnt(" #n ")" ::: "memory")
; #define PG8_BAR __builtin_amdgcn_s_barrier()
; #define PG8_SCHED __builtin_amdgcn_sched_barrier(0)
; template <class Epi, class Sched, bool ALIGN_EPI = false, bool SP2 = false>
; __device__ __forceinline__ void gemm_phase(PG8_LAS unsigned char* lds, const Gemm g, const Sched& S, const Epi& E, const int tid) {
;     ...
;             PG8_WAIT_V(8); PG8_WAIT_L(0); PG8_BAR; PG8_MMA(1, 0, At, B0); PG8_MMA(1, 1, At, B1); PG8_BAR; PG8_SCHED;
;             PG8_LDB(B0, 1, 0); PG8_LDB(B1, 1, 1); PG8_SCHED; PG8_LDA(At, 1, 0); PG8_STAGE(PG8_SA(0, 1), a2 + hstep, voffA);
;             PG8_WAIT_V(8); PG8_WAIT_L(0); PG8_BAR; PG8_MMA(0, 0, At, B0); PG8_MMA(0, 1, At, B1); PG8_BAR; PG8_SCHED;
	v_mfma_f32_16x16x32_bf16 v[60:63], v[144:147], v[176:179], 0
	v_mfma_f32_16x16x32_bf16 v[56:59], v[152:155], v[176:179], 0
	v_mfma_f32_16x16x32_bf16 v[44:47], v[144:147], v[184:187], 0
	v_mfma_f32_16x16x32_bf16 v[40:43], v[152:155], v[184:187], 0
	v_mfma_f32_16x16x32_bf16 v[28:31], v[144:147], v[192:195], 0
	v_mfma_f32_16x16x32_bf16 v[24:27], v[152:155], v[192:195], 0
	v_mfma_f32_16x16x32_bf16 v[12:15], v[144:147], v[200:203], 0
	v_mfma_f32_16x16x32_bf16 v[8:11], v[152:155], v[200:203], 0
	v_mfma_f32_16x16x32_bf16 v[60:63], v[148:151], v[180:183], v[60:63]
	v_mfma_f32_16x16x32_bf16 v[56:59], v[156:159], v[180:183], v[56:59]
	v_mfma_f32_16x16x32_bf16 v[44:47], v[148:151], v[188:191], v[44:47]
	v_mfma_f32_16x16x32_bf16 v[40:43], v[156:159], v[188:191], v[40:43]
	v_mfma_f32_16x16x32_bf16 v[28:31], v[148:151], v[196:199], v[28:31]
	v_mfma_f32_16x16x32_bf16 v[24:27], v[156:159], v[196:199], v[24:27]
	v_mfma_f32_16x16x32_bf16 v[12:15], v[148:151], v[206:209], v[12:15]
	v_mfma_f32_16x16x32_bf16 v[8:11], v[156:159], v[206:209], v[8:11]
	s_setprio 0
	s_setprio 1
	v_mfma_f32_16x16x32_bf16 v[52:55], v[160:163], v[176:179], 0
	v_mfma_f32_16x16x32_bf16 v[48:51], v[168:171], v[176:179], 0
	v_mfma_f32_16x16x32_bf16 v[36:39], v[160:163], v[184:187], 0
	v_mfma_f32_16x16x32_bf16 v[32:35], v[168:171], v[184:187], 0
	v_mfma_f32_16x16x32_bf16 v[20:23], v[160:163], v[192:195], 0
	v_mfma_f32_16x16x32_bf16 v[16:19], v[168:171], v[192:195], 0
	v_mfma_f32_16x16x32_bf16 v[4:7], v[160:163], v[200:203], 0
	v_mfma_f32_16x16x32_bf16 v[0:3], v[168:171], v[200:203], 0
	v_mfma_f32_16x16x32_bf16 v[52:55], v[164:167], v[180:183], v[52:55]
	v_mfma_f32_16x16x32_bf16 v[48:51], v[172:175], v[180:183], v[48:51]
	v_mfma_f32_16x16x32_bf16 v[36:39], v[164:167], v[188:191], v[36:39]
	v_mfma_f32_16x16x32_bf16 v[32:35], v[172:175], v[188:191], v[32:35]
	v_mfma_f32_16x16x32_bf16 v[20:23], v[164:167], v[196:199], v[20:23]
	v_mfma_f32_16x16x32_bf16 v[16:19], v[172:175], v[196:199], v[16:19]
	v_mfma_f32_16x16x32_bf16 v[4:7], v[164:167], v[206:209], v[4:7]
	v_mfma_f32_16x16x32_bf16 v[0:3], v[172:175], v[206:209], v[0:3]
	s_barrier
	s_setprio 0
	s_add_i32 s55, 0, 0x18000
	v_add_u32_e32 v138, s55, v139
	s_add_i32 s62, 0, 0x1c000
	ds_read_b128 v[144:147], v138
	ds_read_b128 v[148:151], v138 offset:1024
	ds_read_b128 v[152:155], v138 offset:2048
	ds_read_b128 v[156:159], v138 offset:3072
	v_add_u32_e32 v138, s62, v139
	ds_read_b128 v[160:163], v138
	ds_read_b128 v[164:167], v138 offset:1024
	ds_read_b128 v[168:171], v138 offset:2048
	ds_read_b128 v[172:175], v138 offset:3072
	s_add_u32 s30, s30, 0x80000
	s_addc_u32 s31, s31, 0
	s_mov_b32 m0, s40
	v_lshl_add_u64 v[216:217], s[30:31], 0, v[128:129]
	ds_read_b128 v[176:179], v143 offset:32768
	ds_read_b128 v[180:183], v143 offset:33792
	ds_read_b128 v[184:187], v143 offset:34816
	ds_read_b128 v[188:191], v143 offset:35840
	ds_read_b128 v[192:195], v143 offset:36864
	ds_read_b128 v[196:199], v143 offset:37888
	ds_read_b128 v[200:203], v143 offset:38912
	ds_read_b128 v[206:209], v143 offset:39936
	global_load_lds_dwordx4 v[216:217], off
	v_lshl_add_u64 v[216:217], s[30:31], 0, v[130:131]
	s_mov_b32 m0, s42
	s_nop 0
	global_load_lds_dwordx4 v[216:217], off
	s_waitcnt vmcnt(8)
	s_waitcnt lgkmcnt(0)
	s_setprio 1
	s_barrier
	v_mfma_f32_16x16x32_bf16 v[124:127], v[144:147], v[176:179], v[124:127]
	v_mfma_f32_16x16x32_bf16 v[120:123], v[152:155], v[176:179], v[120:123]
	v_mfma_f32_16x16x32_bf16 v[108:111], v[144:147], v[184:187], v[108:111]
	v_mfma_f32_16x16x32_bf16 v[104:107], v[152:155], v[184:187], v[104:107]
	v_mfma_f32_16x16x32_bf16 v[92:95], v[144:147], v[192:195], v[92:95]
	v_mfma_f32_16x16x32_bf16 v[88:91], v[152:155], v[192:195], v[88:91]
	v_mfma_f32_16x16x32_bf16 v[76:79], v[144:147], v[200:203], v[76:79]
	v_mfma_f32_16x16x32_bf16 v[72:75], v[152:155], v[200:203], v[72:75]
	v_mfma_f32_16x16x32_bf16 v[124:127], v[148:151], v[180:183], v[124:127]
	v_mfma_f32_16x16x32_bf16 v[120:123], v[156:159], v[180:183], v[120:123]
	v_mfma_f32_16x16x32_bf16 v[108:111], v[148:151], v[188:191], v[108:111]
	v_mfma_f32_16x16x32_bf16 v[104:107], v[156:159], v[188:191], v[104:107]
	v_mfma_f32_16x16x32_bf16 v[92:95], v[148:151], v[196:199], v[92:95]
	v_mfma_f32_16x16x32_bf16 v[88:91], v[156:159], v[196:199], v[88:91]
	v_mfma_f32_16x16x32_bf16 v[76:79], v[148:151], v[206:209], v[76:79]
	v_mfma_f32_16x16x32_bf16 v[72:75], v[156:159], v[206:209], v[72:75]
	s_setprio 0
	s_setprio 1
	v_mfma_f32_16x16x32_bf16 v[116:119], v[160:163], v[176:179], v[116:119]
	v_mfma_f32_16x16x32_bf16 v[112:115], v[168:171], v[176:179], v[112:115]
	v_mfma_f32_16x16x32_bf16 v[100:103], v[160:163], v[184:187], v[100:103]
	v_mfma_f32_16x16x32_bf16 v[96:99], v[168:171], v[184:187], v[96:99]
	v_mfma_f32_16x16x32_bf16 v[84:87], v[160:163], v[192:195], v[84:87]
	v_mfma_f32_16x16x32_bf16 v[80:83], v[168:171], v[192:195], v[80:83]
	v_mfma_f32_16x16x32_bf16 v[68:71], v[160:163], v[200:203], v[68:71]
	v_mfma_f32_16x16x32_bf16 v[64:67], v[168:171], v[200:203], v[64:67]
	v_mfma_f32_16x16x32_bf16 v[116:119], v[164:167], v[180:183], v[116:119]
	v_mfma_f32_16x16x32_bf16 v[112:115], v[172:175], v[180:183], v[112:115]
	v_mfma_f32_16x16x32_bf16 v[100:103], v[164:167], v[188:191], v[100:103]
	v_mfma_f32_16x16x32_bf16 v[96:99], v[172:175], v[188:191], v[96:99]
	v_mfma_f32_16x16x32_bf16 v[84:87], v[164:167], v[196:199], v[84:87]
	v_mfma_f32_16x16x32_bf16 v[80:83], v[172:175], v[196:199], v[80:83]
	v_mfma_f32_16x16x32_bf16 v[68:71], v[164:167], v[206:209], v[68:71]
	v_mfma_f32_16x16x32_bf16 v[64:67], v[172:175], v[206:209], v[64:67]
	s_barrier
; #define PG8_STAGE(bufoff, gbase, voff) do { _Pragma("unroll") for (int _i = 0; _i < 2; ++_i) \
;         __builtin_amdgcn_global_load_lds((const unsigned*)((const char*)(gbase) + (voff)[_i]), (PG8_LAS unsigned*)(lds + (bufoff) + ldsw + _i * 8192), 16, 0, 0); } while (0)
; #define PG8_LDA(dst, b, h) do { _Pragma("unroll") for (int m = 0; m < 4; ++m) _Pragma("unroll") for (int k = 0; k < 2; ++k) dst[m][k] = *(const PG8_LAS bf16x8*)(lds + PG8_SA(b, h) + aoff + m * 2048 + k * 1024); } while (0)
; #define PG8_WAIT_V(n) asm volatile("s_waitcnt vmcnt(" #n ")" ::: "memory")
; #define PG8_WAIT_L(n) asm volatile("s_waitcnt lgkmcnt(" #n ")" ::: "memory")
; #define PG8_BAR __builtin_amdgcn_s_barrier()
; template <class Epi, class Sched, bool ALIGN_EPI = false, bool SP2 = false>
; __device__ __forceinline__ void gemm_phase(PG8_LAS unsigned char* lds, const Gemm g, const Sched& S, const Epi& E, const int tid) {
;     ...
;         for (int t = 0; t < nt; t += 2) {
;             const bool last = (t == nt - 2);
;             const char* a1 = cA + (size_t)(t + 1) * kstep;
;             const char* a2 = last ? nA : cA + (size_t)(t + 2) * kstep; const char* b2 = last ? nB : cB + (size_t)(t + 2) * kstep;
;             const char* a3 = a2 + kstep; const char* b3 = b2 + kstep;
;             if (last && has_next) S.a_ready(nxt);
;             if constexpr (SP2) {
;             PG8_LDB(B0, 0, 0); PG8_LDB(B1, 0, 1); PG8_SCHED; PG8_LDA(At, 0, 0); PG8_STAGE(PG8_SA(1, 1), a1 + hstep, voffA);
;             PG8_WAIT_V(8); PG8_WAIT_L(0); PG8_BAR; PG8_MMA(0, 0, At, B0); PG8_MMA(0, 1, At, B1); PG8_BAR; PG8_SCHED;
;             PG8_LDA(At, 0, 1); PG8_STAGE(PG8_SB(0, 0), b2, voffB); PG8_STAGE(PG8_SB(0, 1), b2 + hstep, voffB); PG8_STAGE(PG8_SA(0, 0), a2, voffA);
;             PG8_WAIT_V(8); PG8_WAIT_L(0); PG8_BAR; PG8_MMA(1, 0, At, B0); PG8_MMA(1, 1, At, B1); PG8_BAR; PG8_SCHED;
;             PG8_LDB(B0, 1, 0); PG8_LDB(B1, 1, 1); PG8_SCHED; PG8_LDA(At, 1, 0); PG8_STAGE(PG8_SA(0, 1), a2 + hstep, voffA);
;             PG8_WAIT_V(8); PG8_WAIT_L(0); PG8_BAR; PG8_MMA(0, 0, At, B0); PG8_MMA(0, 1, At, B1); PG8_BAR; PG8_SCHED;
;             PG8_LDA(At, 1, 1); PG8_STAGE(PG8_SB(1, 0), b3, voffB); PG8_STAGE(PG8_SB(1, 1), b3 + hstep, voffB); PG8_STAGE(PG8_SA(1, 0), a3, voffA);
;             PG8_WAIT_V(8); PG8_WAIT_L(0); PG8_BAR; PG8_MMA(1, 0, At, B0); PG8_MMA(1, 1, At, B1); PG8_BAR; PG8_SCHED;
	s_setprio 0
	s_add_i32 s30, s55, s36
	v_lshl_add_u64 v[140:141], v[140:141], 0, s[70:71]
	s_mov_b32 m0, s30
	ds_read_b128 v[176:179], v143 offset:49152
	ds_read_b128 v[180:183], v143 offset:50176
	ds_read_b128 v[184:187], v143 offset:51200
	ds_read_b128 v[188:191], v143 offset:52224
	ds_read_b128 v[192:195], v143 offset:53248
	ds_read_b128 v[196:199], v143 offset:54272
	ds_read_b128 v[200:203], v143 offset:55296
	ds_read_b128 v[206:209], v143 offset:56320
	global_load_lds_dwordx4 v[140:141], off
	s_add_i32 m0, s30, 0x2000
	s_add_u32 s28, s28, 0x80080
	v_lshl_add_u64 v[140:141], v[210:211], 0, s[70:71]
	s_addc_u32 s29, s29, 0
	s_add_i32 s30, s62, s36
	global_load_lds_dwordx4 v[140:141], off
	v_lshl_add_u64 v[140:141], s[28:29], 0, v[204:205]
	s_mov_b32 m0, s30
	s_nop 0
	global_load_lds_dwordx4 v[140:141], off
	v_lshl_add_u64 v[140:141], s[28:29], 0, v[132:133]
	s_add_i32 m0, s30, 0x2000
	s_nop 0
	global_load_lds_dwordx4 v[140:141], off
	v_lshl_add_u64 v[140:141], v[212:213], 0, s[70:71]
	s_mov_b32 m0, s46
	s_nop 0
	global_load_lds_dwordx4 v[140:141], off
	v_lshl_add_u64 v[140:141], v[214:215], 0, s[70:71]
	s_mov_b32 m0, s47
	s_nop 0
	global_load_lds_dwordx4 v[140:141], off
	s_waitcnt vmcnt(8)
	s_waitcnt lgkmcnt(0)
	s_setprio 1
	s_barrier
	v_mfma_f32_16x16x32_bf16 v[60:63], v[144:147], v[176:179], v[60:63]
	v_mfma_f32_16x16x32_bf16 v[56:59], v[152:155], v[176:179], v[56:59]
	v_mfma_f32_16x16x32_bf16 v[44:47], v[144:147], v[184:187], v[44:47]
	v_mfma_f32_16x16x32_bf16 v[40:43], v[152:155], v[184:187], v[40:43]
	v_mfma_f32_16x16x32_bf16 v[28:31], v[144:147], v[192:195], v[28:31]
	v_mfma_f32_16x16x32_bf16 v[24:27], v[152:155], v[192:195], v[24:27]
	v_mfma_f32_16x16x32_bf16 v[12:15], v[144:147], v[200:203], v[12:15]
	v_mfma_f32_16x16x32_bf16 v[8:11], v[152:155], v[200:203], v[8:11]
	v_mfma_f32_16x16x32_bf16 v[60:63], v[148:151], v[180:183], v[60:63]
	v_mfma_f32_16x16x32_bf16 v[56:59], v[156:159], v[180:183], v[56:59]
	v_mfma_f32_16x16x32_bf16 v[44:47], v[148:151], v[188:191], v[44:47]
	v_mfma_f32_16x16x32_bf16 v[40:43], v[156:159], v[188:191], v[40:43]
	v_mfma_f32_16x16x32_bf16 v[28:31], v[148:151], v[196:199], v[28:31]
	v_mfma_f32_16x16x32_bf16 v[24:27], v[156:159], v[196:199], v[24:27]
	v_mfma_f32_16x16x32_bf16 v[12:15], v[148:151], v[206:209], v[12:15]
	v_mfma_f32_16x16x32_bf16 v[8:11], v[156:159], v[206:209], v[8:11]
	s_setprio 0
	s_setprio 1
	v_mfma_f32_16x16x32_bf16 v[52:55], v[160:163], v[176:179], v[52:55]
	v_mfma_f32_16x16x32_bf16 v[48:51], v[168:171], v[176:179], v[48:51]
	v_mfma_f32_16x16x32_bf16 v[36:39], v[160:163], v[184:187], v[36:39]
	v_mfma_f32_16x16x32_bf16 v[32:35], v[168:171], v[184:187], v[32:35]
	v_mfma_f32_16x16x32_bf16 v[20:23], v[160:163], v[192:195], v[20:23]
	v_mfma_f32_16x16x32_bf16 v[16:19], v[168:171], v[192:195], v[16:19]
	v_mfma_f32_16x16x32_bf16 v[4:7], v[160:163], v[200:203], v[4:7]
	v_mfma_f32_16x16x32_bf16 v[0:3], v[168:171], v[200:203], v[0:3]
	v_mfma_f32_16x16x32_bf16 v[52:55], v[164:167], v[180:183], v[52:55]
	v_mfma_f32_16x16x32_bf16 v[48:51], v[172:175], v[180:183], v[48:51]
	v_mfma_f32_16x16x32_bf16 v[36:39], v[164:167], v[188:191], v[36:39]
	v_mfma_f32_16x16x32_bf16 v[32:35], v[172:175], v[188:191], v[32:35]
	v_mfma_f32_16x16x32_bf16 v[20:23], v[164:167], v[196:199], v[20:23]
	v_mfma_f32_16x16x32_bf16 v[16:19], v[172:175], v[196:199], v[16:19]
	v_mfma_f32_16x16x32_bf16 v[4:7], v[164:167], v[206:209], v[4:7]
	v_mfma_f32_16x16x32_bf16 v[0:3], v[172:175], v[206:209], v[0:3]
	s_barrier
	s_setprio 0
	s_add_i32 s54, s54, 2
	s_add_u32 s26, s26, 0x100
	s_addc_u32 s27, s27, 0
	s_add_u32 s52, s52, 0x100
	s_addc_u32 s53, s53, 0
.LBB0_1088:
	s_add_u32 s28, s26, 0xfff80080
	s_addc_u32 s29, s27, -1
	s_add_i32 s55, 0, 0x10000
	s_cmp_eq_u32 s54, 28
	s_cselect_b32 s31, s19, s29
	s_cselect_b32 s30, s50, s28
	v_add_u32_e32 v138, s55, v139
	s_cselect_b32 s29, s17, s53
	s_cselect_b32 s28, s51, s52
	s_add_i32 s62, 0, 0x14000
	ds_read_b128 v[144:147], v138
	ds_read_b128 v[148:151], v138 offset:1024
	ds_read_b128 v[152:155], v138 offset:2048
	ds_read_b128 v[156:159], v138 offset:3072
	v_add_u32_e32 v138, s62, v139
	ds_read_b128 v[160:163], v138
	ds_read_b128 v[164:167], v138 offset:1024
	ds_read_b128 v[168:171], v138 offset:2048
	ds_read_b128 v[172:175], v138 offset:3072
	v_lshl_add_u64 v[140:141], s[26:27], 0, v[134:135]
	s_add_i32 m0, s37, 0xc000
	ds_read_b128 v[176:179], v143
	ds_read_b128 v[180:183], v143 offset:1024
	ds_read_b128 v[184:187], v143 offset:2048
	ds_read_b128 v[188:191], v143 offset:3072
	ds_read_b128 v[192:195], v143 offset:4096
	ds_read_b128 v[196:199], v143 offset:5120
	ds_read_b128 v[200:203], v143 offset:6144
	ds_read_b128 v[206:209], v143 offset:7168
	global_load_lds_dwordx4 v[140:141], off
	v_lshl_add_u64 v[140:141], s[26:27], 0, v[136:137]
	s_add_i32 m0, s37, 0xe000
	s_nop 0
	global_load_lds_dwordx4 v[140:141], off
	s_waitcnt vmcnt(8)
	s_waitcnt lgkmcnt(0)
	s_setprio 1
	s_barrier
; #define PG8_STAGE(bufoff, gbase, voff) do { _Pragma("unroll") for (int _i = 0; _i < 2; ++_i) \
;         __builtin_amdgcn_global_load_lds((const unsigned*)((const char*)(gbase) + (voff)[_i]), (PG8_LAS unsigned*)(lds + (bufoff) + ldsw + _i * 8192), 16, 0, 0); } while (0)
; #define PG8_LDA(dst, b, h) do { _Pragma("unroll") for (int m = 0; m < 4; ++m) _Pragma("unroll") for (int k = 0; k < 2; ++k) dst[m][k] = *(const PG8_LAS bf16x8*)(lds + PG8_SA(b, h) + aoff + m * 2048 + k * 1024); } while (0)
; #define PG8_LDB(dst, b, h) do { _Pragma("unroll") for (int n = 0; n < 2; ++n) _Pragma("unroll") for (int k = 0; k < 2; ++k) dst[n][k] = *(const PG8_LAS bf16x8*)(lds + PG8_SB(b, h) + boff + n * 2048 + k * 1024); } while (0)
; #define PG8_MMA(ai, bj, At, Bt) do { __builtin_amdgcn_s_setprio(1); _Pragma("unroll") for (int m = 0; m < 4; ++m) _Pragma("unroll") for (int n = 0; n < 2; ++n) _Pragma("unroll") for (int k = 0; k < 2; ++k) \
;         acc[ai][bj][m][n] = __builtin_amdgcn_mfma_f32_16x16x32_bf16(Bt[n][k], At[m][k], acc[ai][bj][m][n], 0, 0, 0); __builtin_amdgcn_s_setprio(0); } while (0)
; #define PG8_WAIT_V(n) asm volatile("s_waitcnt vmcnt(" #n ")" ::: "memory")
; #define PG8_WAIT_L(n) asm volatile("s_waitcnt lgkmcnt(" #n ")" ::: "memory")
; #define PG8_BAR __builtin_amdgcn_s_barrier()
; #define PG8_SCHED __builtin_amdgcn_sched_barrier(0)
; template <class Epi, class Sched, bool ALIGN_EPI = false, bool SP2 = false>
; __device__ __forceinline__ void gemm_phase(PG8_LAS unsigned char* lds, const Gemm g, const Sched& S, const Epi& E, const int tid) {
;     ...
;             PG8_WAIT_V(8); PG8_WAIT_L(0); PG8_BAR; PG8_MMA(0, 0, At, B0); PG8_MMA(0, 1, At, B1); PG8_BAR; PG8_SCHED;
;             PG8_LDA(At, 0, 1); PG8_STAGE(PG8_SB(0, 0), b2, voffB); PG8_STAGE(PG8_SB(0, 1), b2 + hstep, voffB); PG8_STAGE(PG8_SA(0, 0), a2, voffA);
;             PG8_WAIT_V(8); PG8_WAIT_L(0); PG8_BAR; PG8_MMA(1, 0, At, B0); PG8_MMA(1, 1, At, B1); PG8_BAR; PG8_SCHED;
;             PG8_LDB(B0, 1, 0); PG8_LDB(B1, 1, 1); PG8_SCHED; PG8_LDA(At, 1, 0); PG8_STAGE(PG8_SA(0, 1), a2 + hstep, voffA);
;             PG8_WAIT_V(8); PG8_WAIT_L(0); PG8_BAR; PG8_MMA(0, 0, At, B0); PG8_MMA(0, 1, At, B1); PG8_BAR; PG8_SCHED;
	v_mfma_f32_16x16x32_bf16 v[124:127], v[144:147], v[176:179], v[124:127]
	v_mfma_f32_16x16x32_bf16 v[120:123], v[152:155], v[176:179], v[120:123]
	v_mfma_f32_16x16x32_bf16 v[108:111], v[144:147], v[184:187], v[108:111]
	v_mfma_f32_16x16x32_bf16 v[104:107], v[152:155], v[184:187], v[104:107]
	v_mfma_f32_16x16x32_bf16 v[92:95], v[144:147], v[192:195], v[92:95]
	v_mfma_f32_16x16x32_bf16 v[88:91], v[152:155], v[192:195], v[88:91]
	v_mfma_f32_16x16x32_bf16 v[76:79], v[144:147], v[200:203], v[76:79]
	v_mfma_f32_16x16x32_bf16 v[72:75], v[152:155], v[200:203], v[72:75]
	v_mfma_f32_16x16x32_bf16 v[124:127], v[148:151], v[180:183], v[124:127]
	v_mfma_f32_16x16x32_bf16 v[120:123], v[156:159], v[180:183], v[120:123]
	v_mfma_f32_16x16x32_bf16 v[108:111], v[148:151], v[188:191], v[108:111]
	v_mfma_f32_16x16x32_bf16 v[104:107], v[156:159], v[188:191], v[104:107]
	v_mfma_f32_16x16x32_bf16 v[92:95], v[148:151], v[196:199], v[92:95]
	v_mfma_f32_16x16x32_bf16 v[88:91], v[156:159], v[196:199], v[88:91]
	v_mfma_f32_16x16x32_bf16 v[76:79], v[148:151], v[206:209], v[76:79]
	v_mfma_f32_16x16x32_bf16 v[72:75], v[156:159], v[206:209], v[72:75]
	s_setprio 0
	s_setprio 1
	v_mfma_f32_16x16x32_bf16 v[116:119], v[160:163], v[176:179], v[116:119]
	v_mfma_f32_16x16x32_bf16 v[112:115], v[168:171], v[176:179], v[112:115]
	v_mfma_f32_16x16x32_bf16 v[100:103], v[160:163], v[184:187], v[100:103]
	v_mfma_f32_16x16x32_bf16 v[96:99], v[168:171], v[184:187], v[96:99]
	v_mfma_f32_16x16x32_bf16 v[84:87], v[160:163], v[192:195], v[84:87]
	v_mfma_f32_16x16x32_bf16 v[80:83], v[168:171], v[192:195], v[80:83]
	v_mfma_f32_16x16x32_bf16 v[68:71], v[160:163], v[200:203], v[68:71]
	v_mfma_f32_16x16x32_bf16 v[64:67], v[168:171], v[200:203], v[64:67]
	v_mfma_f32_16x16x32_bf16 v[116:119], v[164:167], v[180:183], v[116:119]
	v_mfma_f32_16x16x32_bf16 v[112:115], v[172:175], v[180:183], v[112:115]
	v_mfma_f32_16x16x32_bf16 v[100:103], v[164:167], v[188:191], v[100:103]
	v_mfma_f32_16x16x32_bf16 v[96:99], v[172:175], v[188:191], v[96:99]
	v_mfma_f32_16x16x32_bf16 v[84:87], v[164:167], v[196:199], v[84:87]
	v_mfma_f32_16x16x32_bf16 v[80:83], v[172:175], v[196:199], v[80:83]
	v_mfma_f32_16x16x32_bf16 v[68:71], v[164:167], v[206:209], v[68:71]
	v_mfma_f32_16x16x32_bf16 v[64:67], v[172:175], v[206:209], v[64:67]
	s_barrier
	s_setprio 0
	s_add_i32 s55, s55, s36
	v_lshl_add_u64 v[140:141], s[28:29], 0, v[204:205]
	s_mov_b32 m0, s55
	ds_read_b128 v[176:179], v143 offset:16384
	ds_read_b128 v[180:183], v143 offset:17408
	ds_read_b128 v[184:187], v143 offset:18432
	ds_read_b128 v[188:191], v143 offset:19456
	ds_read_b128 v[192:195], v143 offset:20480
	ds_read_b128 v[196:199], v143 offset:21504
	ds_read_b128 v[200:203], v143 offset:22528
	ds_read_b128 v[206:209], v143 offset:23552
	global_load_lds_dwordx4 v[140:141], off
	s_add_i32 m0, s55, 0x2000
	s_add_u32 s64, s28, 0x80000
	v_lshl_add_u64 v[210:211], s[28:29], 0, v[132:133]
	s_addc_u32 s65, s29, 0
	s_add_i32 s55, s62, s36
	global_load_lds_dwordx4 v[210:211], off
	v_lshl_add_u64 v[212:213], s[64:65], 0, v[204:205]
	s_mov_b32 m0, s55
	v_lshl_add_u64 v[214:215], s[30:31], 0, v[130:131]
	global_load_lds_dwordx4 v[212:213], off
	v_lshl_add_u64 v[212:213], s[64:65], 0, v[132:133]
	s_add_i32 m0, s55, 0x2000
	s_nop 0
	global_load_lds_dwordx4 v[212:213], off
	v_lshl_add_u64 v[212:213], s[30:31], 0, v[128:129]
	s_mov_b32 m0, s37
	s_nop 0
	global_load_lds_dwordx4 v[212:213], off
	s_mov_b32 m0, s38
	s_nop 0
	global_load_lds_dwordx4 v[214:215], off
	s_waitcnt vmcnt(8)
	s_waitcnt lgkmcnt(0)
	s_setprio 1
	s_barrier
	v_mfma_f32_16x16x32_bf16 v[60:63], v[144:147], v[176:179], v[60:63]
	v_mfma_f32_16x16x32_bf16 v[56:59], v[152:155], v[176:179], v[56:59]
	v_mfma_f32_16x16x32_bf16 v[44:47], v[144:147], v[184:187], v[44:47]
	v_mfma_f32_16x16x32_bf16 v[40:43], v[152:155], v[184:187], v[40:43]
	v_mfma_f32_16x16x32_bf16 v[28:31], v[144:147], v[192:195], v[28:31]
	v_mfma_f32_16x16x32_bf16 v[24:27], v[152:155], v[192:195], v[24:27]
	v_mfma_f32_16x16x32_bf16 v[12:15], v[144:147], v[200:203], v[12:15]
	v_mfma_f32_16x16x32_bf16 v[8:11], v[152:155], v[200:203], v[8:11]
	v_mfma_f32_16x16x32_bf16 v[60:63], v[148:151], v[180:183], v[60:63]
	v_mfma_f32_16x16x32_bf16 v[56:59], v[156:159], v[180:183], v[56:59]
	v_mfma_f32_16x16x32_bf16 v[44:47], v[148:151], v[188:191], v[44:47]
	v_mfma_f32_16x16x32_bf16 v[40:43], v[156:159], v[188:191], v[40:43]
	v_mfma_f32_16x16x32_bf16 v[28:31], v[148:151], v[196:199], v[28:31]
	v_mfma_f32_16x16x32_bf16 v[24:27], v[156:159], v[196:199], v[24:27]
	v_mfma_f32_16x16x32_bf16 v[12:15], v[148:151], v[206:209], v[12:15]
	v_mfma_f32_16x16x32_bf16 v[8:11], v[156:159], v[206:209], v[8:11]
	s_setprio 0
	s_setprio 1
	v_mfma_f32_16x16x32_bf16 v[52:55], v[160:163], v[176:179], v[52:55]
	v_mfma_f32_16x16x32_bf16 v[48:51], v[168:171], v[176:179], v[48:51]
	v_mfma_f32_16x16x32_bf16 v[36:39], v[160:163], v[184:187], v[36:39]
	v_mfma_f32_16x16x32_bf16 v[32:35], v[168:171], v[184:187], v[32:35]
	v_mfma_f32_16x16x32_bf16 v[20:23], v[160:163], v[192:195], v[20:23]
	v_mfma_f32_16x16x32_bf16 v[16:19], v[168:171], v[192:195], v[16:19]
	v_mfma_f32_16x16x32_bf16 v[4:7], v[160:163], v[200:203], v[4:7]
	v_mfma_f32_16x16x32_bf16 v[0:3], v[168:171], v[200:203], v[0:3]
	v_mfma_f32_16x16x32_bf16 v[52:55], v[164:167], v[180:183], v[52:55]
	v_mfma_f32_16x16x32_bf16 v[48:51], v[172:175], v[180:183], v[48:51]
	v_mfma_f32_16x16x32_bf16 v[36:39], v[164:167], v[188:191], v[36:39]
	v_mfma_f32_16x16x32_bf16 v[32:35], v[172:175], v[188:191], v[32:35]
	v_mfma_f32_16x16x32_bf16 v[20:23], v[164:167], v[196:199], v[20:23]
	v_mfma_f32_16x16x32_bf16 v[16:19], v[172:175], v[196:199], v[16:19]
	v_mfma_f32_16x16x32_bf16 v[4:7], v[164:167], v[206:209], v[4:7]
	v_mfma_f32_16x16x32_bf16 v[0:3], v[172:175], v[206:209], v[0:3]
	s_barrier
; #define PG8_STAGE(bufoff, gbase, voff) do { _Pragma("unroll") for (int _i = 0; _i < 2; ++_i) \
;         __builtin_amdgcn_global_load_lds((const unsigned*)((const char*)(gbase) + (voff)[_i]), (PG8_LAS unsigned*)(lds + (bufoff) + ldsw + _i * 8192), 16, 0, 0); } while (0)
; #define PG8_LDA(dst, b, h) do { _Pragma("unroll") for (int m = 0; m < 4; ++m) _Pragma("unroll") for (int k = 0; k < 2; ++k) dst[m][k] = *(const PG8_LAS bf16x8*)(lds + PG8_SA(b, h) + aoff + m * 2048 + k * 1024); } while (0)
; #define PG8_LDB(dst, b, h) do { _Pragma("unroll") for (int n = 0; n < 2; ++n) _Pragma("unroll") for (int k = 0; k < 2; ++k) dst[n][k] = *(const PG8_LAS bf16x8*)(lds + PG8_SB(b, h) + boff + n * 2048 + k * 1024); } while (0)
; #define PG8_MMA(ai, bj, At, Bt) do { __builtin_amdgcn_s_setprio(1); _Pragma("unroll") for (int m = 0; m < 4; ++m) _Pragma("unroll") for (int n = 0; n < 2; ++n) _Pragma("unroll") for (int k = 0; k < 2; ++k) \
;         acc[ai][bj][m][n] = __builtin_amdgcn_mfma_f32_16x16x32_bf16(Bt[n][k], At[m][k], acc[ai][bj][m][n], 0, 0, 0); __builtin_amdgcn_s_setprio(0); } while (0)
; #define PG8_WAIT_V(n) asm volatile("s_waitcnt vmcnt(" #n ")" ::: "memory")
; #define PG8_WAIT_L(n) asm volatile("s_waitcnt lgkmcnt(" #n ")" ::: "memory")
; #define PG8_BAR __builtin_amdgcn_s_barrier()
; #define PG8_SCHED __builtin_amdgcn_sched_barrier(0)
; template <class Epi, class Sched, bool ALIGN_EPI = false, bool SP2 = false>
; __device__ __forceinline__ void gemm_phase(PG8_LAS unsigned char* lds, const Gemm g, const Sched& S, const Epi& E, const int tid) {
;     ...
;             PG8_LDB(B0, 1, 0); PG8_LDB(B1, 1, 1); PG8_SCHED; PG8_LDA(At, 1, 0); PG8_STAGE(PG8_SA(0, 1), a2 + hstep, voffA);
;             PG8_WAIT_V(8); PG8_WAIT_L(0); PG8_BAR; PG8_MMA(0, 0, At, B0); PG8_MMA(0, 1, At, B1); PG8_BAR; PG8_SCHED;
;             PG8_LDA(At, 1, 1); PG8_STAGE(PG8_SB(1, 0), b3, voffB); PG8_STAGE(PG8_SB(1, 1), b3 + hstep, voffB); PG8_STAGE(PG8_SA(1, 0), a3, voffA);
;             PG8_WAIT_V(8); PG8_WAIT_L(0); PG8_BAR; PG8_MMA(1, 0, At, B0); PG8_MMA(1, 1, At, B1); PG8_BAR; PG8_SCHED;
	s_setprio 0
	s_add_i32 s55, 0, 0x18000
	v_add_u32_e32 v138, s55, v139
	s_add_i32 s62, 0, 0x1c000
	ds_read_b128 v[144:147], v138
	ds_read_b128 v[148:151], v138 offset:1024
	ds_read_b128 v[152:155], v138 offset:2048
	ds_read_b128 v[156:159], v138 offset:3072
	v_add_u32_e32 v138, s62, v139
	ds_read_b128 v[160:163], v138
	ds_read_b128 v[164:167], v138 offset:1024
	ds_read_b128 v[168:171], v138 offset:2048
	ds_read_b128 v[172:175], v138 offset:3072
	s_add_u32 s30, s30, 0x80000
	s_addc_u32 s31, s31, 0
	s_mov_b32 m0, s40
	v_lshl_add_u64 v[216:217], s[30:31], 0, v[128:129]
	ds_read_b128 v[176:179], v143 offset:32768
	ds_read_b128 v[180:183], v143 offset:33792
	ds_read_b128 v[184:187], v143 offset:34816
	ds_read_b128 v[188:191], v143 offset:35840
	ds_read_b128 v[192:195], v143 offset:36864
	ds_read_b128 v[196:199], v143 offset:37888
	ds_read_b128 v[200:203], v143 offset:38912
	ds_read_b128 v[206:209], v143 offset:39936
	global_load_lds_dwordx4 v[216:217], off
	v_lshl_add_u64 v[216:217], s[30:31], 0, v[130:131]
	s_mov_b32 m0, s42
	s_nop 0
	global_load_lds_dwordx4 v[216:217], off
	s_waitcnt vmcnt(8)
	s_waitcnt lgkmcnt(0)
	s_setprio 1
	s_barrier
	v_mfma_f32_16x16x32_bf16 v[124:127], v[144:147], v[176:179], v[124:127]
	v_mfma_f32_16x16x32_bf16 v[120:123], v[152:155], v[176:179], v[120:123]
	v_mfma_f32_16x16x32_bf16 v[108:111], v[144:147], v[184:187], v[108:111]
	v_mfma_f32_16x16x32_bf16 v[104:107], v[152:155], v[184:187], v[104:107]
	v_mfma_f32_16x16x32_bf16 v[92:95], v[144:147], v[192:195], v[92:95]
	v_mfma_f32_16x16x32_bf16 v[88:91], v[152:155], v[192:195], v[88:91]
	v_mfma_f32_16x16x32_bf16 v[76:79], v[144:147], v[200:203], v[76:79]
	v_mfma_f32_16x16x32_bf16 v[72:75], v[152:155], v[200:203], v[72:75]
	v_mfma_f32_16x16x32_bf16 v[124:127], v[148:151], v[180:183], v[124:127]
	v_mfma_f32_16x16x32_bf16 v[120:123], v[156:159], v[180:183], v[120:123]
	v_mfma_f32_16x16x32_bf16 v[108:111], v[148:151], v[188:191], v[108:111]
	v_mfma_f32_16x16x32_bf16 v[104:107], v[156:159], v[188:191], v[104:107]
	v_mfma_f32_16x16x32_bf16 v[92:95], v[148:151], v[196:199], v[92:95]
	v_mfma_f32_16x16x32_bf16 v[88:91], v[156:159], v[196:199], v[88:91]
	v_mfma_f32_16x16x32_bf16 v[76:79], v[148:151], v[206:209], v[76:79]
	v_mfma_f32_16x16x32_bf16 v[72:75], v[156:159], v[206:209], v[72:75]
	s_setprio 0
	s_setprio 1
	v_mfma_f32_16x16x32_bf16 v[116:119], v[160:163], v[176:179], v[116:119]
	v_mfma_f32_16x16x32_bf16 v[112:115], v[168:171], v[176:179], v[112:115]
	v_mfma_f32_16x16x32_bf16 v[100:103], v[160:163], v[184:187], v[100:103]
	v_mfma_f32_16x16x32_bf16 v[96:99], v[168:171], v[184:187], v[96:99]
	v_mfma_f32_16x16x32_bf16 v[84:87], v[160:163], v[192:195], v[84:87]
	v_mfma_f32_16x16x32_bf16 v[80:83], v[168:171], v[192:195], v[80:83]
	v_mfma_f32_16x16x32_bf16 v[68:71], v[160:163], v[200:203], v[68:71]
	v_mfma_f32_16x16x32_bf16 v[64:67], v[168:171], v[200:203], v[64:67]
	v_mfma_f32_16x16x32_bf16 v[116:119], v[164:167], v[180:183], v[116:119]
	v_mfma_f32_16x16x32_bf16 v[112:115], v[172:175], v[180:183], v[112:115]
	v_mfma_f32_16x16x32_bf16 v[100:103], v[164:167], v[188:191], v[100:103]
	v_mfma_f32_16x16x32_bf16 v[96:99], v[172:175], v[188:191], v[96:99]
	v_mfma_f32_16x16x32_bf16 v[84:87], v[164:167], v[196:199], v[84:87]
	v_mfma_f32_16x16x32_bf16 v[80:83], v[172:175], v[196:199], v[80:83]
	v_mfma_f32_16x16x32_bf16 v[68:71], v[164:167], v[206:209], v[68:71]
	v_mfma_f32_16x16x32_bf16 v[64:67], v[172:175], v[206:209], v[64:67]
	s_barrier
; #define PG8_STAGE(bufoff, gbase, voff) do { _Pragma("unroll") for (int _i = 0; _i < 2; ++_i) \
;         __builtin_amdgcn_global_load_lds((const unsigned*)((const char*)(gbase) + (voff)[_i]), (PG8_LAS unsigned*)(lds + (bufoff) + ldsw + _i * 8192), 16, 0, 0); } while (0)
; #define PG8_LDA(dst, b, h) do { _Pragma("unroll") for (int m = 0; m < 4; ++m) _Pragma("unroll") for (int k = 0; k < 2; ++k) dst[m][k] = *(const PG8_LAS bf16x8*)(lds + PG8_SA(b, h) + aoff + m * 2048 + k * 1024); } while (0)
; #define PG8_BAR __builtin_amdgcn_s_barrier()
; template <class Epi, class Sched, bool ALIGN_EPI = false, bool SP2 = false>
; __device__ __forceinline__ void gemm_phase(PG8_LAS unsigned char* lds, const Gemm g, const Sched& S, const Epi& E, const int tid) {
;     ...
;             PG8_LDA(At, 1, 1); PG8_STAGE(PG8_SB(1, 0), b3, voffB); PG8_STAGE(PG8_SB(1, 1), b3 + hstep, voffB); PG8_STAGE(PG8_SA(1, 0), a3, voffA);
;             PG8_WAIT_V(8); PG8_WAIT_L(0); PG8_BAR; PG8_MMA(1, 0, At, B0); PG8_MMA(1, 1, At, B1); PG8_BAR; PG8_SCHED;
;             } else {
;             PG8_LDB(B0, 0, 0); PG8_SCHED; PG8_LDA(At, 0, 0); PG8_STAGE(PG8_SA(1, 1), a1 + hstep, voffA);
;             PG8_WAIT_L(8); PG8_BAR; PG8_WAIT_L(0); PG8_MMA(0, 0, At, B0); PG8_BAR; PG8_SCHED;
;             PG8_LDB(B1, 0, 1); PG8_STAGE(PG8_SB(0, 0), b2, voffB);
;             PG8_BAR; PG8_WAIT_L(0); PG8_MMA(0, 1, At, B1); PG8_BAR;
;             PG8_LDA(At, 0, 1); PG8_STAGE(PG8_SA(0, 0), a2, voffA);
;             PG8_BAR; PG8_WAIT_L(0); PG8_MMA(1, 0, At, B0); PG8_BAR; PG8_SCHED;
;             PG8_STAGE(PG8_SB(0, 1), b2 + hstep, voffB);
;             PG8_WAIT_V(6); PG8_BAR; PG8_MMA(1, 1, At, B1); PG8_BAR;
;             PG8_LDB(B0, 1, 0); PG8_SCHED; PG8_LDA(At, 1, 0); PG8_STAGE(PG8_SA(0, 1), a2 + hstep, voffA);
;             PG8_WAIT_L(8); PG8_BAR; PG8_WAIT_L(0); PG8_MMA(0, 0, At, B0); PG8_BAR; PG8_SCHED;
;             PG8_LDB(B1, 1, 1); PG8_STAGE(PG8_SB(1, 0), b3, voffB);
;             PG8_BAR; PG8_WAIT_L(0); PG8_MMA(0, 1, At, B1); PG8_BAR;
;             PG8_LDA(At, 1, 1); PG8_STAGE(PG8_SA(1, 0), a3, voffA);
;             PG8_BAR; PG8_WAIT_L(0); PG8_MMA(1, 0, At, B0); PG8_BAR; PG8_SCHED;
;             PG8_STAGE(PG8_SB(1, 1), b3 + hstep, voffB);
;             PG8_WAIT_V(6); PG8_BAR; PG8_MMA(1, 1, At, B1); PG8_BAR;
;             }
;         }
;         if constexpr (ALIGN_EPI) { if (wr == 0) PG8_BAR; }
	s_setprio 0
	s_add_i32 s30, s55, s36
	v_lshl_add_u64 v[140:141], v[140:141], 0, s[70:71]
	s_mov_b32 m0, s30
	ds_read_b128 v[176:179], v143 offset:49152
	ds_read_b128 v[180:183], v143 offset:50176
	ds_read_b128 v[184:187], v143 offset:51200
	ds_read_b128 v[188:191], v143 offset:52224
	ds_read_b128 v[192:195], v143 offset:53248
	ds_read_b128 v[196:199], v143 offset:54272
	ds_read_b128 v[200:203], v143 offset:55296
	ds_read_b128 v[206:209], v143 offset:56320
	global_load_lds_dwordx4 v[140:141], off
	s_add_i32 m0, s30, 0x2000
	s_add_u32 s28, s28, 0x80080
	v_lshl_add_u64 v[140:141], v[210:211], 0, s[70:71]
	s_addc_u32 s29, s29, 0
	s_add_i32 s30, s62, s36
	global_load_lds_dwordx4 v[140:141], off
	v_lshl_add_u64 v[140:141], s[28:29], 0, v[204:205]
	s_mov_b32 m0, s30
	s_nop 0
	global_load_lds_dwordx4 v[140:141], off
	v_lshl_add_u64 v[140:141], s[28:29], 0, v[132:133]
	s_add_i32 m0, s30, 0x2000
	s_nop 0
	global_load_lds_dwordx4 v[140:141], off
	v_lshl_add_u64 v[140:141], v[212:213], 0, s[70:71]
	s_mov_b32 m0, s46
	s_nop 0
	global_load_lds_dwordx4 v[140:141], off
	v_lshl_add_u64 v[140:141], v[214:215], 0, s[70:71]
	s_mov_b32 m0, s47
	s_nop 0
	global_load_lds_dwordx4 v[140:141], off
	s_waitcnt vmcnt(8)
	s_waitcnt lgkmcnt(0)
	s_setprio 1
	s_barrier
	v_mfma_f32_16x16x32_bf16 v[60:63], v[144:147], v[176:179], v[60:63]
	v_mfma_f32_16x16x32_bf16 v[56:59], v[152:155], v[176:179], v[56:59]
	v_mfma_f32_16x16x32_bf16 v[44:47], v[144:147], v[184:187], v[44:47]
	v_mfma_f32_16x16x32_bf16 v[40:43], v[152:155], v[184:187], v[40:43]
	v_mfma_f32_16x16x32_bf16 v[28:31], v[144:147], v[192:195], v[28:31]
	v_mfma_f32_16x16x32_bf16 v[24:27], v[152:155], v[192:195], v[24:27]
	v_mfma_f32_16x16x32_bf16 v[12:15], v[144:147], v[200:203], v[12:15]
	v_mfma_f32_16x16x32_bf16 v[8:11], v[152:155], v[200:203], v[8:11]
	v_mfma_f32_16x16x32_bf16 v[60:63], v[148:151], v[180:183], v[60:63]
	v_mfma_f32_16x16x32_bf16 v[56:59], v[156:159], v[180:183], v[56:59]
	v_mfma_f32_16x16x32_bf16 v[44:47], v[148:151], v[188:191], v[44:47]
	v_mfma_f32_16x16x32_bf16 v[40:43], v[156:159], v[188:191], v[40:43]
	v_mfma_f32_16x16x32_bf16 v[28:31], v[148:151], v[196:199], v[28:31]
	v_mfma_f32_16x16x32_bf16 v[24:27], v[156:159], v[196:199], v[24:27]
	v_mfma_f32_16x16x32_bf16 v[12:15], v[148:151], v[206:209], v[12:15]
	v_mfma_f32_16x16x32_bf16 v[8:11], v[156:159], v[206:209], v[8:11]
	s_setprio 0
	s_setprio 1
	v_mfma_f32_16x16x32_bf16 v[52:55], v[160:163], v[176:179], v[52:55]
	v_mfma_f32_16x16x32_bf16 v[48:51], v[168:171], v[176:179], v[48:51]
	v_mfma_f32_16x16x32_bf16 v[36:39], v[160:163], v[184:187], v[36:39]
	v_mfma_f32_16x16x32_bf16 v[32:35], v[168:171], v[184:187], v[32:35]
	v_mfma_f32_16x16x32_bf16 v[20:23], v[160:163], v[192:195], v[20:23]
	v_mfma_f32_16x16x32_bf16 v[16:19], v[168:171], v[192:195], v[16:19]
	v_mfma_f32_16x16x32_bf16 v[4:7], v[160:163], v[200:203], v[4:7]
	v_mfma_f32_16x16x32_bf16 v[0:3], v[168:171], v[200:203], v[0:3]
	v_mfma_f32_16x16x32_bf16 v[52:55], v[164:167], v[180:183], v[52:55]
	v_mfma_f32_16x16x32_bf16 v[48:51], v[172:175], v[180:183], v[48:51]
	v_mfma_f32_16x16x32_bf16 v[36:39], v[164:167], v[188:191], v[36:39]
	v_mfma_f32_16x16x32_bf16 v[32:35], v[172:175], v[188:191], v[32:35]
	v_mfma_f32_16x16x32_bf16 v[20:23], v[164:167], v[196:199], v[20:23]
	v_mfma_f32_16x16x32_bf16 v[16:19], v[172:175], v[196:199], v[16:19]
	v_mfma_f32_16x16x32_bf16 v[4:7], v[164:167], v[206:209], v[4:7]
	v_mfma_f32_16x16x32_bf16 v[0:3], v[172:175], v[206:209], v[0:3]
	s_barrier
	s_setprio 0
	s_add_i32 s54, s54, 2
	s_add_u32 s26, s26, 0x100
	s_addc_u32 s27, s27, 0
	s_add_u32 s52, s52, 0x100
	s_addc_u32 s53, s53, 0
	s_cmp_gt_u32 s54, 29
	s_cbranch_scc0 .LBB0_1088
	s_and_b64 vcc, exec, s[14:15]
	s_cbranch_vccz .LBB0_1091
	s_barrier

; #define PG8_STAGE(bufoff, gbase, voff) do { _Pragma("unroll") for (int _i = 0; _i < 2; ++_i) \
;         __builtin_amdgcn_global_load_lds((const unsigned*)((const char*)(gbase) + (voff)[_i]), (PG8_LAS unsigned*)(lds + (bufoff) + ldsw + _i * 8192), 16, 0, 0); } while (0)
; #define PG8_LDA(dst, b, h) do { _Pragma("unroll") for (int m = 0; m < 4; ++m) _Pragma("unroll") for (int k = 0; k < 2; ++k) dst[m][k] = *(const PG8_LAS bf16x8*)(lds + PG8_SA(b, h) + aoff + m * 2048 + k * 1024); } while (0)
; #define PG8_LDB(dst, b, h) do { _Pragma("unroll") for (int n = 0; n < 2; ++n) _Pragma("unroll") for (int k = 0; k < 2; ++k) dst[n][k] = *(const PG8_LAS bf16x8*)(lds + PG8_SB(b, h) + boff + n * 2048 + k * 1024); } while (0)
; #define PG8_WAIT_V(n) asm volatile("s_waitcnt vmcnt(" #n ")" ::: "memory")
; #define PG8_WAIT_L(n) asm volatile("s_waitcnt lgkmcnt(" #n ")" ::: "memory")
; #define PG8_BAR __builtin_amdgcn_s_barrier()
; #define PG8_SCHED __builtin_amdgcn_sched_barrier(0)
; template <class Epi, class Sched, bool ALIGN_EPI = false, bool SP2 = false>
; __device__ __forceinline__ void gemm_phase(PG8_LAS unsigned char* lds, const Gemm g, const Sched& S, const Epi& E, const int tid) {
;     ...
;         const bool has_next = S.next(ui + 1, nxt);
;         const char* nA = has_next ? (const char*)g.A + (size_t)nxt.pm * tstep : cA; const char* nB = has_next ? (const char*)g.Bt + (size_t)nxt.pn * tstep : cB;
;         for (int t = 0; t < nt; t += 2) {
;             const bool last = (t == nt - 2);
;             const char* a1 = cA + (size_t)(t + 1) * kstep;
;             const char* a2 = last ? nA : cA + (size_t)(t + 2) * kstep; const char* b2 = last ? nB : cB + (size_t)(t + 2) * kstep;
;             const char* a3 = a2 + kstep; const char* b3 = b2 + kstep;
;             if (last && has_next) S.a_ready(nxt);
;             if constexpr (SP2) {
;             PG8_LDB(B0, 0, 0); PG8_LDB(B1, 0, 1); PG8_SCHED; PG8_LDA(At, 0, 0); PG8_STAGE(PG8_SA(1, 1), a1 + hstep, voffA);
;             PG8_WAIT_V(8); PG8_WAIT_L(0); PG8_BAR; PG8_MMA(0, 0, At, B0); PG8_MMA(0, 1, At, B1); PG8_BAR; PG8_SCHED;
;             PG8_LDA(At, 0, 1); PG8_STAGE(PG8_SB(0, 0), b2, voffB); PG8_STAGE(PG8_SB(0, 1), b2 + hstep, voffB); PG8_STAGE(PG8_SA(0, 0), a2, voffA);
;             PG8_WAIT_V(8); PG8_WAIT_L(0); PG8_BAR; PG8_MMA(1, 0, At, B0); PG8_MMA(1, 1, At, B1); PG8_BAR; PG8_SCHED;
.LBB0_1113:
	s_ashr_i32 s21, s20, 31
	s_lshl_b64 s[22:23], s[20:21], 17
	s_add_u32 s22, s0, s22
	s_addc_u32 s23, s10, s23
	s_and_b64 s[24:25], s[4:5], exec
	s_cselect_b32 s43, s23, s31
	s_cselect_b32 s42, s22, s30
	s_ashr_i32 s19, s18, 31
	s_lshl_b64 s[24:25], s[18:19], 17
	s_add_u32 s24, s11, s24
	s_addc_u32 s25, s33, s25
	s_and_b64 s[36:37], s[4:5], exec
	s_cselect_b32 s37, s25, s35
	s_cselect_b32 s36, s24, s34
	s_add_i32 s40, 0, 0x10000
	s_add_i32 s27, 0, 0x14000
	v_add_u32_e32 v212, s40, v138
	v_add_u32_e32 v213, s27, v138
	s_waitcnt lgkmcnt(0)
	ds_read_b128 v[0:3], v212
	ds_read_b128 v[4:7], v212 offset:1024
	ds_read_b128 v[8:11], v212 offset:2048
	ds_read_b128 v[12:15], v212 offset:3072
	ds_read_b128 v[16:19], v213
	ds_read_b128 v[20:23], v213 offset:1024
	ds_read_b128 v[24:27], v213 offset:2048
	ds_read_b128 v[28:31], v213 offset:3072
	v_mov_b32_e32 v249, 0x358637bd
	v_mov_b64_e32 v[222:223], 0x400
	v_mov_b64_e32 v[250:251], 0x3ff
	s_add_u32 s64, s30, 0x10080
	s_addc_u32 s65, s31, 0
	s_add_i32 s62, s44, 0xc000
	v_lshl_add_u64 v[64:65], s[64:65], 0, v[128:129]
	s_mov_b32 m0, s62
	s_add_i32 s19, s44, 0xe000
	ds_read_b128 v[32:35], v139
	ds_read_b128 v[36:39], v139 offset:1024
	ds_read_b128 v[40:43], v139 offset:2048
	ds_read_b128 v[44:47], v139 offset:3072
	ds_read_b128 v[48:51], v139 offset:4096
	ds_read_b128 v[52:55], v139 offset:5120
	ds_read_b128 v[56:59], v139 offset:6144
	ds_read_b128 v[60:63], v139 offset:7168
	global_load_lds_dwordx4 v[64:65], off
	v_lshl_add_u64 v[64:65], s[64:65], 0, v[130:131]
	s_mov_b32 m0, s19
	s_nop 0
	global_load_lds_dwordx4 v[64:65], off
	s_waitcnt vmcnt(8)
	s_waitcnt lgkmcnt(0)
	s_setprio 1
	s_barrier
	v_mfma_f32_16x16x32_bf16 v[64:67], v[0:3], v[32:35], 0
	v_mfma_f32_16x16x32_bf16 v[68:71], v[8:11], v[32:35], 0
	v_mfma_f32_16x16x32_bf16 v[72:75], v[0:3], v[40:43], 0
	v_mfma_f32_16x16x32_bf16 v[76:79], v[8:11], v[40:43], 0
	v_mfma_f32_16x16x32_bf16 v[80:83], v[0:3], v[48:51], 0
	v_mfma_f32_16x16x32_bf16 v[84:87], v[8:11], v[48:51], 0
	v_mfma_f32_16x16x32_bf16 v[88:91], v[0:3], v[56:59], 0
	v_mfma_f32_16x16x32_bf16 v[92:95], v[8:11], v[56:59], 0
	v_mfma_f32_16x16x32_bf16 v[64:67], v[4:7], v[36:39], v[64:67]
	v_mfma_f32_16x16x32_bf16 v[68:71], v[12:15], v[36:39], v[68:71]
	v_mfma_f32_16x16x32_bf16 v[72:75], v[4:7], v[44:47], v[72:75]
	v_mfma_f32_16x16x32_bf16 v[76:79], v[12:15], v[44:47], v[76:79]
	v_mfma_f32_16x16x32_bf16 v[80:83], v[4:7], v[52:55], v[80:83]
	v_mfma_f32_16x16x32_bf16 v[84:87], v[12:15], v[52:55], v[84:87]
	v_mfma_f32_16x16x32_bf16 v[88:91], v[4:7], v[60:63], v[88:91]
	v_mfma_f32_16x16x32_bf16 v[92:95], v[12:15], v[60:63], v[92:95]
	s_setprio 0
	s_setprio 1
	v_mfma_f32_16x16x32_bf16 v[96:99], v[16:19], v[32:35], 0
	v_mfma_f32_16x16x32_bf16 v[32:35], v[24:27], v[32:35], 0
	v_mfma_f32_16x16x32_bf16 v[96:99], v[20:23], v[36:39], v[96:99]
	v_mfma_f32_16x16x32_bf16 v[32:35], v[28:31], v[36:39], v[32:35]
	v_mfma_f32_16x16x32_bf16 v[36:39], v[16:19], v[40:43], 0
	v_mfma_f32_16x16x32_bf16 v[40:43], v[24:27], v[40:43], 0
	v_mfma_f32_16x16x32_bf16 v[36:39], v[20:23], v[44:47], v[36:39]
	v_mfma_f32_16x16x32_bf16 v[40:43], v[28:31], v[44:47], v[40:43]
	v_mfma_f32_16x16x32_bf16 v[44:47], v[16:19], v[48:51], 0
	v_mfma_f32_16x16x32_bf16 v[48:51], v[24:27], v[48:51], 0
	v_mfma_f32_16x16x32_bf16 v[44:47], v[20:23], v[52:55], v[44:47]
	v_mfma_f32_16x16x32_bf16 v[48:51], v[28:31], v[52:55], v[48:51]
	v_mfma_f32_16x16x32_bf16 v[52:55], v[16:19], v[56:59], 0
	v_mfma_f32_16x16x32_bf16 v[56:59], v[24:27], v[56:59], 0
	v_mfma_f32_16x16x32_bf16 v[52:55], v[20:23], v[60:63], v[52:55]
	v_mfma_f32_16x16x32_bf16 v[56:59], v[28:31], v[60:63], v[56:59]
	s_barrier
	s_setprio 0
	s_add_i32 s40, s40, s38
	v_lshl_add_u64 v[200:201], s[34:35], 0, v[204:205]
	s_add_i32 s21, s40, 0x2000
	v_lshl_add_u64 v[134:135], v[200:201], 0, s[72:73]
	s_mov_b32 m0, s40
	v_lshl_add_u64 v[202:203], s[34:35], 0, v[132:133]
	s_add_u32 s64, s34, 0x10100
	ds_read_b128 v[60:63], v139 offset:16384
	ds_read_b128 v[100:103], v139 offset:17408
	ds_read_b128 v[104:107], v139 offset:18432
	ds_read_b128 v[108:111], v139 offset:19456
	ds_read_b128 v[112:115], v139 offset:20480
	ds_read_b128 v[116:119], v139 offset:21504
	ds_read_b128 v[120:123], v139 offset:22528
	ds_read_b128 v[124:127], v139 offset:23552
	global_load_lds_dwordx4 v[134:135], off
	v_lshl_add_u64 v[134:135], v[202:203], 0, s[72:73]
	s_mov_b32 m0, s21
	s_addc_u32 s65, s35, 0
	s_add_i32 s27, s27, s38
	global_load_lds_dwordx4 v[134:135], off
	v_lshl_add_u64 v[134:135], s[64:65], 0, v[204:205]
	s_mov_b32 m0, s27
	s_add_i32 s29, s27, 0x2000
	global_load_lds_dwordx4 v[134:135], off
	v_lshl_add_u64 v[134:135], s[64:65], 0, v[132:133]
	s_mov_b32 m0, s29
	v_lshl_add_u64 v[206:207], s[30:31], 0, v[128:129]
	global_load_lds_dwordx4 v[134:135], off
	v_lshl_add_u64 v[134:135], v[206:207], 0, s[72:73]
	s_mov_b32 m0, s44
	v_lshl_add_u64 v[208:209], s[30:31], 0, v[130:131]
	global_load_lds_dwordx4 v[134:135], off
	v_lshl_add_u64 v[134:135], v[208:209], 0, s[72:73]
	s_mov_b32 m0, s45
	s_nop 0
	global_load_lds_dwordx4 v[134:135], off
	s_waitcnt vmcnt(8)
	s_waitcnt lgkmcnt(0)
	s_setprio 1
	s_barrier
; #define PG8_STAGE(bufoff, gbase, voff) do { _Pragma("unroll") for (int _i = 0; _i < 2; ++_i) \
;         __builtin_amdgcn_global_load_lds((const unsigned*)((const char*)(gbase) + (voff)[_i]), (PG8_LAS unsigned*)(lds + (bufoff) + ldsw + _i * 8192), 16, 0, 0); } while (0)
; #define PG8_LDA(dst, b, h) do { _Pragma("unroll") for (int m = 0; m < 4; ++m) _Pragma("unroll") for (int k = 0; k < 2; ++k) dst[m][k] = *(const PG8_LAS bf16x8*)(lds + PG8_SA(b, h) + aoff + m * 2048 + k * 1024); } while (0)
; #define PG8_LDB(dst, b, h) do { _Pragma("unroll") for (int n = 0; n < 2; ++n) _Pragma("unroll") for (int k = 0; k < 2; ++k) dst[n][k] = *(const PG8_LAS bf16x8*)(lds + PG8_SB(b, h) + boff + n * 2048 + k * 1024); } while (0)
; #define PG8_MMA(ai, bj, At, Bt) do { __builtin_amdgcn_s_setprio(1); _Pragma("unroll") for (int m = 0; m < 4; ++m) _Pragma("unroll") for (int n = 0; n < 2; ++n) _Pragma("unroll") for (int k = 0; k < 2; ++k) \
;         acc[ai][bj][m][n] = __builtin_amdgcn_mfma_f32_16x16x32_bf16(Bt[n][k], At[m][k], acc[ai][bj][m][n], 0, 0, 0); __builtin_amdgcn_s_setprio(0); } while (0)
; #define PG8_WAIT_V(n) asm volatile("s_waitcnt vmcnt(" #n ")" ::: "memory")
; #define PG8_WAIT_L(n) asm volatile("s_waitcnt lgkmcnt(" #n ")" ::: "memory")
; #define PG8_BAR __builtin_amdgcn_s_barrier()
; #define PG8_SCHED __builtin_amdgcn_sched_barrier(0)
; template <class Epi, class Sched, bool ALIGN_EPI = false, bool SP2 = false>
; __device__ __forceinline__ void gemm_phase(PG8_LAS unsigned char* lds, const Gemm g, const Sched& S, const Epi& E, const int tid) {
;     ...
;             PG8_WAIT_V(8); PG8_WAIT_L(0); PG8_BAR; PG8_MMA(1, 0, At, B0); PG8_MMA(1, 1, At, B1); PG8_BAR; PG8_SCHED;
;             PG8_LDB(B0, 1, 0); PG8_LDB(B1, 1, 1); PG8_SCHED; PG8_LDA(At, 1, 0); PG8_STAGE(PG8_SA(0, 1), a2 + hstep, voffA);
;             PG8_WAIT_V(8); PG8_WAIT_L(0); PG8_BAR; PG8_MMA(0, 0, At, B0); PG8_MMA(0, 1, At, B1); PG8_BAR; PG8_SCHED;
	v_mfma_f32_16x16x32_bf16 v[134:137], v[0:3], v[60:63], 0
	v_mfma_f32_16x16x32_bf16 v[144:147], v[0:3], v[104:107], 0
	v_mfma_f32_16x16x32_bf16 v[152:155], v[0:3], v[112:115], 0
	v_mfma_f32_16x16x32_bf16 v[0:3], v[0:3], v[120:123], 0
	v_mfma_f32_16x16x32_bf16 v[134:137], v[4:7], v[100:103], v[134:137]
	v_mfma_f32_16x16x32_bf16 v[144:147], v[4:7], v[108:111], v[144:147]
	v_mfma_f32_16x16x32_bf16 v[152:155], v[4:7], v[116:119], v[152:155]
	v_mfma_f32_16x16x32_bf16 v[0:3], v[4:7], v[124:127], v[0:3]
	v_mfma_f32_16x16x32_bf16 v[4:7], v[8:11], v[120:123], 0
	v_mfma_f32_16x16x32_bf16 v[140:143], v[8:11], v[60:63], 0
	v_mfma_f32_16x16x32_bf16 v[148:151], v[8:11], v[104:107], 0
	v_mfma_f32_16x16x32_bf16 v[156:159], v[8:11], v[112:115], 0
	v_mfma_f32_16x16x32_bf16 v[4:7], v[12:15], v[124:127], v[4:7]
	v_mfma_f32_16x16x32_bf16 v[140:143], v[12:15], v[100:103], v[140:143]
	v_mfma_f32_16x16x32_bf16 v[148:151], v[12:15], v[108:111], v[148:151]
	v_mfma_f32_16x16x32_bf16 v[156:159], v[12:15], v[116:119], v[156:159]
	s_setprio 0
	s_setprio 1
	v_mfma_f32_16x16x32_bf16 v[8:11], v[16:19], v[60:63], 0
	v_mfma_f32_16x16x32_bf16 v[12:15], v[24:27], v[60:63], 0
	v_mfma_f32_16x16x32_bf16 v[8:11], v[20:23], v[100:103], v[8:11]
	v_mfma_f32_16x16x32_bf16 v[12:15], v[28:31], v[100:103], v[12:15]
	v_mfma_f32_16x16x32_bf16 v[60:63], v[16:19], v[104:107], 0
	v_mfma_f32_16x16x32_bf16 v[100:103], v[24:27], v[104:107], 0
	v_mfma_f32_16x16x32_bf16 v[104:107], v[16:19], v[112:115], 0
	v_mfma_f32_16x16x32_bf16 v[16:19], v[16:19], v[120:123], 0
	v_mfma_f32_16x16x32_bf16 v[60:63], v[20:23], v[108:111], v[60:63]
	v_mfma_f32_16x16x32_bf16 v[100:103], v[28:31], v[108:111], v[100:103]
	v_mfma_f32_16x16x32_bf16 v[104:107], v[20:23], v[116:119], v[104:107]
	v_mfma_f32_16x16x32_bf16 v[108:111], v[24:27], v[112:115], 0
	v_mfma_f32_16x16x32_bf16 v[16:19], v[20:23], v[124:127], v[16:19]
	v_mfma_f32_16x16x32_bf16 v[20:23], v[24:27], v[120:123], 0
	v_mfma_f32_16x16x32_bf16 v[108:111], v[28:31], v[116:119], v[108:111]
	v_mfma_f32_16x16x32_bf16 v[20:23], v[28:31], v[124:127], v[20:23]
	s_barrier
	s_setprio 0
	s_add_i32 s55, 0, 0x18000
	s_add_i32 s75, 0, 0x1c000
	v_add_u32_e32 v214, s55, v138
	v_add_u32_e32 v215, s75, v138
	ds_read_b128 v[24:27], v214
	ds_read_b128 v[28:31], v214 offset:1024
	ds_read_b128 v[112:115], v214 offset:2048
	ds_read_b128 v[116:119], v214 offset:3072
	ds_read_b128 v[120:123], v215
	ds_read_b128 v[124:127], v215 offset:1024
	ds_read_b128 v[160:163], v215 offset:2048
	ds_read_b128 v[164:167], v215 offset:3072
	s_add_u32 s64, s30, 0x10100
	s_addc_u32 s65, s31, 0
	s_mov_b32 m0, s46
	v_lshl_add_u64 v[210:211], s[64:65], 0, v[128:129]
	ds_read_b128 v[168:171], v139 offset:32768
	ds_read_b128 v[172:175], v139 offset:33792
	ds_read_b128 v[176:179], v139 offset:34816
	ds_read_b128 v[180:183], v139 offset:35840
	ds_read_b128 v[184:187], v139 offset:36864
	ds_read_b128 v[188:191], v139 offset:37888
	ds_read_b128 v[192:195], v139 offset:38912
	ds_read_b128 v[196:199], v139 offset:39936
	global_load_lds_dwordx4 v[210:211], off
	v_lshl_add_u64 v[210:211], s[64:65], 0, v[130:131]
	s_mov_b32 m0, s47
	s_nop 0
	global_load_lds_dwordx4 v[210:211], off
	s_waitcnt vmcnt(8)
	s_waitcnt lgkmcnt(0)
	s_setprio 1
	s_barrier
	v_mfma_f32_16x16x32_bf16 v[64:67], v[24:27], v[168:171], v[64:67]
	v_mfma_f32_16x16x32_bf16 v[68:71], v[112:115], v[168:171], v[68:71]
	v_mfma_f32_16x16x32_bf16 v[72:75], v[24:27], v[176:179], v[72:75]
	v_mfma_f32_16x16x32_bf16 v[76:79], v[112:115], v[176:179], v[76:79]
	v_mfma_f32_16x16x32_bf16 v[80:83], v[24:27], v[184:187], v[80:83]
	v_mfma_f32_16x16x32_bf16 v[84:87], v[112:115], v[184:187], v[84:87]
	v_mfma_f32_16x16x32_bf16 v[88:91], v[24:27], v[192:195], v[88:91]
	v_mfma_f32_16x16x32_bf16 v[92:95], v[112:115], v[192:195], v[92:95]
	v_mfma_f32_16x16x32_bf16 v[64:67], v[28:31], v[172:175], v[64:67]
	v_mfma_f32_16x16x32_bf16 v[68:71], v[116:119], v[172:175], v[68:71]
	v_mfma_f32_16x16x32_bf16 v[72:75], v[28:31], v[180:183], v[72:75]
	v_mfma_f32_16x16x32_bf16 v[76:79], v[116:119], v[180:183], v[76:79]
	v_mfma_f32_16x16x32_bf16 v[80:83], v[28:31], v[188:191], v[80:83]
	v_mfma_f32_16x16x32_bf16 v[84:87], v[116:119], v[188:191], v[84:87]
	v_mfma_f32_16x16x32_bf16 v[88:91], v[28:31], v[196:199], v[88:91]
	v_mfma_f32_16x16x32_bf16 v[92:95], v[116:119], v[196:199], v[92:95]
	s_setprio 0
	s_setprio 1
	v_mfma_f32_16x16x32_bf16 v[96:99], v[120:123], v[168:171], v[96:99]
	v_mfma_f32_16x16x32_bf16 v[32:35], v[160:163], v[168:171], v[32:35]
	v_mfma_f32_16x16x32_bf16 v[36:39], v[120:123], v[176:179], v[36:39]
	v_mfma_f32_16x16x32_bf16 v[40:43], v[160:163], v[176:179], v[40:43]
	v_mfma_f32_16x16x32_bf16 v[44:47], v[120:123], v[184:187], v[44:47]
	v_mfma_f32_16x16x32_bf16 v[48:51], v[160:163], v[184:187], v[48:51]
	v_mfma_f32_16x16x32_bf16 v[52:55], v[120:123], v[192:195], v[52:55]
	v_mfma_f32_16x16x32_bf16 v[56:59], v[160:163], v[192:195], v[56:59]
	v_mfma_f32_16x16x32_bf16 v[96:99], v[124:127], v[172:175], v[96:99]
	v_mfma_f32_16x16x32_bf16 v[32:35], v[164:167], v[172:175], v[32:35]
	v_mfma_f32_16x16x32_bf16 v[36:39], v[124:127], v[180:183], v[36:39]
	v_mfma_f32_16x16x32_bf16 v[40:43], v[164:167], v[180:183], v[40:43]
	v_mfma_f32_16x16x32_bf16 v[44:47], v[124:127], v[188:191], v[44:47]
	v_mfma_f32_16x16x32_bf16 v[48:51], v[164:167], v[188:191], v[48:51]
	v_mfma_f32_16x16x32_bf16 v[52:55], v[124:127], v[196:199], v[52:55]
	v_mfma_f32_16x16x32_bf16 v[56:59], v[164:167], v[196:199], v[56:59]
	s_barrier
; #define PG8_STAGE(bufoff, gbase, voff) do { _Pragma("unroll") for (int _i = 0; _i < 2; ++_i) \
;         __builtin_amdgcn_global_load_lds((const unsigned*)((const char*)(gbase) + (voff)[_i]), (PG8_LAS unsigned*)(lds + (bufoff) + ldsw + _i * 8192), 16, 0, 0); } while (0)
; #define PG8_LDA(dst, b, h) do { _Pragma("unroll") for (int m = 0; m < 4; ++m) _Pragma("unroll") for (int k = 0; k < 2; ++k) dst[m][k] = *(const PG8_LAS bf16x8*)(lds + PG8_SA(b, h) + aoff + m * 2048 + k * 1024); } while (0)
; #define PG8_LDB(dst, b, h) do { _Pragma("unroll") for (int n = 0; n < 2; ++n) _Pragma("unroll") for (int k = 0; k < 2; ++k) dst[n][k] = *(const PG8_LAS bf16x8*)(lds + PG8_SB(b, h) + boff + n * 2048 + k * 1024); } while (0)
; #define PG8_MMA(ai, bj, At, Bt) do { __builtin_amdgcn_s_setprio(1); _Pragma("unroll") for (int m = 0; m < 4; ++m) _Pragma("unroll") for (int n = 0; n < 2; ++n) _Pragma("unroll") for (int k = 0; k < 2; ++k) \
;         acc[ai][bj][m][n] = __builtin_amdgcn_mfma_f32_16x16x32_bf16(Bt[n][k], At[m][k], acc[ai][bj][m][n], 0, 0, 0); __builtin_amdgcn_s_setprio(0); } while (0)
; #define PG8_BAR __builtin_amdgcn_s_barrier()
; template <class Epi, class Sched, bool ALIGN_EPI = false, bool SP2 = false>
; __device__ __forceinline__ void gemm_phase(PG8_LAS unsigned char* lds, const Gemm g, const Sched& S, const Epi& E, const int tid) {
;     ...
;             PG8_LDB(B0, 0, 0); PG8_LDB(B1, 0, 1); PG8_SCHED; PG8_LDA(At, 0, 0); PG8_STAGE(PG8_SA(1, 1), a1 + hstep, voffA);
;             PG8_WAIT_V(8); PG8_WAIT_L(0); PG8_BAR; PG8_MMA(0, 0, At, B0); PG8_MMA(0, 1, At, B1); PG8_BAR; PG8_SCHED;
;             PG8_LDA(At, 0, 1); PG8_STAGE(PG8_SB(0, 0), b2, voffB); PG8_STAGE(PG8_SB(0, 1), b2 + hstep, voffB); PG8_STAGE(PG8_SA(0, 0), a2, voffA);
;             PG8_WAIT_V(8); PG8_WAIT_L(0); PG8_BAR; PG8_MMA(1, 0, At, B0); PG8_MMA(1, 1, At, B1); PG8_BAR; PG8_SCHED;
;             PG8_LDB(B0, 1, 0); PG8_LDB(B1, 1, 1); PG8_SCHED; PG8_LDA(At, 1, 0); PG8_STAGE(PG8_SA(0, 1), a2 + hstep, voffA);
;             PG8_WAIT_V(8); PG8_WAIT_L(0); PG8_BAR; PG8_MMA(0, 0, At, B0); PG8_MMA(0, 1, At, B1); PG8_BAR; PG8_SCHED;
;             PG8_LDA(At, 1, 1); PG8_STAGE(PG8_SB(1, 0), b3, voffB); PG8_STAGE(PG8_SB(1, 1), b3 + hstep, voffB); PG8_STAGE(PG8_SA(1, 0), a3, voffA);
;             PG8_WAIT_V(8); PG8_WAIT_L(0); PG8_BAR; PG8_MMA(1, 0, At, B0); PG8_MMA(1, 1, At, B1); PG8_BAR; PG8_SCHED;
	s_setprio 0
	s_add_i32 s64, s55, s38
	s_add_i32 s55, s64, 0x2000
	v_lshl_add_u64 v[200:201], v[200:201], 0, s[88:89]
	s_mov_b32 m0, s64
	s_add_u32 s68, s34, 0x10180
	ds_read_b128 v[168:171], v139 offset:49152
	ds_read_b128 v[172:175], v139 offset:50176
	ds_read_b128 v[176:179], v139 offset:51200
	ds_read_b128 v[180:183], v139 offset:52224
	ds_read_b128 v[184:187], v139 offset:53248
	ds_read_b128 v[188:191], v139 offset:54272
	ds_read_b128 v[192:195], v139 offset:55296
	ds_read_b128 v[196:199], v139 offset:56320
	global_load_lds_dwordx4 v[200:201], off
	v_lshl_add_u64 v[200:201], v[202:203], 0, s[88:89]
	s_mov_b32 m0, s55
	s_addc_u32 s69, s35, 0
	s_add_i32 s34, s75, s38
	global_load_lds_dwordx4 v[200:201], off
	v_lshl_add_u64 v[200:201], s[68:69], 0, v[204:205]
	s_mov_b32 m0, s34
	s_add_i32 s35, s34, 0x2000
	global_load_lds_dwordx4 v[200:201], off
	v_lshl_add_u64 v[200:201], s[68:69], 0, v[132:133]
	s_mov_b32 m0, s35
	s_nop 0
	global_load_lds_dwordx4 v[200:201], off
	v_lshl_add_u64 v[200:201], v[206:207], 0, s[88:89]
	s_mov_b32 m0, s52
	s_nop 0
	global_load_lds_dwordx4 v[200:201], off
	v_lshl_add_u64 v[200:201], v[208:209], 0, s[88:89]
	s_mov_b32 m0, s53
	s_nop 0
	global_load_lds_dwordx4 v[200:201], off
	s_waitcnt vmcnt(8)
	s_waitcnt lgkmcnt(0)
	s_setprio 1
	s_barrier
	v_mfma_f32_16x16x32_bf16 v[0:3], v[24:27], v[192:195], v[0:3]
	v_mfma_f32_16x16x32_bf16 v[4:7], v[112:115], v[192:195], v[4:7]
	v_mfma_f32_16x16x32_bf16 v[134:137], v[24:27], v[168:171], v[134:137]
	v_mfma_f32_16x16x32_bf16 v[140:143], v[112:115], v[168:171], v[140:143]
	v_mfma_f32_16x16x32_bf16 v[144:147], v[24:27], v[176:179], v[144:147]
	v_mfma_f32_16x16x32_bf16 v[148:151], v[112:115], v[176:179], v[148:151]
	v_mfma_f32_16x16x32_bf16 v[152:155], v[24:27], v[184:187], v[152:155]
	v_mfma_f32_16x16x32_bf16 v[156:159], v[112:115], v[184:187], v[156:159]
	v_mfma_f32_16x16x32_bf16 v[0:3], v[28:31], v[196:199], v[0:3]
	v_mfma_f32_16x16x32_bf16 v[4:7], v[116:119], v[196:199], v[4:7]
	v_mfma_f32_16x16x32_bf16 v[134:137], v[28:31], v[172:175], v[134:137]
	v_mfma_f32_16x16x32_bf16 v[140:143], v[116:119], v[172:175], v[140:143]
	v_mfma_f32_16x16x32_bf16 v[144:147], v[28:31], v[180:183], v[144:147]
	v_mfma_f32_16x16x32_bf16 v[148:151], v[116:119], v[180:183], v[148:151]
	v_mfma_f32_16x16x32_bf16 v[152:155], v[28:31], v[188:191], v[152:155]
	v_mfma_f32_16x16x32_bf16 v[156:159], v[116:119], v[188:191], v[156:159]
	s_setprio 0
	s_setprio 1
	v_mfma_f32_16x16x32_bf16 v[8:11], v[120:123], v[168:171], v[8:11]
	v_mfma_f32_16x16x32_bf16 v[12:15], v[160:163], v[168:171], v[12:15]
	v_mfma_f32_16x16x32_bf16 v[24:27], v[120:123], v[176:179], v[60:63]
	v_mfma_f32_16x16x32_bf16 v[28:31], v[160:163], v[176:179], v[100:103]
	v_mfma_f32_16x16x32_bf16 v[60:63], v[120:123], v[184:187], v[104:107]
	v_mfma_f32_16x16x32_bf16 v[100:103], v[160:163], v[184:187], v[108:111]
	v_mfma_f32_16x16x32_bf16 v[16:19], v[120:123], v[192:195], v[16:19]
	v_mfma_f32_16x16x32_bf16 v[20:23], v[160:163], v[192:195], v[20:23]
	v_mfma_f32_16x16x32_bf16 v[8:11], v[124:127], v[172:175], v[8:11]
	v_mfma_f32_16x16x32_bf16 v[12:15], v[164:167], v[172:175], v[12:15]
	v_mfma_f32_16x16x32_bf16 v[24:27], v[124:127], v[180:183], v[24:27]
	v_mfma_f32_16x16x32_bf16 v[28:31], v[164:167], v[180:183], v[28:31]
	v_mfma_f32_16x16x32_bf16 v[60:63], v[124:127], v[188:191], v[60:63]
	v_mfma_f32_16x16x32_bf16 v[100:103], v[164:167], v[188:191], v[100:103]
	v_mfma_f32_16x16x32_bf16 v[16:19], v[124:127], v[196:199], v[16:19]
	v_mfma_f32_16x16x32_bf16 v[20:23], v[164:167], v[196:199], v[20:23]
	s_barrier
	s_setprio 0
	ds_read_b128 v[104:107], v212
	ds_read_b128 v[108:111], v212 offset:1024
	ds_read_b128 v[112:115], v212 offset:2048
	ds_read_b128 v[116:119], v212 offset:3072
	ds_read_b128 v[120:123], v213
	ds_read_b128 v[124:127], v213 offset:1024
	ds_read_b128 v[160:163], v213 offset:2048
	ds_read_b128 v[164:167], v213 offset:3072
	s_add_u32 s30, s30, 0x10180
	s_addc_u32 s31, s31, 0
	s_mov_b32 m0, s62
	v_lshl_add_u64 v[200:201], s[30:31], 0, v[128:129]
	ds_read_b128 v[168:171], v139
	ds_read_b128 v[172:175], v139 offset:1024
	ds_read_b128 v[176:179], v139 offset:2048
	ds_read_b128 v[180:183], v139 offset:3072
	ds_read_b128 v[184:187], v139 offset:4096
	ds_read_b128 v[188:191], v139 offset:5120
	ds_read_b128 v[192:195], v139 offset:6144
	ds_read_b128 v[196:199], v139 offset:7168
	global_load_lds_dwordx4 v[200:201], off
	v_lshl_add_u64 v[200:201], s[30:31], 0, v[130:131]
	s_mov_b32 m0, s19
	s_nop 0
	global_load_lds_dwordx4 v[200:201], off
	s_waitcnt vmcnt(8)
	s_waitcnt lgkmcnt(0)
	s_setprio 1
	s_barrier
; #define PG8_STAGE(bufoff, gbase, voff) do { _Pragma("unroll") for (int _i = 0; _i < 2; ++_i) \
;         __builtin_amdgcn_global_load_lds((const unsigned*)((const char*)(gbase) + (voff)[_i]), (PG8_LAS unsigned*)(lds + (bufoff) + ldsw + _i * 8192), 16, 0, 0); } while (0)
; #define PG8_LDA(dst, b, h) do { _Pragma("unroll") for (int m = 0; m < 4; ++m) _Pragma("unroll") for (int k = 0; k < 2; ++k) dst[m][k] = *(const PG8_LAS bf16x8*)(lds + PG8_SA(b, h) + aoff + m * 2048 + k * 1024); } while (0)
; #define PG8_LDB(dst, b, h) do { _Pragma("unroll") for (int n = 0; n < 2; ++n) _Pragma("unroll") for (int k = 0; k < 2; ++k) dst[n][k] = *(const PG8_LAS bf16x8*)(lds + PG8_SB(b, h) + boff + n * 2048 + k * 1024); } while (0)
; #define PG8_MMA(ai, bj, At, Bt) do { __builtin_amdgcn_s_setprio(1); _Pragma("unroll") for (int m = 0; m < 4; ++m) _Pragma("unroll") for (int n = 0; n < 2; ++n) _Pragma("unroll") for (int k = 0; k < 2; ++k) \
;         acc[ai][bj][m][n] = __builtin_amdgcn_mfma_f32_16x16x32_bf16(Bt[n][k], At[m][k], acc[ai][bj][m][n], 0, 0, 0); __builtin_amdgcn_s_setprio(0); } while (0)
; #define PG8_WAIT_V(n) asm volatile("s_waitcnt vmcnt(" #n ")" ::: "memory")
; #define PG8_WAIT_L(n) asm volatile("s_waitcnt lgkmcnt(" #n ")" ::: "memory")
; #define PG8_BAR __builtin_amdgcn_s_barrier()
; #define PG8_SCHED __builtin_amdgcn_sched_barrier(0)
; template <class Epi, class Sched, bool ALIGN_EPI = false, bool SP2 = false>
; __device__ __forceinline__ void gemm_phase(PG8_LAS unsigned char* lds, const Gemm g, const Sched& S, const Epi& E, const int tid) {
;     ...
;             PG8_WAIT_V(8); PG8_WAIT_L(0); PG8_BAR; PG8_MMA(0, 0, At, B0); PG8_MMA(0, 1, At, B1); PG8_BAR; PG8_SCHED;
;             PG8_LDA(At, 0, 1); PG8_STAGE(PG8_SB(0, 0), b2, voffB); PG8_STAGE(PG8_SB(0, 1), b2 + hstep, voffB); PG8_STAGE(PG8_SA(0, 0), a2, voffA);
;             PG8_WAIT_V(8); PG8_WAIT_L(0); PG8_BAR; PG8_MMA(1, 0, At, B0); PG8_MMA(1, 1, At, B1); PG8_BAR; PG8_SCHED;
;             PG8_LDB(B0, 1, 0); PG8_LDB(B1, 1, 1); PG8_SCHED; PG8_LDA(At, 1, 0); PG8_STAGE(PG8_SA(0, 1), a2 + hstep, voffA);
;             PG8_WAIT_V(8); PG8_WAIT_L(0); PG8_BAR; PG8_MMA(0, 0, At, B0); PG8_MMA(0, 1, At, B1); PG8_BAR; PG8_SCHED;
	v_mfma_f32_16x16x32_bf16 v[64:67], v[104:107], v[168:171], v[64:67]
	v_mfma_f32_16x16x32_bf16 v[68:71], v[112:115], v[168:171], v[68:71]
	v_mfma_f32_16x16x32_bf16 v[72:75], v[104:107], v[176:179], v[72:75]
	v_mfma_f32_16x16x32_bf16 v[76:79], v[112:115], v[176:179], v[76:79]
	v_mfma_f32_16x16x32_bf16 v[80:83], v[104:107], v[184:187], v[80:83]
	v_mfma_f32_16x16x32_bf16 v[84:87], v[112:115], v[184:187], v[84:87]
	v_mfma_f32_16x16x32_bf16 v[88:91], v[104:107], v[192:195], v[88:91]
	v_mfma_f32_16x16x32_bf16 v[64:67], v[108:111], v[172:175], v[64:67]
	v_mfma_f32_16x16x32_bf16 v[68:71], v[116:119], v[172:175], v[68:71]
	v_mfma_f32_16x16x32_bf16 v[72:75], v[108:111], v[180:183], v[72:75]
	v_mfma_f32_16x16x32_bf16 v[76:79], v[116:119], v[180:183], v[76:79]
	v_mfma_f32_16x16x32_bf16 v[80:83], v[108:111], v[188:191], v[80:83]
	v_mfma_f32_16x16x32_bf16 v[84:87], v[116:119], v[188:191], v[84:87]
	v_mfma_f32_16x16x32_bf16 v[88:91], v[108:111], v[196:199], v[88:91]
	v_mfma_f32_16x16x32_bf16 v[92:95], v[112:115], v[192:195], v[92:95]
	v_mfma_f32_16x16x32_bf16 v[200:203], v[116:119], v[196:199], v[92:95]
	s_setprio 0
	s_setprio 1
	v_mfma_f32_16x16x32_bf16 v[32:35], v[160:163], v[168:171], v[32:35]
	v_mfma_f32_16x16x32_bf16 v[36:39], v[120:123], v[176:179], v[36:39]
	v_mfma_f32_16x16x32_bf16 v[40:43], v[160:163], v[176:179], v[40:43]
	v_mfma_f32_16x16x32_bf16 v[44:47], v[120:123], v[184:187], v[44:47]
	v_mfma_f32_16x16x32_bf16 v[48:51], v[160:163], v[184:187], v[48:51]
	v_mfma_f32_16x16x32_bf16 v[52:55], v[120:123], v[192:195], v[52:55]
	v_mfma_f32_16x16x32_bf16 v[56:59], v[160:163], v[192:195], v[56:59]
	v_mfma_f32_16x16x32_bf16 v[92:95], v[120:123], v[168:171], v[96:99]
	v_mfma_f32_16x16x32_bf16 v[32:35], v[164:167], v[172:175], v[32:35]
	v_mfma_f32_16x16x32_bf16 v[36:39], v[124:127], v[180:183], v[36:39]
	v_mfma_f32_16x16x32_bf16 v[40:43], v[164:167], v[180:183], v[40:43]
	v_mfma_f32_16x16x32_bf16 v[44:47], v[124:127], v[188:191], v[44:47]
	v_mfma_f32_16x16x32_bf16 v[48:51], v[164:167], v[188:191], v[48:51]
	v_mfma_f32_16x16x32_bf16 v[52:55], v[124:127], v[196:199], v[52:55]
	v_mfma_f32_16x16x32_bf16 v[56:59], v[164:167], v[196:199], v[56:59]
	v_mfma_f32_16x16x32_bf16 v[206:209], v[124:127], v[172:175], v[92:95]
	s_barrier
	s_setprio 0
	s_mov_b32 m0, s40
	v_lshl_add_u64 v[240:241], s[36:37], 0, v[204:205]
	s_add_u32 s30, s36, 0x10000
	ds_read_b128 v[92:95], v139 offset:16384
	ds_read_b128 v[96:99], v139 offset:17408
	ds_read_b128 v[168:171], v139 offset:18432
	ds_read_b128 v[172:175], v139 offset:19456
	ds_read_b128 v[176:179], v139 offset:20480
	ds_read_b128 v[180:183], v139 offset:21504
	ds_read_b128 v[184:187], v139 offset:22528
	ds_read_b128 v[188:191], v139 offset:23552
	global_load_lds_dwordx4 v[240:241], off
	v_lshl_add_u64 v[242:243], s[36:37], 0, v[132:133]
	s_mov_b32 m0, s21
	s_addc_u32 s31, s37, 0
	global_load_lds_dwordx4 v[242:243], off
	v_lshl_add_u64 v[192:193], s[30:31], 0, v[204:205]
	s_mov_b32 m0, s27
	v_lshl_add_u64 v[244:245], s[42:43], 0, v[128:129]
	global_load_lds_dwordx4 v[192:193], off
	v_lshl_add_u64 v[192:193], s[30:31], 0, v[132:133]
	s_mov_b32 m0, s29
	v_lshl_add_u64 v[246:247], s[42:43], 0, v[130:131]
	global_load_lds_dwordx4 v[192:193], off
	s_mov_b32 m0, s44
	s_nop 0
	global_load_lds_dwordx4 v[244:245], off
	s_mov_b32 m0, s45
	s_nop 0
	global_load_lds_dwordx4 v[246:247], off
	s_waitcnt vmcnt(8)
	s_waitcnt lgkmcnt(0)
	s_setprio 1
	s_barrier
	v_mfma_f32_16x16x32_bf16 v[0:3], v[104:107], v[184:187], v[0:3]
	v_mfma_f32_16x16x32_bf16 v[4:7], v[112:115], v[184:187], v[4:7]
	v_mfma_f32_16x16x32_bf16 v[134:137], v[104:107], v[92:95], v[134:137]
	v_mfma_f32_16x16x32_bf16 v[140:143], v[112:115], v[92:95], v[140:143]
	v_mfma_f32_16x16x32_bf16 v[144:147], v[104:107], v[168:171], v[144:147]
	v_mfma_f32_16x16x32_bf16 v[148:151], v[112:115], v[168:171], v[148:151]
	v_mfma_f32_16x16x32_bf16 v[152:155], v[104:107], v[176:179], v[152:155]
	v_mfma_f32_16x16x32_bf16 v[156:159], v[112:115], v[176:179], v[156:159]
	v_mfma_f32_16x16x32_bf16 v[0:3], v[108:111], v[188:191], v[0:3]
	v_mfma_f32_16x16x32_bf16 v[4:7], v[116:119], v[188:191], v[4:7]
	v_mfma_f32_16x16x32_bf16 v[134:137], v[108:111], v[96:99], v[134:137]
	v_mfma_f32_16x16x32_bf16 v[140:143], v[116:119], v[96:99], v[140:143]
	v_mfma_f32_16x16x32_bf16 v[144:147], v[108:111], v[172:175], v[144:147]
	v_mfma_f32_16x16x32_bf16 v[148:151], v[116:119], v[172:175], v[148:151]
	v_mfma_f32_16x16x32_bf16 v[152:155], v[108:111], v[180:183], v[152:155]
	v_mfma_f32_16x16x32_bf16 v[156:159], v[116:119], v[180:183], v[156:159]
	s_setprio 0
	s_setprio 1
	v_mfma_f32_16x16x32_bf16 v[12:15], v[160:163], v[92:95], v[12:15]
	v_mfma_f32_16x16x32_bf16 v[192:195], v[164:167], v[96:99], v[12:15]
	v_mfma_f32_16x16x32_bf16 v[12:15], v[120:123], v[168:171], v[24:27]
	v_mfma_f32_16x16x32_bf16 v[24:27], v[124:127], v[172:175], v[12:15]
	v_mfma_f32_16x16x32_bf16 v[12:15], v[160:163], v[168:171], v[28:31]
	v_mfma_f32_16x16x32_bf16 v[168:171], v[164:167], v[172:175], v[12:15]
	v_mfma_f32_16x16x32_bf16 v[12:15], v[120:123], v[176:179], v[60:63]
	v_mfma_f32_16x16x32_bf16 v[172:175], v[124:127], v[180:183], v[12:15]
	v_mfma_f32_16x16x32_bf16 v[12:15], v[160:163], v[176:179], v[100:103]
	v_mfma_f32_16x16x32_bf16 v[8:11], v[120:123], v[92:95], v[8:11]
	v_mfma_f32_16x16x32_bf16 v[176:179], v[164:167], v[180:183], v[12:15]
	v_mfma_f32_16x16x32_bf16 v[12:15], v[120:123], v[184:187], v[16:19]
	v_mfma_f32_16x16x32_bf16 v[8:11], v[124:127], v[96:99], v[8:11]
	v_mfma_f32_16x16x32_bf16 v[180:183], v[124:127], v[188:191], v[12:15]
	v_mfma_f32_16x16x32_bf16 v[12:15], v[160:163], v[184:187], v[20:23]
	v_mfma_f32_16x16x32_bf16 v[160:163], v[164:167], v[188:191], v[12:15]
	s_barrier
; #define PG8_STAGE(bufoff, gbase, voff) do { _Pragma("unroll") for (int _i = 0; _i < 2; ++_i) \
;         __builtin_amdgcn_global_load_lds((const unsigned*)((const char*)(gbase) + (voff)[_i]), (PG8_LAS unsigned*)(lds + (bufoff) + ldsw + _i * 8192), 16, 0, 0); } while (0)
; #define PG8_BAR __builtin_amdgcn_s_barrier()
; template <class Epi, class Sched, bool ALIGN_EPI = false, bool SP2 = false>
; __device__ __forceinline__ void gemm_phase(PG8_LAS unsigned char* lds, const Gemm g, const Sched& S, const Epi& E, const int tid) {
;     ...
;             PG8_LDB(B0, 1, 0); PG8_LDB(B1, 1, 1); PG8_SCHED; PG8_LDA(At, 1, 0); PG8_STAGE(PG8_SA(0, 1), a2 + hstep, voffA);
;             PG8_WAIT_V(8); PG8_WAIT_L(0); PG8_BAR; PG8_MMA(0, 0, At, B0); PG8_MMA(0, 1, At, B1); PG8_BAR; PG8_SCHED;
;             PG8_LDA(At, 1, 1); PG8_STAGE(PG8_SB(1, 0), b3, voffB); PG8_STAGE(PG8_SB(1, 1), b3 + hstep, voffB); PG8_STAGE(PG8_SA(1, 0), a3, voffA);
;             PG8_WAIT_V(8); PG8_WAIT_L(0); PG8_BAR; PG8_MMA(1, 0, At, B0); PG8_MMA(1, 1, At, B1); PG8_BAR; PG8_SCHED;
;             } else {
;             PG8_LDB(B0, 0, 0); PG8_SCHED; PG8_LDA(At, 0, 0); PG8_STAGE(PG8_SA(1, 1), a1 + hstep, voffA);
;             PG8_WAIT_L(8); PG8_BAR; PG8_WAIT_L(0); PG8_MMA(0, 0, At, B0); PG8_BAR; PG8_SCHED;
;             PG8_LDB(B1, 0, 1); PG8_STAGE(PG8_SB(0, 0), b2, voffB);
;             PG8_BAR; PG8_WAIT_L(0); PG8_MMA(0, 1, At, B1); PG8_BAR;
;             PG8_LDA(At, 0, 1); PG8_STAGE(PG8_SA(0, 0), a2, voffA);
;             PG8_BAR; PG8_WAIT_L(0); PG8_MMA(1, 0, At, B0); PG8_BAR; PG8_SCHED;
;             PG8_STAGE(PG8_SB(0, 1), b2 + hstep, voffB);
;             PG8_WAIT_V(6); PG8_BAR; PG8_MMA(1, 1, At, B1); PG8_BAR;
;             PG8_LDB(B0, 1, 0); PG8_SCHED; PG8_LDA(At, 1, 0); PG8_STAGE(PG8_SA(0, 1), a2 + hstep, voffA);
;             PG8_WAIT_L(8); PG8_BAR; PG8_WAIT_L(0); PG8_MMA(0, 0, At, B0); PG8_BAR; PG8_SCHED;
;             PG8_LDB(B1, 1, 1); PG8_STAGE(PG8_SB(1, 0), b3, voffB);
;             PG8_BAR; PG8_WAIT_L(0); PG8_MMA(0, 1, At, B1); PG8_BAR;
;             PG8_LDA(At, 1, 1); PG8_STAGE(PG8_SA(1, 0), a3, voffA);
;             PG8_BAR; PG8_WAIT_L(0); PG8_MMA(1, 0, At, B0); PG8_BAR; PG8_SCHED;
;             PG8_STAGE(PG8_SB(1, 1), b3 + hstep, voffB);
;             PG8_WAIT_V(6); PG8_BAR; PG8_MMA(1, 1, At, B1); PG8_BAR;
;             }
;         }
;         if constexpr (ALIGN_EPI) { if (wr == 0) PG8_BAR; }
	s_setprio 0
	s_nop 4
	ds_read_b128 v[12:15], v214
	ds_read_b128 v[20:23], v214 offset:1024
	ds_read_b128 v[164:167], v214 offset:2048
	ds_read_b128 v[184:187], v214 offset:3072
	ds_read_b128 v[188:191], v215
	ds_read_b128 v[196:199], v215 offset:1024
	ds_read_b128 v[210:213], v215 offset:2048
	ds_read_b128 v[214:217], v215 offset:3072
	s_add_u32 s30, s42, 0x10000
	s_addc_u32 s31, s43, 0
	s_mov_b32 m0, s46
	v_lshl_add_u64 v[60:61], s[30:31], 0, v[128:129]
	ds_read_b128 v[16:19], v139 offset:32768
	ds_read_b128 v[28:31], v139 offset:33792
	ds_read_b128 v[104:107], v139 offset:34816
	ds_read_b128 v[218:221], v139 offset:35840
	ds_read_b128 v[224:227], v139 offset:36864
	ds_read_b128 v[228:231], v139 offset:37888
	ds_read_b128 v[232:235], v139 offset:38912
	ds_read_b128 v[236:239], v139 offset:39936
	global_load_lds_dwordx4 v[60:61], off
	v_lshl_add_u64 v[60:61], s[30:31], 0, v[130:131]
	s_mov_b32 m0, s47
	s_nop 0
	global_load_lds_dwordx4 v[60:61], off
	s_waitcnt vmcnt(8)
	s_waitcnt lgkmcnt(0)
	s_setprio 1
	s_barrier
	v_mfma_f32_16x16x32_bf16 v[60:63], v[12:15], v[16:19], v[64:67]
	v_mfma_f32_16x16x32_bf16 v[124:127], v[20:23], v[28:31], v[60:63]
	v_mfma_f32_16x16x32_bf16 v[60:63], v[164:167], v[16:19], v[68:71]
	v_mfma_f32_16x16x32_bf16 v[112:115], v[184:187], v[28:31], v[60:63]
	v_mfma_f32_16x16x32_bf16 v[60:63], v[12:15], v[104:107], v[72:75]
	v_mfma_f32_16x16x32_bf16 v[108:111], v[20:23], v[218:221], v[60:63]
	v_mfma_f32_16x16x32_bf16 v[60:63], v[164:167], v[104:107], v[76:79]
	v_mfma_f32_16x16x32_bf16 v[96:99], v[184:187], v[218:221], v[60:63]
	v_mfma_f32_16x16x32_bf16 v[60:63], v[12:15], v[224:227], v[80:83]
	v_mfma_f32_16x16x32_bf16 v[92:95], v[20:23], v[228:231], v[60:63]
	v_mfma_f32_16x16x32_bf16 v[60:63], v[164:167], v[224:227], v[84:87]
	v_mfma_f32_16x16x32_bf16 v[80:83], v[184:187], v[228:231], v[60:63]
	v_mfma_f32_16x16x32_bf16 v[60:63], v[12:15], v[232:235], v[88:91]
	v_mfma_f32_16x16x32_bf16 v[76:79], v[20:23], v[236:239], v[60:63]
	v_mfma_f32_16x16x32_bf16 v[60:63], v[164:167], v[232:235], v[200:203]
	v_mfma_f32_16x16x32_bf16 v[60:63], v[184:187], v[236:239], v[60:63]
	s_setprio 0
	s_setprio 1
	v_mfma_f32_16x16x32_bf16 v[64:67], v[188:191], v[16:19], v[206:209]
	v_mfma_f32_16x16x32_bf16 v[16:19], v[210:213], v[16:19], v[32:35]
	v_mfma_f32_16x16x32_bf16 v[120:123], v[214:217], v[28:31], v[16:19]
	v_mfma_f32_16x16x32_bf16 v[16:19], v[188:191], v[104:107], v[36:39]
	v_mfma_f32_16x16x32_bf16 v[100:103], v[196:199], v[218:221], v[16:19]
	v_mfma_f32_16x16x32_bf16 v[16:19], v[210:213], v[104:107], v[40:43]
	v_mfma_f32_16x16x32_bf16 v[104:107], v[214:217], v[218:221], v[16:19]
	v_mfma_f32_16x16x32_bf16 v[16:19], v[188:191], v[224:227], v[44:47]
	v_mfma_f32_16x16x32_bf16 v[84:87], v[196:199], v[228:231], v[16:19]
	v_mfma_f32_16x16x32_bf16 v[16:19], v[210:213], v[224:227], v[48:51]
	v_mfma_f32_16x16x32_bf16 v[88:91], v[214:217], v[228:231], v[16:19]
	v_mfma_f32_16x16x32_bf16 v[16:19], v[188:191], v[232:235], v[52:55]
	v_mfma_f32_16x16x32_bf16 v[68:71], v[196:199], v[236:239], v[16:19]
	v_mfma_f32_16x16x32_bf16 v[16:19], v[210:213], v[232:235], v[56:59]
	v_mfma_f32_16x16x32_bf16 v[116:119], v[196:199], v[28:31], v[64:67]
	v_mfma_f32_16x16x32_bf16 v[72:75], v[214:217], v[236:239], v[16:19]
	s_barrier
	s_setprio 0
	s_mov_b32 m0, s64
	s_nop 2
	v_lshl_add_u64 v[16:17], v[240:241], 0, s[70:71]
	s_add_u32 s30, s36, 0x10080
	ds_read_b128 v[36:39], v139 offset:49152
	ds_read_b128 v[40:43], v139 offset:50176
	ds_read_b128 v[200:203], v139 offset:51200
	ds_read_b128 v[206:209], v139 offset:52224
	ds_read_b128 v[218:221], v139 offset:53248
	ds_read_b128 v[224:227], v139 offset:54272
	ds_read_b128 v[228:231], v139 offset:55296
	ds_read_b128 v[232:235], v139 offset:56320
	global_load_lds_dwordx4 v[16:17], off
	v_lshl_add_u64 v[16:17], v[242:243], 0, s[70:71]
	s_mov_b32 m0, s55
	s_addc_u32 s31, s37, 0
	global_load_lds_dwordx4 v[16:17], off
	v_lshl_add_u64 v[16:17], s[30:31], 0, v[204:205]
	s_mov_b32 m0, s34
	s_nop 0
	global_load_lds_dwordx4 v[16:17], off
	v_lshl_add_u64 v[16:17], s[30:31], 0, v[132:133]
	s_mov_b32 m0, s35
	s_nop 0
	global_load_lds_dwordx4 v[16:17], off
	v_lshl_add_u64 v[16:17], v[244:245], 0, s[70:71]
	s_mov_b32 m0, s52
	s_nop 0
	global_load_lds_dwordx4 v[16:17], off
	v_lshl_add_u64 v[16:17], v[246:247], 0, s[70:71]
	s_mov_b32 m0, s53
	s_nop 0
	global_load_lds_dwordx4 v[16:17], off
	s_waitcnt vmcnt(8)
	s_waitcnt lgkmcnt(0)
	s_setprio 1
	s_barrier
	v_mfma_f32_16x16x32_bf16 v[16:19], v[12:15], v[36:39], v[134:137]
	v_mfma_f32_16x16x32_bf16 v[64:67], v[20:23], v[40:43], v[16:19]
	v_mfma_f32_16x16x32_bf16 v[16:19], v[164:167], v[36:39], v[140:143]
	v_mfma_f32_16x16x32_bf16 v[48:51], v[184:187], v[40:43], v[16:19]
	v_mfma_f32_16x16x32_bf16 v[16:19], v[12:15], v[200:203], v[144:147]
	v_mfma_f32_16x16x32_bf16 v[44:47], v[20:23], v[206:209], v[16:19]
	v_mfma_f32_16x16x32_bf16 v[16:19], v[164:167], v[200:203], v[148:151]
	v_mfma_f32_16x16x32_bf16 v[32:35], v[184:187], v[206:209], v[16:19]
	v_mfma_f32_16x16x32_bf16 v[16:19], v[12:15], v[218:221], v[152:155]
	v_mfma_f32_16x16x32_bf16 v[0:3], v[12:15], v[228:231], v[0:3]
	v_mfma_f32_16x16x32_bf16 v[28:31], v[20:23], v[224:227], v[16:19]
	v_mfma_f32_16x16x32_bf16 v[16:19], v[164:167], v[218:221], v[156:159]
	v_mfma_f32_16x16x32_bf16 v[12:15], v[20:23], v[232:235], v[0:3]
	v_mfma_f32_16x16x32_bf16 v[0:3], v[164:167], v[228:231], v[4:7]
	v_mfma_f32_16x16x32_bf16 v[16:19], v[184:187], v[224:227], v[16:19]
	v_mfma_f32_16x16x32_bf16 v[0:3], v[184:187], v[232:235], v[0:3]
	s_setprio 0
	s_setprio 1
	v_mfma_f32_16x16x32_bf16 v[4:7], v[188:191], v[36:39], v[8:11]
	v_mfma_f32_16x16x32_bf16 v[52:55], v[196:199], v[40:43], v[4:7]
	v_mfma_f32_16x16x32_bf16 v[4:7], v[210:213], v[36:39], v[192:195]
	v_mfma_f32_16x16x32_bf16 v[56:59], v[214:217], v[40:43], v[4:7]
	v_mfma_f32_16x16x32_bf16 v[4:7], v[188:191], v[200:203], v[24:27]
	v_mfma_f32_16x16x32_bf16 v[36:39], v[196:199], v[206:209], v[4:7]
	v_mfma_f32_16x16x32_bf16 v[4:7], v[210:213], v[200:203], v[168:171]
	v_mfma_f32_16x16x32_bf16 v[40:43], v[214:217], v[206:209], v[4:7]
	v_mfma_f32_16x16x32_bf16 v[4:7], v[188:191], v[218:221], v[172:175]
	v_mfma_f32_16x16x32_bf16 v[20:23], v[196:199], v[224:227], v[4:7]
	v_mfma_f32_16x16x32_bf16 v[4:7], v[210:213], v[218:221], v[176:179]
	v_mfma_f32_16x16x32_bf16 v[24:27], v[214:217], v[224:227], v[4:7]
	v_mfma_f32_16x16x32_bf16 v[4:7], v[188:191], v[228:231], v[180:183]
	v_mfma_f32_16x16x32_bf16 v[8:11], v[210:213], v[228:231], v[160:163]
	v_mfma_f32_16x16x32_bf16 v[4:7], v[196:199], v[232:235], v[4:7]
	v_mfma_f32_16x16x32_bf16 v[8:11], v[214:217], v[232:235], v[8:11]
	s_barrier
	s_setprio 0
	s_andn2_b64 vcc, exec, s[14:15]
	s_cbranch_vccnz .LBB0_1115
	s_barrier

; #define PG8_STAGE(bufoff, gbase, voff) do { _Pragma("unroll") for (int _i = 0; _i < 2; ++_i) \
;         __builtin_amdgcn_global_load_lds((const unsigned*)((const char*)(gbase) + (voff)[_i]), (PG8_LAS unsigned*)(lds + (bufoff) + ldsw + _i * 8192), 16, 0, 0); } while (0)
; #define PG8_LDA(dst, b, h) do { _Pragma("unroll") for (int m = 0; m < 4; ++m) _Pragma("unroll") for (int k = 0; k < 2; ++k) dst[m][k] = *(const PG8_LAS bf16x8*)(lds + PG8_SA(b, h) + aoff + m * 2048 + k * 1024); } while (0)
; #define PG8_LDB(dst, b, h) do { _Pragma("unroll") for (int n = 0; n < 2; ++n) _Pragma("unroll") for (int k = 0; k < 2; ++k) dst[n][k] = *(const PG8_LAS bf16x8*)(lds + PG8_SB(b, h) + boff + n * 2048 + k * 1024); } while (0)
; #define PG8_MMA(ai, bj, At, Bt) do { __builtin_amdgcn_s_setprio(1); _Pragma("unroll") for (int m = 0; m < 4; ++m) _Pragma("unroll") for (int n = 0; n < 2; ++n) _Pragma("unroll") for (int k = 0; k < 2; ++k) \
;         acc[ai][bj][m][n] = __builtin_amdgcn_mfma_f32_16x16x32_bf16(Bt[n][k], At[m][k], acc[ai][bj][m][n], 0, 0, 0); __builtin_amdgcn_s_setprio(0); } while (0)
; #define PG8_WAIT_V(n) asm volatile("s_waitcnt vmcnt(" #n ")" ::: "memory")
; #define PG8_BAR __builtin_amdgcn_s_barrier()
; template <class Epi, class Sched, bool ALIGN_EPI = false, bool SP2 = false>
; __device__ __forceinline__ void gemm_phase(PG8_LAS unsigned char* lds, const Gemm g, const Sched& S, const Epi& E, const int tid) {
;     ...
;         for (int t = 0; t < nt; t += 2) {
;             const bool last = (t == nt - 2);
;             const char* a1 = cA + (size_t)(t + 1) * kstep;
;             const char* a2 = last ? nA : cA + (size_t)(t + 2) * kstep; const char* b2 = last ? nB : cB + (size_t)(t + 2) * kstep;
;             const char* a3 = a2 + kstep; const char* b3 = b2 + kstep;
;             if (last && has_next) S.a_ready(nxt);
;             if constexpr (SP2) {
;             PG8_LDB(B0, 0, 0); PG8_LDB(B1, 0, 1); PG8_SCHED; PG8_LDA(At, 0, 0); PG8_STAGE(PG8_SA(1, 1), a1 + hstep, voffA);
;             PG8_WAIT_V(8); PG8_WAIT_L(0); PG8_BAR; PG8_MMA(0, 0, At, B0); PG8_MMA(0, 1, At, B1); PG8_BAR; PG8_SCHED;
;             PG8_LDA(At, 0, 1); PG8_STAGE(PG8_SB(0, 0), b2, voffB); PG8_STAGE(PG8_SB(0, 1), b2 + hstep, voffB); PG8_STAGE(PG8_SA(0, 0), a2, voffA);
;             PG8_WAIT_V(8); PG8_WAIT_L(0); PG8_BAR; PG8_MMA(1, 0, At, B0); PG8_MMA(1, 1, At, B1); PG8_BAR; PG8_SCHED;
.LBB0_1198:
	s_add_u32 s28, s30, 0xffe00080
	s_addc_u32 s29, s31, -1
	s_add_i32 s65, 0, 0x10000
	s_cmpk_eq_i32 s64, 0x7c
	s_cselect_b32 s35, s19, s29
	s_cselect_b32 s34, s40, s28
	s_cselect_b32 s29, s17, s62
	s_cselect_b32 s28, s54, s55
	s_add_i32 s75, 0, 0x14000
	v_add_u32_e32 v140, s65, v216
	v_add_u32_e32 v156, s75, v216
	ds_read_b128 v[128:131], v140
	ds_read_b128 v[132:135], v140 offset:1024
	ds_read_b128 v[136:139], v140 offset:2048
	ds_read_b128 v[140:143], v140 offset:3072
	ds_read_b128 v[144:147], v156
	ds_read_b128 v[148:151], v156 offset:1024
	ds_read_b128 v[152:155], v156 offset:2048
	ds_read_b128 v[156:159], v156 offset:3072
	v_lshl_add_u64 v[202:203], s[30:31], 0, v[198:199]
	s_add_i32 m0, s44, 0xc000
	ds_read_b128 v[160:163], v217
	ds_read_b128 v[164:167], v217 offset:1024
	ds_read_b128 v[168:171], v217 offset:2048
	ds_read_b128 v[172:175], v217 offset:3072
	ds_read_b128 v[176:179], v217 offset:4096
	ds_read_b128 v[180:183], v217 offset:5120
	ds_read_b128 v[184:187], v217 offset:6144
	ds_read_b128 v[188:191], v217 offset:7168
	global_load_lds_dwordx4 v[202:203], off
	v_lshl_add_u64 v[202:203], s[30:31], 0, v[200:201]
	s_add_i32 m0, s44, 0xe000
	s_nop 0
	global_load_lds_dwordx4 v[202:203], off
	s_waitcnt vmcnt(8)
	s_waitcnt lgkmcnt(0)
	s_setprio 1
	s_barrier
	v_mfma_f32_16x16x32_bf16 v[120:123], v[128:131], v[160:163], v[120:123]
	v_mfma_f32_16x16x32_bf16 v[124:127], v[136:139], v[160:163], v[124:127]
	v_mfma_f32_16x16x32_bf16 v[104:107], v[128:131], v[168:171], v[104:107]
	v_mfma_f32_16x16x32_bf16 v[108:111], v[136:139], v[168:171], v[108:111]
	v_mfma_f32_16x16x32_bf16 v[88:91], v[128:131], v[176:179], v[88:91]
	v_mfma_f32_16x16x32_bf16 v[92:95], v[136:139], v[176:179], v[92:95]
	v_mfma_f32_16x16x32_bf16 v[72:75], v[128:131], v[184:187], v[72:75]
	v_mfma_f32_16x16x32_bf16 v[76:79], v[136:139], v[184:187], v[76:79]
	v_mfma_f32_16x16x32_bf16 v[120:123], v[132:135], v[164:167], v[120:123]
	v_mfma_f32_16x16x32_bf16 v[124:127], v[140:143], v[164:167], v[124:127]
	v_mfma_f32_16x16x32_bf16 v[104:107], v[132:135], v[172:175], v[104:107]
	v_mfma_f32_16x16x32_bf16 v[108:111], v[140:143], v[172:175], v[108:111]
	v_mfma_f32_16x16x32_bf16 v[88:91], v[132:135], v[180:183], v[88:91]
	v_mfma_f32_16x16x32_bf16 v[92:95], v[140:143], v[180:183], v[92:95]
	v_mfma_f32_16x16x32_bf16 v[72:75], v[132:135], v[188:191], v[72:75]
	v_mfma_f32_16x16x32_bf16 v[76:79], v[140:143], v[188:191], v[76:79]
	s_setprio 0
	s_setprio 1
	v_mfma_f32_16x16x32_bf16 v[112:115], v[144:147], v[160:163], v[112:115]
	v_mfma_f32_16x16x32_bf16 v[116:119], v[152:155], v[160:163], v[116:119]
	v_mfma_f32_16x16x32_bf16 v[96:99], v[144:147], v[168:171], v[96:99]
	v_mfma_f32_16x16x32_bf16 v[100:103], v[152:155], v[168:171], v[100:103]
	v_mfma_f32_16x16x32_bf16 v[80:83], v[144:147], v[176:179], v[80:83]
	v_mfma_f32_16x16x32_bf16 v[84:87], v[152:155], v[176:179], v[84:87]
	v_mfma_f32_16x16x32_bf16 v[64:67], v[144:147], v[184:187], v[64:67]
	v_mfma_f32_16x16x32_bf16 v[68:71], v[152:155], v[184:187], v[68:71]
	v_mfma_f32_16x16x32_bf16 v[112:115], v[148:151], v[164:167], v[112:115]
	v_mfma_f32_16x16x32_bf16 v[116:119], v[156:159], v[164:167], v[116:119]
	v_mfma_f32_16x16x32_bf16 v[96:99], v[148:151], v[172:175], v[96:99]
	v_mfma_f32_16x16x32_bf16 v[100:103], v[156:159], v[172:175], v[100:103]
	v_mfma_f32_16x16x32_bf16 v[80:83], v[148:151], v[180:183], v[80:83]
	v_mfma_f32_16x16x32_bf16 v[84:87], v[156:159], v[180:183], v[84:87]
	v_mfma_f32_16x16x32_bf16 v[64:67], v[148:151], v[188:191], v[64:67]
	v_mfma_f32_16x16x32_bf16 v[68:71], v[156:159], v[188:191], v[68:71]
	s_barrier
	s_setprio 0
	s_add_i32 s65, s65, s38
	v_lshl_add_u64 v[202:203], s[28:29], 0, v[204:205]
	s_mov_b32 m0, s65
	ds_read_b128 v[160:163], v217 offset:16384
	ds_read_b128 v[164:167], v217 offset:17408
	ds_read_b128 v[168:171], v217 offset:18432
	ds_read_b128 v[172:175], v217 offset:19456
	ds_read_b128 v[176:179], v217 offset:20480
	ds_read_b128 v[180:183], v217 offset:21504
	ds_read_b128 v[184:187], v217 offset:22528
	ds_read_b128 v[188:191], v217 offset:23552
	global_load_lds_dwordx4 v[202:203], off
	s_add_i32 m0, s65, 0x2000
	s_add_u32 s68, s28, 0x200000
	v_lshl_add_u64 v[206:207], s[28:29], 0, v[196:197]
	s_addc_u32 s69, s29, 0
	s_add_i32 s65, s75, s38
	global_load_lds_dwordx4 v[206:207], off
	v_lshl_add_u64 v[208:209], s[68:69], 0, v[204:205]
	s_mov_b32 m0, s65
	v_lshl_add_u64 v[210:211], s[34:35], 0, v[194:195]
	global_load_lds_dwordx4 v[208:209], off
	v_lshl_add_u64 v[208:209], s[68:69], 0, v[196:197]
	s_add_i32 m0, s65, 0x2000
	s_nop 0
	global_load_lds_dwordx4 v[208:209], off
	v_lshl_add_u64 v[208:209], s[34:35], 0, v[192:193]
	s_mov_b32 m0, s44
	s_nop 0
	global_load_lds_dwordx4 v[208:209], off
	s_mov_b32 m0, s45
	s_nop 0
	global_load_lds_dwordx4 v[210:211], off
	s_waitcnt vmcnt(8)
	s_waitcnt lgkmcnt(0)
	s_setprio 1
	s_barrier
; #define PG8_STAGE(bufoff, gbase, voff) do { _Pragma("unroll") for (int _i = 0; _i < 2; ++_i) \
;         __builtin_amdgcn_global_load_lds((const unsigned*)((const char*)(gbase) + (voff)[_i]), (PG8_LAS unsigned*)(lds + (bufoff) + ldsw + _i * 8192), 16, 0, 0); } while (0)
; #define PG8_LDA(dst, b, h) do { _Pragma("unroll") for (int m = 0; m < 4; ++m) _Pragma("unroll") for (int k = 0; k < 2; ++k) dst[m][k] = *(const PG8_LAS bf16x8*)(lds + PG8_SA(b, h) + aoff + m * 2048 + k * 1024); } while (0)
; #define PG8_LDB(dst, b, h) do { _Pragma("unroll") for (int n = 0; n < 2; ++n) _Pragma("unroll") for (int k = 0; k < 2; ++k) dst[n][k] = *(const PG8_LAS bf16x8*)(lds + PG8_SB(b, h) + boff + n * 2048 + k * 1024); } while (0)
; #define PG8_MMA(ai, bj, At, Bt) do { __builtin_amdgcn_s_setprio(1); _Pragma("unroll") for (int m = 0; m < 4; ++m) _Pragma("unroll") for (int n = 0; n < 2; ++n) _Pragma("unroll") for (int k = 0; k < 2; ++k) \
;         acc[ai][bj][m][n] = __builtin_amdgcn_mfma_f32_16x16x32_bf16(Bt[n][k], At[m][k], acc[ai][bj][m][n], 0, 0, 0); __builtin_amdgcn_s_setprio(0); } while (0)
; #define PG8_WAIT_V(n) asm volatile("s_waitcnt vmcnt(" #n ")" ::: "memory")
; #define PG8_WAIT_L(n) asm volatile("s_waitcnt lgkmcnt(" #n ")" ::: "memory")
; #define PG8_BAR __builtin_amdgcn_s_barrier()
; #define PG8_SCHED __builtin_amdgcn_sched_barrier(0)
; template <class Epi, class Sched, bool ALIGN_EPI = false, bool SP2 = false>
; __device__ __forceinline__ void gemm_phase(PG8_LAS unsigned char* lds, const Gemm g, const Sched& S, const Epi& E, const int tid) {
;     ...
;             PG8_LDA(At, 0, 1); PG8_STAGE(PG8_SB(0, 0), b2, voffB); PG8_STAGE(PG8_SB(0, 1), b2 + hstep, voffB); PG8_STAGE(PG8_SA(0, 0), a2, voffA);
;             PG8_WAIT_V(8); PG8_WAIT_L(0); PG8_BAR; PG8_MMA(1, 0, At, B0); PG8_MMA(1, 1, At, B1); PG8_BAR; PG8_SCHED;
;             PG8_LDB(B0, 1, 0); PG8_LDB(B1, 1, 1); PG8_SCHED; PG8_LDA(At, 1, 0); PG8_STAGE(PG8_SA(0, 1), a2 + hstep, voffA);
;             PG8_WAIT_V(8); PG8_WAIT_L(0); PG8_BAR; PG8_MMA(0, 0, At, B0); PG8_MMA(0, 1, At, B1); PG8_BAR; PG8_SCHED;
	v_mfma_f32_16x16x32_bf16 v[52:55], v[128:131], v[160:163], v[52:55]
	v_mfma_f32_16x16x32_bf16 v[56:59], v[136:139], v[160:163], v[56:59]
	v_mfma_f32_16x16x32_bf16 v[24:27], v[128:131], v[168:171], v[24:27]
	v_mfma_f32_16x16x32_bf16 v[60:63], v[136:139], v[168:171], v[60:63]
	v_mfma_f32_16x16x32_bf16 v[28:31], v[128:131], v[176:179], v[28:31]
	v_mfma_f32_16x16x32_bf16 v[32:35], v[136:139], v[176:179], v[32:35]
	v_mfma_f32_16x16x32_bf16 v[8:11], v[128:131], v[184:187], v[8:11]
	v_mfma_f32_16x16x32_bf16 v[12:15], v[136:139], v[184:187], v[12:15]
	v_mfma_f32_16x16x32_bf16 v[52:55], v[132:135], v[164:167], v[52:55]
	v_mfma_f32_16x16x32_bf16 v[56:59], v[140:143], v[164:167], v[56:59]
	v_mfma_f32_16x16x32_bf16 v[24:27], v[132:135], v[172:175], v[24:27]
	v_mfma_f32_16x16x32_bf16 v[60:63], v[140:143], v[172:175], v[60:63]
	v_mfma_f32_16x16x32_bf16 v[28:31], v[132:135], v[180:183], v[28:31]
	v_mfma_f32_16x16x32_bf16 v[32:35], v[140:143], v[180:183], v[32:35]
	v_mfma_f32_16x16x32_bf16 v[8:11], v[132:135], v[188:191], v[8:11]
	v_mfma_f32_16x16x32_bf16 v[12:15], v[140:143], v[188:191], v[12:15]
	s_setprio 0
	s_setprio 1
	v_mfma_f32_16x16x32_bf16 v[36:39], v[144:147], v[160:163], v[36:39]
	v_mfma_f32_16x16x32_bf16 v[40:43], v[152:155], v[160:163], v[40:43]
	v_mfma_f32_16x16x32_bf16 v[44:47], v[144:147], v[168:171], v[44:47]
	v_mfma_f32_16x16x32_bf16 v[48:51], v[152:155], v[168:171], v[48:51]
	v_mfma_f32_16x16x32_bf16 v[16:19], v[144:147], v[176:179], v[16:19]
	v_mfma_f32_16x16x32_bf16 v[20:23], v[152:155], v[176:179], v[20:23]
	v_mfma_f32_16x16x32_bf16 v[0:3], v[144:147], v[184:187], v[0:3]
	v_mfma_f32_16x16x32_bf16 v[4:7], v[152:155], v[184:187], v[4:7]
	v_mfma_f32_16x16x32_bf16 v[36:39], v[148:151], v[164:167], v[36:39]
	v_mfma_f32_16x16x32_bf16 v[40:43], v[156:159], v[164:167], v[40:43]
	v_mfma_f32_16x16x32_bf16 v[44:47], v[148:151], v[172:175], v[44:47]
	v_mfma_f32_16x16x32_bf16 v[48:51], v[156:159], v[172:175], v[48:51]
	v_mfma_f32_16x16x32_bf16 v[16:19], v[148:151], v[180:183], v[16:19]
	v_mfma_f32_16x16x32_bf16 v[20:23], v[156:159], v[180:183], v[20:23]
	v_mfma_f32_16x16x32_bf16 v[0:3], v[148:151], v[188:191], v[0:3]
	v_mfma_f32_16x16x32_bf16 v[4:7], v[156:159], v[188:191], v[4:7]
	s_barrier
	s_setprio 0
	s_add_i32 s65, 0, 0x18000
	s_add_i32 s68, 0, 0x1c000
	v_add_u32_e32 v140, s65, v216
	v_add_u32_e32 v156, s68, v216
	ds_read_b128 v[128:131], v140
	ds_read_b128 v[132:135], v140 offset:1024
	ds_read_b128 v[136:139], v140 offset:2048
	ds_read_b128 v[140:143], v140 offset:3072
	ds_read_b128 v[144:147], v156
	ds_read_b128 v[148:151], v156 offset:1024
	ds_read_b128 v[152:155], v156 offset:2048
	ds_read_b128 v[156:159], v156 offset:3072
	s_add_u32 s34, s34, 0x200000
	s_addc_u32 s35, s35, 0
	s_mov_b32 m0, s46
	v_lshl_add_u64 v[212:213], s[34:35], 0, v[192:193]
	ds_read_b128 v[160:163], v217 offset:32768
	ds_read_b128 v[164:167], v217 offset:33792
	ds_read_b128 v[168:171], v217 offset:34816
	ds_read_b128 v[172:175], v217 offset:35840
	ds_read_b128 v[176:179], v217 offset:36864
	ds_read_b128 v[180:183], v217 offset:37888
	ds_read_b128 v[184:187], v217 offset:38912
	ds_read_b128 v[188:191], v217 offset:39936
	global_load_lds_dwordx4 v[212:213], off
	v_lshl_add_u64 v[212:213], s[34:35], 0, v[194:195]
	s_mov_b32 m0, s47
	s_nop 0
	global_load_lds_dwordx4 v[212:213], off
	s_waitcnt vmcnt(8)
	s_waitcnt lgkmcnt(0)
	s_setprio 1
	s_barrier
	v_mfma_f32_16x16x32_bf16 v[120:123], v[128:131], v[160:163], v[120:123]
	v_mfma_f32_16x16x32_bf16 v[124:127], v[136:139], v[160:163], v[124:127]
	v_mfma_f32_16x16x32_bf16 v[104:107], v[128:131], v[168:171], v[104:107]
	v_mfma_f32_16x16x32_bf16 v[108:111], v[136:139], v[168:171], v[108:111]
	v_mfma_f32_16x16x32_bf16 v[88:91], v[128:131], v[176:179], v[88:91]
	v_mfma_f32_16x16x32_bf16 v[92:95], v[136:139], v[176:179], v[92:95]
	v_mfma_f32_16x16x32_bf16 v[72:75], v[128:131], v[184:187], v[72:75]
	v_mfma_f32_16x16x32_bf16 v[76:79], v[136:139], v[184:187], v[76:79]
	v_mfma_f32_16x16x32_bf16 v[120:123], v[132:135], v[164:167], v[120:123]
	v_mfma_f32_16x16x32_bf16 v[124:127], v[140:143], v[164:167], v[124:127]
	v_mfma_f32_16x16x32_bf16 v[104:107], v[132:135], v[172:175], v[104:107]
	v_mfma_f32_16x16x32_bf16 v[108:111], v[140:143], v[172:175], v[108:111]
	v_mfma_f32_16x16x32_bf16 v[88:91], v[132:135], v[180:183], v[88:91]
	v_mfma_f32_16x16x32_bf16 v[92:95], v[140:143], v[180:183], v[92:95]
	v_mfma_f32_16x16x32_bf16 v[72:75], v[132:135], v[188:191], v[72:75]
	v_mfma_f32_16x16x32_bf16 v[76:79], v[140:143], v[188:191], v[76:79]
	s_setprio 0
	s_setprio 1
	v_mfma_f32_16x16x32_bf16 v[112:115], v[144:147], v[160:163], v[112:115]
	v_mfma_f32_16x16x32_bf16 v[116:119], v[152:155], v[160:163], v[116:119]
	v_mfma_f32_16x16x32_bf16 v[96:99], v[144:147], v[168:171], v[96:99]
	v_mfma_f32_16x16x32_bf16 v[100:103], v[152:155], v[168:171], v[100:103]
	v_mfma_f32_16x16x32_bf16 v[80:83], v[144:147], v[176:179], v[80:83]
	v_mfma_f32_16x16x32_bf16 v[84:87], v[152:155], v[176:179], v[84:87]
	v_mfma_f32_16x16x32_bf16 v[64:67], v[144:147], v[184:187], v[64:67]
	v_mfma_f32_16x16x32_bf16 v[68:71], v[152:155], v[184:187], v[68:71]
	v_mfma_f32_16x16x32_bf16 v[112:115], v[148:151], v[164:167], v[112:115]
	v_mfma_f32_16x16x32_bf16 v[116:119], v[156:159], v[164:167], v[116:119]
	v_mfma_f32_16x16x32_bf16 v[96:99], v[148:151], v[172:175], v[96:99]
	v_mfma_f32_16x16x32_bf16 v[100:103], v[156:159], v[172:175], v[100:103]
	v_mfma_f32_16x16x32_bf16 v[80:83], v[148:151], v[180:183], v[80:83]
	v_mfma_f32_16x16x32_bf16 v[84:87], v[156:159], v[180:183], v[84:87]
	v_mfma_f32_16x16x32_bf16 v[64:67], v[148:151], v[188:191], v[64:67]
	v_mfma_f32_16x16x32_bf16 v[68:71], v[156:159], v[188:191], v[68:71]
	s_barrier
; #define PG8_STAGE(bufoff, gbase, voff) do { _Pragma("unroll") for (int _i = 0; _i < 2; ++_i) \
;         __builtin_amdgcn_global_load_lds((const unsigned*)((const char*)(gbase) + (voff)[_i]), (PG8_LAS unsigned*)(lds + (bufoff) + ldsw + _i * 8192), 16, 0, 0); } while (0)
; #define PG8_LDA(dst, b, h) do { _Pragma("unroll") for (int m = 0; m < 4; ++m) _Pragma("unroll") for (int k = 0; k < 2; ++k) dst[m][k] = *(const PG8_LAS bf16x8*)(lds + PG8_SA(b, h) + aoff + m * 2048 + k * 1024); } while (0)
; #define PG8_BAR __builtin_amdgcn_s_barrier()
; template <class Epi, class Sched, bool ALIGN_EPI = false, bool SP2 = false>
; __device__ __forceinline__ void gemm_phase(PG8_LAS unsigned char* lds, const Gemm g, const Sched& S, const Epi& E, const int tid) {
;     ...
;             PG8_LDA(At, 1, 1); PG8_STAGE(PG8_SB(1, 0), b3, voffB); PG8_STAGE(PG8_SB(1, 1), b3 + hstep, voffB); PG8_STAGE(PG8_SA(1, 0), a3, voffA);
;             PG8_WAIT_V(8); PG8_WAIT_L(0); PG8_BAR; PG8_MMA(1, 0, At, B0); PG8_MMA(1, 1, At, B1); PG8_BAR; PG8_SCHED;
;             } else {
;             PG8_LDB(B0, 0, 0); PG8_SCHED; PG8_LDA(At, 0, 0); PG8_STAGE(PG8_SA(1, 1), a1 + hstep, voffA);
;             PG8_WAIT_L(8); PG8_BAR; PG8_WAIT_L(0); PG8_MMA(0, 0, At, B0); PG8_BAR; PG8_SCHED;
;             PG8_LDB(B1, 0, 1); PG8_STAGE(PG8_SB(0, 0), b2, voffB);
;             PG8_BAR; PG8_WAIT_L(0); PG8_MMA(0, 1, At, B1); PG8_BAR;
;             PG8_LDA(At, 0, 1); PG8_STAGE(PG8_SA(0, 0), a2, voffA);
;             PG8_BAR; PG8_WAIT_L(0); PG8_MMA(1, 0, At, B0); PG8_BAR; PG8_SCHED;
;             PG8_STAGE(PG8_SB(0, 1), b2 + hstep, voffB);
;             PG8_WAIT_V(6); PG8_BAR; PG8_MMA(1, 1, At, B1); PG8_BAR;
;             PG8_LDB(B0, 1, 0); PG8_SCHED; PG8_LDA(At, 1, 0); PG8_STAGE(PG8_SA(0, 1), a2 + hstep, voffA);
;             PG8_WAIT_L(8); PG8_BAR; PG8_WAIT_L(0); PG8_MMA(0, 0, At, B0); PG8_BAR; PG8_SCHED;
;             PG8_LDB(B1, 1, 1); PG8_STAGE(PG8_SB(1, 0), b3, voffB);
;             PG8_BAR; PG8_WAIT_L(0); PG8_MMA(0, 1, At, B1); PG8_BAR;
;             PG8_LDA(At, 1, 1); PG8_STAGE(PG8_SA(1, 0), a3, voffA);
;             PG8_BAR; PG8_WAIT_L(0); PG8_MMA(1, 0, At, B0); PG8_BAR; PG8_SCHED;
;             PG8_STAGE(PG8_SB(1, 1), b3 + hstep, voffB);
;             PG8_WAIT_V(6); PG8_BAR; PG8_MMA(1, 1, At, B1); PG8_BAR;
;             }
;         }
;         if constexpr (ALIGN_EPI) { if (wr == 0) PG8_BAR; }
	s_setprio 0
	s_add_i32 s34, s65, s38
	v_lshl_add_u64 v[202:203], v[202:203], 0, s[70:71]
	s_mov_b32 m0, s34
	ds_read_b128 v[160:163], v217 offset:49152
	ds_read_b128 v[164:167], v217 offset:50176
	ds_read_b128 v[168:171], v217 offset:51200
	ds_read_b128 v[172:175], v217 offset:52224
	ds_read_b128 v[176:179], v217 offset:53248
	ds_read_b128 v[180:183], v217 offset:54272
	ds_read_b128 v[184:187], v217 offset:55296
	ds_read_b128 v[188:191], v217 offset:56320
	global_load_lds_dwordx4 v[202:203], off
	s_add_i32 m0, s34, 0x2000
	s_add_u32 s28, s28, 0x200080
	v_lshl_add_u64 v[202:203], v[206:207], 0, s[70:71]
	s_addc_u32 s29, s29, 0
	s_add_i32 s34, s68, s38
	global_load_lds_dwordx4 v[202:203], off
	v_lshl_add_u64 v[202:203], s[28:29], 0, v[204:205]
	s_mov_b32 m0, s34
	s_nop 0
	global_load_lds_dwordx4 v[202:203], off
	v_lshl_add_u64 v[202:203], s[28:29], 0, v[196:197]
	s_add_i32 m0, s34, 0x2000
	s_nop 0
	global_load_lds_dwordx4 v[202:203], off
	v_lshl_add_u64 v[202:203], v[208:209], 0, s[70:71]
	s_mov_b32 m0, s49
	s_nop 0
	global_load_lds_dwordx4 v[202:203], off
	v_lshl_add_u64 v[202:203], v[210:211], 0, s[70:71]
	s_mov_b32 m0, s50
	s_nop 0
	global_load_lds_dwordx4 v[202:203], off
	s_waitcnt vmcnt(8)
	s_waitcnt lgkmcnt(0)
	s_setprio 1
	s_barrier
	v_mfma_f32_16x16x32_bf16 v[52:55], v[128:131], v[160:163], v[52:55]
	v_mfma_f32_16x16x32_bf16 v[56:59], v[136:139], v[160:163], v[56:59]
	v_mfma_f32_16x16x32_bf16 v[24:27], v[128:131], v[168:171], v[24:27]
	v_mfma_f32_16x16x32_bf16 v[60:63], v[136:139], v[168:171], v[60:63]
	v_mfma_f32_16x16x32_bf16 v[28:31], v[128:131], v[176:179], v[28:31]
	v_mfma_f32_16x16x32_bf16 v[32:35], v[136:139], v[176:179], v[32:35]
	v_mfma_f32_16x16x32_bf16 v[8:11], v[128:131], v[184:187], v[8:11]
	v_mfma_f32_16x16x32_bf16 v[12:15], v[136:139], v[184:187], v[12:15]
	v_mfma_f32_16x16x32_bf16 v[52:55], v[132:135], v[164:167], v[52:55]
	v_mfma_f32_16x16x32_bf16 v[56:59], v[140:143], v[164:167], v[56:59]
	v_mfma_f32_16x16x32_bf16 v[24:27], v[132:135], v[172:175], v[24:27]
	v_mfma_f32_16x16x32_bf16 v[60:63], v[140:143], v[172:175], v[60:63]
	v_mfma_f32_16x16x32_bf16 v[28:31], v[132:135], v[180:183], v[28:31]
	v_mfma_f32_16x16x32_bf16 v[32:35], v[140:143], v[180:183], v[32:35]
	v_mfma_f32_16x16x32_bf16 v[8:11], v[132:135], v[188:191], v[8:11]
	v_mfma_f32_16x16x32_bf16 v[12:15], v[140:143], v[188:191], v[12:15]
	s_setprio 0
	s_setprio 1
	v_mfma_f32_16x16x32_bf16 v[36:39], v[144:147], v[160:163], v[36:39]
	v_mfma_f32_16x16x32_bf16 v[40:43], v[152:155], v[160:163], v[40:43]
	v_mfma_f32_16x16x32_bf16 v[44:47], v[144:147], v[168:171], v[44:47]
	v_mfma_f32_16x16x32_bf16 v[48:51], v[152:155], v[168:171], v[48:51]
	v_mfma_f32_16x16x32_bf16 v[16:19], v[144:147], v[176:179], v[16:19]
	v_mfma_f32_16x16x32_bf16 v[20:23], v[152:155], v[176:179], v[20:23]
	v_mfma_f32_16x16x32_bf16 v[0:3], v[144:147], v[184:187], v[0:3]
	v_mfma_f32_16x16x32_bf16 v[4:7], v[152:155], v[184:187], v[4:7]
	v_mfma_f32_16x16x32_bf16 v[36:39], v[148:151], v[164:167], v[36:39]
	v_mfma_f32_16x16x32_bf16 v[40:43], v[156:159], v[164:167], v[40:43]
	v_mfma_f32_16x16x32_bf16 v[44:47], v[148:151], v[172:175], v[44:47]
	v_mfma_f32_16x16x32_bf16 v[48:51], v[156:159], v[172:175], v[48:51]
	v_mfma_f32_16x16x32_bf16 v[16:19], v[148:151], v[180:183], v[16:19]
	v_mfma_f32_16x16x32_bf16 v[20:23], v[156:159], v[180:183], v[20:23]
	v_mfma_f32_16x16x32_bf16 v[0:3], v[148:151], v[188:191], v[0:3]
	v_mfma_f32_16x16x32_bf16 v[4:7], v[156:159], v[188:191], v[4:7]
	s_barrier
	s_setprio 0
	s_add_i32 s64, s64, 2
	s_add_u32 s30, s30, 0x100
	s_addc_u32 s31, s31, 0
	s_add_u32 s55, s55, 0x100
	s_addc_u32 s62, s62, 0
	s_cmpk_gt_u32 s64, 0x7d
	s_cbranch_scc0 .LBB0_1198
	s_and_b64 vcc, exec, s[14:15]
	s_cbranch_vccz .LBB0_1201
	s_barrier

; #define PG8_STAGE(bufoff, gbase, voff) do { _Pragma("unroll") for (int _i = 0; _i < 2; ++_i) \
;         __builtin_amdgcn_global_load_lds((const unsigned*)((const char*)(gbase) + (voff)[_i]), (PG8_LAS unsigned*)(lds + (bufoff) + ldsw + _i * 8192), 16, 0, 0); } while (0)
; #define PG8_LDA(dst, b, h) do { _Pragma("unroll") for (int m = 0; m < 4; ++m) _Pragma("unroll") for (int k = 0; k < 2; ++k) dst[m][k] = *(const PG8_LAS bf16x8*)(lds + PG8_SA(b, h) + aoff + m * 2048 + k * 1024); } while (0)
; #define PG8_LDB(dst, b, h) do { _Pragma("unroll") for (int n = 0; n < 2; ++n) _Pragma("unroll") for (int k = 0; k < 2; ++k) dst[n][k] = *(const PG8_LAS bf16x8*)(lds + PG8_SB(b, h) + boff + n * 2048 + k * 1024); } while (0)
; #define PG8_WAIT_V(n) asm volatile("s_waitcnt vmcnt(" #n ")" ::: "memory")
; #define PG8_WAIT_L(n) asm volatile("s_waitcnt lgkmcnt(" #n ")" ::: "memory")
; #define PG8_BAR __builtin_amdgcn_s_barrier()
; #define PG8_SCHED __builtin_amdgcn_sched_barrier(0)
; template <class Epi, class Sched, bool ALIGN_EPI = false, bool SP2 = false>
; __device__ __forceinline__ void gemm_phase(PG8_LAS unsigned char* lds, const Gemm g, const Sched& S, const Epi& E, const int tid) {
;     ...
;         const bool has_next = S.next(ui + 1, nxt);
;         const char* nA = has_next ? (const char*)g.A + (size_t)nxt.pm * tstep : cA; const char* nB = has_next ? (const char*)g.Bt + (size_t)nxt.pn * tstep : cB;
;         for (int t = 0; t < nt; t += 2) {
;             const bool last = (t == nt - 2);
;             const char* a1 = cA + (size_t)(t + 1) * kstep;
;             const char* a2 = last ? nA : cA + (size_t)(t + 2) * kstep; const char* b2 = last ? nB : cB + (size_t)(t + 2) * kstep;
;             const char* a3 = a2 + kstep; const char* b3 = b2 + kstep;
;             if (last && has_next) S.a_ready(nxt);
;             if constexpr (SP2) {
;             PG8_LDB(B0, 0, 0); PG8_LDB(B1, 0, 1); PG8_SCHED; PG8_LDA(At, 0, 0); PG8_STAGE(PG8_SA(1, 1), a1 + hstep, voffA);
;             PG8_WAIT_V(8); PG8_WAIT_L(0); PG8_BAR; PG8_MMA(0, 0, At, B0); PG8_MMA(0, 1, At, B1); PG8_BAR; PG8_SCHED;
;             PG8_LDA(At, 0, 1); PG8_STAGE(PG8_SB(0, 0), b2, voffB); PG8_STAGE(PG8_SB(0, 1), b2 + hstep, voffB); PG8_STAGE(PG8_SA(0, 0), a2, voffA);
;             PG8_WAIT_V(8); PG8_WAIT_L(0); PG8_BAR; PG8_MMA(1, 0, At, B0); PG8_MMA(1, 1, At, B1); PG8_BAR; PG8_SCHED;
.LBB0_1383:
	s_ashr_i32 s27, s26, 31
	s_lshl_b64 s[28:29], s[26:27], 20
	s_add_u32 s28, s6, s28
	s_addc_u32 s29, s7, s29
	s_and_b64 s[30:31], s[4:5], exec
	s_cselect_b32 s27, s29, s43
	s_cselect_b32 s35, s28, s42
	s_ashr_i32 s25, s24, 31
	s_lshl_b64 s[30:31], s[24:25], 20
	s_add_u32 s30, s49, s30
	s_addc_u32 s31, s50, s31
	s_and_b64 s[46:47], s[4:5], exec
	s_cselect_b32 s25, s31, s45
	s_cselect_b32 s37, s30, s44
	s_add_u32 s42, s42, 0x80080
	s_addc_u32 s43, s43, 0
	s_add_u32 s40, s44, 0x100
	s_addc_u32 s69, s45, 0
	s_mov_b32 s75, -2
	s_waitcnt lgkmcnt(0)
	s_add_u32 s44, s42, 0xfff80080
	s_addc_u32 s45, s43, -1
	s_add_i32 s76, 0, 0x10000
	s_cmp_eq_u32 s75, 28
	s_cselect_b32 s47, s27, s45
	s_cselect_b32 s46, s35, s44
	s_cselect_b32 s45, s25, s69
	s_cselect_b32 s44, s37, s40
	s_add_i32 s78, 0, 0x14000
	v_add_u32_e32 v68, s76, v175
	v_add_u32_e32 v156, s78, v175
	ds_read_b128 v[48:51], v68
	ds_read_b128 v[52:55], v68 offset:1024
	ds_read_b128 v[64:67], v68 offset:2048
	ds_read_b128 v[68:71], v68 offset:3072
	ds_read_b128 v[144:147], v156
	ds_read_b128 v[148:151], v156 offset:1024
	ds_read_b128 v[152:155], v156 offset:2048
	ds_read_b128 v[156:159], v156 offset:3072
	v_lshl_add_u64 v[176:177], s[42:43], 0, v[166:167]
	s_add_i32 m0, s52, 0xc000
	ds_read_b128 v[170:173], v179
	ds_read_b128 v[180:183], v179 offset:1024
	ds_read_b128 v[184:187], v179 offset:2048
	ds_read_b128 v[188:191], v179 offset:3072
	ds_read_b128 v[192:195], v179 offset:4096
	ds_read_b128 v[196:199], v179 offset:5120
	ds_read_b128 v[200:203], v179 offset:6144
	ds_read_b128 v[206:209], v179 offset:7168
	global_load_lds_dwordx4 v[176:177], off
	v_lshl_add_u64 v[176:177], s[42:43], 0, v[168:169]
	s_add_i32 m0, s52, 0xe000
	s_nop 0
	global_load_lds_dwordx4 v[176:177], off
	s_waitcnt vmcnt(24)
	s_waitcnt lgkmcnt(0)
	s_setprio 1
	s_barrier
	v_mfma_f32_16x16x32_bf16 v[140:143], v[48:51], v[170:173], 0
	v_mfma_f32_16x16x32_bf16 v[136:139], v[64:67], v[170:173], 0
	v_mfma_f32_16x16x32_bf16 v[124:127], v[48:51], v[184:187], 0
	v_mfma_f32_16x16x32_bf16 v[120:123], v[64:67], v[184:187], 0
	v_mfma_f32_16x16x32_bf16 v[108:111], v[48:51], v[192:195], 0
	v_mfma_f32_16x16x32_bf16 v[104:107], v[64:67], v[192:195], 0
	v_mfma_f32_16x16x32_bf16 v[92:95], v[48:51], v[200:203], 0
	v_mfma_f32_16x16x32_bf16 v[88:91], v[64:67], v[200:203], 0
	v_mfma_f32_16x16x32_bf16 v[140:143], v[52:55], v[180:183], v[140:143]
	v_mfma_f32_16x16x32_bf16 v[136:139], v[68:71], v[180:183], v[136:139]
	v_mfma_f32_16x16x32_bf16 v[124:127], v[52:55], v[188:191], v[124:127]
	v_mfma_f32_16x16x32_bf16 v[120:123], v[68:71], v[188:191], v[120:123]
	v_mfma_f32_16x16x32_bf16 v[108:111], v[52:55], v[196:199], v[108:111]
	v_mfma_f32_16x16x32_bf16 v[104:107], v[68:71], v[196:199], v[104:107]
	v_mfma_f32_16x16x32_bf16 v[92:95], v[52:55], v[206:209], v[92:95]
	v_mfma_f32_16x16x32_bf16 v[88:91], v[68:71], v[206:209], v[88:91]
	s_setprio 0
	s_setprio 1
	v_mfma_f32_16x16x32_bf16 v[132:135], v[144:147], v[170:173], 0
	v_mfma_f32_16x16x32_bf16 v[128:131], v[152:155], v[170:173], 0
	v_mfma_f32_16x16x32_bf16 v[116:119], v[144:147], v[184:187], 0
	v_mfma_f32_16x16x32_bf16 v[112:115], v[152:155], v[184:187], 0
	v_mfma_f32_16x16x32_bf16 v[100:103], v[144:147], v[192:195], 0
	v_mfma_f32_16x16x32_bf16 v[96:99], v[152:155], v[192:195], 0
	v_mfma_f32_16x16x32_bf16 v[84:87], v[144:147], v[200:203], 0
	v_mfma_f32_16x16x32_bf16 v[80:83], v[152:155], v[200:203], 0
	v_mfma_f32_16x16x32_bf16 v[132:135], v[148:151], v[180:183], v[132:135]
	v_mfma_f32_16x16x32_bf16 v[128:131], v[156:159], v[180:183], v[128:131]
	v_mfma_f32_16x16x32_bf16 v[116:119], v[148:151], v[188:191], v[116:119]
	v_mfma_f32_16x16x32_bf16 v[112:115], v[156:159], v[188:191], v[112:115]
	v_mfma_f32_16x16x32_bf16 v[100:103], v[148:151], v[196:199], v[100:103]
	v_mfma_f32_16x16x32_bf16 v[96:99], v[156:159], v[196:199], v[96:99]
	v_mfma_f32_16x16x32_bf16 v[84:87], v[148:151], v[206:209], v[84:87]
	v_mfma_f32_16x16x32_bf16 v[80:83], v[156:159], v[206:209], v[80:83]
	s_barrier
	s_setprio 0
	s_add_i32 s76, s76, s51
	v_lshl_add_u64 v[176:177], s[44:45], 0, v[204:205]
	s_mov_b32 m0, s76
	ds_read_b128 v[170:173], v179 offset:16384
	ds_read_b128 v[180:183], v179 offset:17408
	ds_read_b128 v[184:187], v179 offset:18432
	ds_read_b128 v[188:191], v179 offset:19456
	ds_read_b128 v[192:195], v179 offset:20480
	ds_read_b128 v[196:199], v179 offset:21504
	ds_read_b128 v[200:203], v179 offset:22528
	ds_read_b128 v[206:209], v179 offset:23552
	global_load_lds_dwordx4 v[176:177], off
	s_add_i32 m0, s76, 0x2000
	s_add_u32 s76, s44, 0x80000
	v_lshl_add_u64 v[210:211], s[44:45], 0, v[164:165]
	s_addc_u32 s77, s45, 0
	s_add_i32 s78, s78, s51
	global_load_lds_dwordx4 v[210:211], off
	v_lshl_add_u64 v[212:213], s[76:77], 0, v[204:205]
	s_mov_b32 m0, s78
	v_lshl_add_u64 v[214:215], s[46:47], 0, v[162:163]
	global_load_lds_dwordx4 v[212:213], off
	v_lshl_add_u64 v[212:213], s[76:77], 0, v[164:165]
	s_add_i32 m0, s78, 0x2000
	s_nop 0
	global_load_lds_dwordx4 v[212:213], off
	v_lshl_add_u64 v[212:213], s[46:47], 0, v[160:161]
	s_mov_b32 m0, s52
	s_nop 0
	global_load_lds_dwordx4 v[212:213], off
	s_mov_b32 m0, s0
	s_nop 0
	global_load_lds_dwordx4 v[214:215], off
	s_waitcnt vmcnt(8)
	s_waitcnt lgkmcnt(0)
	s_setprio 1
	s_barrier
; #define PG8_STAGE(bufoff, gbase, voff) do { _Pragma("unroll") for (int _i = 0; _i < 2; ++_i) \
;         __builtin_amdgcn_global_load_lds((const unsigned*)((const char*)(gbase) + (voff)[_i]), (PG8_LAS unsigned*)(lds + (bufoff) + ldsw + _i * 8192), 16, 0, 0); } while (0)
; #define PG8_LDA(dst, b, h) do { _Pragma("unroll") for (int m = 0; m < 4; ++m) _Pragma("unroll") for (int k = 0; k < 2; ++k) dst[m][k] = *(const PG8_LAS bf16x8*)(lds + PG8_SA(b, h) + aoff + m * 2048 + k * 1024); } while (0)
; #define PG8_LDB(dst, b, h) do { _Pragma("unroll") for (int n = 0; n < 2; ++n) _Pragma("unroll") for (int k = 0; k < 2; ++k) dst[n][k] = *(const PG8_LAS bf16x8*)(lds + PG8_SB(b, h) + boff + n * 2048 + k * 1024); } while (0)
; #define PG8_MMA(ai, bj, At, Bt) do { __builtin_amdgcn_s_setprio(1); _Pragma("unroll") for (int m = 0; m < 4; ++m) _Pragma("unroll") for (int n = 0; n < 2; ++n) _Pragma("unroll") for (int k = 0; k < 2; ++k) \
;         acc[ai][bj][m][n] = __builtin_amdgcn_mfma_f32_16x16x32_bf16(Bt[n][k], At[m][k], acc[ai][bj][m][n], 0, 0, 0); __builtin_amdgcn_s_setprio(0); } while (0)
; #define PG8_WAIT_V(n) asm volatile("s_waitcnt vmcnt(" #n ")" ::: "memory")
; #define PG8_WAIT_L(n) asm volatile("s_waitcnt lgkmcnt(" #n ")" ::: "memory")
; #define PG8_BAR __builtin_amdgcn_s_barrier()
; #define PG8_SCHED __builtin_amdgcn_sched_barrier(0)
; template <class Epi, class Sched, bool ALIGN_EPI = false, bool SP2 = false>
; __device__ __forceinline__ void gemm_phase(PG8_LAS unsigned char* lds, const Gemm g, const Sched& S, const Epi& E, const int tid) {
;     ...
;             PG8_WAIT_V(8); PG8_WAIT_L(0); PG8_BAR; PG8_MMA(1, 0, At, B0); PG8_MMA(1, 1, At, B1); PG8_BAR; PG8_SCHED;
;             PG8_LDB(B0, 1, 0); PG8_LDB(B1, 1, 1); PG8_SCHED; PG8_LDA(At, 1, 0); PG8_STAGE(PG8_SA(0, 1), a2 + hstep, voffA);
;             PG8_WAIT_V(8); PG8_WAIT_L(0); PG8_BAR; PG8_MMA(0, 0, At, B0); PG8_MMA(0, 1, At, B1); PG8_BAR; PG8_SCHED;
	v_mfma_f32_16x16x32_bf16 v[76:79], v[48:51], v[170:173], 0
	v_mfma_f32_16x16x32_bf16 v[72:75], v[64:67], v[170:173], 0
	v_mfma_f32_16x16x32_bf16 v[44:47], v[48:51], v[184:187], 0
	v_mfma_f32_16x16x32_bf16 v[40:43], v[64:67], v[184:187], 0
	v_mfma_f32_16x16x32_bf16 v[28:31], v[48:51], v[192:195], 0
	v_mfma_f32_16x16x32_bf16 v[24:27], v[64:67], v[192:195], 0
	v_mfma_f32_16x16x32_bf16 v[12:15], v[48:51], v[200:203], 0
	v_mfma_f32_16x16x32_bf16 v[8:11], v[64:67], v[200:203], 0
	v_mfma_f32_16x16x32_bf16 v[76:79], v[52:55], v[180:183], v[76:79]
	v_mfma_f32_16x16x32_bf16 v[72:75], v[68:71], v[180:183], v[72:75]
	v_mfma_f32_16x16x32_bf16 v[44:47], v[52:55], v[188:191], v[44:47]
	v_mfma_f32_16x16x32_bf16 v[40:43], v[68:71], v[188:191], v[40:43]
	v_mfma_f32_16x16x32_bf16 v[28:31], v[52:55], v[196:199], v[28:31]
	v_mfma_f32_16x16x32_bf16 v[24:27], v[68:71], v[196:199], v[24:27]
	v_mfma_f32_16x16x32_bf16 v[12:15], v[52:55], v[206:209], v[12:15]
	v_mfma_f32_16x16x32_bf16 v[8:11], v[68:71], v[206:209], v[8:11]
	s_setprio 0
	s_setprio 1
	v_mfma_f32_16x16x32_bf16 v[36:39], v[144:147], v[184:187], 0
	v_mfma_f32_16x16x32_bf16 v[32:35], v[152:155], v[184:187], 0
	v_mfma_f32_16x16x32_bf16 v[20:23], v[144:147], v[192:195], 0
	v_mfma_f32_16x16x32_bf16 v[16:19], v[152:155], v[192:195], 0
	v_mfma_f32_16x16x32_bf16 v[4:7], v[144:147], v[200:203], 0
	v_mfma_f32_16x16x32_bf16 v[0:3], v[152:155], v[200:203], 0
	v_mfma_f32_16x16x32_bf16 v[48:51], v[144:147], v[170:173], 0
	v_mfma_f32_16x16x32_bf16 v[52:55], v[152:155], v[170:173], 0
	v_mfma_f32_16x16x32_bf16 v[36:39], v[148:151], v[188:191], v[36:39]
	v_mfma_f32_16x16x32_bf16 v[32:35], v[156:159], v[188:191], v[32:35]
	v_mfma_f32_16x16x32_bf16 v[20:23], v[148:151], v[196:199], v[20:23]
	v_mfma_f32_16x16x32_bf16 v[16:19], v[156:159], v[196:199], v[16:19]
	v_mfma_f32_16x16x32_bf16 v[4:7], v[148:151], v[206:209], v[4:7]
	v_mfma_f32_16x16x32_bf16 v[0:3], v[156:159], v[206:209], v[0:3]
	v_mfma_f32_16x16x32_bf16 v[48:51], v[148:151], v[180:183], v[48:51]
	v_mfma_f32_16x16x32_bf16 v[52:55], v[156:159], v[180:183], v[52:55]
	s_barrier
	s_setprio 0
	s_add_i32 s76, 0, 0x18000
	s_add_i32 s77, 0, 0x1c000
	v_add_u32_e32 v68, s76, v175
	v_add_u32_e32 v156, s77, v175
	ds_read_b128 v[56:59], v68
	ds_read_b128 v[60:63], v68 offset:1024
	ds_read_b128 v[64:67], v68 offset:2048
	ds_read_b128 v[68:71], v68 offset:3072
	ds_read_b128 v[144:147], v156
	ds_read_b128 v[148:151], v156 offset:1024
	ds_read_b128 v[152:155], v156 offset:2048
	ds_read_b128 v[156:159], v156 offset:3072
	s_add_u32 s46, s46, 0x80000
	s_addc_u32 s47, s47, 0
	s_mov_b32 m0, s33
	v_lshl_add_u64 v[216:217], s[46:47], 0, v[160:161]
	ds_read_b128 v[170:173], v179 offset:32768
	ds_read_b128 v[180:183], v179 offset:33792
	ds_read_b128 v[184:187], v179 offset:34816
	ds_read_b128 v[188:191], v179 offset:35840
	ds_read_b128 v[192:195], v179 offset:36864
	ds_read_b128 v[196:199], v179 offset:37888
	ds_read_b128 v[200:203], v179 offset:38912
	ds_read_b128 v[206:209], v179 offset:39936
	global_load_lds_dwordx4 v[216:217], off
	v_lshl_add_u64 v[216:217], s[46:47], 0, v[162:163]
	s_mov_b32 m0, s53
	s_nop 0
	global_load_lds_dwordx4 v[216:217], off
	s_waitcnt vmcnt(8)
	s_waitcnt lgkmcnt(0)
	s_setprio 1
	s_barrier
	v_mfma_f32_16x16x32_bf16 v[140:143], v[56:59], v[170:173], v[140:143]
	v_mfma_f32_16x16x32_bf16 v[136:139], v[64:67], v[170:173], v[136:139]
	v_mfma_f32_16x16x32_bf16 v[124:127], v[56:59], v[184:187], v[124:127]
	v_mfma_f32_16x16x32_bf16 v[120:123], v[64:67], v[184:187], v[120:123]
	v_mfma_f32_16x16x32_bf16 v[108:111], v[56:59], v[192:195], v[108:111]
	v_mfma_f32_16x16x32_bf16 v[104:107], v[64:67], v[192:195], v[104:107]
	v_mfma_f32_16x16x32_bf16 v[92:95], v[56:59], v[200:203], v[92:95]
	v_mfma_f32_16x16x32_bf16 v[88:91], v[64:67], v[200:203], v[88:91]
	v_mfma_f32_16x16x32_bf16 v[140:143], v[60:63], v[180:183], v[140:143]
	v_mfma_f32_16x16x32_bf16 v[136:139], v[68:71], v[180:183], v[136:139]
	v_mfma_f32_16x16x32_bf16 v[124:127], v[60:63], v[188:191], v[124:127]
	v_mfma_f32_16x16x32_bf16 v[120:123], v[68:71], v[188:191], v[120:123]
	v_mfma_f32_16x16x32_bf16 v[108:111], v[60:63], v[196:199], v[108:111]
	v_mfma_f32_16x16x32_bf16 v[104:107], v[68:71], v[196:199], v[104:107]
	v_mfma_f32_16x16x32_bf16 v[92:95], v[60:63], v[206:209], v[92:95]
	v_mfma_f32_16x16x32_bf16 v[88:91], v[68:71], v[206:209], v[88:91]
	s_setprio 0
	s_setprio 1
	v_mfma_f32_16x16x32_bf16 v[132:135], v[144:147], v[170:173], v[132:135]
	v_mfma_f32_16x16x32_bf16 v[128:131], v[152:155], v[170:173], v[128:131]
	v_mfma_f32_16x16x32_bf16 v[116:119], v[144:147], v[184:187], v[116:119]
	v_mfma_f32_16x16x32_bf16 v[112:115], v[152:155], v[184:187], v[112:115]
	v_mfma_f32_16x16x32_bf16 v[100:103], v[144:147], v[192:195], v[100:103]
	v_mfma_f32_16x16x32_bf16 v[96:99], v[152:155], v[192:195], v[96:99]
	v_mfma_f32_16x16x32_bf16 v[84:87], v[144:147], v[200:203], v[84:87]
	v_mfma_f32_16x16x32_bf16 v[80:83], v[152:155], v[200:203], v[80:83]
	v_mfma_f32_16x16x32_bf16 v[132:135], v[148:151], v[180:183], v[132:135]
	v_mfma_f32_16x16x32_bf16 v[128:131], v[156:159], v[180:183], v[128:131]
	v_mfma_f32_16x16x32_bf16 v[116:119], v[148:151], v[188:191], v[116:119]
	v_mfma_f32_16x16x32_bf16 v[112:115], v[156:159], v[188:191], v[112:115]
	v_mfma_f32_16x16x32_bf16 v[100:103], v[148:151], v[196:199], v[100:103]
	v_mfma_f32_16x16x32_bf16 v[96:99], v[156:159], v[196:199], v[96:99]
	v_mfma_f32_16x16x32_bf16 v[84:87], v[148:151], v[206:209], v[84:87]
	v_mfma_f32_16x16x32_bf16 v[80:83], v[156:159], v[206:209], v[80:83]
	s_barrier
; #define PG8_STAGE(bufoff, gbase, voff) do { _Pragma("unroll") for (int _i = 0; _i < 2; ++_i) \
;         __builtin_amdgcn_global_load_lds((const unsigned*)((const char*)(gbase) + (voff)[_i]), (PG8_LAS unsigned*)(lds + (bufoff) + ldsw + _i * 8192), 16, 0, 0); } while (0)
; #define PG8_LDA(dst, b, h) do { _Pragma("unroll") for (int m = 0; m < 4; ++m) _Pragma("unroll") for (int k = 0; k < 2; ++k) dst[m][k] = *(const PG8_LAS bf16x8*)(lds + PG8_SA(b, h) + aoff + m * 2048 + k * 1024); } while (0)
; #define PG8_WAIT_V(n) asm volatile("s_waitcnt vmcnt(" #n ")" ::: "memory")
; #define PG8_WAIT_L(n) asm volatile("s_waitcnt lgkmcnt(" #n ")" ::: "memory")
; #define PG8_BAR __builtin_amdgcn_s_barrier()
; template <class Epi, class Sched, bool ALIGN_EPI = false, bool SP2 = false>
; __device__ __forceinline__ void gemm_phase(PG8_LAS unsigned char* lds, const Gemm g, const Sched& S, const Epi& E, const int tid) {
;     ...
;         for (int t = 0; t < nt; t += 2) {
;             const bool last = (t == nt - 2);
;             const char* a1 = cA + (size_t)(t + 1) * kstep;
;             const char* a2 = last ? nA : cA + (size_t)(t + 2) * kstep; const char* b2 = last ? nB : cB + (size_t)(t + 2) * kstep;
;             const char* a3 = a2 + kstep; const char* b3 = b2 + kstep;
;             if (last && has_next) S.a_ready(nxt);
;             if constexpr (SP2) {
;             PG8_LDB(B0, 0, 0); PG8_LDB(B1, 0, 1); PG8_SCHED; PG8_LDA(At, 0, 0); PG8_STAGE(PG8_SA(1, 1), a1 + hstep, voffA);
;             PG8_WAIT_V(8); PG8_WAIT_L(0); PG8_BAR; PG8_MMA(0, 0, At, B0); PG8_MMA(0, 1, At, B1); PG8_BAR; PG8_SCHED;
;             PG8_LDA(At, 0, 1); PG8_STAGE(PG8_SB(0, 0), b2, voffB); PG8_STAGE(PG8_SB(0, 1), b2 + hstep, voffB); PG8_STAGE(PG8_SA(0, 0), a2, voffA);
;             PG8_WAIT_V(8); PG8_WAIT_L(0); PG8_BAR; PG8_MMA(1, 0, At, B0); PG8_MMA(1, 1, At, B1); PG8_BAR; PG8_SCHED;
;             PG8_LDB(B0, 1, 0); PG8_LDB(B1, 1, 1); PG8_SCHED; PG8_LDA(At, 1, 0); PG8_STAGE(PG8_SA(0, 1), a2 + hstep, voffA);
;             PG8_WAIT_V(8); PG8_WAIT_L(0); PG8_BAR; PG8_MMA(0, 0, At, B0); PG8_MMA(0, 1, At, B1); PG8_BAR; PG8_SCHED;
;             PG8_LDA(At, 1, 1); PG8_STAGE(PG8_SB(1, 0), b3, voffB); PG8_STAGE(PG8_SB(1, 1), b3 + hstep, voffB); PG8_STAGE(PG8_SA(1, 0), a3, voffA);
;             PG8_WAIT_V(8); PG8_WAIT_L(0); PG8_BAR; PG8_MMA(1, 0, At, B0); PG8_MMA(1, 1, At, B1); PG8_BAR; PG8_SCHED;
	s_setprio 0
	s_add_i32 s46, s76, s51
	v_lshl_add_u64 v[176:177], v[176:177], 0, s[70:71]
	s_mov_b32 m0, s46
	ds_read_b128 v[170:173], v179 offset:49152
	ds_read_b128 v[180:183], v179 offset:50176
	ds_read_b128 v[184:187], v179 offset:51200
	ds_read_b128 v[188:191], v179 offset:52224
	ds_read_b128 v[192:195], v179 offset:53248
	ds_read_b128 v[196:199], v179 offset:54272
	ds_read_b128 v[200:203], v179 offset:55296
	ds_read_b128 v[206:209], v179 offset:56320
	global_load_lds_dwordx4 v[176:177], off
	s_add_i32 m0, s46, 0x2000
	s_add_u32 s44, s44, 0x80080
	v_lshl_add_u64 v[176:177], v[210:211], 0, s[70:71]
	s_addc_u32 s45, s45, 0
	s_add_i32 s46, s77, s51
	global_load_lds_dwordx4 v[176:177], off
	v_lshl_add_u64 v[176:177], s[44:45], 0, v[204:205]
	s_mov_b32 m0, s46
	s_nop 0
	global_load_lds_dwordx4 v[176:177], off
	v_lshl_add_u64 v[176:177], s[44:45], 0, v[164:165]
	s_add_i32 m0, s46, 0x2000
	s_nop 0
	global_load_lds_dwordx4 v[176:177], off
	v_lshl_add_u64 v[176:177], v[212:213], 0, s[70:71]
	s_mov_b32 m0, s55
	s_nop 0
	global_load_lds_dwordx4 v[176:177], off
	v_lshl_add_u64 v[176:177], v[214:215], 0, s[70:71]
	s_mov_b32 m0, s62
	s_nop 0
	global_load_lds_dwordx4 v[176:177], off
	s_waitcnt vmcnt(8)
	s_waitcnt lgkmcnt(0)
	s_setprio 1
	s_barrier
	v_mfma_f32_16x16x32_bf16 v[76:79], v[56:59], v[170:173], v[76:79]
	v_mfma_f32_16x16x32_bf16 v[72:75], v[64:67], v[170:173], v[72:75]
	v_mfma_f32_16x16x32_bf16 v[44:47], v[56:59], v[184:187], v[44:47]
	v_mfma_f32_16x16x32_bf16 v[40:43], v[64:67], v[184:187], v[40:43]
	v_mfma_f32_16x16x32_bf16 v[28:31], v[56:59], v[192:195], v[28:31]
	v_mfma_f32_16x16x32_bf16 v[24:27], v[64:67], v[192:195], v[24:27]
	v_mfma_f32_16x16x32_bf16 v[12:15], v[56:59], v[200:203], v[12:15]
	v_mfma_f32_16x16x32_bf16 v[8:11], v[64:67], v[200:203], v[8:11]
	v_mfma_f32_16x16x32_bf16 v[76:79], v[60:63], v[180:183], v[76:79]
	v_mfma_f32_16x16x32_bf16 v[72:75], v[68:71], v[180:183], v[72:75]
	v_mfma_f32_16x16x32_bf16 v[44:47], v[60:63], v[188:191], v[44:47]
	v_mfma_f32_16x16x32_bf16 v[40:43], v[68:71], v[188:191], v[40:43]
	v_mfma_f32_16x16x32_bf16 v[28:31], v[60:63], v[196:199], v[28:31]
	v_mfma_f32_16x16x32_bf16 v[24:27], v[68:71], v[196:199], v[24:27]
	v_mfma_f32_16x16x32_bf16 v[12:15], v[60:63], v[206:209], v[12:15]
	v_mfma_f32_16x16x32_bf16 v[8:11], v[68:71], v[206:209], v[8:11]
	s_setprio 0
	s_setprio 1
	v_mfma_f32_16x16x32_bf16 v[48:51], v[144:147], v[170:173], v[48:51]
	v_mfma_f32_16x16x32_bf16 v[60:63], v[148:151], v[180:183], v[48:51]
	v_mfma_f32_16x16x32_bf16 v[48:51], v[152:155], v[170:173], v[52:55]
	v_mfma_f32_16x16x32_bf16 v[36:39], v[144:147], v[184:187], v[36:39]
	v_mfma_f32_16x16x32_bf16 v[32:35], v[152:155], v[184:187], v[32:35]
	v_mfma_f32_16x16x32_bf16 v[20:23], v[144:147], v[192:195], v[20:23]
	v_mfma_f32_16x16x32_bf16 v[16:19], v[152:155], v[192:195], v[16:19]
	v_mfma_f32_16x16x32_bf16 v[4:7], v[144:147], v[200:203], v[4:7]
	v_mfma_f32_16x16x32_bf16 v[0:3], v[152:155], v[200:203], v[0:3]
	v_mfma_f32_16x16x32_bf16 v[56:59], v[156:159], v[180:183], v[48:51]
	v_mfma_f32_16x16x32_bf16 v[36:39], v[148:151], v[188:191], v[36:39]
	v_mfma_f32_16x16x32_bf16 v[32:35], v[156:159], v[188:191], v[32:35]
	v_mfma_f32_16x16x32_bf16 v[20:23], v[148:151], v[196:199], v[20:23]
	v_mfma_f32_16x16x32_bf16 v[16:19], v[156:159], v[196:199], v[16:19]
	v_mfma_f32_16x16x32_bf16 v[4:7], v[148:151], v[206:209], v[4:7]
	v_mfma_f32_16x16x32_bf16 v[0:3], v[156:159], v[206:209], v[0:3]
	s_barrier
	s_setprio 0
	s_add_i32 s75, s75, 2
	s_add_u32 s42, s42, 0x100
	s_addc_u32 s43, s43, 0
	s_add_u32 s40, s40, 0x100
	s_addc_u32 s69, s69, 0
.LBB0_1384:
	s_add_u32 s44, s42, 0xfff80080
	s_addc_u32 s45, s43, -1
	s_add_i32 s76, 0, 0x10000
	s_cmp_eq_u32 s75, 28
	s_cselect_b32 s47, s27, s45
	s_cselect_b32 s46, s35, s44
	s_cselect_b32 s45, s25, s69
	s_cselect_b32 s44, s37, s40
	s_add_i32 s78, 0, 0x14000
	v_add_u32_e32 v68, s76, v175
	v_add_u32_e32 v156, s78, v175
	ds_read_b128 v[48:51], v68
	ds_read_b128 v[52:55], v68 offset:1024
	ds_read_b128 v[64:67], v68 offset:2048
	ds_read_b128 v[68:71], v68 offset:3072
	ds_read_b128 v[144:147], v156
	ds_read_b128 v[148:151], v156 offset:1024
	ds_read_b128 v[152:155], v156 offset:2048
	ds_read_b128 v[156:159], v156 offset:3072
	v_lshl_add_u64 v[176:177], s[42:43], 0, v[166:167]
	s_add_i32 m0, s52, 0xc000
	ds_read_b128 v[170:173], v179
	ds_read_b128 v[180:183], v179 offset:1024
	ds_read_b128 v[184:187], v179 offset:2048
	ds_read_b128 v[188:191], v179 offset:3072
	ds_read_b128 v[192:195], v179 offset:4096
	ds_read_b128 v[196:199], v179 offset:5120
	ds_read_b128 v[200:203], v179 offset:6144
	ds_read_b128 v[206:209], v179 offset:7168
	global_load_lds_dwordx4 v[176:177], off
	v_lshl_add_u64 v[176:177], s[42:43], 0, v[168:169]
	s_add_i32 m0, s52, 0xe000
	s_nop 0
	global_load_lds_dwordx4 v[176:177], off
	s_waitcnt vmcnt(8)
	s_waitcnt lgkmcnt(0)
	s_setprio 1
	s_barrier
; #define PG8_STAGE(bufoff, gbase, voff) do { _Pragma("unroll") for (int _i = 0; _i < 2; ++_i) \
;         __builtin_amdgcn_global_load_lds((const unsigned*)((const char*)(gbase) + (voff)[_i]), (PG8_LAS unsigned*)(lds + (bufoff) + ldsw + _i * 8192), 16, 0, 0); } while (0)
; #define PG8_LDA(dst, b, h) do { _Pragma("unroll") for (int m = 0; m < 4; ++m) _Pragma("unroll") for (int k = 0; k < 2; ++k) dst[m][k] = *(const PG8_LAS bf16x8*)(lds + PG8_SA(b, h) + aoff + m * 2048 + k * 1024); } while (0)
; #define PG8_LDB(dst, b, h) do { _Pragma("unroll") for (int n = 0; n < 2; ++n) _Pragma("unroll") for (int k = 0; k < 2; ++k) dst[n][k] = *(const PG8_LAS bf16x8*)(lds + PG8_SB(b, h) + boff + n * 2048 + k * 1024); } while (0)
; #define PG8_MMA(ai, bj, At, Bt) do { __builtin_amdgcn_s_setprio(1); _Pragma("unroll") for (int m = 0; m < 4; ++m) _Pragma("unroll") for (int n = 0; n < 2; ++n) _Pragma("unroll") for (int k = 0; k < 2; ++k) \
;         acc[ai][bj][m][n] = __builtin_amdgcn_mfma_f32_16x16x32_bf16(Bt[n][k], At[m][k], acc[ai][bj][m][n], 0, 0, 0); __builtin_amdgcn_s_setprio(0); } while (0)
; #define PG8_WAIT_V(n) asm volatile("s_waitcnt vmcnt(" #n ")" ::: "memory")
; #define PG8_WAIT_L(n) asm volatile("s_waitcnt lgkmcnt(" #n ")" ::: "memory")
; #define PG8_BAR __builtin_amdgcn_s_barrier()
; #define PG8_SCHED __builtin_amdgcn_sched_barrier(0)
; template <class Epi, class Sched, bool ALIGN_EPI = false, bool SP2 = false>
; __device__ __forceinline__ void gemm_phase(PG8_LAS unsigned char* lds, const Gemm g, const Sched& S, const Epi& E, const int tid) {
;     ...
;             PG8_WAIT_V(8); PG8_WAIT_L(0); PG8_BAR; PG8_MMA(0, 0, At, B0); PG8_MMA(0, 1, At, B1); PG8_BAR; PG8_SCHED;
;             PG8_LDA(At, 0, 1); PG8_STAGE(PG8_SB(0, 0), b2, voffB); PG8_STAGE(PG8_SB(0, 1), b2 + hstep, voffB); PG8_STAGE(PG8_SA(0, 0), a2, voffA);
;             PG8_WAIT_V(8); PG8_WAIT_L(0); PG8_BAR; PG8_MMA(1, 0, At, B0); PG8_MMA(1, 1, At, B1); PG8_BAR; PG8_SCHED;
;             PG8_LDB(B0, 1, 0); PG8_LDB(B1, 1, 1); PG8_SCHED; PG8_LDA(At, 1, 0); PG8_STAGE(PG8_SA(0, 1), a2 + hstep, voffA);
;             PG8_WAIT_V(8); PG8_WAIT_L(0); PG8_BAR; PG8_MMA(0, 0, At, B0); PG8_MMA(0, 1, At, B1); PG8_BAR; PG8_SCHED;
	v_mfma_f32_16x16x32_bf16 v[140:143], v[48:51], v[170:173], v[140:143]
	v_mfma_f32_16x16x32_bf16 v[136:139], v[64:67], v[170:173], v[136:139]
	v_mfma_f32_16x16x32_bf16 v[124:127], v[48:51], v[184:187], v[124:127]
	v_mfma_f32_16x16x32_bf16 v[120:123], v[64:67], v[184:187], v[120:123]
	v_mfma_f32_16x16x32_bf16 v[108:111], v[48:51], v[192:195], v[108:111]
	v_mfma_f32_16x16x32_bf16 v[104:107], v[64:67], v[192:195], v[104:107]
	v_mfma_f32_16x16x32_bf16 v[92:95], v[48:51], v[200:203], v[92:95]
	v_mfma_f32_16x16x32_bf16 v[88:91], v[64:67], v[200:203], v[88:91]
	v_mfma_f32_16x16x32_bf16 v[140:143], v[52:55], v[180:183], v[140:143]
	v_mfma_f32_16x16x32_bf16 v[136:139], v[68:71], v[180:183], v[136:139]
	v_mfma_f32_16x16x32_bf16 v[124:127], v[52:55], v[188:191], v[124:127]
	v_mfma_f32_16x16x32_bf16 v[120:123], v[68:71], v[188:191], v[120:123]
	v_mfma_f32_16x16x32_bf16 v[108:111], v[52:55], v[196:199], v[108:111]
	v_mfma_f32_16x16x32_bf16 v[104:107], v[68:71], v[196:199], v[104:107]
	v_mfma_f32_16x16x32_bf16 v[92:95], v[52:55], v[206:209], v[92:95]
	v_mfma_f32_16x16x32_bf16 v[88:91], v[68:71], v[206:209], v[88:91]
	s_setprio 0
	s_setprio 1
	v_mfma_f32_16x16x32_bf16 v[132:135], v[144:147], v[170:173], v[132:135]
	v_mfma_f32_16x16x32_bf16 v[128:131], v[152:155], v[170:173], v[128:131]
	v_mfma_f32_16x16x32_bf16 v[116:119], v[144:147], v[184:187], v[116:119]
	v_mfma_f32_16x16x32_bf16 v[112:115], v[152:155], v[184:187], v[112:115]
	v_mfma_f32_16x16x32_bf16 v[100:103], v[144:147], v[192:195], v[100:103]
	v_mfma_f32_16x16x32_bf16 v[96:99], v[152:155], v[192:195], v[96:99]
	v_mfma_f32_16x16x32_bf16 v[84:87], v[144:147], v[200:203], v[84:87]
	v_mfma_f32_16x16x32_bf16 v[80:83], v[152:155], v[200:203], v[80:83]
	v_mfma_f32_16x16x32_bf16 v[132:135], v[148:151], v[180:183], v[132:135]
	v_mfma_f32_16x16x32_bf16 v[128:131], v[156:159], v[180:183], v[128:131]
	v_mfma_f32_16x16x32_bf16 v[116:119], v[148:151], v[188:191], v[116:119]
	v_mfma_f32_16x16x32_bf16 v[112:115], v[156:159], v[188:191], v[112:115]
	v_mfma_f32_16x16x32_bf16 v[100:103], v[148:151], v[196:199], v[100:103]
	v_mfma_f32_16x16x32_bf16 v[96:99], v[156:159], v[196:199], v[96:99]
	v_mfma_f32_16x16x32_bf16 v[84:87], v[148:151], v[206:209], v[84:87]
	v_mfma_f32_16x16x32_bf16 v[80:83], v[156:159], v[206:209], v[80:83]
	s_barrier
	s_setprio 0
	s_add_i32 s76, s76, s51
	v_lshl_add_u64 v[176:177], s[44:45], 0, v[204:205]
	s_mov_b32 m0, s76
	ds_read_b128 v[170:173], v179 offset:16384
	ds_read_b128 v[180:183], v179 offset:17408
	ds_read_b128 v[184:187], v179 offset:18432
	ds_read_b128 v[188:191], v179 offset:19456
	ds_read_b128 v[192:195], v179 offset:20480
	ds_read_b128 v[196:199], v179 offset:21504
	ds_read_b128 v[200:203], v179 offset:22528
	ds_read_b128 v[206:209], v179 offset:23552
	global_load_lds_dwordx4 v[176:177], off
	s_add_i32 m0, s76, 0x2000
	s_add_u32 s76, s44, 0x80000
	v_lshl_add_u64 v[210:211], s[44:45], 0, v[164:165]
	s_addc_u32 s77, s45, 0
	s_add_i32 s78, s78, s51
	global_load_lds_dwordx4 v[210:211], off
	v_lshl_add_u64 v[212:213], s[76:77], 0, v[204:205]
	s_mov_b32 m0, s78
	v_lshl_add_u64 v[214:215], s[46:47], 0, v[162:163]
	global_load_lds_dwordx4 v[212:213], off
	v_lshl_add_u64 v[212:213], s[76:77], 0, v[164:165]
	s_add_i32 m0, s78, 0x2000
	s_nop 0
	global_load_lds_dwordx4 v[212:213], off
	v_lshl_add_u64 v[212:213], s[46:47], 0, v[160:161]
	s_mov_b32 m0, s52
	s_nop 0
	global_load_lds_dwordx4 v[212:213], off
	s_mov_b32 m0, s0
	s_nop 0
	global_load_lds_dwordx4 v[214:215], off
	s_waitcnt vmcnt(8)
	s_waitcnt lgkmcnt(0)
	s_setprio 1
	s_barrier
	v_mfma_f32_16x16x32_bf16 v[76:79], v[48:51], v[170:173], v[76:79]
	v_mfma_f32_16x16x32_bf16 v[72:75], v[64:67], v[170:173], v[72:75]
	v_mfma_f32_16x16x32_bf16 v[44:47], v[48:51], v[184:187], v[44:47]
	v_mfma_f32_16x16x32_bf16 v[40:43], v[64:67], v[184:187], v[40:43]
	v_mfma_f32_16x16x32_bf16 v[28:31], v[48:51], v[192:195], v[28:31]
	v_mfma_f32_16x16x32_bf16 v[24:27], v[64:67], v[192:195], v[24:27]
	v_mfma_f32_16x16x32_bf16 v[12:15], v[48:51], v[200:203], v[12:15]
	v_mfma_f32_16x16x32_bf16 v[8:11], v[64:67], v[200:203], v[8:11]
	v_mfma_f32_16x16x32_bf16 v[76:79], v[52:55], v[180:183], v[76:79]
	v_mfma_f32_16x16x32_bf16 v[72:75], v[68:71], v[180:183], v[72:75]
	v_mfma_f32_16x16x32_bf16 v[44:47], v[52:55], v[188:191], v[44:47]
	v_mfma_f32_16x16x32_bf16 v[40:43], v[68:71], v[188:191], v[40:43]
	v_mfma_f32_16x16x32_bf16 v[28:31], v[52:55], v[196:199], v[28:31]
	v_mfma_f32_16x16x32_bf16 v[24:27], v[68:71], v[196:199], v[24:27]
	v_mfma_f32_16x16x32_bf16 v[12:15], v[52:55], v[206:209], v[12:15]
	v_mfma_f32_16x16x32_bf16 v[8:11], v[68:71], v[206:209], v[8:11]
	s_setprio 0
	s_setprio 1
	v_mfma_f32_16x16x32_bf16 v[36:39], v[144:147], v[184:187], v[36:39]
	v_mfma_f32_16x16x32_bf16 v[32:35], v[152:155], v[184:187], v[32:35]
	v_mfma_f32_16x16x32_bf16 v[20:23], v[144:147], v[192:195], v[20:23]
	v_mfma_f32_16x16x32_bf16 v[16:19], v[152:155], v[192:195], v[16:19]
	v_mfma_f32_16x16x32_bf16 v[4:7], v[144:147], v[200:203], v[4:7]
	v_mfma_f32_16x16x32_bf16 v[0:3], v[152:155], v[200:203], v[0:3]
	v_mfma_f32_16x16x32_bf16 v[48:51], v[144:147], v[170:173], v[60:63]
	v_mfma_f32_16x16x32_bf16 v[52:55], v[152:155], v[170:173], v[56:59]
	v_mfma_f32_16x16x32_bf16 v[36:39], v[148:151], v[188:191], v[36:39]
	v_mfma_f32_16x16x32_bf16 v[32:35], v[156:159], v[188:191], v[32:35]
	v_mfma_f32_16x16x32_bf16 v[20:23], v[148:151], v[196:199], v[20:23]
	v_mfma_f32_16x16x32_bf16 v[16:19], v[156:159], v[196:199], v[16:19]
	v_mfma_f32_16x16x32_bf16 v[4:7], v[148:151], v[206:209], v[4:7]
	v_mfma_f32_16x16x32_bf16 v[0:3], v[156:159], v[206:209], v[0:3]
	v_mfma_f32_16x16x32_bf16 v[48:51], v[148:151], v[180:183], v[48:51]
	v_mfma_f32_16x16x32_bf16 v[52:55], v[156:159], v[180:183], v[52:55]
	s_barrier
; #define PG8_STAGE(bufoff, gbase, voff) do { _Pragma("unroll") for (int _i = 0; _i < 2; ++_i) \
;         __builtin_amdgcn_global_load_lds((const unsigned*)((const char*)(gbase) + (voff)[_i]), (PG8_LAS unsigned*)(lds + (bufoff) + ldsw + _i * 8192), 16, 0, 0); } while (0)
; #define PG8_LDA(dst, b, h) do { _Pragma("unroll") for (int m = 0; m < 4; ++m) _Pragma("unroll") for (int k = 0; k < 2; ++k) dst[m][k] = *(const PG8_LAS bf16x8*)(lds + PG8_SA(b, h) + aoff + m * 2048 + k * 1024); } while (0)
; #define PG8_LDB(dst, b, h) do { _Pragma("unroll") for (int n = 0; n < 2; ++n) _Pragma("unroll") for (int k = 0; k < 2; ++k) dst[n][k] = *(const PG8_LAS bf16x8*)(lds + PG8_SB(b, h) + boff + n * 2048 + k * 1024); } while (0)
; #define PG8_MMA(ai, bj, At, Bt) do { __builtin_amdgcn_s_setprio(1); _Pragma("unroll") for (int m = 0; m < 4; ++m) _Pragma("unroll") for (int n = 0; n < 2; ++n) _Pragma("unroll") for (int k = 0; k < 2; ++k) \
;         acc[ai][bj][m][n] = __builtin_amdgcn_mfma_f32_16x16x32_bf16(Bt[n][k], At[m][k], acc[ai][bj][m][n], 0, 0, 0); __builtin_amdgcn_s_setprio(0); } while (0)
; #define PG8_WAIT_V(n) asm volatile("s_waitcnt vmcnt(" #n ")" ::: "memory")
; #define PG8_WAIT_L(n) asm volatile("s_waitcnt lgkmcnt(" #n ")" ::: "memory")
; #define PG8_BAR __builtin_amdgcn_s_barrier()
; #define PG8_SCHED __builtin_amdgcn_sched_barrier(0)
; template <class Epi, class Sched, bool ALIGN_EPI = false, bool SP2 = false>
; __device__ __forceinline__ void gemm_phase(PG8_LAS unsigned char* lds, const Gemm g, const Sched& S, const Epi& E, const int tid) {
;     ...
;             PG8_LDB(B0, 1, 0); PG8_LDB(B1, 1, 1); PG8_SCHED; PG8_LDA(At, 1, 0); PG8_STAGE(PG8_SA(0, 1), a2 + hstep, voffA);
;             PG8_WAIT_V(8); PG8_WAIT_L(0); PG8_BAR; PG8_MMA(0, 0, At, B0); PG8_MMA(0, 1, At, B1); PG8_BAR; PG8_SCHED;
;             PG8_LDA(At, 1, 1); PG8_STAGE(PG8_SB(1, 0), b3, voffB); PG8_STAGE(PG8_SB(1, 1), b3 + hstep, voffB); PG8_STAGE(PG8_SA(1, 0), a3, voffA);
;             PG8_WAIT_V(8); PG8_WAIT_L(0); PG8_BAR; PG8_MMA(1, 0, At, B0); PG8_MMA(1, 1, At, B1); PG8_BAR; PG8_SCHED;
	s_setprio 0
	s_add_i32 s76, 0, 0x18000
	s_add_i32 s77, 0, 0x1c000
	v_add_u32_e32 v68, s76, v175
	v_add_u32_e32 v156, s77, v175
	ds_read_b128 v[56:59], v68
	ds_read_b128 v[60:63], v68 offset:1024
	ds_read_b128 v[64:67], v68 offset:2048
	ds_read_b128 v[68:71], v68 offset:3072
	ds_read_b128 v[144:147], v156
	ds_read_b128 v[148:151], v156 offset:1024
	ds_read_b128 v[152:155], v156 offset:2048
	ds_read_b128 v[156:159], v156 offset:3072
	s_add_u32 s46, s46, 0x80000
	s_addc_u32 s47, s47, 0
	s_mov_b32 m0, s33
	v_lshl_add_u64 v[216:217], s[46:47], 0, v[160:161]
	ds_read_b128 v[170:173], v179 offset:32768
	ds_read_b128 v[180:183], v179 offset:33792
	ds_read_b128 v[184:187], v179 offset:34816
	ds_read_b128 v[188:191], v179 offset:35840
	ds_read_b128 v[192:195], v179 offset:36864
	ds_read_b128 v[196:199], v179 offset:37888
	ds_read_b128 v[200:203], v179 offset:38912
	ds_read_b128 v[206:209], v179 offset:39936
	global_load_lds_dwordx4 v[216:217], off
	v_lshl_add_u64 v[216:217], s[46:47], 0, v[162:163]
	s_mov_b32 m0, s53
	s_nop 0
	global_load_lds_dwordx4 v[216:217], off
	s_waitcnt vmcnt(8)
	s_waitcnt lgkmcnt(0)
	s_setprio 1
	s_barrier
	v_mfma_f32_16x16x32_bf16 v[140:143], v[56:59], v[170:173], v[140:143]
	v_mfma_f32_16x16x32_bf16 v[136:139], v[64:67], v[170:173], v[136:139]
	v_mfma_f32_16x16x32_bf16 v[124:127], v[56:59], v[184:187], v[124:127]
	v_mfma_f32_16x16x32_bf16 v[120:123], v[64:67], v[184:187], v[120:123]
	v_mfma_f32_16x16x32_bf16 v[108:111], v[56:59], v[192:195], v[108:111]
	v_mfma_f32_16x16x32_bf16 v[104:107], v[64:67], v[192:195], v[104:107]
	v_mfma_f32_16x16x32_bf16 v[92:95], v[56:59], v[200:203], v[92:95]
	v_mfma_f32_16x16x32_bf16 v[88:91], v[64:67], v[200:203], v[88:91]
	v_mfma_f32_16x16x32_bf16 v[140:143], v[60:63], v[180:183], v[140:143]
	v_mfma_f32_16x16x32_bf16 v[136:139], v[68:71], v[180:183], v[136:139]
	v_mfma_f32_16x16x32_bf16 v[124:127], v[60:63], v[188:191], v[124:127]
	v_mfma_f32_16x16x32_bf16 v[120:123], v[68:71], v[188:191], v[120:123]
	v_mfma_f32_16x16x32_bf16 v[108:111], v[60:63], v[196:199], v[108:111]
	v_mfma_f32_16x16x32_bf16 v[104:107], v[68:71], v[196:199], v[104:107]
	v_mfma_f32_16x16x32_bf16 v[92:95], v[60:63], v[206:209], v[92:95]
	v_mfma_f32_16x16x32_bf16 v[88:91], v[68:71], v[206:209], v[88:91]
	s_setprio 0
	s_setprio 1
	v_mfma_f32_16x16x32_bf16 v[132:135], v[144:147], v[170:173], v[132:135]
	v_mfma_f32_16x16x32_bf16 v[128:131], v[152:155], v[170:173], v[128:131]
	v_mfma_f32_16x16x32_bf16 v[116:119], v[144:147], v[184:187], v[116:119]
	v_mfma_f32_16x16x32_bf16 v[112:115], v[152:155], v[184:187], v[112:115]
	v_mfma_f32_16x16x32_bf16 v[100:103], v[144:147], v[192:195], v[100:103]
	v_mfma_f32_16x16x32_bf16 v[96:99], v[152:155], v[192:195], v[96:99]
	v_mfma_f32_16x16x32_bf16 v[84:87], v[144:147], v[200:203], v[84:87]
	v_mfma_f32_16x16x32_bf16 v[80:83], v[152:155], v[200:203], v[80:83]
	v_mfma_f32_16x16x32_bf16 v[132:135], v[148:151], v[180:183], v[132:135]
	v_mfma_f32_16x16x32_bf16 v[128:131], v[156:159], v[180:183], v[128:131]
	v_mfma_f32_16x16x32_bf16 v[116:119], v[148:151], v[188:191], v[116:119]
	v_mfma_f32_16x16x32_bf16 v[112:115], v[156:159], v[188:191], v[112:115]
	v_mfma_f32_16x16x32_bf16 v[100:103], v[148:151], v[196:199], v[100:103]
	v_mfma_f32_16x16x32_bf16 v[96:99], v[156:159], v[196:199], v[96:99]
	v_mfma_f32_16x16x32_bf16 v[84:87], v[148:151], v[206:209], v[84:87]
	v_mfma_f32_16x16x32_bf16 v[80:83], v[156:159], v[206:209], v[80:83]
	s_barrier
; #define PG8_STAGE(bufoff, gbase, voff) do { _Pragma("unroll") for (int _i = 0; _i < 2; ++_i) \
;         __builtin_amdgcn_global_load_lds((const unsigned*)((const char*)(gbase) + (voff)[_i]), (PG8_LAS unsigned*)(lds + (bufoff) + ldsw + _i * 8192), 16, 0, 0); } while (0)
; #define PG8_LDA(dst, b, h) do { _Pragma("unroll") for (int m = 0; m < 4; ++m) _Pragma("unroll") for (int k = 0; k < 2; ++k) dst[m][k] = *(const PG8_LAS bf16x8*)(lds + PG8_SA(b, h) + aoff + m * 2048 + k * 1024); } while (0)
; #define PG8_BAR __builtin_amdgcn_s_barrier()
; template <class Epi, class Sched, bool ALIGN_EPI = false, bool SP2 = false>
; __device__ __forceinline__ void gemm_phase(PG8_LAS unsigned char* lds, const Gemm g, const Sched& S, const Epi& E, const int tid) {
;     ...
;             PG8_LDA(At, 1, 1); PG8_STAGE(PG8_SB(1, 0), b3, voffB); PG8_STAGE(PG8_SB(1, 1), b3 + hstep, voffB); PG8_STAGE(PG8_SA(1, 0), a3, voffA);
;             PG8_WAIT_V(8); PG8_WAIT_L(0); PG8_BAR; PG8_MMA(1, 0, At, B0); PG8_MMA(1, 1, At, B1); PG8_BAR; PG8_SCHED;
;             } else {
;             PG8_LDB(B0, 0, 0); PG8_SCHED; PG8_LDA(At, 0, 0); PG8_STAGE(PG8_SA(1, 1), a1 + hstep, voffA);
;             PG8_WAIT_L(8); PG8_BAR; PG8_WAIT_L(0); PG8_MMA(0, 0, At, B0); PG8_BAR; PG8_SCHED;
;             PG8_LDB(B1, 0, 1); PG8_STAGE(PG8_SB(0, 0), b2, voffB);
;             PG8_BAR; PG8_WAIT_L(0); PG8_MMA(0, 1, At, B1); PG8_BAR;
;             PG8_LDA(At, 0, 1); PG8_STAGE(PG8_SA(0, 0), a2, voffA);
;             PG8_BAR; PG8_WAIT_L(0); PG8_MMA(1, 0, At, B0); PG8_BAR; PG8_SCHED;
;             PG8_STAGE(PG8_SB(0, 1), b2 + hstep, voffB);
;             PG8_WAIT_V(6); PG8_BAR; PG8_MMA(1, 1, At, B1); PG8_BAR;
;             PG8_LDB(B0, 1, 0); PG8_SCHED; PG8_LDA(At, 1, 0); PG8_STAGE(PG8_SA(0, 1), a2 + hstep, voffA);
;             PG8_WAIT_L(8); PG8_BAR; PG8_WAIT_L(0); PG8_MMA(0, 0, At, B0); PG8_BAR; PG8_SCHED;
;             PG8_LDB(B1, 1, 1); PG8_STAGE(PG8_SB(1, 0), b3, voffB);
;             PG8_BAR; PG8_WAIT_L(0); PG8_MMA(0, 1, At, B1); PG8_BAR;
;             PG8_LDA(At, 1, 1); PG8_STAGE(PG8_SA(1, 0), a3, voffA);
;             PG8_BAR; PG8_WAIT_L(0); PG8_MMA(1, 0, At, B0); PG8_BAR; PG8_SCHED;
;             PG8_STAGE(PG8_SB(1, 1), b3 + hstep, voffB);
;             PG8_WAIT_V(6); PG8_BAR; PG8_MMA(1, 1, At, B1); PG8_BAR;
;             }
;         }
;         if constexpr (ALIGN_EPI) { if (wr == 0) PG8_BAR; }
	s_setprio 0
	s_add_i32 s46, s76, s51
	v_lshl_add_u64 v[176:177], v[176:177], 0, s[70:71]
	s_mov_b32 m0, s46
	ds_read_b128 v[170:173], v179 offset:49152
	ds_read_b128 v[180:183], v179 offset:50176
	ds_read_b128 v[184:187], v179 offset:51200
	ds_read_b128 v[188:191], v179 offset:52224
	ds_read_b128 v[192:195], v179 offset:53248
	ds_read_b128 v[196:199], v179 offset:54272
	ds_read_b128 v[200:203], v179 offset:55296
	ds_read_b128 v[206:209], v179 offset:56320
	global_load_lds_dwordx4 v[176:177], off
	s_add_i32 m0, s46, 0x2000
	s_add_u32 s44, s44, 0x80080
	v_lshl_add_u64 v[176:177], v[210:211], 0, s[70:71]
	s_addc_u32 s45, s45, 0
	s_add_i32 s46, s77, s51
	global_load_lds_dwordx4 v[176:177], off
	v_lshl_add_u64 v[176:177], s[44:45], 0, v[204:205]
	s_mov_b32 m0, s46
	s_nop 0
	global_load_lds_dwordx4 v[176:177], off
	v_lshl_add_u64 v[176:177], s[44:45], 0, v[164:165]
	s_add_i32 m0, s46, 0x2000
	s_nop 0
	global_load_lds_dwordx4 v[176:177], off
	v_lshl_add_u64 v[176:177], v[212:213], 0, s[70:71]
	s_mov_b32 m0, s55
	s_nop 0
	global_load_lds_dwordx4 v[176:177], off
	v_lshl_add_u64 v[176:177], v[214:215], 0, s[70:71]
	s_mov_b32 m0, s62
	s_nop 0
	global_load_lds_dwordx4 v[176:177], off
	s_waitcnt vmcnt(8)
	s_waitcnt lgkmcnt(0)
	s_setprio 1
	s_barrier
	v_mfma_f32_16x16x32_bf16 v[76:79], v[56:59], v[170:173], v[76:79]
	v_mfma_f32_16x16x32_bf16 v[72:75], v[64:67], v[170:173], v[72:75]
	v_mfma_f32_16x16x32_bf16 v[44:47], v[56:59], v[184:187], v[44:47]
	v_mfma_f32_16x16x32_bf16 v[40:43], v[64:67], v[184:187], v[40:43]
	v_mfma_f32_16x16x32_bf16 v[28:31], v[56:59], v[192:195], v[28:31]
	v_mfma_f32_16x16x32_bf16 v[24:27], v[64:67], v[192:195], v[24:27]
	v_mfma_f32_16x16x32_bf16 v[12:15], v[56:59], v[200:203], v[12:15]
	v_mfma_f32_16x16x32_bf16 v[8:11], v[64:67], v[200:203], v[8:11]
	v_mfma_f32_16x16x32_bf16 v[76:79], v[60:63], v[180:183], v[76:79]
	v_mfma_f32_16x16x32_bf16 v[72:75], v[68:71], v[180:183], v[72:75]
	v_mfma_f32_16x16x32_bf16 v[44:47], v[60:63], v[188:191], v[44:47]
	v_mfma_f32_16x16x32_bf16 v[40:43], v[68:71], v[188:191], v[40:43]
	v_mfma_f32_16x16x32_bf16 v[28:31], v[60:63], v[196:199], v[28:31]
	v_mfma_f32_16x16x32_bf16 v[24:27], v[68:71], v[196:199], v[24:27]
	v_mfma_f32_16x16x32_bf16 v[12:15], v[60:63], v[206:209], v[12:15]
	v_mfma_f32_16x16x32_bf16 v[8:11], v[68:71], v[206:209], v[8:11]
	s_setprio 0
	s_setprio 1
	v_mfma_f32_16x16x32_bf16 v[48:51], v[144:147], v[170:173], v[48:51]
	v_mfma_f32_16x16x32_bf16 v[60:63], v[148:151], v[180:183], v[48:51]
	v_mfma_f32_16x16x32_bf16 v[48:51], v[152:155], v[170:173], v[52:55]
	v_mfma_f32_16x16x32_bf16 v[36:39], v[144:147], v[184:187], v[36:39]
	v_mfma_f32_16x16x32_bf16 v[32:35], v[152:155], v[184:187], v[32:35]
	v_mfma_f32_16x16x32_bf16 v[20:23], v[144:147], v[192:195], v[20:23]
	v_mfma_f32_16x16x32_bf16 v[16:19], v[152:155], v[192:195], v[16:19]
	v_mfma_f32_16x16x32_bf16 v[4:7], v[144:147], v[200:203], v[4:7]
	v_mfma_f32_16x16x32_bf16 v[0:3], v[152:155], v[200:203], v[0:3]
	v_mfma_f32_16x16x32_bf16 v[56:59], v[156:159], v[180:183], v[48:51]
	v_mfma_f32_16x16x32_bf16 v[36:39], v[148:151], v[188:191], v[36:39]
	v_mfma_f32_16x16x32_bf16 v[32:35], v[156:159], v[188:191], v[32:35]
	v_mfma_f32_16x16x32_bf16 v[20:23], v[148:151], v[196:199], v[20:23]
	v_mfma_f32_16x16x32_bf16 v[16:19], v[156:159], v[196:199], v[16:19]
	v_mfma_f32_16x16x32_bf16 v[4:7], v[148:151], v[206:209], v[4:7]
	v_mfma_f32_16x16x32_bf16 v[0:3], v[156:159], v[206:209], v[0:3]
	s_barrier
	s_setprio 0
	s_add_i32 s75, s75, 2
	s_add_u32 s42, s42, 0x100
	s_addc_u32 s43, s43, 0
	s_add_u32 s40, s40, 0x100
	s_addc_u32 s69, s69, 0
	s_cmp_gt_u32 s75, 29
	s_cbranch_scc0 .LBB0_1384
	s_and_b64 vcc, exec, s[22:23]
	s_cbranch_vccz .LBB0_1387
	s_barrier

; #define PG8_STAGE(bufoff, gbase, voff) do { _Pragma("unroll") for (int _i = 0; _i < 2; ++_i) \
;         __builtin_amdgcn_global_load_lds((const unsigned*)((const char*)(gbase) + (voff)[_i]), (PG8_LAS unsigned*)(lds + (bufoff) + ldsw + _i * 8192), 16, 0, 0); } while (0)
; #define PG8_LDA(dst, b, h) do { _Pragma("unroll") for (int m = 0; m < 4; ++m) _Pragma("unroll") for (int k = 0; k < 2; ++k) dst[m][k] = *(const PG8_LAS bf16x8*)(lds + PG8_SA(b, h) + aoff + m * 2048 + k * 1024); } while (0)
; #define PG8_LDB(dst, b, h) do { _Pragma("unroll") for (int n = 0; n < 2; ++n) _Pragma("unroll") for (int k = 0; k < 2; ++k) dst[n][k] = *(const PG8_LAS bf16x8*)(lds + PG8_SB(b, h) + boff + n * 2048 + k * 1024); } while (0)
; #define PG8_WAIT_V(n) asm volatile("s_waitcnt vmcnt(" #n ")" ::: "memory")
; #define PG8_WAIT_L(n) asm volatile("s_waitcnt lgkmcnt(" #n ")" ::: "memory")
; #define PG8_BAR __builtin_amdgcn_s_barrier()
; #define PG8_SCHED __builtin_amdgcn_sched_barrier(0)
; template <class Epi, class Sched, bool ALIGN_EPI = false, bool SP2 = false>
; __device__ __forceinline__ void gemm_phase(PG8_LAS unsigned char* lds, const Gemm g, const Sched& S, const Epi& E, const int tid) {
;     ...
;         const bool has_next = S.next(ui + 1, nxt);
;         const char* nA = has_next ? (const char*)g.A + (size_t)nxt.pm * tstep : cA; const char* nB = has_next ? (const char*)g.Bt + (size_t)nxt.pn * tstep : cB;
;         for (int t = 0; t < nt; t += 2) {
;             const bool last = (t == nt - 2);
;             const char* a1 = cA + (size_t)(t + 1) * kstep;
;             const char* a2 = last ? nA : cA + (size_t)(t + 2) * kstep; const char* b2 = last ? nB : cB + (size_t)(t + 2) * kstep;
;             const char* a3 = a2 + kstep; const char* b3 = b2 + kstep;
;             if (last && has_next) S.a_ready(nxt);
;             if constexpr (SP2) {
;             PG8_LDB(B0, 0, 0); PG8_LDB(B1, 0, 1); PG8_SCHED; PG8_LDA(At, 0, 0); PG8_STAGE(PG8_SA(1, 1), a1 + hstep, voffA);
;             PG8_WAIT_V(8); PG8_WAIT_L(0); PG8_BAR; PG8_MMA(0, 0, At, B0); PG8_MMA(0, 1, At, B1); PG8_BAR; PG8_SCHED;
;             PG8_LDA(At, 0, 1); PG8_STAGE(PG8_SB(0, 0), b2, voffB); PG8_STAGE(PG8_SB(0, 1), b2 + hstep, voffB); PG8_STAGE(PG8_SA(0, 0), a2, voffA);
;             PG8_WAIT_V(8); PG8_WAIT_L(0); PG8_BAR; PG8_MMA(1, 0, At, B0); PG8_MMA(1, 1, At, B1); PG8_BAR; PG8_SCHED;
.LBB0_1425:
	s_ashr_i32 s27, s26, 31
	s_lshl_b64 s[28:29], s[26:27], 20
	s_add_u32 s28, s6, s28
	s_addc_u32 s29, s7, s29
	s_and_b64 s[30:31], s[4:5], exec
	s_cselect_b32 s27, s29, s37
	s_cselect_b32 s62, s28, s36
	s_ashr_i32 s25, s24, 31
	s_lshl_b64 s[30:31], s[24:25], 20
	s_add_u32 s30, s11, s30
	s_addc_u32 s31, s33, s31
	s_and_b64 s[44:45], s[4:5], exec
	s_cselect_b32 s25, s31, s43
	s_cselect_b32 s64, s30, s42
	s_add_u32 s36, s36, 0x80080
	s_addc_u32 s37, s37, 0
	s_add_u32 s65, s42, 0x100
	s_addc_u32 s68, s43, 0
	s_mov_b32 s69, -2
	s_add_u32 s42, s36, 0xfff80080
	s_addc_u32 s43, s37, -1
	s_add_i32 s75, 0, 0x10000
	s_cmp_eq_u32 s69, 28
	s_cselect_b32 s45, s27, s43
	s_cselect_b32 s44, s62, s42
	s_cselect_b32 s43, s25, s68
	s_cselect_b32 s42, s64, s65
	s_add_i32 s78, 0, 0x14000
	v_add_u32_e32 v84, s75, v167
	v_add_u32_e32 v166, s78, v167
	ds_read_b128 v[64:67], v84
	ds_read_b128 v[68:71], v84 offset:1024
	ds_read_b128 v[80:83], v84 offset:2048
	ds_read_b128 v[84:87], v84 offset:3072
	ds_read_b128 v[144:147], v166
	ds_read_b128 v[148:151], v166 offset:1024
	ds_read_b128 v[152:155], v166 offset:2048
	ds_read_b128 v[170:173], v166 offset:3072
	v_lshl_add_u64 v[202:203], s[36:37], 0, v[162:163]
	s_add_i32 m0, s35, 0xc000
	ds_read_b128 v[174:177], v169
	ds_read_b128 v[178:181], v169 offset:1024
	ds_read_b128 v[182:185], v169 offset:2048
	ds_read_b128 v[186:189], v169 offset:3072
	ds_read_b128 v[190:193], v169 offset:4096
	ds_read_b128 v[194:197], v169 offset:5120
	ds_read_b128 v[198:201], v169 offset:6144
	ds_read_b128 v[206:209], v169 offset:7168
	global_load_lds_dwordx4 v[202:203], off
	v_lshl_add_u64 v[202:203], s[36:37], 0, v[164:165]
	s_add_i32 m0, s35, 0xe000
	s_nop 0
	global_load_lds_dwordx4 v[202:203], off
	s_waitcnt vmcnt(24)
	s_waitcnt lgkmcnt(0)
	s_setprio 1
	s_barrier
	v_mfma_f32_16x16x32_bf16 v[140:143], v[64:67], v[174:177], 0
	v_mfma_f32_16x16x32_bf16 v[136:139], v[80:83], v[174:177], 0
	v_mfma_f32_16x16x32_bf16 v[124:127], v[64:67], v[182:185], 0
	v_mfma_f32_16x16x32_bf16 v[120:123], v[80:83], v[182:185], 0
	v_mfma_f32_16x16x32_bf16 v[108:111], v[64:67], v[190:193], 0
	v_mfma_f32_16x16x32_bf16 v[104:107], v[80:83], v[190:193], 0
	v_mfma_f32_16x16x32_bf16 v[92:95], v[64:67], v[198:201], 0
	v_mfma_f32_16x16x32_bf16 v[88:91], v[80:83], v[198:201], 0
	v_mfma_f32_16x16x32_bf16 v[140:143], v[68:71], v[178:181], v[140:143]
	v_mfma_f32_16x16x32_bf16 v[136:139], v[84:87], v[178:181], v[136:139]
	v_mfma_f32_16x16x32_bf16 v[124:127], v[68:71], v[186:189], v[124:127]
	v_mfma_f32_16x16x32_bf16 v[120:123], v[84:87], v[186:189], v[120:123]
	v_mfma_f32_16x16x32_bf16 v[108:111], v[68:71], v[194:197], v[108:111]
	v_mfma_f32_16x16x32_bf16 v[104:107], v[84:87], v[194:197], v[104:107]
	v_mfma_f32_16x16x32_bf16 v[92:95], v[68:71], v[206:209], v[92:95]
	v_mfma_f32_16x16x32_bf16 v[88:91], v[84:87], v[206:209], v[88:91]
	s_setprio 0
	s_setprio 1
	v_mfma_f32_16x16x32_bf16 v[132:135], v[144:147], v[174:177], 0
	v_mfma_f32_16x16x32_bf16 v[128:131], v[152:155], v[174:177], 0
	v_mfma_f32_16x16x32_bf16 v[116:119], v[144:147], v[182:185], 0
	v_mfma_f32_16x16x32_bf16 v[112:115], v[152:155], v[182:185], 0
	v_mfma_f32_16x16x32_bf16 v[100:103], v[144:147], v[190:193], 0
	v_mfma_f32_16x16x32_bf16 v[96:99], v[152:155], v[190:193], 0
	v_mfma_f32_16x16x32_bf16 v[76:79], v[144:147], v[198:201], 0
	v_mfma_f32_16x16x32_bf16 v[72:75], v[152:155], v[198:201], 0
	v_mfma_f32_16x16x32_bf16 v[132:135], v[148:151], v[178:181], v[132:135]
	v_mfma_f32_16x16x32_bf16 v[128:131], v[170:173], v[178:181], v[128:131]
	v_mfma_f32_16x16x32_bf16 v[116:119], v[148:151], v[186:189], v[116:119]
	v_mfma_f32_16x16x32_bf16 v[112:115], v[170:173], v[186:189], v[112:115]
	v_mfma_f32_16x16x32_bf16 v[100:103], v[148:151], v[194:197], v[100:103]
	v_mfma_f32_16x16x32_bf16 v[96:99], v[170:173], v[194:197], v[96:99]
	v_mfma_f32_16x16x32_bf16 v[76:79], v[148:151], v[206:209], v[76:79]
	v_mfma_f32_16x16x32_bf16 v[72:75], v[170:173], v[206:209], v[72:75]
	s_barrier
	s_setprio 0
	s_add_i32 s75, s75, s38
	v_lshl_add_u64 v[202:203], s[42:43], 0, v[204:205]
	s_mov_b32 m0, s75
	ds_read_b128 v[174:177], v169 offset:16384
	ds_read_b128 v[178:181], v169 offset:17408
	ds_read_b128 v[182:185], v169 offset:18432
	ds_read_b128 v[186:189], v169 offset:19456
	ds_read_b128 v[190:193], v169 offset:20480
	ds_read_b128 v[194:197], v169 offset:21504
	ds_read_b128 v[198:201], v169 offset:22528
	ds_read_b128 v[206:209], v169 offset:23552
	global_load_lds_dwordx4 v[202:203], off
	s_add_i32 m0, s75, 0x2000
	s_add_u32 s76, s42, 0x80000
	v_lshl_add_u64 v[210:211], s[42:43], 0, v[160:161]
	s_addc_u32 s77, s43, 0
	s_add_i32 s75, s78, s38
	global_load_lds_dwordx4 v[210:211], off
	v_lshl_add_u64 v[212:213], s[76:77], 0, v[204:205]
	s_mov_b32 m0, s75
	v_lshl_add_u64 v[214:215], s[44:45], 0, v[158:159]
	global_load_lds_dwordx4 v[212:213], off
	v_lshl_add_u64 v[212:213], s[76:77], 0, v[160:161]
	s_add_i32 m0, s75, 0x2000
	s_nop 0
	global_load_lds_dwordx4 v[212:213], off
	v_lshl_add_u64 v[212:213], s[44:45], 0, v[156:157]
	s_mov_b32 m0, s35
	s_nop 0
	global_load_lds_dwordx4 v[212:213], off
	s_mov_b32 m0, s40
	s_nop 0
	global_load_lds_dwordx4 v[214:215], off
	s_waitcnt vmcnt(8)
	s_waitcnt lgkmcnt(0)
	s_setprio 1
	s_barrier
; #define PG8_STAGE(bufoff, gbase, voff) do { _Pragma("unroll") for (int _i = 0; _i < 2; ++_i) \
;         __builtin_amdgcn_global_load_lds((const unsigned*)((const char*)(gbase) + (voff)[_i]), (PG8_LAS unsigned*)(lds + (bufoff) + ldsw + _i * 8192), 16, 0, 0); } while (0)
; #define PG8_LDA(dst, b, h) do { _Pragma("unroll") for (int m = 0; m < 4; ++m) _Pragma("unroll") for (int k = 0; k < 2; ++k) dst[m][k] = *(const PG8_LAS bf16x8*)(lds + PG8_SA(b, h) + aoff + m * 2048 + k * 1024); } while (0)
; #define PG8_LDB(dst, b, h) do { _Pragma("unroll") for (int n = 0; n < 2; ++n) _Pragma("unroll") for (int k = 0; k < 2; ++k) dst[n][k] = *(const PG8_LAS bf16x8*)(lds + PG8_SB(b, h) + boff + n * 2048 + k * 1024); } while (0)
; #define PG8_MMA(ai, bj, At, Bt) do { __builtin_amdgcn_s_setprio(1); _Pragma("unroll") for (int m = 0; m < 4; ++m) _Pragma("unroll") for (int n = 0; n < 2; ++n) _Pragma("unroll") for (int k = 0; k < 2; ++k) \
;         acc[ai][bj][m][n] = __builtin_amdgcn_mfma_f32_16x16x32_bf16(Bt[n][k], At[m][k], acc[ai][bj][m][n], 0, 0, 0); __builtin_amdgcn_s_setprio(0); } while (0)
; #define PG8_WAIT_V(n) asm volatile("s_waitcnt vmcnt(" #n ")" ::: "memory")
; #define PG8_WAIT_L(n) asm volatile("s_waitcnt lgkmcnt(" #n ")" ::: "memory")
; #define PG8_BAR __builtin_amdgcn_s_barrier()
; #define PG8_SCHED __builtin_amdgcn_sched_barrier(0)
; template <class Epi, class Sched, bool ALIGN_EPI = false, bool SP2 = false>
; __device__ __forceinline__ void gemm_phase(PG8_LAS unsigned char* lds, const Gemm g, const Sched& S, const Epi& E, const int tid) {
;     ...
;             PG8_WAIT_V(8); PG8_WAIT_L(0); PG8_BAR; PG8_MMA(1, 0, At, B0); PG8_MMA(1, 1, At, B1); PG8_BAR; PG8_SCHED;
;             PG8_LDB(B0, 1, 0); PG8_LDB(B1, 1, 1); PG8_SCHED; PG8_LDA(At, 1, 0); PG8_STAGE(PG8_SA(0, 1), a2 + hstep, voffA);
;             PG8_WAIT_V(8); PG8_WAIT_L(0); PG8_BAR; PG8_MMA(0, 0, At, B0); PG8_MMA(0, 1, At, B1); PG8_BAR; PG8_SCHED;
	v_mfma_f32_16x16x32_bf16 v[60:63], v[64:67], v[174:177], 0
	v_mfma_f32_16x16x32_bf16 v[56:59], v[80:83], v[174:177], 0
	v_mfma_f32_16x16x32_bf16 v[44:47], v[64:67], v[182:185], 0
	v_mfma_f32_16x16x32_bf16 v[40:43], v[80:83], v[182:185], 0
	v_mfma_f32_16x16x32_bf16 v[28:31], v[64:67], v[190:193], 0
	v_mfma_f32_16x16x32_bf16 v[24:27], v[80:83], v[190:193], 0
	v_mfma_f32_16x16x32_bf16 v[12:15], v[64:67], v[198:201], 0
	v_mfma_f32_16x16x32_bf16 v[8:11], v[80:83], v[198:201], 0
	v_mfma_f32_16x16x32_bf16 v[60:63], v[68:71], v[178:181], v[60:63]
	v_mfma_f32_16x16x32_bf16 v[56:59], v[84:87], v[178:181], v[56:59]
	v_mfma_f32_16x16x32_bf16 v[44:47], v[68:71], v[186:189], v[44:47]
	v_mfma_f32_16x16x32_bf16 v[40:43], v[84:87], v[186:189], v[40:43]
	v_mfma_f32_16x16x32_bf16 v[28:31], v[68:71], v[194:197], v[28:31]
	v_mfma_f32_16x16x32_bf16 v[24:27], v[84:87], v[194:197], v[24:27]
	v_mfma_f32_16x16x32_bf16 v[12:15], v[68:71], v[206:209], v[12:15]
	v_mfma_f32_16x16x32_bf16 v[8:11], v[84:87], v[206:209], v[8:11]
	s_setprio 0
	s_setprio 1
	v_mfma_f32_16x16x32_bf16 v[52:55], v[144:147], v[174:177], 0
	v_mfma_f32_16x16x32_bf16 v[48:51], v[152:155], v[174:177], 0
	v_mfma_f32_16x16x32_bf16 v[36:39], v[144:147], v[182:185], 0
	v_mfma_f32_16x16x32_bf16 v[32:35], v[152:155], v[182:185], 0
	v_mfma_f32_16x16x32_bf16 v[20:23], v[144:147], v[190:193], 0
	v_mfma_f32_16x16x32_bf16 v[16:19], v[152:155], v[190:193], 0
	v_mfma_f32_16x16x32_bf16 v[4:7], v[144:147], v[198:201], 0
	v_mfma_f32_16x16x32_bf16 v[0:3], v[152:155], v[198:201], 0
	v_mfma_f32_16x16x32_bf16 v[52:55], v[148:151], v[178:181], v[52:55]
	v_mfma_f32_16x16x32_bf16 v[48:51], v[170:173], v[178:181], v[48:51]
	v_mfma_f32_16x16x32_bf16 v[36:39], v[148:151], v[186:189], v[36:39]
	v_mfma_f32_16x16x32_bf16 v[32:35], v[170:173], v[186:189], v[32:35]
	v_mfma_f32_16x16x32_bf16 v[20:23], v[148:151], v[194:197], v[20:23]
	v_mfma_f32_16x16x32_bf16 v[16:19], v[170:173], v[194:197], v[16:19]
	v_mfma_f32_16x16x32_bf16 v[4:7], v[148:151], v[206:209], v[4:7]
	v_mfma_f32_16x16x32_bf16 v[0:3], v[170:173], v[206:209], v[0:3]
	s_barrier
	s_setprio 0
	s_add_i32 s75, 0, 0x18000
	s_add_i32 s76, 0, 0x1c000
	v_add_u32_e32 v84, s75, v167
	v_add_u32_e32 v166, s76, v167
	ds_read_b128 v[64:67], v84
	ds_read_b128 v[68:71], v84 offset:1024
	ds_read_b128 v[80:83], v84 offset:2048
	ds_read_b128 v[84:87], v84 offset:3072
	ds_read_b128 v[144:147], v166
	ds_read_b128 v[148:151], v166 offset:1024
	ds_read_b128 v[152:155], v166 offset:2048
	ds_read_b128 v[170:173], v166 offset:3072
	s_add_u32 s44, s44, 0x80000
	s_addc_u32 s45, s45, 0
	s_mov_b32 m0, s46
	v_lshl_add_u64 v[216:217], s[44:45], 0, v[156:157]
	ds_read_b128 v[174:177], v169 offset:32768
	ds_read_b128 v[178:181], v169 offset:33792
	ds_read_b128 v[182:185], v169 offset:34816
	ds_read_b128 v[186:189], v169 offset:35840
	ds_read_b128 v[190:193], v169 offset:36864
	ds_read_b128 v[194:197], v169 offset:37888
	ds_read_b128 v[198:201], v169 offset:38912
	ds_read_b128 v[206:209], v169 offset:39936
	global_load_lds_dwordx4 v[216:217], off
	v_lshl_add_u64 v[216:217], s[44:45], 0, v[158:159]
	s_mov_b32 m0, s47
	s_nop 0
	global_load_lds_dwordx4 v[216:217], off
	s_waitcnt vmcnt(8)
	s_waitcnt lgkmcnt(0)
	s_setprio 1
	s_barrier
	v_mfma_f32_16x16x32_bf16 v[140:143], v[64:67], v[174:177], v[140:143]
	v_mfma_f32_16x16x32_bf16 v[136:139], v[80:83], v[174:177], v[136:139]
	v_mfma_f32_16x16x32_bf16 v[124:127], v[64:67], v[182:185], v[124:127]
	v_mfma_f32_16x16x32_bf16 v[120:123], v[80:83], v[182:185], v[120:123]
	v_mfma_f32_16x16x32_bf16 v[108:111], v[64:67], v[190:193], v[108:111]
	v_mfma_f32_16x16x32_bf16 v[104:107], v[80:83], v[190:193], v[104:107]
	v_mfma_f32_16x16x32_bf16 v[92:95], v[64:67], v[198:201], v[92:95]
	v_mfma_f32_16x16x32_bf16 v[88:91], v[80:83], v[198:201], v[88:91]
	v_mfma_f32_16x16x32_bf16 v[140:143], v[68:71], v[178:181], v[140:143]
	v_mfma_f32_16x16x32_bf16 v[136:139], v[84:87], v[178:181], v[136:139]
	v_mfma_f32_16x16x32_bf16 v[124:127], v[68:71], v[186:189], v[124:127]
	v_mfma_f32_16x16x32_bf16 v[120:123], v[84:87], v[186:189], v[120:123]
	v_mfma_f32_16x16x32_bf16 v[108:111], v[68:71], v[194:197], v[108:111]
	v_mfma_f32_16x16x32_bf16 v[104:107], v[84:87], v[194:197], v[104:107]
	v_mfma_f32_16x16x32_bf16 v[92:95], v[68:71], v[206:209], v[92:95]
	v_mfma_f32_16x16x32_bf16 v[88:91], v[84:87], v[206:209], v[88:91]
	s_setprio 0
	s_setprio 1
	v_mfma_f32_16x16x32_bf16 v[132:135], v[144:147], v[174:177], v[132:135]
	v_mfma_f32_16x16x32_bf16 v[128:131], v[152:155], v[174:177], v[128:131]
	v_mfma_f32_16x16x32_bf16 v[116:119], v[144:147], v[182:185], v[116:119]
	v_mfma_f32_16x16x32_bf16 v[112:115], v[152:155], v[182:185], v[112:115]
	v_mfma_f32_16x16x32_bf16 v[100:103], v[144:147], v[190:193], v[100:103]
	v_mfma_f32_16x16x32_bf16 v[96:99], v[152:155], v[190:193], v[96:99]
	v_mfma_f32_16x16x32_bf16 v[76:79], v[144:147], v[198:201], v[76:79]
	v_mfma_f32_16x16x32_bf16 v[72:75], v[152:155], v[198:201], v[72:75]
	v_mfma_f32_16x16x32_bf16 v[132:135], v[148:151], v[178:181], v[132:135]
	v_mfma_f32_16x16x32_bf16 v[128:131], v[170:173], v[178:181], v[128:131]
	v_mfma_f32_16x16x32_bf16 v[116:119], v[148:151], v[186:189], v[116:119]
	v_mfma_f32_16x16x32_bf16 v[112:115], v[170:173], v[186:189], v[112:115]
	v_mfma_f32_16x16x32_bf16 v[100:103], v[148:151], v[194:197], v[100:103]
	v_mfma_f32_16x16x32_bf16 v[96:99], v[170:173], v[194:197], v[96:99]
	v_mfma_f32_16x16x32_bf16 v[76:79], v[148:151], v[206:209], v[76:79]
	v_mfma_f32_16x16x32_bf16 v[72:75], v[170:173], v[206:209], v[72:75]
	s_barrier
; #define PG8_STAGE(bufoff, gbase, voff) do { _Pragma("unroll") for (int _i = 0; _i < 2; ++_i) \
;         __builtin_amdgcn_global_load_lds((const unsigned*)((const char*)(gbase) + (voff)[_i]), (PG8_LAS unsigned*)(lds + (bufoff) + ldsw + _i * 8192), 16, 0, 0); } while (0)
; #define PG8_LDA(dst, b, h) do { _Pragma("unroll") for (int m = 0; m < 4; ++m) _Pragma("unroll") for (int k = 0; k < 2; ++k) dst[m][k] = *(const PG8_LAS bf16x8*)(lds + PG8_SA(b, h) + aoff + m * 2048 + k * 1024); } while (0)
; #define PG8_LDB(dst, b, h) do { _Pragma("unroll") for (int n = 0; n < 2; ++n) _Pragma("unroll") for (int k = 0; k < 2; ++k) dst[n][k] = *(const PG8_LAS bf16x8*)(lds + PG8_SB(b, h) + boff + n * 2048 + k * 1024); } while (0)
; #define PG8_MMA(ai, bj, At, Bt) do { __builtin_amdgcn_s_setprio(1); _Pragma("unroll") for (int m = 0; m < 4; ++m) _Pragma("unroll") for (int n = 0; n < 2; ++n) _Pragma("unroll") for (int k = 0; k < 2; ++k) \
;         acc[ai][bj][m][n] = __builtin_amdgcn_mfma_f32_16x16x32_bf16(Bt[n][k], At[m][k], acc[ai][bj][m][n], 0, 0, 0); __builtin_amdgcn_s_setprio(0); } while (0)
; template <class Epi, class Sched, bool ALIGN_EPI = false, bool SP2 = false>
; __device__ __forceinline__ void gemm_phase(PG8_LAS unsigned char* lds, const Gemm g, const Sched& S, const Epi& E, const int tid) {
;     ...
;     for (;;) {
;         const bool has_next = S.next(ui + 1, nxt);
;         const char* nA = has_next ? (const char*)g.A + (size_t)nxt.pm * tstep : cA; const char* nB = has_next ? (const char*)g.Bt + (size_t)nxt.pn * tstep : cB;
;         for (int t = 0; t < nt; t += 2) {
;             const bool last = (t == nt - 2);
;             const char* a1 = cA + (size_t)(t + 1) * kstep;
;             const char* a2 = last ? nA : cA + (size_t)(t + 2) * kstep; const char* b2 = last ? nB : cB + (size_t)(t + 2) * kstep;
;             const char* a3 = a2 + kstep; const char* b3 = b2 + kstep;
;             if (last && has_next) S.a_ready(nxt);
;             if constexpr (SP2) {
;             PG8_LDB(B0, 0, 0); PG8_LDB(B1, 0, 1); PG8_SCHED; PG8_LDA(At, 0, 0); PG8_STAGE(PG8_SA(1, 1), a1 + hstep, voffA);
;     ...
;             PG8_LDA(At, 1, 1); PG8_STAGE(PG8_SB(1, 0), b3, voffB); PG8_STAGE(PG8_SB(1, 1), b3 + hstep, voffB); PG8_STAGE(PG8_SA(1, 0), a3, voffA);
;             PG8_WAIT_V(8); PG8_WAIT_L(0); PG8_BAR; PG8_MMA(1, 0, At, B0); PG8_MMA(1, 1, At, B1); PG8_BAR; PG8_SCHED;
	s_setprio 0
	s_add_i32 s44, s75, s38
	v_lshl_add_u64 v[202:203], v[202:203], 0, s[70:71]
	s_mov_b32 m0, s44
	ds_read_b128 v[174:177], v169 offset:49152
	ds_read_b128 v[178:181], v169 offset:50176
	ds_read_b128 v[182:185], v169 offset:51200
	ds_read_b128 v[186:189], v169 offset:52224
	ds_read_b128 v[190:193], v169 offset:53248
	ds_read_b128 v[194:197], v169 offset:54272
	ds_read_b128 v[198:201], v169 offset:55296
	ds_read_b128 v[206:209], v169 offset:56320
	global_load_lds_dwordx4 v[202:203], off
	s_add_i32 m0, s44, 0x2000
	s_add_u32 s42, s42, 0x80080
	v_lshl_add_u64 v[202:203], v[210:211], 0, s[70:71]
	s_addc_u32 s43, s43, 0
	s_add_i32 s44, s76, s38
	global_load_lds_dwordx4 v[202:203], off
	v_lshl_add_u64 v[202:203], s[42:43], 0, v[204:205]
	s_mov_b32 m0, s44
	s_nop 0
	global_load_lds_dwordx4 v[202:203], off
	v_lshl_add_u64 v[202:203], s[42:43], 0, v[160:161]
	s_add_i32 m0, s44, 0x2000
	s_nop 0
	global_load_lds_dwordx4 v[202:203], off
	v_lshl_add_u64 v[202:203], v[212:213], 0, s[70:71]
	s_mov_b32 m0, s51
	s_nop 0
	global_load_lds_dwordx4 v[202:203], off
	v_lshl_add_u64 v[202:203], v[214:215], 0, s[70:71]
	s_mov_b32 m0, s52
	s_nop 0
	global_load_lds_dwordx4 v[202:203], off
	s_waitcnt vmcnt(8)
	s_waitcnt lgkmcnt(0)
	s_setprio 1
	s_barrier
	v_mfma_f32_16x16x32_bf16 v[60:63], v[64:67], v[174:177], v[60:63]
	v_mfma_f32_16x16x32_bf16 v[56:59], v[80:83], v[174:177], v[56:59]
	v_mfma_f32_16x16x32_bf16 v[44:47], v[64:67], v[182:185], v[44:47]
	v_mfma_f32_16x16x32_bf16 v[40:43], v[80:83], v[182:185], v[40:43]
	v_mfma_f32_16x16x32_bf16 v[28:31], v[64:67], v[190:193], v[28:31]
	v_mfma_f32_16x16x32_bf16 v[24:27], v[80:83], v[190:193], v[24:27]
	v_mfma_f32_16x16x32_bf16 v[12:15], v[64:67], v[198:201], v[12:15]
	v_mfma_f32_16x16x32_bf16 v[8:11], v[80:83], v[198:201], v[8:11]
	v_mfma_f32_16x16x32_bf16 v[60:63], v[68:71], v[178:181], v[60:63]
	v_mfma_f32_16x16x32_bf16 v[56:59], v[84:87], v[178:181], v[56:59]
	v_mfma_f32_16x16x32_bf16 v[44:47], v[68:71], v[186:189], v[44:47]
	v_mfma_f32_16x16x32_bf16 v[40:43], v[84:87], v[186:189], v[40:43]
	v_mfma_f32_16x16x32_bf16 v[28:31], v[68:71], v[194:197], v[28:31]
	v_mfma_f32_16x16x32_bf16 v[24:27], v[84:87], v[194:197], v[24:27]
	v_mfma_f32_16x16x32_bf16 v[12:15], v[68:71], v[206:209], v[12:15]
	v_mfma_f32_16x16x32_bf16 v[8:11], v[84:87], v[206:209], v[8:11]
	s_setprio 0
	s_setprio 1
	v_mfma_f32_16x16x32_bf16 v[52:55], v[144:147], v[174:177], v[52:55]
	v_mfma_f32_16x16x32_bf16 v[48:51], v[152:155], v[174:177], v[48:51]
	v_mfma_f32_16x16x32_bf16 v[36:39], v[144:147], v[182:185], v[36:39]
	v_mfma_f32_16x16x32_bf16 v[32:35], v[152:155], v[182:185], v[32:35]
	v_mfma_f32_16x16x32_bf16 v[20:23], v[144:147], v[190:193], v[20:23]
	v_mfma_f32_16x16x32_bf16 v[16:19], v[152:155], v[190:193], v[16:19]
	v_mfma_f32_16x16x32_bf16 v[4:7], v[144:147], v[198:201], v[4:7]
	v_mfma_f32_16x16x32_bf16 v[0:3], v[152:155], v[198:201], v[0:3]
	v_mfma_f32_16x16x32_bf16 v[52:55], v[148:151], v[178:181], v[52:55]
	v_mfma_f32_16x16x32_bf16 v[48:51], v[170:173], v[178:181], v[48:51]
	v_mfma_f32_16x16x32_bf16 v[36:39], v[148:151], v[186:189], v[36:39]
	v_mfma_f32_16x16x32_bf16 v[32:35], v[170:173], v[186:189], v[32:35]
	v_mfma_f32_16x16x32_bf16 v[20:23], v[148:151], v[194:197], v[20:23]
	v_mfma_f32_16x16x32_bf16 v[16:19], v[170:173], v[194:197], v[16:19]
	v_mfma_f32_16x16x32_bf16 v[4:7], v[148:151], v[206:209], v[4:7]
	v_mfma_f32_16x16x32_bf16 v[0:3], v[170:173], v[206:209], v[0:3]
	s_barrier
	s_setprio 0
	s_add_i32 s69, s69, 2
	s_add_u32 s36, s36, 0x100
	s_addc_u32 s37, s37, 0
	s_add_u32 s65, s65, 0x100
	s_addc_u32 s68, s68, 0
.LBB0_1426:
	s_add_u32 s42, s36, 0xfff80080
	s_addc_u32 s43, s37, -1
	s_add_i32 s75, 0, 0x10000
	s_cmp_eq_u32 s69, 28
	s_cselect_b32 s45, s27, s43
	s_cselect_b32 s44, s62, s42
	s_cselect_b32 s43, s25, s68
	s_cselect_b32 s42, s64, s65
	s_add_i32 s78, 0, 0x14000
	v_add_u32_e32 v84, s75, v167
	v_add_u32_e32 v166, s78, v167
	ds_read_b128 v[64:67], v84
	ds_read_b128 v[68:71], v84 offset:1024
	ds_read_b128 v[80:83], v84 offset:2048
	ds_read_b128 v[84:87], v84 offset:3072
	ds_read_b128 v[144:147], v166
	ds_read_b128 v[148:151], v166 offset:1024
	ds_read_b128 v[152:155], v166 offset:2048
	ds_read_b128 v[170:173], v166 offset:3072
	v_lshl_add_u64 v[202:203], s[36:37], 0, v[162:163]
	s_add_i32 m0, s35, 0xc000
	ds_read_b128 v[174:177], v169
	ds_read_b128 v[178:181], v169 offset:1024
	ds_read_b128 v[182:185], v169 offset:2048
	ds_read_b128 v[186:189], v169 offset:3072
	ds_read_b128 v[190:193], v169 offset:4096
	ds_read_b128 v[194:197], v169 offset:5120
	ds_read_b128 v[198:201], v169 offset:6144
	ds_read_b128 v[206:209], v169 offset:7168
	global_load_lds_dwordx4 v[202:203], off
	v_lshl_add_u64 v[202:203], s[36:37], 0, v[164:165]
	s_add_i32 m0, s35, 0xe000
	s_nop 0
	global_load_lds_dwordx4 v[202:203], off
	s_waitcnt vmcnt(8)
	s_waitcnt lgkmcnt(0)
	s_setprio 1
	s_barrier
; #define PG8_STAGE(bufoff, gbase, voff) do { _Pragma("unroll") for (int _i = 0; _i < 2; ++_i) \
;         __builtin_amdgcn_global_load_lds((const unsigned*)((const char*)(gbase) + (voff)[_i]), (PG8_LAS unsigned*)(lds + (bufoff) + ldsw + _i * 8192), 16, 0, 0); } while (0)
; #define PG8_LDA(dst, b, h) do { _Pragma("unroll") for (int m = 0; m < 4; ++m) _Pragma("unroll") for (int k = 0; k < 2; ++k) dst[m][k] = *(const PG8_LAS bf16x8*)(lds + PG8_SA(b, h) + aoff + m * 2048 + k * 1024); } while (0)
; #define PG8_MMA(ai, bj, At, Bt) do { __builtin_amdgcn_s_setprio(1); _Pragma("unroll") for (int m = 0; m < 4; ++m) _Pragma("unroll") for (int n = 0; n < 2; ++n) _Pragma("unroll") for (int k = 0; k < 2; ++k) \
;         acc[ai][bj][m][n] = __builtin_amdgcn_mfma_f32_16x16x32_bf16(Bt[n][k], At[m][k], acc[ai][bj][m][n], 0, 0, 0); __builtin_amdgcn_s_setprio(0); } while (0)
; #define PG8_WAIT_V(n) asm volatile("s_waitcnt vmcnt(" #n ")" ::: "memory")
; #define PG8_WAIT_L(n) asm volatile("s_waitcnt lgkmcnt(" #n ")" ::: "memory")
; #define PG8_BAR __builtin_amdgcn_s_barrier()
; #define PG8_SCHED __builtin_amdgcn_sched_barrier(0)
; template <class Epi, class Sched, bool ALIGN_EPI = false, bool SP2 = false>
; __device__ __forceinline__ void gemm_phase(PG8_LAS unsigned char* lds, const Gemm g, const Sched& S, const Epi& E, const int tid) {
;     ...
;             PG8_WAIT_V(8); PG8_WAIT_L(0); PG8_BAR; PG8_MMA(0, 0, At, B0); PG8_MMA(0, 1, At, B1); PG8_BAR; PG8_SCHED;
;             PG8_LDA(At, 0, 1); PG8_STAGE(PG8_SB(0, 0), b2, voffB); PG8_STAGE(PG8_SB(0, 1), b2 + hstep, voffB); PG8_STAGE(PG8_SA(0, 0), a2, voffA);
;             PG8_WAIT_V(8); PG8_WAIT_L(0); PG8_BAR; PG8_MMA(1, 0, At, B0); PG8_MMA(1, 1, At, B1); PG8_BAR; PG8_SCHED;
	v_mfma_f32_16x16x32_bf16 v[140:143], v[64:67], v[174:177], v[140:143]
	v_mfma_f32_16x16x32_bf16 v[136:139], v[80:83], v[174:177], v[136:139]
	v_mfma_f32_16x16x32_bf16 v[124:127], v[64:67], v[182:185], v[124:127]
	v_mfma_f32_16x16x32_bf16 v[120:123], v[80:83], v[182:185], v[120:123]
	v_mfma_f32_16x16x32_bf16 v[108:111], v[64:67], v[190:193], v[108:111]
	v_mfma_f32_16x16x32_bf16 v[104:107], v[80:83], v[190:193], v[104:107]
	v_mfma_f32_16x16x32_bf16 v[92:95], v[64:67], v[198:201], v[92:95]
	v_mfma_f32_16x16x32_bf16 v[88:91], v[80:83], v[198:201], v[88:91]
	v_mfma_f32_16x16x32_bf16 v[140:143], v[68:71], v[178:181], v[140:143]
	v_mfma_f32_16x16x32_bf16 v[136:139], v[84:87], v[178:181], v[136:139]
	v_mfma_f32_16x16x32_bf16 v[124:127], v[68:71], v[186:189], v[124:127]
	v_mfma_f32_16x16x32_bf16 v[120:123], v[84:87], v[186:189], v[120:123]
	v_mfma_f32_16x16x32_bf16 v[108:111], v[68:71], v[194:197], v[108:111]
	v_mfma_f32_16x16x32_bf16 v[104:107], v[84:87], v[194:197], v[104:107]
	v_mfma_f32_16x16x32_bf16 v[92:95], v[68:71], v[206:209], v[92:95]
	v_mfma_f32_16x16x32_bf16 v[88:91], v[84:87], v[206:209], v[88:91]
	s_setprio 0
	s_setprio 1
	v_mfma_f32_16x16x32_bf16 v[132:135], v[144:147], v[174:177], v[132:135]
	v_mfma_f32_16x16x32_bf16 v[128:131], v[152:155], v[174:177], v[128:131]
	v_mfma_f32_16x16x32_bf16 v[116:119], v[144:147], v[182:185], v[116:119]
	v_mfma_f32_16x16x32_bf16 v[112:115], v[152:155], v[182:185], v[112:115]
	v_mfma_f32_16x16x32_bf16 v[100:103], v[144:147], v[190:193], v[100:103]
	v_mfma_f32_16x16x32_bf16 v[96:99], v[152:155], v[190:193], v[96:99]
	v_mfma_f32_16x16x32_bf16 v[76:79], v[144:147], v[198:201], v[76:79]
	v_mfma_f32_16x16x32_bf16 v[72:75], v[152:155], v[198:201], v[72:75]
	v_mfma_f32_16x16x32_bf16 v[132:135], v[148:151], v[178:181], v[132:135]
	v_mfma_f32_16x16x32_bf16 v[128:131], v[170:173], v[178:181], v[128:131]
	v_mfma_f32_16x16x32_bf16 v[116:119], v[148:151], v[186:189], v[116:119]
	v_mfma_f32_16x16x32_bf16 v[112:115], v[170:173], v[186:189], v[112:115]
	v_mfma_f32_16x16x32_bf16 v[100:103], v[148:151], v[194:197], v[100:103]
	v_mfma_f32_16x16x32_bf16 v[96:99], v[170:173], v[194:197], v[96:99]
	v_mfma_f32_16x16x32_bf16 v[76:79], v[148:151], v[206:209], v[76:79]
	v_mfma_f32_16x16x32_bf16 v[72:75], v[170:173], v[206:209], v[72:75]
	s_barrier
	s_setprio 0
	s_add_i32 s75, s75, s38
	v_lshl_add_u64 v[202:203], s[42:43], 0, v[204:205]
	s_mov_b32 m0, s75
	ds_read_b128 v[174:177], v169 offset:16384
	ds_read_b128 v[178:181], v169 offset:17408
	ds_read_b128 v[182:185], v169 offset:18432
	ds_read_b128 v[186:189], v169 offset:19456
	ds_read_b128 v[190:193], v169 offset:20480
	ds_read_b128 v[194:197], v169 offset:21504
	ds_read_b128 v[198:201], v169 offset:22528
	ds_read_b128 v[206:209], v169 offset:23552
	global_load_lds_dwordx4 v[202:203], off
	s_add_i32 m0, s75, 0x2000
	s_add_u32 s76, s42, 0x80000
	v_lshl_add_u64 v[210:211], s[42:43], 0, v[160:161]
	s_addc_u32 s77, s43, 0
	s_add_i32 s75, s78, s38
	global_load_lds_dwordx4 v[210:211], off
	v_lshl_add_u64 v[212:213], s[76:77], 0, v[204:205]
	s_mov_b32 m0, s75
	v_lshl_add_u64 v[214:215], s[44:45], 0, v[158:159]
	global_load_lds_dwordx4 v[212:213], off
	v_lshl_add_u64 v[212:213], s[76:77], 0, v[160:161]
	s_add_i32 m0, s75, 0x2000
	s_nop 0
	global_load_lds_dwordx4 v[212:213], off
	v_lshl_add_u64 v[212:213], s[44:45], 0, v[156:157]
	s_mov_b32 m0, s35
	s_nop 0
	global_load_lds_dwordx4 v[212:213], off
	s_mov_b32 m0, s40
	s_nop 0
	global_load_lds_dwordx4 v[214:215], off
	s_waitcnt vmcnt(8)
	s_waitcnt lgkmcnt(0)
	s_setprio 1
	s_barrier
	v_mfma_f32_16x16x32_bf16 v[60:63], v[64:67], v[174:177], v[60:63]
	v_mfma_f32_16x16x32_bf16 v[56:59], v[80:83], v[174:177], v[56:59]
	v_mfma_f32_16x16x32_bf16 v[44:47], v[64:67], v[182:185], v[44:47]
	v_mfma_f32_16x16x32_bf16 v[40:43], v[80:83], v[182:185], v[40:43]
	v_mfma_f32_16x16x32_bf16 v[28:31], v[64:67], v[190:193], v[28:31]
	v_mfma_f32_16x16x32_bf16 v[24:27], v[80:83], v[190:193], v[24:27]
	v_mfma_f32_16x16x32_bf16 v[12:15], v[64:67], v[198:201], v[12:15]
	v_mfma_f32_16x16x32_bf16 v[8:11], v[80:83], v[198:201], v[8:11]
	v_mfma_f32_16x16x32_bf16 v[60:63], v[68:71], v[178:181], v[60:63]
	v_mfma_f32_16x16x32_bf16 v[56:59], v[84:87], v[178:181], v[56:59]
	v_mfma_f32_16x16x32_bf16 v[44:47], v[68:71], v[186:189], v[44:47]
	v_mfma_f32_16x16x32_bf16 v[40:43], v[84:87], v[186:189], v[40:43]
	v_mfma_f32_16x16x32_bf16 v[28:31], v[68:71], v[194:197], v[28:31]
	v_mfma_f32_16x16x32_bf16 v[24:27], v[84:87], v[194:197], v[24:27]
	v_mfma_f32_16x16x32_bf16 v[12:15], v[68:71], v[206:209], v[12:15]
	v_mfma_f32_16x16x32_bf16 v[8:11], v[84:87], v[206:209], v[8:11]
	s_setprio 0
	s_setprio 1
	v_mfma_f32_16x16x32_bf16 v[52:55], v[144:147], v[174:177], v[52:55]
	v_mfma_f32_16x16x32_bf16 v[48:51], v[152:155], v[174:177], v[48:51]
	v_mfma_f32_16x16x32_bf16 v[36:39], v[144:147], v[182:185], v[36:39]
	v_mfma_f32_16x16x32_bf16 v[32:35], v[152:155], v[182:185], v[32:35]
	v_mfma_f32_16x16x32_bf16 v[20:23], v[144:147], v[190:193], v[20:23]
	v_mfma_f32_16x16x32_bf16 v[16:19], v[152:155], v[190:193], v[16:19]
	v_mfma_f32_16x16x32_bf16 v[4:7], v[144:147], v[198:201], v[4:7]
	v_mfma_f32_16x16x32_bf16 v[0:3], v[152:155], v[198:201], v[0:3]
	v_mfma_f32_16x16x32_bf16 v[52:55], v[148:151], v[178:181], v[52:55]
	v_mfma_f32_16x16x32_bf16 v[48:51], v[170:173], v[178:181], v[48:51]
	v_mfma_f32_16x16x32_bf16 v[36:39], v[148:151], v[186:189], v[36:39]
	v_mfma_f32_16x16x32_bf16 v[32:35], v[170:173], v[186:189], v[32:35]
	v_mfma_f32_16x16x32_bf16 v[20:23], v[148:151], v[194:197], v[20:23]
	v_mfma_f32_16x16x32_bf16 v[16:19], v[170:173], v[194:197], v[16:19]
	v_mfma_f32_16x16x32_bf16 v[4:7], v[148:151], v[206:209], v[4:7]
	v_mfma_f32_16x16x32_bf16 v[0:3], v[170:173], v[206:209], v[0:3]
	s_barrier
; #define PG8_STAGE(bufoff, gbase, voff) do { _Pragma("unroll") for (int _i = 0; _i < 2; ++_i) \
;         __builtin_amdgcn_global_load_lds((const unsigned*)((const char*)(gbase) + (voff)[_i]), (PG8_LAS unsigned*)(lds + (bufoff) + ldsw + _i * 8192), 16, 0, 0); } while (0)
; #define PG8_LDA(dst, b, h) do { _Pragma("unroll") for (int m = 0; m < 4; ++m) _Pragma("unroll") for (int k = 0; k < 2; ++k) dst[m][k] = *(const PG8_LAS bf16x8*)(lds + PG8_SA(b, h) + aoff + m * 2048 + k * 1024); } while (0)
; #define PG8_LDB(dst, b, h) do { _Pragma("unroll") for (int n = 0; n < 2; ++n) _Pragma("unroll") for (int k = 0; k < 2; ++k) dst[n][k] = *(const PG8_LAS bf16x8*)(lds + PG8_SB(b, h) + boff + n * 2048 + k * 1024); } while (0)
; #define PG8_MMA(ai, bj, At, Bt) do { __builtin_amdgcn_s_setprio(1); _Pragma("unroll") for (int m = 0; m < 4; ++m) _Pragma("unroll") for (int n = 0; n < 2; ++n) _Pragma("unroll") for (int k = 0; k < 2; ++k) \
;         acc[ai][bj][m][n] = __builtin_amdgcn_mfma_f32_16x16x32_bf16(Bt[n][k], At[m][k], acc[ai][bj][m][n], 0, 0, 0); __builtin_amdgcn_s_setprio(0); } while (0)
; #define PG8_WAIT_V(n) asm volatile("s_waitcnt vmcnt(" #n ")" ::: "memory")
; #define PG8_WAIT_L(n) asm volatile("s_waitcnt lgkmcnt(" #n ")" ::: "memory")
; #define PG8_BAR __builtin_amdgcn_s_barrier()
; #define PG8_SCHED __builtin_amdgcn_sched_barrier(0)
; template <class Epi, class Sched, bool ALIGN_EPI = false, bool SP2 = false>
; __device__ __forceinline__ void gemm_phase(PG8_LAS unsigned char* lds, const Gemm g, const Sched& S, const Epi& E, const int tid) {
;     ...
;             PG8_LDB(B0, 1, 0); PG8_LDB(B1, 1, 1); PG8_SCHED; PG8_LDA(At, 1, 0); PG8_STAGE(PG8_SA(0, 1), a2 + hstep, voffA);
;             PG8_WAIT_V(8); PG8_WAIT_L(0); PG8_BAR; PG8_MMA(0, 0, At, B0); PG8_MMA(0, 1, At, B1); PG8_BAR; PG8_SCHED;
	s_setprio 0
	s_add_i32 s75, 0, 0x18000
	s_add_i32 s76, 0, 0x1c000
	v_add_u32_e32 v84, s75, v167
	v_add_u32_e32 v166, s76, v167
	ds_read_b128 v[64:67], v84
	ds_read_b128 v[68:71], v84 offset:1024
	ds_read_b128 v[80:83], v84 offset:2048
	ds_read_b128 v[84:87], v84 offset:3072
	ds_read_b128 v[144:147], v166
	ds_read_b128 v[148:151], v166 offset:1024
	ds_read_b128 v[152:155], v166 offset:2048
	ds_read_b128 v[170:173], v166 offset:3072
	s_add_u32 s44, s44, 0x80000
	s_addc_u32 s45, s45, 0
	s_mov_b32 m0, s46
	v_lshl_add_u64 v[216:217], s[44:45], 0, v[156:157]
	ds_read_b128 v[174:177], v169 offset:32768
	ds_read_b128 v[178:181], v169 offset:33792
	ds_read_b128 v[182:185], v169 offset:34816
	ds_read_b128 v[186:189], v169 offset:35840
	ds_read_b128 v[190:193], v169 offset:36864
	ds_read_b128 v[194:197], v169 offset:37888
	ds_read_b128 v[198:201], v169 offset:38912
	ds_read_b128 v[206:209], v169 offset:39936
	global_load_lds_dwordx4 v[216:217], off
	v_lshl_add_u64 v[216:217], s[44:45], 0, v[158:159]
	s_mov_b32 m0, s47
	s_nop 0
	global_load_lds_dwordx4 v[216:217], off
	s_waitcnt vmcnt(8)
	s_waitcnt lgkmcnt(0)
	s_setprio 1
	s_barrier
	v_mfma_f32_16x16x32_bf16 v[140:143], v[64:67], v[174:177], v[140:143]
	v_mfma_f32_16x16x32_bf16 v[136:139], v[80:83], v[174:177], v[136:139]
	v_mfma_f32_16x16x32_bf16 v[124:127], v[64:67], v[182:185], v[124:127]
	v_mfma_f32_16x16x32_bf16 v[120:123], v[80:83], v[182:185], v[120:123]
	v_mfma_f32_16x16x32_bf16 v[108:111], v[64:67], v[190:193], v[108:111]
	v_mfma_f32_16x16x32_bf16 v[104:107], v[80:83], v[190:193], v[104:107]
	v_mfma_f32_16x16x32_bf16 v[92:95], v[64:67], v[198:201], v[92:95]
	v_mfma_f32_16x16x32_bf16 v[88:91], v[80:83], v[198:201], v[88:91]
	v_mfma_f32_16x16x32_bf16 v[140:143], v[68:71], v[178:181], v[140:143]
	v_mfma_f32_16x16x32_bf16 v[136:139], v[84:87], v[178:181], v[136:139]
	v_mfma_f32_16x16x32_bf16 v[124:127], v[68:71], v[186:189], v[124:127]
	v_mfma_f32_16x16x32_bf16 v[120:123], v[84:87], v[186:189], v[120:123]
	v_mfma_f32_16x16x32_bf16 v[108:111], v[68:71], v[194:197], v[108:111]
	v_mfma_f32_16x16x32_bf16 v[104:107], v[84:87], v[194:197], v[104:107]
	v_mfma_f32_16x16x32_bf16 v[92:95], v[68:71], v[206:209], v[92:95]
	v_mfma_f32_16x16x32_bf16 v[88:91], v[84:87], v[206:209], v[88:91]
	s_setprio 0
	s_setprio 1
	v_mfma_f32_16x16x32_bf16 v[132:135], v[144:147], v[174:177], v[132:135]
	v_mfma_f32_16x16x32_bf16 v[128:131], v[152:155], v[174:177], v[128:131]
	v_mfma_f32_16x16x32_bf16 v[116:119], v[144:147], v[182:185], v[116:119]
	v_mfma_f32_16x16x32_bf16 v[112:115], v[152:155], v[182:185], v[112:115]
	v_mfma_f32_16x16x32_bf16 v[100:103], v[144:147], v[190:193], v[100:103]
	v_mfma_f32_16x16x32_bf16 v[96:99], v[152:155], v[190:193], v[96:99]
	v_mfma_f32_16x16x32_bf16 v[76:79], v[144:147], v[198:201], v[76:79]
	v_mfma_f32_16x16x32_bf16 v[72:75], v[152:155], v[198:201], v[72:75]
	v_mfma_f32_16x16x32_bf16 v[132:135], v[148:151], v[178:181], v[132:135]
	v_mfma_f32_16x16x32_bf16 v[128:131], v[170:173], v[178:181], v[128:131]
	v_mfma_f32_16x16x32_bf16 v[116:119], v[148:151], v[186:189], v[116:119]
	v_mfma_f32_16x16x32_bf16 v[112:115], v[170:173], v[186:189], v[112:115]
	v_mfma_f32_16x16x32_bf16 v[100:103], v[148:151], v[194:197], v[100:103]
	v_mfma_f32_16x16x32_bf16 v[96:99], v[170:173], v[194:197], v[96:99]
	v_mfma_f32_16x16x32_bf16 v[76:79], v[148:151], v[206:209], v[76:79]
	v_mfma_f32_16x16x32_bf16 v[72:75], v[170:173], v[206:209], v[72:75]
	s_barrier
; #define PG8_STAGE(bufoff, gbase, voff) do { _Pragma("unroll") for (int _i = 0; _i < 2; ++_i) \
;         __builtin_amdgcn_global_load_lds((const unsigned*)((const char*)(gbase) + (voff)[_i]), (PG8_LAS unsigned*)(lds + (bufoff) + ldsw + _i * 8192), 16, 0, 0); } while (0)
; #define PG8_LDA(dst, b, h) do { _Pragma("unroll") for (int m = 0; m < 4; ++m) _Pragma("unroll") for (int k = 0; k < 2; ++k) dst[m][k] = *(const PG8_LAS bf16x8*)(lds + PG8_SA(b, h) + aoff + m * 2048 + k * 1024); } while (0)
; #define PG8_MMA(ai, bj, At, Bt) do { __builtin_amdgcn_s_setprio(1); _Pragma("unroll") for (int m = 0; m < 4; ++m) _Pragma("unroll") for (int n = 0; n < 2; ++n) _Pragma("unroll") for (int k = 0; k < 2; ++k) \
;         acc[ai][bj][m][n] = __builtin_amdgcn_mfma_f32_16x16x32_bf16(Bt[n][k], At[m][k], acc[ai][bj][m][n], 0, 0, 0); __builtin_amdgcn_s_setprio(0); } while (0)
; #define PG8_WAIT_V(n) asm volatile("s_waitcnt vmcnt(" #n ")" ::: "memory")
; #define PG8_WAIT_L(n) asm volatile("s_waitcnt lgkmcnt(" #n ")" ::: "memory")
; #define PG8_BAR __builtin_amdgcn_s_barrier()
; #define PG8_SCHED __builtin_amdgcn_sched_barrier(0)
; template <class Epi, class Sched, bool ALIGN_EPI = false, bool SP2 = false>
; __device__ __forceinline__ void gemm_phase(PG8_LAS unsigned char* lds, const Gemm g, const Sched& S, const Epi& E, const int tid) {
;     ...
;             PG8_LDA(At, 1, 1); PG8_STAGE(PG8_SB(1, 0), b3, voffB); PG8_STAGE(PG8_SB(1, 1), b3 + hstep, voffB); PG8_STAGE(PG8_SA(1, 0), a3, voffA);
;             PG8_WAIT_V(8); PG8_WAIT_L(0); PG8_BAR; PG8_MMA(1, 0, At, B0); PG8_MMA(1, 1, At, B1); PG8_BAR; PG8_SCHED;
;     ...
;         if constexpr (ALIGN_EPI) { if (wr == 0) PG8_BAR; }
	s_setprio 0
	s_add_i32 s44, s75, s38
	v_lshl_add_u64 v[202:203], v[202:203], 0, s[70:71]
	s_mov_b32 m0, s44
	ds_read_b128 v[174:177], v169 offset:49152
	ds_read_b128 v[178:181], v169 offset:50176
	ds_read_b128 v[182:185], v169 offset:51200
	ds_read_b128 v[186:189], v169 offset:52224
	ds_read_b128 v[190:193], v169 offset:53248
	ds_read_b128 v[194:197], v169 offset:54272
	ds_read_b128 v[198:201], v169 offset:55296
	ds_read_b128 v[206:209], v169 offset:56320
	global_load_lds_dwordx4 v[202:203], off
	s_add_i32 m0, s44, 0x2000
	s_add_u32 s42, s42, 0x80080
	v_lshl_add_u64 v[202:203], v[210:211], 0, s[70:71]
	s_addc_u32 s43, s43, 0
	s_add_i32 s44, s76, s38
	global_load_lds_dwordx4 v[202:203], off
	v_lshl_add_u64 v[202:203], s[42:43], 0, v[204:205]
	s_mov_b32 m0, s44
	s_nop 0
	global_load_lds_dwordx4 v[202:203], off
	v_lshl_add_u64 v[202:203], s[42:43], 0, v[160:161]
	s_add_i32 m0, s44, 0x2000
	s_nop 0
	global_load_lds_dwordx4 v[202:203], off
	v_lshl_add_u64 v[202:203], v[212:213], 0, s[70:71]
	s_mov_b32 m0, s51
	s_nop 0
	global_load_lds_dwordx4 v[202:203], off
	v_lshl_add_u64 v[202:203], v[214:215], 0, s[70:71]
	s_mov_b32 m0, s52
	s_nop 0
	global_load_lds_dwordx4 v[202:203], off
	s_waitcnt vmcnt(8)
	s_waitcnt lgkmcnt(0)
	s_setprio 1
	s_barrier
	v_mfma_f32_16x16x32_bf16 v[60:63], v[64:67], v[174:177], v[60:63]
	v_mfma_f32_16x16x32_bf16 v[56:59], v[80:83], v[174:177], v[56:59]
	v_mfma_f32_16x16x32_bf16 v[44:47], v[64:67], v[182:185], v[44:47]
	v_mfma_f32_16x16x32_bf16 v[40:43], v[80:83], v[182:185], v[40:43]
	v_mfma_f32_16x16x32_bf16 v[28:31], v[64:67], v[190:193], v[28:31]
	v_mfma_f32_16x16x32_bf16 v[24:27], v[80:83], v[190:193], v[24:27]
	v_mfma_f32_16x16x32_bf16 v[12:15], v[64:67], v[198:201], v[12:15]
	v_mfma_f32_16x16x32_bf16 v[8:11], v[80:83], v[198:201], v[8:11]
	v_mfma_f32_16x16x32_bf16 v[60:63], v[68:71], v[178:181], v[60:63]
	v_mfma_f32_16x16x32_bf16 v[56:59], v[84:87], v[178:181], v[56:59]
	v_mfma_f32_16x16x32_bf16 v[44:47], v[68:71], v[186:189], v[44:47]
	v_mfma_f32_16x16x32_bf16 v[40:43], v[84:87], v[186:189], v[40:43]
	v_mfma_f32_16x16x32_bf16 v[28:31], v[68:71], v[194:197], v[28:31]
	v_mfma_f32_16x16x32_bf16 v[24:27], v[84:87], v[194:197], v[24:27]
	v_mfma_f32_16x16x32_bf16 v[12:15], v[68:71], v[206:209], v[12:15]
	v_mfma_f32_16x16x32_bf16 v[8:11], v[84:87], v[206:209], v[8:11]
	s_setprio 0
	s_setprio 1
	v_mfma_f32_16x16x32_bf16 v[52:55], v[144:147], v[174:177], v[52:55]
	v_mfma_f32_16x16x32_bf16 v[48:51], v[152:155], v[174:177], v[48:51]
	v_mfma_f32_16x16x32_bf16 v[36:39], v[144:147], v[182:185], v[36:39]
	v_mfma_f32_16x16x32_bf16 v[32:35], v[152:155], v[182:185], v[32:35]
	v_mfma_f32_16x16x32_bf16 v[20:23], v[144:147], v[190:193], v[20:23]
	v_mfma_f32_16x16x32_bf16 v[16:19], v[152:155], v[190:193], v[16:19]
	v_mfma_f32_16x16x32_bf16 v[4:7], v[144:147], v[198:201], v[4:7]
	v_mfma_f32_16x16x32_bf16 v[0:3], v[152:155], v[198:201], v[0:3]
	v_mfma_f32_16x16x32_bf16 v[52:55], v[148:151], v[178:181], v[52:55]
	v_mfma_f32_16x16x32_bf16 v[48:51], v[170:173], v[178:181], v[48:51]
	v_mfma_f32_16x16x32_bf16 v[36:39], v[148:151], v[186:189], v[36:39]
	v_mfma_f32_16x16x32_bf16 v[32:35], v[170:173], v[186:189], v[32:35]
	v_mfma_f32_16x16x32_bf16 v[20:23], v[148:151], v[194:197], v[20:23]
	v_mfma_f32_16x16x32_bf16 v[16:19], v[170:173], v[194:197], v[16:19]
	v_mfma_f32_16x16x32_bf16 v[4:7], v[148:151], v[206:209], v[4:7]
	v_mfma_f32_16x16x32_bf16 v[0:3], v[170:173], v[206:209], v[0:3]
	s_barrier
	s_setprio 0
	s_add_i32 s69, s69, 2
	s_add_u32 s36, s36, 0x100
	s_addc_u32 s37, s37, 0
	s_add_u32 s65, s65, 0x100
	s_addc_u32 s68, s68, 0
	s_cmp_gt_u32 s69, 29
	s_cbranch_scc0 .LBB0_1426
	s_and_b64 vcc, exec, s[22:23]
	s_cbranch_vccz .LBB0_1429
	s_barrier

; #define PG8_STAGE(bufoff, gbase, voff) do { _Pragma("unroll") for (int _i = 0; _i < 2; ++_i) \
;         __builtin_amdgcn_global_load_lds((const unsigned*)((const char*)(gbase) + (voff)[_i]), (PG8_LAS unsigned*)(lds + (bufoff) + ldsw + _i * 8192), 16, 0, 0); } while (0)
; #define PG8_LDA(dst, b, h) do { _Pragma("unroll") for (int m = 0; m < 4; ++m) _Pragma("unroll") for (int k = 0; k < 2; ++k) dst[m][k] = *(const PG8_LAS bf16x8*)(lds + PG8_SA(b, h) + aoff + m * 2048 + k * 1024); } while (0)
; #define PG8_LDB(dst, b, h) do { _Pragma("unroll") for (int n = 0; n < 2; ++n) _Pragma("unroll") for (int k = 0; k < 2; ++k) dst[n][k] = *(const PG8_LAS bf16x8*)(lds + PG8_SB(b, h) + boff + n * 2048 + k * 1024); } while (0)
; #define PG8_WAIT_V(n) asm volatile("s_waitcnt vmcnt(" #n ")" ::: "memory")
; #define PG8_WAIT_L(n) asm volatile("s_waitcnt lgkmcnt(" #n ")" ::: "memory")
; #define PG8_BAR __builtin_amdgcn_s_barrier()
; #define PG8_SCHED __builtin_amdgcn_sched_barrier(0)
; template <class Epi, class Sched, bool ALIGN_EPI = false, bool SP2 = false>
; __device__ __forceinline__ void gemm_phase(PG8_LAS unsigned char* lds, const Gemm g, const Sched& S, const Epi& E, const int tid) {
;     ...
;         const bool has_next = S.next(ui + 1, nxt);
;         const char* nA = has_next ? (const char*)g.A + (size_t)nxt.pm * tstep : cA; const char* nB = has_next ? (const char*)g.Bt + (size_t)nxt.pn * tstep : cB;
;         for (int t = 0; t < nt; t += 2) {
;             const bool last = (t == nt - 2);
;             const char* a1 = cA + (size_t)(t + 1) * kstep;
;             const char* a2 = last ? nA : cA + (size_t)(t + 2) * kstep; const char* b2 = last ? nB : cB + (size_t)(t + 2) * kstep;
;             const char* a3 = a2 + kstep; const char* b3 = b2 + kstep;
;             if (last && has_next) S.a_ready(nxt);
;             if constexpr (SP2) {
;             PG8_LDB(B0, 0, 0); PG8_LDB(B1, 0, 1); PG8_SCHED; PG8_LDA(At, 0, 0); PG8_STAGE(PG8_SA(1, 1), a1 + hstep, voffA);
;             PG8_WAIT_V(8); PG8_WAIT_L(0); PG8_BAR; PG8_MMA(0, 0, At, B0); PG8_MMA(0, 1, At, B1); PG8_BAR; PG8_SCHED;
;             PG8_LDA(At, 0, 1); PG8_STAGE(PG8_SB(0, 0), b2, voffB); PG8_STAGE(PG8_SB(0, 1), b2 + hstep, voffB); PG8_STAGE(PG8_SA(0, 0), a2, voffA);
;             PG8_WAIT_V(8); PG8_WAIT_L(0); PG8_BAR; PG8_MMA(1, 0, At, B0); PG8_MMA(1, 1, At, B1); PG8_BAR; PG8_SCHED;
.LBB0_1548:
	s_ashr_i32 s17, s16, 31
	s_lshl_b64 s[18:19], s[16:17], 18
	s_add_u32 s18, s10, s18
	s_addc_u32 s19, s11, s19
	s_and_b64 s[20:21], s[4:5], exec
	s_cselect_b32 s17, s19, s25
	s_cselect_b32 s48, s18, s24
	s_ashr_i32 s15, s14, 31
	s_lshl_b64 s[20:21], s[14:15], 18
	s_add_u32 s20, s30, s20
	s_addc_u32 s21, s31, s21
	s_and_b64 s[28:29], s[4:5], exec
	s_cselect_b32 s15, s21, s27
	s_cselect_b32 s49, s20, s26
	s_add_u32 s24, s24, 0x20080
	s_addc_u32 s25, s25, 0
	s_add_u32 s50, s26, 0x100
	s_addc_u32 s51, s27, 0
	s_mov_b32 s52, -2
	s_add_u32 s26, s24, 0xfffe0080
	s_addc_u32 s27, s25, -1
	s_add_i32 s53, 0, 0x10000
	s_cmp_eq_u32 s52, 4
	s_cselect_b32 s29, s17, s27
	s_cselect_b32 s28, s48, s26
	s_cselect_b32 s27, s15, s51
	s_cselect_b32 s26, s49, s50
	s_add_i32 s62, 0, 0x14000
	v_add_u32_e32 v152, s53, v142
	v_add_u32_e32 v168, s62, v142
	ds_read_b128 v[138:141], v152
	ds_read_b128 v[144:147], v152 offset:1024
	ds_read_b128 v[148:151], v152 offset:2048
	ds_read_b128 v[152:155], v152 offset:3072
	ds_read_b128 v[156:159], v168
	ds_read_b128 v[160:163], v168 offset:1024
	ds_read_b128 v[164:167], v168 offset:2048
	ds_read_b128 v[168:171], v168 offset:3072
	v_lshl_add_u64 v[206:207], s[24:25], 0, v[134:135]
	s_add_i32 m0, s23, 0xc000
	ds_read_b128 v[172:175], v143
	ds_read_b128 v[176:179], v143 offset:1024
	ds_read_b128 v[180:183], v143 offset:2048
	ds_read_b128 v[184:187], v143 offset:3072
	ds_read_b128 v[188:191], v143 offset:4096
	ds_read_b128 v[192:195], v143 offset:5120
	ds_read_b128 v[196:199], v143 offset:6144
	ds_read_b128 v[200:203], v143 offset:7168
	global_load_lds_dwordx4 v[206:207], off
	v_lshl_add_u64 v[206:207], s[24:25], 0, v[136:137]
	s_add_i32 m0, s23, 0xe000
	s_nop 0
	global_load_lds_dwordx4 v[206:207], off
	s_waitcnt vmcnt(24)
	s_waitcnt lgkmcnt(0)
	s_setprio 1
	s_barrier
	v_mfma_f32_16x16x32_bf16 v[124:127], v[138:141], v[172:175], 0
	v_mfma_f32_16x16x32_bf16 v[120:123], v[148:151], v[172:175], 0
	v_mfma_f32_16x16x32_bf16 v[116:119], v[138:141], v[180:183], 0
	v_mfma_f32_16x16x32_bf16 v[108:111], v[148:151], v[180:183], 0
	v_mfma_f32_16x16x32_bf16 v[100:103], v[138:141], v[188:191], 0
	v_mfma_f32_16x16x32_bf16 v[92:95], v[148:151], v[188:191], 0
	v_mfma_f32_16x16x32_bf16 v[84:87], v[138:141], v[196:199], 0
	v_mfma_f32_16x16x32_bf16 v[76:79], v[148:151], v[196:199], 0
	v_mfma_f32_16x16x32_bf16 v[124:127], v[144:147], v[176:179], v[124:127]
	v_mfma_f32_16x16x32_bf16 v[120:123], v[152:155], v[176:179], v[120:123]
	v_mfma_f32_16x16x32_bf16 v[116:119], v[144:147], v[184:187], v[116:119]
	v_mfma_f32_16x16x32_bf16 v[108:111], v[152:155], v[184:187], v[108:111]
	v_mfma_f32_16x16x32_bf16 v[100:103], v[144:147], v[192:195], v[100:103]
	v_mfma_f32_16x16x32_bf16 v[92:95], v[152:155], v[192:195], v[92:95]
	v_mfma_f32_16x16x32_bf16 v[84:87], v[144:147], v[200:203], v[84:87]
	v_mfma_f32_16x16x32_bf16 v[76:79], v[152:155], v[200:203], v[76:79]
	s_setprio 0
	s_setprio 1
	v_mfma_f32_16x16x32_bf16 v[112:115], v[156:159], v[172:175], 0
	v_mfma_f32_16x16x32_bf16 v[104:107], v[164:167], v[172:175], 0
	v_mfma_f32_16x16x32_bf16 v[96:99], v[156:159], v[180:183], 0
	v_mfma_f32_16x16x32_bf16 v[88:91], v[164:167], v[180:183], 0
	v_mfma_f32_16x16x32_bf16 v[80:83], v[156:159], v[188:191], 0
	v_mfma_f32_16x16x32_bf16 v[72:75], v[164:167], v[188:191], 0
	v_mfma_f32_16x16x32_bf16 v[68:71], v[156:159], v[196:199], 0
	v_mfma_f32_16x16x32_bf16 v[64:67], v[164:167], v[196:199], 0
	v_mfma_f32_16x16x32_bf16 v[112:115], v[160:163], v[176:179], v[112:115]
	v_mfma_f32_16x16x32_bf16 v[104:107], v[168:171], v[176:179], v[104:107]
	v_mfma_f32_16x16x32_bf16 v[96:99], v[160:163], v[184:187], v[96:99]
	v_mfma_f32_16x16x32_bf16 v[88:91], v[168:171], v[184:187], v[88:91]
	v_mfma_f32_16x16x32_bf16 v[80:83], v[160:163], v[192:195], v[80:83]
	v_mfma_f32_16x16x32_bf16 v[72:75], v[168:171], v[192:195], v[72:75]
	v_mfma_f32_16x16x32_bf16 v[68:71], v[160:163], v[200:203], v[68:71]
	v_mfma_f32_16x16x32_bf16 v[64:67], v[168:171], v[200:203], v[64:67]
	s_barrier
	s_setprio 0
	s_add_i32 s53, s53, s33
	v_lshl_add_u64 v[206:207], s[26:27], 0, v[204:205]
	s_mov_b32 m0, s53
	ds_read_b128 v[172:175], v143 offset:16384
	ds_read_b128 v[176:179], v143 offset:17408
	ds_read_b128 v[180:183], v143 offset:18432
	ds_read_b128 v[184:187], v143 offset:19456
	ds_read_b128 v[188:191], v143 offset:20480
	ds_read_b128 v[192:195], v143 offset:21504
	ds_read_b128 v[196:199], v143 offset:22528
	ds_read_b128 v[200:203], v143 offset:23552
	global_load_lds_dwordx4 v[206:207], off
	s_add_i32 m0, s53, 0x2000
	s_add_u32 s54, s26, 0x20000
	v_lshl_add_u64 v[208:209], s[26:27], 0, v[128:129]
	s_addc_u32 s55, s27, 0
	s_add_i32 s53, s62, s33
	global_load_lds_dwordx4 v[208:209], off
	v_lshl_add_u64 v[210:211], s[54:55], 0, v[204:205]
	s_mov_b32 m0, s53
	v_lshl_add_u64 v[212:213], s[28:29], 0, v[130:131]
	global_load_lds_dwordx4 v[210:211], off
	v_lshl_add_u64 v[210:211], s[54:55], 0, v[128:129]
	s_add_i32 m0, s53, 0x2000
	s_nop 0
	global_load_lds_dwordx4 v[210:211], off
	v_lshl_add_u64 v[210:211], s[28:29], 0, v[132:133]
	s_mov_b32 m0, s23
	s_nop 0
	global_load_lds_dwordx4 v[210:211], off
	s_mov_b32 m0, s35
	s_nop 0
	global_load_lds_dwordx4 v[212:213], off
	s_waitcnt vmcnt(8)
	s_waitcnt lgkmcnt(0)
	s_setprio 1
	s_barrier
; #define PG8_STAGE(bufoff, gbase, voff) do { _Pragma("unroll") for (int _i = 0; _i < 2; ++_i) \
;         __builtin_amdgcn_global_load_lds((const unsigned*)((const char*)(gbase) + (voff)[_i]), (PG8_LAS unsigned*)(lds + (bufoff) + ldsw + _i * 8192), 16, 0, 0); } while (0)
; #define PG8_LDA(dst, b, h) do { _Pragma("unroll") for (int m = 0; m < 4; ++m) _Pragma("unroll") for (int k = 0; k < 2; ++k) dst[m][k] = *(const PG8_LAS bf16x8*)(lds + PG8_SA(b, h) + aoff + m * 2048 + k * 1024); } while (0)
; #define PG8_LDB(dst, b, h) do { _Pragma("unroll") for (int n = 0; n < 2; ++n) _Pragma("unroll") for (int k = 0; k < 2; ++k) dst[n][k] = *(const PG8_LAS bf16x8*)(lds + PG8_SB(b, h) + boff + n * 2048 + k * 1024); } while (0)
; #define PG8_MMA(ai, bj, At, Bt) do { __builtin_amdgcn_s_setprio(1); _Pragma("unroll") for (int m = 0; m < 4; ++m) _Pragma("unroll") for (int n = 0; n < 2; ++n) _Pragma("unroll") for (int k = 0; k < 2; ++k) \
;         acc[ai][bj][m][n] = __builtin_amdgcn_mfma_f32_16x16x32_bf16(Bt[n][k], At[m][k], acc[ai][bj][m][n], 0, 0, 0); __builtin_amdgcn_s_setprio(0); } while (0)
; #define PG8_WAIT_V(n) asm volatile("s_waitcnt vmcnt(" #n ")" ::: "memory")
; #define PG8_WAIT_L(n) asm volatile("s_waitcnt lgkmcnt(" #n ")" ::: "memory")
; #define PG8_BAR __builtin_amdgcn_s_barrier()
; #define PG8_SCHED __builtin_amdgcn_sched_barrier(0)
; template <class Epi, class Sched, bool ALIGN_EPI = false, bool SP2 = false>
; __device__ __forceinline__ void gemm_phase(PG8_LAS unsigned char* lds, const Gemm g, const Sched& S, const Epi& E, const int tid) {
;     ...
;             PG8_WAIT_V(8); PG8_WAIT_L(0); PG8_BAR; PG8_MMA(1, 0, At, B0); PG8_MMA(1, 1, At, B1); PG8_BAR; PG8_SCHED;
;             PG8_LDB(B0, 1, 0); PG8_LDB(B1, 1, 1); PG8_SCHED; PG8_LDA(At, 1, 0); PG8_STAGE(PG8_SA(0, 1), a2 + hstep, voffA);
;             PG8_WAIT_V(8); PG8_WAIT_L(0); PG8_BAR; PG8_MMA(0, 0, At, B0); PG8_MMA(0, 1, At, B1); PG8_BAR; PG8_SCHED;
	v_mfma_f32_16x16x32_bf16 v[60:63], v[138:141], v[172:175], 0
	v_mfma_f32_16x16x32_bf16 v[56:59], v[148:151], v[172:175], 0
	v_mfma_f32_16x16x32_bf16 v[52:55], v[138:141], v[180:183], 0
	v_mfma_f32_16x16x32_bf16 v[44:47], v[148:151], v[180:183], 0
	v_mfma_f32_16x16x32_bf16 v[36:39], v[138:141], v[188:191], 0
	v_mfma_f32_16x16x32_bf16 v[28:31], v[148:151], v[188:191], 0
	v_mfma_f32_16x16x32_bf16 v[20:23], v[138:141], v[196:199], 0
	v_mfma_f32_16x16x32_bf16 v[12:15], v[148:151], v[196:199], 0
	v_mfma_f32_16x16x32_bf16 v[60:63], v[144:147], v[176:179], v[60:63]
	v_mfma_f32_16x16x32_bf16 v[56:59], v[152:155], v[176:179], v[56:59]
	v_mfma_f32_16x16x32_bf16 v[52:55], v[144:147], v[184:187], v[52:55]
	v_mfma_f32_16x16x32_bf16 v[44:47], v[152:155], v[184:187], v[44:47]
	v_mfma_f32_16x16x32_bf16 v[36:39], v[144:147], v[192:195], v[36:39]
	v_mfma_f32_16x16x32_bf16 v[28:31], v[152:155], v[192:195], v[28:31]
	v_mfma_f32_16x16x32_bf16 v[20:23], v[144:147], v[200:203], v[20:23]
	v_mfma_f32_16x16x32_bf16 v[12:15], v[152:155], v[200:203], v[12:15]
	s_setprio 0
	s_setprio 1
	v_mfma_f32_16x16x32_bf16 v[48:51], v[156:159], v[172:175], 0
	v_mfma_f32_16x16x32_bf16 v[40:43], v[164:167], v[172:175], 0
	v_mfma_f32_16x16x32_bf16 v[32:35], v[156:159], v[180:183], 0
	v_mfma_f32_16x16x32_bf16 v[24:27], v[164:167], v[180:183], 0
	v_mfma_f32_16x16x32_bf16 v[16:19], v[156:159], v[188:191], 0
	v_mfma_f32_16x16x32_bf16 v[8:11], v[164:167], v[188:191], 0
	v_mfma_f32_16x16x32_bf16 v[4:7], v[156:159], v[196:199], 0
	v_mfma_f32_16x16x32_bf16 v[0:3], v[164:167], v[196:199], 0
	v_mfma_f32_16x16x32_bf16 v[48:51], v[160:163], v[176:179], v[48:51]
	v_mfma_f32_16x16x32_bf16 v[40:43], v[168:171], v[176:179], v[40:43]
	v_mfma_f32_16x16x32_bf16 v[32:35], v[160:163], v[184:187], v[32:35]
	v_mfma_f32_16x16x32_bf16 v[24:27], v[168:171], v[184:187], v[24:27]
	v_mfma_f32_16x16x32_bf16 v[16:19], v[160:163], v[192:195], v[16:19]
	v_mfma_f32_16x16x32_bf16 v[8:11], v[168:171], v[192:195], v[8:11]
	v_mfma_f32_16x16x32_bf16 v[4:7], v[160:163], v[200:203], v[4:7]
	v_mfma_f32_16x16x32_bf16 v[0:3], v[168:171], v[200:203], v[0:3]
	s_barrier
	s_setprio 0
	s_add_i32 s53, 0, 0x18000
	s_add_i32 s54, 0, 0x1c000
	v_add_u32_e32 v152, s53, v142
	v_add_u32_e32 v168, s54, v142
	ds_read_b128 v[138:141], v152
	ds_read_b128 v[144:147], v152 offset:1024
	ds_read_b128 v[148:151], v152 offset:2048
	ds_read_b128 v[152:155], v152 offset:3072
	ds_read_b128 v[156:159], v168
	ds_read_b128 v[160:163], v168 offset:1024
	ds_read_b128 v[164:167], v168 offset:2048
	ds_read_b128 v[168:171], v168 offset:3072
	s_add_u32 s28, s28, 0x20000
	s_addc_u32 s29, s29, 0
	s_mov_b32 m0, s36
	v_lshl_add_u64 v[214:215], s[28:29], 0, v[132:133]
	ds_read_b128 v[172:175], v143 offset:32768
	ds_read_b128 v[176:179], v143 offset:33792
	ds_read_b128 v[180:183], v143 offset:34816
	ds_read_b128 v[184:187], v143 offset:35840
	ds_read_b128 v[188:191], v143 offset:36864
	ds_read_b128 v[192:195], v143 offset:37888
	ds_read_b128 v[196:199], v143 offset:38912
	ds_read_b128 v[200:203], v143 offset:39936
	global_load_lds_dwordx4 v[214:215], off
	v_lshl_add_u64 v[214:215], s[28:29], 0, v[130:131]
	s_mov_b32 m0, s37
	s_nop 0
	global_load_lds_dwordx4 v[214:215], off
	s_waitcnt vmcnt(8)
	s_waitcnt lgkmcnt(0)
	s_setprio 1
	s_barrier
	v_mfma_f32_16x16x32_bf16 v[124:127], v[138:141], v[172:175], v[124:127]
	v_mfma_f32_16x16x32_bf16 v[120:123], v[148:151], v[172:175], v[120:123]
	v_mfma_f32_16x16x32_bf16 v[116:119], v[138:141], v[180:183], v[116:119]
	v_mfma_f32_16x16x32_bf16 v[108:111], v[148:151], v[180:183], v[108:111]
	v_mfma_f32_16x16x32_bf16 v[100:103], v[138:141], v[188:191], v[100:103]
	v_mfma_f32_16x16x32_bf16 v[92:95], v[148:151], v[188:191], v[92:95]
	v_mfma_f32_16x16x32_bf16 v[84:87], v[138:141], v[196:199], v[84:87]
	v_mfma_f32_16x16x32_bf16 v[76:79], v[148:151], v[196:199], v[76:79]
	v_mfma_f32_16x16x32_bf16 v[124:127], v[144:147], v[176:179], v[124:127]
	v_mfma_f32_16x16x32_bf16 v[120:123], v[152:155], v[176:179], v[120:123]
	v_mfma_f32_16x16x32_bf16 v[116:119], v[144:147], v[184:187], v[116:119]
	v_mfma_f32_16x16x32_bf16 v[108:111], v[152:155], v[184:187], v[108:111]
	v_mfma_f32_16x16x32_bf16 v[100:103], v[144:147], v[192:195], v[100:103]
	v_mfma_f32_16x16x32_bf16 v[92:95], v[152:155], v[192:195], v[92:95]
	v_mfma_f32_16x16x32_bf16 v[84:87], v[144:147], v[200:203], v[84:87]
	v_mfma_f32_16x16x32_bf16 v[76:79], v[152:155], v[200:203], v[76:79]
	s_setprio 0
	s_setprio 1
	v_mfma_f32_16x16x32_bf16 v[112:115], v[156:159], v[172:175], v[112:115]
	v_mfma_f32_16x16x32_bf16 v[104:107], v[164:167], v[172:175], v[104:107]
	v_mfma_f32_16x16x32_bf16 v[96:99], v[156:159], v[180:183], v[96:99]
	v_mfma_f32_16x16x32_bf16 v[88:91], v[164:167], v[180:183], v[88:91]
	v_mfma_f32_16x16x32_bf16 v[80:83], v[156:159], v[188:191], v[80:83]
	v_mfma_f32_16x16x32_bf16 v[72:75], v[164:167], v[188:191], v[72:75]
	v_mfma_f32_16x16x32_bf16 v[68:71], v[156:159], v[196:199], v[68:71]
	v_mfma_f32_16x16x32_bf16 v[64:67], v[164:167], v[196:199], v[64:67]
	v_mfma_f32_16x16x32_bf16 v[112:115], v[160:163], v[176:179], v[112:115]
	v_mfma_f32_16x16x32_bf16 v[104:107], v[168:171], v[176:179], v[104:107]
	v_mfma_f32_16x16x32_bf16 v[96:99], v[160:163], v[184:187], v[96:99]
	v_mfma_f32_16x16x32_bf16 v[88:91], v[168:171], v[184:187], v[88:91]
	v_mfma_f32_16x16x32_bf16 v[80:83], v[160:163], v[192:195], v[80:83]
	v_mfma_f32_16x16x32_bf16 v[72:75], v[168:171], v[192:195], v[72:75]
	v_mfma_f32_16x16x32_bf16 v[68:71], v[160:163], v[200:203], v[68:71]
	v_mfma_f32_16x16x32_bf16 v[64:67], v[168:171], v[200:203], v[64:67]
	s_barrier
; #define PG8_STAGE(bufoff, gbase, voff) do { _Pragma("unroll") for (int _i = 0; _i < 2; ++_i) \
;         __builtin_amdgcn_global_load_lds((const unsigned*)((const char*)(gbase) + (voff)[_i]), (PG8_LAS unsigned*)(lds + (bufoff) + ldsw + _i * 8192), 16, 0, 0); } while (0)
; #define PG8_LDA(dst, b, h) do { _Pragma("unroll") for (int m = 0; m < 4; ++m) _Pragma("unroll") for (int k = 0; k < 2; ++k) dst[m][k] = *(const PG8_LAS bf16x8*)(lds + PG8_SA(b, h) + aoff + m * 2048 + k * 1024); } while (0)
; #define PG8_LDB(dst, b, h) do { _Pragma("unroll") for (int n = 0; n < 2; ++n) _Pragma("unroll") for (int k = 0; k < 2; ++k) dst[n][k] = *(const PG8_LAS bf16x8*)(lds + PG8_SB(b, h) + boff + n * 2048 + k * 1024); } while (0)
; #define PG8_MMA(ai, bj, At, Bt) do { __builtin_amdgcn_s_setprio(1); _Pragma("unroll") for (int m = 0; m < 4; ++m) _Pragma("unroll") for (int n = 0; n < 2; ++n) _Pragma("unroll") for (int k = 0; k < 2; ++k) \
;         acc[ai][bj][m][n] = __builtin_amdgcn_mfma_f32_16x16x32_bf16(Bt[n][k], At[m][k], acc[ai][bj][m][n], 0, 0, 0); __builtin_amdgcn_s_setprio(0); } while (0)
; template <class Epi, class Sched, bool ALIGN_EPI = false, bool SP2 = false>
; __device__ __forceinline__ void gemm_phase(PG8_LAS unsigned char* lds, const Gemm g, const Sched& S, const Epi& E, const int tid) {
;     ...
;     for (;;) {
;         const bool has_next = S.next(ui + 1, nxt);
;         const char* nA = has_next ? (const char*)g.A + (size_t)nxt.pm * tstep : cA; const char* nB = has_next ? (const char*)g.Bt + (size_t)nxt.pn * tstep : cB;
;         for (int t = 0; t < nt; t += 2) {
;             const bool last = (t == nt - 2);
;             const char* a1 = cA + (size_t)(t + 1) * kstep;
;             const char* a2 = last ? nA : cA + (size_t)(t + 2) * kstep; const char* b2 = last ? nB : cB + (size_t)(t + 2) * kstep;
;             const char* a3 = a2 + kstep; const char* b3 = b2 + kstep;
;             if (last && has_next) S.a_ready(nxt);
;             if constexpr (SP2) {
;             PG8_LDB(B0, 0, 0); PG8_LDB(B1, 0, 1); PG8_SCHED; PG8_LDA(At, 0, 0); PG8_STAGE(PG8_SA(1, 1), a1 + hstep, voffA);
;     ...
;             PG8_LDA(At, 1, 1); PG8_STAGE(PG8_SB(1, 0), b3, voffB); PG8_STAGE(PG8_SB(1, 1), b3 + hstep, voffB); PG8_STAGE(PG8_SA(1, 0), a3, voffA);
;             PG8_WAIT_V(8); PG8_WAIT_L(0); PG8_BAR; PG8_MMA(1, 0, At, B0); PG8_MMA(1, 1, At, B1); PG8_BAR; PG8_SCHED;
	s_setprio 0
	s_add_i32 s28, s53, s33
	v_lshl_add_u64 v[206:207], v[206:207], 0, s[70:71]
	s_mov_b32 m0, s28
	ds_read_b128 v[172:175], v143 offset:49152
	ds_read_b128 v[176:179], v143 offset:50176
	ds_read_b128 v[180:183], v143 offset:51200
	ds_read_b128 v[184:187], v143 offset:52224
	ds_read_b128 v[188:191], v143 offset:53248
	ds_read_b128 v[192:195], v143 offset:54272
	ds_read_b128 v[196:199], v143 offset:55296
	ds_read_b128 v[200:203], v143 offset:56320
	global_load_lds_dwordx4 v[206:207], off
	s_add_i32 m0, s28, 0x2000
	s_add_u32 s26, s26, 0x20080
	v_lshl_add_u64 v[206:207], v[208:209], 0, s[70:71]
	s_addc_u32 s27, s27, 0
	s_add_i32 s28, s54, s33
	global_load_lds_dwordx4 v[206:207], off
	v_lshl_add_u64 v[206:207], s[26:27], 0, v[204:205]
	s_mov_b32 m0, s28
	s_nop 0
	global_load_lds_dwordx4 v[206:207], off
	v_lshl_add_u64 v[206:207], s[26:27], 0, v[128:129]
	s_add_i32 m0, s28, 0x2000
	s_nop 0
	global_load_lds_dwordx4 v[206:207], off
	v_lshl_add_u64 v[206:207], v[210:211], 0, s[70:71]
	s_mov_b32 m0, s43
	s_nop 0
	global_load_lds_dwordx4 v[206:207], off
	v_lshl_add_u64 v[206:207], v[212:213], 0, s[70:71]
	s_mov_b32 m0, s44
	s_nop 0
	global_load_lds_dwordx4 v[206:207], off
	s_waitcnt vmcnt(8)
	s_waitcnt lgkmcnt(0)
	s_setprio 1
	s_barrier
	v_mfma_f32_16x16x32_bf16 v[60:63], v[138:141], v[172:175], v[60:63]
	v_mfma_f32_16x16x32_bf16 v[56:59], v[148:151], v[172:175], v[56:59]
	v_mfma_f32_16x16x32_bf16 v[52:55], v[138:141], v[180:183], v[52:55]
	v_mfma_f32_16x16x32_bf16 v[44:47], v[148:151], v[180:183], v[44:47]
	v_mfma_f32_16x16x32_bf16 v[36:39], v[138:141], v[188:191], v[36:39]
	v_mfma_f32_16x16x32_bf16 v[28:31], v[148:151], v[188:191], v[28:31]
	v_mfma_f32_16x16x32_bf16 v[20:23], v[138:141], v[196:199], v[20:23]
	v_mfma_f32_16x16x32_bf16 v[12:15], v[148:151], v[196:199], v[12:15]
	v_mfma_f32_16x16x32_bf16 v[60:63], v[144:147], v[176:179], v[60:63]
	v_mfma_f32_16x16x32_bf16 v[56:59], v[152:155], v[176:179], v[56:59]
	v_mfma_f32_16x16x32_bf16 v[52:55], v[144:147], v[184:187], v[52:55]
	v_mfma_f32_16x16x32_bf16 v[44:47], v[152:155], v[184:187], v[44:47]
	v_mfma_f32_16x16x32_bf16 v[36:39], v[144:147], v[192:195], v[36:39]
	v_mfma_f32_16x16x32_bf16 v[28:31], v[152:155], v[192:195], v[28:31]
	v_mfma_f32_16x16x32_bf16 v[20:23], v[144:147], v[200:203], v[20:23]
	v_mfma_f32_16x16x32_bf16 v[12:15], v[152:155], v[200:203], v[12:15]
	s_setprio 0
	s_setprio 1
	v_mfma_f32_16x16x32_bf16 v[48:51], v[156:159], v[172:175], v[48:51]
	v_mfma_f32_16x16x32_bf16 v[40:43], v[164:167], v[172:175], v[40:43]
	v_mfma_f32_16x16x32_bf16 v[32:35], v[156:159], v[180:183], v[32:35]
	v_mfma_f32_16x16x32_bf16 v[24:27], v[164:167], v[180:183], v[24:27]
	v_mfma_f32_16x16x32_bf16 v[16:19], v[156:159], v[188:191], v[16:19]
	v_mfma_f32_16x16x32_bf16 v[8:11], v[164:167], v[188:191], v[8:11]
	v_mfma_f32_16x16x32_bf16 v[4:7], v[156:159], v[196:199], v[4:7]
	v_mfma_f32_16x16x32_bf16 v[0:3], v[164:167], v[196:199], v[0:3]
	v_mfma_f32_16x16x32_bf16 v[48:51], v[160:163], v[176:179], v[48:51]
	v_mfma_f32_16x16x32_bf16 v[40:43], v[168:171], v[176:179], v[40:43]
	v_mfma_f32_16x16x32_bf16 v[32:35], v[160:163], v[184:187], v[32:35]
	v_mfma_f32_16x16x32_bf16 v[24:27], v[168:171], v[184:187], v[24:27]
	v_mfma_f32_16x16x32_bf16 v[16:19], v[160:163], v[192:195], v[16:19]
	v_mfma_f32_16x16x32_bf16 v[8:11], v[168:171], v[192:195], v[8:11]
	v_mfma_f32_16x16x32_bf16 v[4:7], v[160:163], v[200:203], v[4:7]
	v_mfma_f32_16x16x32_bf16 v[0:3], v[168:171], v[200:203], v[0:3]
	s_barrier
	s_setprio 0
	s_add_i32 s52, s52, 2
	s_add_u32 s24, s24, 0x100
	s_addc_u32 s25, s25, 0
	s_add_u32 s50, s50, 0x100
	s_addc_u32 s51, s51, 0
.LBB0_1549:
	s_add_u32 s26, s24, 0xfffe0080
	s_addc_u32 s27, s25, -1
	s_add_i32 s53, 0, 0x10000
	s_cmp_eq_u32 s52, 4
	s_cselect_b32 s29, s17, s27
	s_cselect_b32 s28, s48, s26
	s_cselect_b32 s27, s15, s51
	s_cselect_b32 s26, s49, s50
	s_add_i32 s62, 0, 0x14000
	v_add_u32_e32 v152, s53, v142
	v_add_u32_e32 v168, s62, v142
	ds_read_b128 v[138:141], v152
	ds_read_b128 v[144:147], v152 offset:1024
	ds_read_b128 v[148:151], v152 offset:2048
	ds_read_b128 v[152:155], v152 offset:3072
	ds_read_b128 v[156:159], v168
	ds_read_b128 v[160:163], v168 offset:1024
	ds_read_b128 v[164:167], v168 offset:2048
	ds_read_b128 v[168:171], v168 offset:3072
	v_lshl_add_u64 v[206:207], s[24:25], 0, v[134:135]
	s_add_i32 m0, s23, 0xc000
	ds_read_b128 v[172:175], v143
	ds_read_b128 v[176:179], v143 offset:1024
	ds_read_b128 v[180:183], v143 offset:2048
	ds_read_b128 v[184:187], v143 offset:3072
	ds_read_b128 v[188:191], v143 offset:4096
	ds_read_b128 v[192:195], v143 offset:5120
	ds_read_b128 v[196:199], v143 offset:6144
	ds_read_b128 v[200:203], v143 offset:7168
	global_load_lds_dwordx4 v[206:207], off
	v_lshl_add_u64 v[206:207], s[24:25], 0, v[136:137]
	s_add_i32 m0, s23, 0xe000
	s_nop 0
	global_load_lds_dwordx4 v[206:207], off
	s_waitcnt vmcnt(8)
	s_waitcnt lgkmcnt(0)
	s_setprio 1
	s_barrier
; #define PG8_STAGE(bufoff, gbase, voff) do { _Pragma("unroll") for (int _i = 0; _i < 2; ++_i) \
;         __builtin_amdgcn_global_load_lds((const unsigned*)((const char*)(gbase) + (voff)[_i]), (PG8_LAS unsigned*)(lds + (bufoff) + ldsw + _i * 8192), 16, 0, 0); } while (0)
; #define PG8_LDA(dst, b, h) do { _Pragma("unroll") for (int m = 0; m < 4; ++m) _Pragma("unroll") for (int k = 0; k < 2; ++k) dst[m][k] = *(const PG8_LAS bf16x8*)(lds + PG8_SA(b, h) + aoff + m * 2048 + k * 1024); } while (0)
; #define PG8_MMA(ai, bj, At, Bt) do { __builtin_amdgcn_s_setprio(1); _Pragma("unroll") for (int m = 0; m < 4; ++m) _Pragma("unroll") for (int n = 0; n < 2; ++n) _Pragma("unroll") for (int k = 0; k < 2; ++k) \
;         acc[ai][bj][m][n] = __builtin_amdgcn_mfma_f32_16x16x32_bf16(Bt[n][k], At[m][k], acc[ai][bj][m][n], 0, 0, 0); __builtin_amdgcn_s_setprio(0); } while (0)
; #define PG8_WAIT_V(n) asm volatile("s_waitcnt vmcnt(" #n ")" ::: "memory")
; #define PG8_WAIT_L(n) asm volatile("s_waitcnt lgkmcnt(" #n ")" ::: "memory")
; #define PG8_BAR __builtin_amdgcn_s_barrier()
; #define PG8_SCHED __builtin_amdgcn_sched_barrier(0)
; template <class Epi, class Sched, bool ALIGN_EPI = false, bool SP2 = false>
; __device__ __forceinline__ void gemm_phase(PG8_LAS unsigned char* lds, const Gemm g, const Sched& S, const Epi& E, const int tid) {
;     ...
;             PG8_WAIT_V(8); PG8_WAIT_L(0); PG8_BAR; PG8_MMA(0, 0, At, B0); PG8_MMA(0, 1, At, B1); PG8_BAR; PG8_SCHED;
;             PG8_LDA(At, 0, 1); PG8_STAGE(PG8_SB(0, 0), b2, voffB); PG8_STAGE(PG8_SB(0, 1), b2 + hstep, voffB); PG8_STAGE(PG8_SA(0, 0), a2, voffA);
;             PG8_WAIT_V(8); PG8_WAIT_L(0); PG8_BAR; PG8_MMA(1, 0, At, B0); PG8_MMA(1, 1, At, B1); PG8_BAR; PG8_SCHED;
	v_mfma_f32_16x16x32_bf16 v[124:127], v[138:141], v[172:175], v[124:127]
	v_mfma_f32_16x16x32_bf16 v[120:123], v[148:151], v[172:175], v[120:123]
	v_mfma_f32_16x16x32_bf16 v[116:119], v[138:141], v[180:183], v[116:119]
	v_mfma_f32_16x16x32_bf16 v[108:111], v[148:151], v[180:183], v[108:111]
	v_mfma_f32_16x16x32_bf16 v[100:103], v[138:141], v[188:191], v[100:103]
	v_mfma_f32_16x16x32_bf16 v[92:95], v[148:151], v[188:191], v[92:95]
	v_mfma_f32_16x16x32_bf16 v[84:87], v[138:141], v[196:199], v[84:87]
	v_mfma_f32_16x16x32_bf16 v[76:79], v[148:151], v[196:199], v[76:79]
	v_mfma_f32_16x16x32_bf16 v[124:127], v[144:147], v[176:179], v[124:127]
	v_mfma_f32_16x16x32_bf16 v[120:123], v[152:155], v[176:179], v[120:123]
	v_mfma_f32_16x16x32_bf16 v[116:119], v[144:147], v[184:187], v[116:119]
	v_mfma_f32_16x16x32_bf16 v[108:111], v[152:155], v[184:187], v[108:111]
	v_mfma_f32_16x16x32_bf16 v[100:103], v[144:147], v[192:195], v[100:103]
	v_mfma_f32_16x16x32_bf16 v[92:95], v[152:155], v[192:195], v[92:95]
	v_mfma_f32_16x16x32_bf16 v[84:87], v[144:147], v[200:203], v[84:87]
	v_mfma_f32_16x16x32_bf16 v[76:79], v[152:155], v[200:203], v[76:79]
	s_setprio 0
	s_setprio 1
	v_mfma_f32_16x16x32_bf16 v[112:115], v[156:159], v[172:175], v[112:115]
	v_mfma_f32_16x16x32_bf16 v[104:107], v[164:167], v[172:175], v[104:107]
	v_mfma_f32_16x16x32_bf16 v[96:99], v[156:159], v[180:183], v[96:99]
	v_mfma_f32_16x16x32_bf16 v[88:91], v[164:167], v[180:183], v[88:91]
	v_mfma_f32_16x16x32_bf16 v[80:83], v[156:159], v[188:191], v[80:83]
	v_mfma_f32_16x16x32_bf16 v[72:75], v[164:167], v[188:191], v[72:75]
	v_mfma_f32_16x16x32_bf16 v[68:71], v[156:159], v[196:199], v[68:71]
	v_mfma_f32_16x16x32_bf16 v[64:67], v[164:167], v[196:199], v[64:67]
	v_mfma_f32_16x16x32_bf16 v[112:115], v[160:163], v[176:179], v[112:115]
	v_mfma_f32_16x16x32_bf16 v[104:107], v[168:171], v[176:179], v[104:107]
	v_mfma_f32_16x16x32_bf16 v[96:99], v[160:163], v[184:187], v[96:99]
	v_mfma_f32_16x16x32_bf16 v[88:91], v[168:171], v[184:187], v[88:91]
	v_mfma_f32_16x16x32_bf16 v[80:83], v[160:163], v[192:195], v[80:83]
	v_mfma_f32_16x16x32_bf16 v[72:75], v[168:171], v[192:195], v[72:75]
	v_mfma_f32_16x16x32_bf16 v[68:71], v[160:163], v[200:203], v[68:71]
	v_mfma_f32_16x16x32_bf16 v[64:67], v[168:171], v[200:203], v[64:67]
	s_barrier
	s_setprio 0
	s_add_i32 s53, s53, s33
	v_lshl_add_u64 v[206:207], s[26:27], 0, v[204:205]
	s_mov_b32 m0, s53
	ds_read_b128 v[172:175], v143 offset:16384
	ds_read_b128 v[176:179], v143 offset:17408
	ds_read_b128 v[180:183], v143 offset:18432
	ds_read_b128 v[184:187], v143 offset:19456
	ds_read_b128 v[188:191], v143 offset:20480
	ds_read_b128 v[192:195], v143 offset:21504
	ds_read_b128 v[196:199], v143 offset:22528
	ds_read_b128 v[200:203], v143 offset:23552
	global_load_lds_dwordx4 v[206:207], off
	s_add_i32 m0, s53, 0x2000
	s_add_u32 s54, s26, 0x20000
	v_lshl_add_u64 v[208:209], s[26:27], 0, v[128:129]
	s_addc_u32 s55, s27, 0
	s_add_i32 s53, s62, s33
	global_load_lds_dwordx4 v[208:209], off
	v_lshl_add_u64 v[210:211], s[54:55], 0, v[204:205]
	s_mov_b32 m0, s53
	v_lshl_add_u64 v[212:213], s[28:29], 0, v[130:131]
	global_load_lds_dwordx4 v[210:211], off
	v_lshl_add_u64 v[210:211], s[54:55], 0, v[128:129]
	s_add_i32 m0, s53, 0x2000
	s_nop 0
	global_load_lds_dwordx4 v[210:211], off
	v_lshl_add_u64 v[210:211], s[28:29], 0, v[132:133]
	s_mov_b32 m0, s23
	s_nop 0
	global_load_lds_dwordx4 v[210:211], off
	s_mov_b32 m0, s35
	s_nop 0
	global_load_lds_dwordx4 v[212:213], off
	s_waitcnt vmcnt(8)
	s_waitcnt lgkmcnt(0)
	s_setprio 1
	s_barrier
	v_mfma_f32_16x16x32_bf16 v[60:63], v[138:141], v[172:175], v[60:63]
	v_mfma_f32_16x16x32_bf16 v[56:59], v[148:151], v[172:175], v[56:59]
	v_mfma_f32_16x16x32_bf16 v[52:55], v[138:141], v[180:183], v[52:55]
	v_mfma_f32_16x16x32_bf16 v[44:47], v[148:151], v[180:183], v[44:47]
	v_mfma_f32_16x16x32_bf16 v[36:39], v[138:141], v[188:191], v[36:39]
	v_mfma_f32_16x16x32_bf16 v[28:31], v[148:151], v[188:191], v[28:31]
	v_mfma_f32_16x16x32_bf16 v[20:23], v[138:141], v[196:199], v[20:23]
	v_mfma_f32_16x16x32_bf16 v[12:15], v[148:151], v[196:199], v[12:15]
	v_mfma_f32_16x16x32_bf16 v[60:63], v[144:147], v[176:179], v[60:63]
	v_mfma_f32_16x16x32_bf16 v[56:59], v[152:155], v[176:179], v[56:59]
	v_mfma_f32_16x16x32_bf16 v[52:55], v[144:147], v[184:187], v[52:55]
	v_mfma_f32_16x16x32_bf16 v[44:47], v[152:155], v[184:187], v[44:47]
	v_mfma_f32_16x16x32_bf16 v[36:39], v[144:147], v[192:195], v[36:39]
	v_mfma_f32_16x16x32_bf16 v[28:31], v[152:155], v[192:195], v[28:31]
	v_mfma_f32_16x16x32_bf16 v[20:23], v[144:147], v[200:203], v[20:23]
	v_mfma_f32_16x16x32_bf16 v[12:15], v[152:155], v[200:203], v[12:15]
	s_setprio 0
	s_setprio 1
	v_mfma_f32_16x16x32_bf16 v[48:51], v[156:159], v[172:175], v[48:51]
	v_mfma_f32_16x16x32_bf16 v[40:43], v[164:167], v[172:175], v[40:43]
	v_mfma_f32_16x16x32_bf16 v[32:35], v[156:159], v[180:183], v[32:35]
	v_mfma_f32_16x16x32_bf16 v[24:27], v[164:167], v[180:183], v[24:27]
	v_mfma_f32_16x16x32_bf16 v[16:19], v[156:159], v[188:191], v[16:19]
	v_mfma_f32_16x16x32_bf16 v[8:11], v[164:167], v[188:191], v[8:11]
	v_mfma_f32_16x16x32_bf16 v[4:7], v[156:159], v[196:199], v[4:7]
	v_mfma_f32_16x16x32_bf16 v[0:3], v[164:167], v[196:199], v[0:3]
	v_mfma_f32_16x16x32_bf16 v[48:51], v[160:163], v[176:179], v[48:51]
	v_mfma_f32_16x16x32_bf16 v[40:43], v[168:171], v[176:179], v[40:43]
	v_mfma_f32_16x16x32_bf16 v[32:35], v[160:163], v[184:187], v[32:35]
	v_mfma_f32_16x16x32_bf16 v[24:27], v[168:171], v[184:187], v[24:27]
	v_mfma_f32_16x16x32_bf16 v[16:19], v[160:163], v[192:195], v[16:19]
	v_mfma_f32_16x16x32_bf16 v[8:11], v[168:171], v[192:195], v[8:11]
	v_mfma_f32_16x16x32_bf16 v[4:7], v[160:163], v[200:203], v[4:7]
	v_mfma_f32_16x16x32_bf16 v[0:3], v[168:171], v[200:203], v[0:3]
	s_barrier
; #define PG8_STAGE(bufoff, gbase, voff) do { _Pragma("unroll") for (int _i = 0; _i < 2; ++_i) \
;         __builtin_amdgcn_global_load_lds((const unsigned*)((const char*)(gbase) + (voff)[_i]), (PG8_LAS unsigned*)(lds + (bufoff) + ldsw + _i * 8192), 16, 0, 0); } while (0)
; #define PG8_LDA(dst, b, h) do { _Pragma("unroll") for (int m = 0; m < 4; ++m) _Pragma("unroll") for (int k = 0; k < 2; ++k) dst[m][k] = *(const PG8_LAS bf16x8*)(lds + PG8_SA(b, h) + aoff + m * 2048 + k * 1024); } while (0)
; #define PG8_LDB(dst, b, h) do { _Pragma("unroll") for (int n = 0; n < 2; ++n) _Pragma("unroll") for (int k = 0; k < 2; ++k) dst[n][k] = *(const PG8_LAS bf16x8*)(lds + PG8_SB(b, h) + boff + n * 2048 + k * 1024); } while (0)
; #define PG8_MMA(ai, bj, At, Bt) do { __builtin_amdgcn_s_setprio(1); _Pragma("unroll") for (int m = 0; m < 4; ++m) _Pragma("unroll") for (int n = 0; n < 2; ++n) _Pragma("unroll") for (int k = 0; k < 2; ++k) \
;         acc[ai][bj][m][n] = __builtin_amdgcn_mfma_f32_16x16x32_bf16(Bt[n][k], At[m][k], acc[ai][bj][m][n], 0, 0, 0); __builtin_amdgcn_s_setprio(0); } while (0)
; #define PG8_WAIT_V(n) asm volatile("s_waitcnt vmcnt(" #n ")" ::: "memory")
; #define PG8_WAIT_L(n) asm volatile("s_waitcnt lgkmcnt(" #n ")" ::: "memory")
; #define PG8_BAR __builtin_amdgcn_s_barrier()
; #define PG8_SCHED __builtin_amdgcn_sched_barrier(0)
; template <class Epi, class Sched, bool ALIGN_EPI = false, bool SP2 = false>
; __device__ __forceinline__ void gemm_phase(PG8_LAS unsigned char* lds, const Gemm g, const Sched& S, const Epi& E, const int tid) {
;     ...
;             PG8_LDB(B0, 1, 0); PG8_LDB(B1, 1, 1); PG8_SCHED; PG8_LDA(At, 1, 0); PG8_STAGE(PG8_SA(0, 1), a2 + hstep, voffA);
;             PG8_WAIT_V(8); PG8_WAIT_L(0); PG8_BAR; PG8_MMA(0, 0, At, B0); PG8_MMA(0, 1, At, B1); PG8_BAR; PG8_SCHED;
	s_setprio 0
	s_add_i32 s53, 0, 0x18000
	s_add_i32 s54, 0, 0x1c000
	v_add_u32_e32 v152, s53, v142
	v_add_u32_e32 v168, s54, v142
	ds_read_b128 v[138:141], v152
	ds_read_b128 v[144:147], v152 offset:1024
	ds_read_b128 v[148:151], v152 offset:2048
	ds_read_b128 v[152:155], v152 offset:3072
	ds_read_b128 v[156:159], v168
	ds_read_b128 v[160:163], v168 offset:1024
	ds_read_b128 v[164:167], v168 offset:2048
	ds_read_b128 v[168:171], v168 offset:3072
	s_add_u32 s28, s28, 0x20000
	s_addc_u32 s29, s29, 0
	s_mov_b32 m0, s36
	v_lshl_add_u64 v[214:215], s[28:29], 0, v[132:133]
	ds_read_b128 v[172:175], v143 offset:32768
	ds_read_b128 v[176:179], v143 offset:33792
	ds_read_b128 v[180:183], v143 offset:34816
	ds_read_b128 v[184:187], v143 offset:35840
	ds_read_b128 v[188:191], v143 offset:36864
	ds_read_b128 v[192:195], v143 offset:37888
	ds_read_b128 v[196:199], v143 offset:38912
	ds_read_b128 v[200:203], v143 offset:39936
	global_load_lds_dwordx4 v[214:215], off
	v_lshl_add_u64 v[214:215], s[28:29], 0, v[130:131]
	s_mov_b32 m0, s37
	s_nop 0
	global_load_lds_dwordx4 v[214:215], off
	s_waitcnt vmcnt(8)
	s_waitcnt lgkmcnt(0)
	s_setprio 1
	s_barrier
	v_mfma_f32_16x16x32_bf16 v[124:127], v[138:141], v[172:175], v[124:127]
	v_mfma_f32_16x16x32_bf16 v[120:123], v[148:151], v[172:175], v[120:123]
	v_mfma_f32_16x16x32_bf16 v[116:119], v[138:141], v[180:183], v[116:119]
	v_mfma_f32_16x16x32_bf16 v[108:111], v[148:151], v[180:183], v[108:111]
	v_mfma_f32_16x16x32_bf16 v[100:103], v[138:141], v[188:191], v[100:103]
	v_mfma_f32_16x16x32_bf16 v[92:95], v[148:151], v[188:191], v[92:95]
	v_mfma_f32_16x16x32_bf16 v[84:87], v[138:141], v[196:199], v[84:87]
	v_mfma_f32_16x16x32_bf16 v[76:79], v[148:151], v[196:199], v[76:79]
	v_mfma_f32_16x16x32_bf16 v[124:127], v[144:147], v[176:179], v[124:127]
	v_mfma_f32_16x16x32_bf16 v[120:123], v[152:155], v[176:179], v[120:123]
	v_mfma_f32_16x16x32_bf16 v[116:119], v[144:147], v[184:187], v[116:119]
	v_mfma_f32_16x16x32_bf16 v[108:111], v[152:155], v[184:187], v[108:111]
	v_mfma_f32_16x16x32_bf16 v[100:103], v[144:147], v[192:195], v[100:103]
	v_mfma_f32_16x16x32_bf16 v[92:95], v[152:155], v[192:195], v[92:95]
	v_mfma_f32_16x16x32_bf16 v[84:87], v[144:147], v[200:203], v[84:87]
	v_mfma_f32_16x16x32_bf16 v[76:79], v[152:155], v[200:203], v[76:79]
	s_setprio 0
	s_setprio 1
	v_mfma_f32_16x16x32_bf16 v[112:115], v[156:159], v[172:175], v[112:115]
	v_mfma_f32_16x16x32_bf16 v[104:107], v[164:167], v[172:175], v[104:107]
	v_mfma_f32_16x16x32_bf16 v[96:99], v[156:159], v[180:183], v[96:99]
	v_mfma_f32_16x16x32_bf16 v[88:91], v[164:167], v[180:183], v[88:91]
	v_mfma_f32_16x16x32_bf16 v[80:83], v[156:159], v[188:191], v[80:83]
	v_mfma_f32_16x16x32_bf16 v[72:75], v[164:167], v[188:191], v[72:75]
	v_mfma_f32_16x16x32_bf16 v[68:71], v[156:159], v[196:199], v[68:71]
	v_mfma_f32_16x16x32_bf16 v[64:67], v[164:167], v[196:199], v[64:67]
	v_mfma_f32_16x16x32_bf16 v[112:115], v[160:163], v[176:179], v[112:115]
	v_mfma_f32_16x16x32_bf16 v[104:107], v[168:171], v[176:179], v[104:107]
	v_mfma_f32_16x16x32_bf16 v[96:99], v[160:163], v[184:187], v[96:99]
	v_mfma_f32_16x16x32_bf16 v[88:91], v[168:171], v[184:187], v[88:91]
	v_mfma_f32_16x16x32_bf16 v[80:83], v[160:163], v[192:195], v[80:83]
	v_mfma_f32_16x16x32_bf16 v[72:75], v[168:171], v[192:195], v[72:75]
	v_mfma_f32_16x16x32_bf16 v[68:71], v[160:163], v[200:203], v[68:71]
	v_mfma_f32_16x16x32_bf16 v[64:67], v[168:171], v[200:203], v[64:67]
	s_barrier
; #define PG8_STAGE(bufoff, gbase, voff) do { _Pragma("unroll") for (int _i = 0; _i < 2; ++_i) \
;         __builtin_amdgcn_global_load_lds((const unsigned*)((const char*)(gbase) + (voff)[_i]), (PG8_LAS unsigned*)(lds + (bufoff) + ldsw + _i * 8192), 16, 0, 0); } while (0)
; #define PG8_LDA(dst, b, h) do { _Pragma("unroll") for (int m = 0; m < 4; ++m) _Pragma("unroll") for (int k = 0; k < 2; ++k) dst[m][k] = *(const PG8_LAS bf16x8*)(lds + PG8_SA(b, h) + aoff + m * 2048 + k * 1024); } while (0)
; #define PG8_MMA(ai, bj, At, Bt) do { __builtin_amdgcn_s_setprio(1); _Pragma("unroll") for (int m = 0; m < 4; ++m) _Pragma("unroll") for (int n = 0; n < 2; ++n) _Pragma("unroll") for (int k = 0; k < 2; ++k) \
;         acc[ai][bj][m][n] = __builtin_amdgcn_mfma_f32_16x16x32_bf16(Bt[n][k], At[m][k], acc[ai][bj][m][n], 0, 0, 0); __builtin_amdgcn_s_setprio(0); } while (0)
; #define PG8_WAIT_V(n) asm volatile("s_waitcnt vmcnt(" #n ")" ::: "memory")
; #define PG8_WAIT_L(n) asm volatile("s_waitcnt lgkmcnt(" #n ")" ::: "memory")
; #define PG8_BAR __builtin_amdgcn_s_barrier()
; #define PG8_SCHED __builtin_amdgcn_sched_barrier(0)
; template <class Epi, class Sched, bool ALIGN_EPI = false, bool SP2 = false>
; __device__ __forceinline__ void gemm_phase(PG8_LAS unsigned char* lds, const Gemm g, const Sched& S, const Epi& E, const int tid) {
;     ...
;             PG8_LDA(At, 1, 1); PG8_STAGE(PG8_SB(1, 0), b3, voffB); PG8_STAGE(PG8_SB(1, 1), b3 + hstep, voffB); PG8_STAGE(PG8_SA(1, 0), a3, voffA);
;             PG8_WAIT_V(8); PG8_WAIT_L(0); PG8_BAR; PG8_MMA(1, 0, At, B0); PG8_MMA(1, 1, At, B1); PG8_BAR; PG8_SCHED;
;     ...
;         if constexpr (ALIGN_EPI) { if (wr == 0) PG8_BAR; }
	s_setprio 0
	s_add_i32 s28, s53, s33
	v_lshl_add_u64 v[206:207], v[206:207], 0, s[70:71]
	s_mov_b32 m0, s28
	ds_read_b128 v[172:175], v143 offset:49152
	ds_read_b128 v[176:179], v143 offset:50176
	ds_read_b128 v[180:183], v143 offset:51200
	ds_read_b128 v[184:187], v143 offset:52224
	ds_read_b128 v[188:191], v143 offset:53248
	ds_read_b128 v[192:195], v143 offset:54272
	ds_read_b128 v[196:199], v143 offset:55296
	ds_read_b128 v[200:203], v143 offset:56320
	global_load_lds_dwordx4 v[206:207], off
	s_add_i32 m0, s28, 0x2000
	s_add_u32 s26, s26, 0x20080
	v_lshl_add_u64 v[206:207], v[208:209], 0, s[70:71]
	s_addc_u32 s27, s27, 0
	s_add_i32 s28, s54, s33
	global_load_lds_dwordx4 v[206:207], off
	v_lshl_add_u64 v[206:207], s[26:27], 0, v[204:205]
	s_mov_b32 m0, s28
	s_nop 0
	global_load_lds_dwordx4 v[206:207], off
	v_lshl_add_u64 v[206:207], s[26:27], 0, v[128:129]
	s_add_i32 m0, s28, 0x2000
	s_nop 0
	global_load_lds_dwordx4 v[206:207], off
	v_lshl_add_u64 v[206:207], v[210:211], 0, s[70:71]
	s_mov_b32 m0, s43
	s_nop 0
	global_load_lds_dwordx4 v[206:207], off
	v_lshl_add_u64 v[206:207], v[212:213], 0, s[70:71]
	s_mov_b32 m0, s44
	s_nop 0
	global_load_lds_dwordx4 v[206:207], off
	s_waitcnt vmcnt(8)
	s_waitcnt lgkmcnt(0)
	s_setprio 1
	s_barrier
	v_mfma_f32_16x16x32_bf16 v[60:63], v[138:141], v[172:175], v[60:63]
	v_mfma_f32_16x16x32_bf16 v[56:59], v[148:151], v[172:175], v[56:59]
	v_mfma_f32_16x16x32_bf16 v[52:55], v[138:141], v[180:183], v[52:55]
	v_mfma_f32_16x16x32_bf16 v[44:47], v[148:151], v[180:183], v[44:47]
	v_mfma_f32_16x16x32_bf16 v[36:39], v[138:141], v[188:191], v[36:39]
	v_mfma_f32_16x16x32_bf16 v[28:31], v[148:151], v[188:191], v[28:31]
	v_mfma_f32_16x16x32_bf16 v[20:23], v[138:141], v[196:199], v[20:23]
	v_mfma_f32_16x16x32_bf16 v[12:15], v[148:151], v[196:199], v[12:15]
	v_mfma_f32_16x16x32_bf16 v[60:63], v[144:147], v[176:179], v[60:63]
	v_mfma_f32_16x16x32_bf16 v[56:59], v[152:155], v[176:179], v[56:59]
	v_mfma_f32_16x16x32_bf16 v[52:55], v[144:147], v[184:187], v[52:55]
	v_mfma_f32_16x16x32_bf16 v[44:47], v[152:155], v[184:187], v[44:47]
	v_mfma_f32_16x16x32_bf16 v[36:39], v[144:147], v[192:195], v[36:39]
	v_mfma_f32_16x16x32_bf16 v[28:31], v[152:155], v[192:195], v[28:31]
	v_mfma_f32_16x16x32_bf16 v[20:23], v[144:147], v[200:203], v[20:23]
	v_mfma_f32_16x16x32_bf16 v[12:15], v[152:155], v[200:203], v[12:15]
	s_setprio 0
	s_setprio 1
	v_mfma_f32_16x16x32_bf16 v[48:51], v[156:159], v[172:175], v[48:51]
	v_mfma_f32_16x16x32_bf16 v[40:43], v[164:167], v[172:175], v[40:43]
	v_mfma_f32_16x16x32_bf16 v[32:35], v[156:159], v[180:183], v[32:35]
	v_mfma_f32_16x16x32_bf16 v[24:27], v[164:167], v[180:183], v[24:27]
	v_mfma_f32_16x16x32_bf16 v[16:19], v[156:159], v[188:191], v[16:19]
	v_mfma_f32_16x16x32_bf16 v[8:11], v[164:167], v[188:191], v[8:11]
	v_mfma_f32_16x16x32_bf16 v[4:7], v[156:159], v[196:199], v[4:7]
	v_mfma_f32_16x16x32_bf16 v[0:3], v[164:167], v[196:199], v[0:3]
	v_mfma_f32_16x16x32_bf16 v[48:51], v[160:163], v[176:179], v[48:51]
	v_mfma_f32_16x16x32_bf16 v[40:43], v[168:171], v[176:179], v[40:43]
	v_mfma_f32_16x16x32_bf16 v[32:35], v[160:163], v[184:187], v[32:35]
	v_mfma_f32_16x16x32_bf16 v[24:27], v[168:171], v[184:187], v[24:27]
	v_mfma_f32_16x16x32_bf16 v[16:19], v[160:163], v[192:195], v[16:19]
	v_mfma_f32_16x16x32_bf16 v[8:11], v[168:171], v[192:195], v[8:11]
	v_mfma_f32_16x16x32_bf16 v[4:7], v[160:163], v[200:203], v[4:7]
	v_mfma_f32_16x16x32_bf16 v[0:3], v[168:171], v[200:203], v[0:3]
	s_barrier
	s_setprio 0
	s_add_i32 s52, s52, 2
	s_add_u32 s24, s24, 0x100
	s_addc_u32 s25, s25, 0
	s_add_u32 s50, s50, 0x100
	s_addc_u32 s51, s51, 0
	s_cmp_gt_u32 s52, 5
	s_cbranch_scc0 .LBB0_1549
	s_and_b64 vcc, exec, s[12:13]
	s_cbranch_vccz .LBB0_1552
	s_barrier

; #define PG8_STAGE(bufoff, gbase, voff) do { _Pragma("unroll") for (int _i = 0; _i < 2; ++_i) \
;         __builtin_amdgcn_global_load_lds((const unsigned*)((const char*)(gbase) + (voff)[_i]), (PG8_LAS unsigned*)(lds + (bufoff) + ldsw + _i * 8192), 16, 0, 0); } while (0)
; #define PG8_LDA(dst, b, h) do { _Pragma("unroll") for (int m = 0; m < 4; ++m) _Pragma("unroll") for (int k = 0; k < 2; ++k) dst[m][k] = *(const PG8_LAS bf16x8*)(lds + PG8_SA(b, h) + aoff + m * 2048 + k * 1024); } while (0)
; #define PG8_LDB(dst, b, h) do { _Pragma("unroll") for (int n = 0; n < 2; ++n) _Pragma("unroll") for (int k = 0; k < 2; ++k) dst[n][k] = *(const PG8_LAS bf16x8*)(lds + PG8_SB(b, h) + boff + n * 2048 + k * 1024); } while (0)
; #define PG8_WAIT_V(n) asm volatile("s_waitcnt vmcnt(" #n ")" ::: "memory")
; #define PG8_WAIT_L(n) asm volatile("s_waitcnt lgkmcnt(" #n ")" ::: "memory")
; #define PG8_BAR __builtin_amdgcn_s_barrier()
; #define PG8_SCHED __builtin_amdgcn_sched_barrier(0)
; template <class Epi, class Sched, bool ALIGN_EPI = false, bool SP2 = false>
; __device__ __forceinline__ void gemm_phase(PG8_LAS unsigned char* lds, const Gemm g, const Sched& S, const Epi& E, const int tid) {
;     ...
;         const bool has_next = S.next(ui + 1, nxt);
;         const char* nA = has_next ? (const char*)g.A + (size_t)nxt.pm * tstep : cA; const char* nB = has_next ? (const char*)g.Bt + (size_t)nxt.pn * tstep : cB;
;         for (int t = 0; t < nt; t += 2) {
;             const bool last = (t == nt - 2);
;             const char* a1 = cA + (size_t)(t + 1) * kstep;
;             const char* a2 = last ? nA : cA + (size_t)(t + 2) * kstep; const char* b2 = last ? nB : cB + (size_t)(t + 2) * kstep;
;             const char* a3 = a2 + kstep; const char* b3 = b2 + kstep;
;             if (last && has_next) S.a_ready(nxt);
;             if constexpr (SP2) {
;             PG8_LDB(B0, 0, 0); PG8_LDB(B1, 0, 1); PG8_SCHED; PG8_LDA(At, 0, 0); PG8_STAGE(PG8_SA(1, 1), a1 + hstep, voffA);
;             PG8_WAIT_V(8); PG8_WAIT_L(0); PG8_BAR; PG8_MMA(0, 0, At, B0); PG8_MMA(0, 1, At, B1); PG8_BAR; PG8_SCHED;
;             PG8_LDA(At, 0, 1); PG8_STAGE(PG8_SB(0, 0), b2, voffB); PG8_STAGE(PG8_SB(0, 1), b2 + hstep, voffB); PG8_STAGE(PG8_SA(0, 0), a2, voffA);
;             PG8_WAIT_V(8); PG8_WAIT_L(0); PG8_BAR; PG8_MMA(1, 0, At, B0); PG8_MMA(1, 1, At, B1); PG8_BAR; PG8_SCHED;
.LBB0_1572:
	s_ashr_i32 s17, s16, 31
	s_lshl_b64 s[18:19], s[16:17], 18
	s_add_u32 s18, s11, s18
	s_addc_u32 s19, s30, s19
	s_and_b64 s[20:21], s[4:5], exec
	s_cselect_b32 s17, s19, s25
	s_cselect_b32 s48, s18, s24
	s_ashr_i32 s15, s14, 31
	s_lshl_b64 s[20:21], s[14:15], 18
	s_add_u32 s20, s31, s20
	s_addc_u32 s21, s33, s21
	s_and_b64 s[28:29], s[4:5], exec
	s_cselect_b32 s15, s21, s27
	s_cselect_b32 s49, s20, s26
	s_add_u32 s24, s24, 0x20080
	s_addc_u32 s25, s25, 0
	s_add_u32 s50, s26, 0x100
	s_addc_u32 s51, s27, 0
	s_mov_b32 s52, -2
	s_add_u32 s26, s24, 0xfffe0080
	s_addc_u32 s27, s25, -1
	s_add_i32 s53, 0, 0x10000
	s_cmp_eq_u32 s52, 4
	s_cselect_b32 s29, s17, s27
	s_cselect_b32 s28, s48, s26
	v_add_u32_e32 v138, s53, v140
	s_cselect_b32 s27, s15, s51
	s_cselect_b32 s26, s49, s50
	s_add_i32 s62, 0, 0x14000
	ds_read_b128 v[142:145], v138
	ds_read_b128 v[146:149], v138 offset:1024
	ds_read_b128 v[150:153], v138 offset:2048
	ds_read_b128 v[154:157], v138 offset:3072
	v_add_u32_e32 v138, s62, v140
	ds_read_b128 v[158:161], v138
	ds_read_b128 v[162:165], v138 offset:1024
	ds_read_b128 v[166:169], v138 offset:2048
	ds_read_b128 v[170:173], v138 offset:3072
	v_lshl_add_u64 v[138:139], s[24:25], 0, v[134:135]
	s_add_i32 m0, s23, 0xc000
	ds_read_b128 v[174:177], v141
	ds_read_b128 v[178:181], v141 offset:1024
	ds_read_b128 v[182:185], v141 offset:2048
	ds_read_b128 v[186:189], v141 offset:3072
	ds_read_b128 v[190:193], v141 offset:4096
	ds_read_b128 v[194:197], v141 offset:5120
	ds_read_b128 v[198:201], v141 offset:6144
	ds_read_b128 v[206:209], v141 offset:7168
	global_load_lds_dwordx4 v[138:139], off
	v_lshl_add_u64 v[138:139], s[24:25], 0, v[136:137]
	s_add_i32 m0, s23, 0xe000
	s_nop 0
	global_load_lds_dwordx4 v[138:139], off
	s_waitcnt vmcnt(24)
	s_waitcnt lgkmcnt(0)
	s_setprio 1
	s_barrier
	v_mfma_f32_16x16x32_bf16 v[124:127], v[142:145], v[174:177], 0
	v_mfma_f32_16x16x32_bf16 v[120:123], v[150:153], v[174:177], 0
	v_mfma_f32_16x16x32_bf16 v[116:119], v[142:145], v[182:185], 0
	v_mfma_f32_16x16x32_bf16 v[108:111], v[150:153], v[182:185], 0
	v_mfma_f32_16x16x32_bf16 v[100:103], v[142:145], v[190:193], 0
	v_mfma_f32_16x16x32_bf16 v[92:95], v[150:153], v[190:193], 0
	v_mfma_f32_16x16x32_bf16 v[84:87], v[142:145], v[198:201], 0
	v_mfma_f32_16x16x32_bf16 v[76:79], v[150:153], v[198:201], 0
	v_mfma_f32_16x16x32_bf16 v[124:127], v[146:149], v[178:181], v[124:127]
	v_mfma_f32_16x16x32_bf16 v[120:123], v[154:157], v[178:181], v[120:123]
	v_mfma_f32_16x16x32_bf16 v[116:119], v[146:149], v[186:189], v[116:119]
	v_mfma_f32_16x16x32_bf16 v[108:111], v[154:157], v[186:189], v[108:111]
	v_mfma_f32_16x16x32_bf16 v[100:103], v[146:149], v[194:197], v[100:103]
	v_mfma_f32_16x16x32_bf16 v[92:95], v[154:157], v[194:197], v[92:95]
	v_mfma_f32_16x16x32_bf16 v[84:87], v[146:149], v[206:209], v[84:87]
	v_mfma_f32_16x16x32_bf16 v[76:79], v[154:157], v[206:209], v[76:79]
	s_setprio 0
	s_setprio 1
	v_mfma_f32_16x16x32_bf16 v[112:115], v[158:161], v[174:177], 0
	v_mfma_f32_16x16x32_bf16 v[104:107], v[166:169], v[174:177], 0
	v_mfma_f32_16x16x32_bf16 v[96:99], v[158:161], v[182:185], 0
	v_mfma_f32_16x16x32_bf16 v[88:91], v[166:169], v[182:185], 0
	v_mfma_f32_16x16x32_bf16 v[80:83], v[158:161], v[190:193], 0
	v_mfma_f32_16x16x32_bf16 v[72:75], v[166:169], v[190:193], 0
	v_mfma_f32_16x16x32_bf16 v[68:71], v[158:161], v[198:201], 0
	v_mfma_f32_16x16x32_bf16 v[64:67], v[166:169], v[198:201], 0
	v_mfma_f32_16x16x32_bf16 v[112:115], v[162:165], v[178:181], v[112:115]
	v_mfma_f32_16x16x32_bf16 v[104:107], v[170:173], v[178:181], v[104:107]
	v_mfma_f32_16x16x32_bf16 v[96:99], v[162:165], v[186:189], v[96:99]
	v_mfma_f32_16x16x32_bf16 v[88:91], v[170:173], v[186:189], v[88:91]
	v_mfma_f32_16x16x32_bf16 v[80:83], v[162:165], v[194:197], v[80:83]
	v_mfma_f32_16x16x32_bf16 v[72:75], v[170:173], v[194:197], v[72:75]
	v_mfma_f32_16x16x32_bf16 v[68:71], v[162:165], v[206:209], v[68:71]
	v_mfma_f32_16x16x32_bf16 v[64:67], v[170:173], v[206:209], v[64:67]
	s_barrier
	s_setprio 0
	s_add_i32 s53, s53, s34
	v_lshl_add_u64 v[138:139], s[26:27], 0, v[204:205]
	s_mov_b32 m0, s53
	ds_read_b128 v[174:177], v141 offset:16384
	ds_read_b128 v[178:181], v141 offset:17408
	ds_read_b128 v[182:185], v141 offset:18432
	ds_read_b128 v[186:189], v141 offset:19456
	ds_read_b128 v[190:193], v141 offset:20480
	ds_read_b128 v[194:197], v141 offset:21504
	ds_read_b128 v[198:201], v141 offset:22528
	ds_read_b128 v[206:209], v141 offset:23552
	global_load_lds_dwordx4 v[138:139], off
	s_add_i32 m0, s53, 0x2000
	s_add_u32 s54, s26, 0x20000
	v_lshl_add_u64 v[202:203], s[26:27], 0, v[132:133]
	s_addc_u32 s55, s27, 0
	s_add_i32 s53, s62, s34
	global_load_lds_dwordx4 v[202:203], off
	v_lshl_add_u64 v[210:211], s[54:55], 0, v[204:205]
	s_mov_b32 m0, s53
	v_lshl_add_u64 v[212:213], s[28:29], 0, v[130:131]
	global_load_lds_dwordx4 v[210:211], off
	v_lshl_add_u64 v[210:211], s[54:55], 0, v[132:133]
	s_add_i32 m0, s53, 0x2000
	s_nop 0
	global_load_lds_dwordx4 v[210:211], off
	v_lshl_add_u64 v[210:211], s[28:29], 0, v[128:129]
	s_mov_b32 m0, s23
	s_nop 0
	global_load_lds_dwordx4 v[210:211], off
	s_mov_b32 m0, s35
	s_nop 0
	global_load_lds_dwordx4 v[212:213], off
	s_waitcnt vmcnt(8)
	s_waitcnt lgkmcnt(0)
	s_setprio 1
	s_barrier
; #define PG8_STAGE(bufoff, gbase, voff) do { _Pragma("unroll") for (int _i = 0; _i < 2; ++_i) \
;         __builtin_amdgcn_global_load_lds((const unsigned*)((const char*)(gbase) + (voff)[_i]), (PG8_LAS unsigned*)(lds + (bufoff) + ldsw + _i * 8192), 16, 0, 0); } while (0)
; #define PG8_LDA(dst, b, h) do { _Pragma("unroll") for (int m = 0; m < 4; ++m) _Pragma("unroll") for (int k = 0; k < 2; ++k) dst[m][k] = *(const PG8_LAS bf16x8*)(lds + PG8_SA(b, h) + aoff + m * 2048 + k * 1024); } while (0)
; #define PG8_LDB(dst, b, h) do { _Pragma("unroll") for (int n = 0; n < 2; ++n) _Pragma("unroll") for (int k = 0; k < 2; ++k) dst[n][k] = *(const PG8_LAS bf16x8*)(lds + PG8_SB(b, h) + boff + n * 2048 + k * 1024); } while (0)
; #define PG8_MMA(ai, bj, At, Bt) do { __builtin_amdgcn_s_setprio(1); _Pragma("unroll") for (int m = 0; m < 4; ++m) _Pragma("unroll") for (int n = 0; n < 2; ++n) _Pragma("unroll") for (int k = 0; k < 2; ++k) \
;         acc[ai][bj][m][n] = __builtin_amdgcn_mfma_f32_16x16x32_bf16(Bt[n][k], At[m][k], acc[ai][bj][m][n], 0, 0, 0); __builtin_amdgcn_s_setprio(0); } while (0)
; #define PG8_WAIT_V(n) asm volatile("s_waitcnt vmcnt(" #n ")" ::: "memory")
; #define PG8_WAIT_L(n) asm volatile("s_waitcnt lgkmcnt(" #n ")" ::: "memory")
; #define PG8_BAR __builtin_amdgcn_s_barrier()
; #define PG8_SCHED __builtin_amdgcn_sched_barrier(0)
; template <class Epi, class Sched, bool ALIGN_EPI = false, bool SP2 = false>
; __device__ __forceinline__ void gemm_phase(PG8_LAS unsigned char* lds, const Gemm g, const Sched& S, const Epi& E, const int tid) {
;     ...
;             PG8_WAIT_V(8); PG8_WAIT_L(0); PG8_BAR; PG8_MMA(1, 0, At, B0); PG8_MMA(1, 1, At, B1); PG8_BAR; PG8_SCHED;
;             PG8_LDB(B0, 1, 0); PG8_LDB(B1, 1, 1); PG8_SCHED; PG8_LDA(At, 1, 0); PG8_STAGE(PG8_SA(0, 1), a2 + hstep, voffA);
;             PG8_WAIT_V(8); PG8_WAIT_L(0); PG8_BAR; PG8_MMA(0, 0, At, B0); PG8_MMA(0, 1, At, B1); PG8_BAR; PG8_SCHED;
	v_mfma_f32_16x16x32_bf16 v[60:63], v[142:145], v[174:177], 0
	v_mfma_f32_16x16x32_bf16 v[56:59], v[150:153], v[174:177], 0
	v_mfma_f32_16x16x32_bf16 v[52:55], v[142:145], v[182:185], 0
	v_mfma_f32_16x16x32_bf16 v[44:47], v[150:153], v[182:185], 0
	v_mfma_f32_16x16x32_bf16 v[36:39], v[142:145], v[190:193], 0
	v_mfma_f32_16x16x32_bf16 v[28:31], v[150:153], v[190:193], 0
	v_mfma_f32_16x16x32_bf16 v[20:23], v[142:145], v[198:201], 0
	v_mfma_f32_16x16x32_bf16 v[12:15], v[150:153], v[198:201], 0
	v_mfma_f32_16x16x32_bf16 v[60:63], v[146:149], v[178:181], v[60:63]
	v_mfma_f32_16x16x32_bf16 v[56:59], v[154:157], v[178:181], v[56:59]
	v_mfma_f32_16x16x32_bf16 v[52:55], v[146:149], v[186:189], v[52:55]
	v_mfma_f32_16x16x32_bf16 v[44:47], v[154:157], v[186:189], v[44:47]
	v_mfma_f32_16x16x32_bf16 v[36:39], v[146:149], v[194:197], v[36:39]
	v_mfma_f32_16x16x32_bf16 v[28:31], v[154:157], v[194:197], v[28:31]
	v_mfma_f32_16x16x32_bf16 v[20:23], v[146:149], v[206:209], v[20:23]
	v_mfma_f32_16x16x32_bf16 v[12:15], v[154:157], v[206:209], v[12:15]
	s_setprio 0
	s_setprio 1
	v_mfma_f32_16x16x32_bf16 v[48:51], v[158:161], v[174:177], 0
	v_mfma_f32_16x16x32_bf16 v[40:43], v[166:169], v[174:177], 0
	v_mfma_f32_16x16x32_bf16 v[32:35], v[158:161], v[182:185], 0
	v_mfma_f32_16x16x32_bf16 v[24:27], v[166:169], v[182:185], 0
	v_mfma_f32_16x16x32_bf16 v[16:19], v[158:161], v[190:193], 0
	v_mfma_f32_16x16x32_bf16 v[8:11], v[166:169], v[190:193], 0
	v_mfma_f32_16x16x32_bf16 v[4:7], v[158:161], v[198:201], 0
	v_mfma_f32_16x16x32_bf16 v[0:3], v[166:169], v[198:201], 0
	v_mfma_f32_16x16x32_bf16 v[48:51], v[162:165], v[178:181], v[48:51]
	v_mfma_f32_16x16x32_bf16 v[40:43], v[170:173], v[178:181], v[40:43]
	v_mfma_f32_16x16x32_bf16 v[32:35], v[162:165], v[186:189], v[32:35]
	v_mfma_f32_16x16x32_bf16 v[24:27], v[170:173], v[186:189], v[24:27]
	v_mfma_f32_16x16x32_bf16 v[16:19], v[162:165], v[194:197], v[16:19]
	v_mfma_f32_16x16x32_bf16 v[8:11], v[170:173], v[194:197], v[8:11]
	v_mfma_f32_16x16x32_bf16 v[4:7], v[162:165], v[206:209], v[4:7]
	v_mfma_f32_16x16x32_bf16 v[0:3], v[170:173], v[206:209], v[0:3]
	s_barrier
	s_setprio 0
	s_add_i32 s53, 0, 0x18000
	s_add_i32 s54, 0, 0x1c000
	v_add_u32_e32 v154, s53, v140
	v_add_u32_e32 v170, s54, v140
	ds_read_b128 v[142:145], v154
	ds_read_b128 v[146:149], v154 offset:1024
	ds_read_b128 v[150:153], v154 offset:2048
	ds_read_b128 v[154:157], v154 offset:3072
	ds_read_b128 v[158:161], v170
	ds_read_b128 v[162:165], v170 offset:1024
	ds_read_b128 v[166:169], v170 offset:2048
	ds_read_b128 v[170:173], v170 offset:3072
	s_add_u32 s28, s28, 0x20000
	s_addc_u32 s29, s29, 0
	s_mov_b32 m0, s36
	v_lshl_add_u64 v[214:215], s[28:29], 0, v[128:129]
	ds_read_b128 v[174:177], v141 offset:32768
	ds_read_b128 v[178:181], v141 offset:33792
	ds_read_b128 v[182:185], v141 offset:34816
	ds_read_b128 v[186:189], v141 offset:35840
	ds_read_b128 v[190:193], v141 offset:36864
	ds_read_b128 v[194:197], v141 offset:37888
	ds_read_b128 v[198:201], v141 offset:38912
	ds_read_b128 v[206:209], v141 offset:39936
	global_load_lds_dwordx4 v[214:215], off
	v_lshl_add_u64 v[214:215], s[28:29], 0, v[130:131]
	s_mov_b32 m0, s37
	s_nop 0
	global_load_lds_dwordx4 v[214:215], off
	s_waitcnt vmcnt(8)
	s_waitcnt lgkmcnt(0)
	s_setprio 1
	s_barrier
	v_mfma_f32_16x16x32_bf16 v[124:127], v[142:145], v[174:177], v[124:127]
	v_mfma_f32_16x16x32_bf16 v[120:123], v[150:153], v[174:177], v[120:123]
	v_mfma_f32_16x16x32_bf16 v[116:119], v[142:145], v[182:185], v[116:119]
	v_mfma_f32_16x16x32_bf16 v[108:111], v[150:153], v[182:185], v[108:111]
	v_mfma_f32_16x16x32_bf16 v[100:103], v[142:145], v[190:193], v[100:103]
	v_mfma_f32_16x16x32_bf16 v[92:95], v[150:153], v[190:193], v[92:95]
	v_mfma_f32_16x16x32_bf16 v[84:87], v[142:145], v[198:201], v[84:87]
	v_mfma_f32_16x16x32_bf16 v[76:79], v[150:153], v[198:201], v[76:79]
	v_mfma_f32_16x16x32_bf16 v[124:127], v[146:149], v[178:181], v[124:127]
	v_mfma_f32_16x16x32_bf16 v[120:123], v[154:157], v[178:181], v[120:123]
	v_mfma_f32_16x16x32_bf16 v[116:119], v[146:149], v[186:189], v[116:119]
	v_mfma_f32_16x16x32_bf16 v[108:111], v[154:157], v[186:189], v[108:111]
	v_mfma_f32_16x16x32_bf16 v[100:103], v[146:149], v[194:197], v[100:103]
	v_mfma_f32_16x16x32_bf16 v[92:95], v[154:157], v[194:197], v[92:95]
	v_mfma_f32_16x16x32_bf16 v[84:87], v[146:149], v[206:209], v[84:87]
	v_mfma_f32_16x16x32_bf16 v[76:79], v[154:157], v[206:209], v[76:79]
	s_setprio 0
	s_setprio 1
	v_mfma_f32_16x16x32_bf16 v[112:115], v[158:161], v[174:177], v[112:115]
	v_mfma_f32_16x16x32_bf16 v[104:107], v[166:169], v[174:177], v[104:107]
	v_mfma_f32_16x16x32_bf16 v[96:99], v[158:161], v[182:185], v[96:99]
	v_mfma_f32_16x16x32_bf16 v[88:91], v[166:169], v[182:185], v[88:91]
	v_mfma_f32_16x16x32_bf16 v[80:83], v[158:161], v[190:193], v[80:83]
	v_mfma_f32_16x16x32_bf16 v[72:75], v[166:169], v[190:193], v[72:75]
	v_mfma_f32_16x16x32_bf16 v[68:71], v[158:161], v[198:201], v[68:71]
	v_mfma_f32_16x16x32_bf16 v[64:67], v[166:169], v[198:201], v[64:67]
	v_mfma_f32_16x16x32_bf16 v[112:115], v[162:165], v[178:181], v[112:115]
	v_mfma_f32_16x16x32_bf16 v[104:107], v[170:173], v[178:181], v[104:107]
	v_mfma_f32_16x16x32_bf16 v[96:99], v[162:165], v[186:189], v[96:99]
	v_mfma_f32_16x16x32_bf16 v[88:91], v[170:173], v[186:189], v[88:91]
	v_mfma_f32_16x16x32_bf16 v[80:83], v[162:165], v[194:197], v[80:83]
	v_mfma_f32_16x16x32_bf16 v[72:75], v[170:173], v[194:197], v[72:75]
	v_mfma_f32_16x16x32_bf16 v[68:71], v[162:165], v[206:209], v[68:71]
	v_mfma_f32_16x16x32_bf16 v[64:67], v[170:173], v[206:209], v[64:67]
	s_barrier
; #define PG8_STAGE(bufoff, gbase, voff) do { _Pragma("unroll") for (int _i = 0; _i < 2; ++_i) \
;         __builtin_amdgcn_global_load_lds((const unsigned*)((const char*)(gbase) + (voff)[_i]), (PG8_LAS unsigned*)(lds + (bufoff) + ldsw + _i * 8192), 16, 0, 0); } while (0)
; #define PG8_LDA(dst, b, h) do { _Pragma("unroll") for (int m = 0; m < 4; ++m) _Pragma("unroll") for (int k = 0; k < 2; ++k) dst[m][k] = *(const PG8_LAS bf16x8*)(lds + PG8_SA(b, h) + aoff + m * 2048 + k * 1024); } while (0)
; #define PG8_LDB(dst, b, h) do { _Pragma("unroll") for (int n = 0; n < 2; ++n) _Pragma("unroll") for (int k = 0; k < 2; ++k) dst[n][k] = *(const PG8_LAS bf16x8*)(lds + PG8_SB(b, h) + boff + n * 2048 + k * 1024); } while (0)
; #define PG8_MMA(ai, bj, At, Bt) do { __builtin_amdgcn_s_setprio(1); _Pragma("unroll") for (int m = 0; m < 4; ++m) _Pragma("unroll") for (int n = 0; n < 2; ++n) _Pragma("unroll") for (int k = 0; k < 2; ++k) \
;         acc[ai][bj][m][n] = __builtin_amdgcn_mfma_f32_16x16x32_bf16(Bt[n][k], At[m][k], acc[ai][bj][m][n], 0, 0, 0); __builtin_amdgcn_s_setprio(0); } while (0)
; template <class Epi, class Sched, bool ALIGN_EPI = false, bool SP2 = false>
; __device__ __forceinline__ void gemm_phase(PG8_LAS unsigned char* lds, const Gemm g, const Sched& S, const Epi& E, const int tid) {
;     ...
;     for (;;) {
;         const bool has_next = S.next(ui + 1, nxt);
;         const char* nA = has_next ? (const char*)g.A + (size_t)nxt.pm * tstep : cA; const char* nB = has_next ? (const char*)g.Bt + (size_t)nxt.pn * tstep : cB;
;         for (int t = 0; t < nt; t += 2) {
;             const bool last = (t == nt - 2);
;             const char* a1 = cA + (size_t)(t + 1) * kstep;
;             const char* a2 = last ? nA : cA + (size_t)(t + 2) * kstep; const char* b2 = last ? nB : cB + (size_t)(t + 2) * kstep;
;             const char* a3 = a2 + kstep; const char* b3 = b2 + kstep;
;             if (last && has_next) S.a_ready(nxt);
;             if constexpr (SP2) {
;             PG8_LDB(B0, 0, 0); PG8_LDB(B1, 0, 1); PG8_SCHED; PG8_LDA(At, 0, 0); PG8_STAGE(PG8_SA(1, 1), a1 + hstep, voffA);
;     ...
;             PG8_LDA(At, 1, 1); PG8_STAGE(PG8_SB(1, 0), b3, voffB); PG8_STAGE(PG8_SB(1, 1), b3 + hstep, voffB); PG8_STAGE(PG8_SA(1, 0), a3, voffA);
;             PG8_WAIT_V(8); PG8_WAIT_L(0); PG8_BAR; PG8_MMA(1, 0, At, B0); PG8_MMA(1, 1, At, B1); PG8_BAR; PG8_SCHED;
	s_setprio 0
	s_add_i32 s28, s53, s34
	v_lshl_add_u64 v[138:139], v[138:139], 0, s[70:71]
	s_mov_b32 m0, s28
	ds_read_b128 v[174:177], v141 offset:49152
	ds_read_b128 v[178:181], v141 offset:50176
	ds_read_b128 v[182:185], v141 offset:51200
	ds_read_b128 v[186:189], v141 offset:52224
	ds_read_b128 v[190:193], v141 offset:53248
	ds_read_b128 v[194:197], v141 offset:54272
	ds_read_b128 v[198:201], v141 offset:55296
	ds_read_b128 v[206:209], v141 offset:56320
	global_load_lds_dwordx4 v[138:139], off
	s_add_i32 m0, s28, 0x2000
	s_add_u32 s26, s26, 0x20080
	v_lshl_add_u64 v[138:139], v[202:203], 0, s[70:71]
	s_addc_u32 s27, s27, 0
	s_add_i32 s28, s54, s34
	global_load_lds_dwordx4 v[138:139], off
	v_lshl_add_u64 v[138:139], s[26:27], 0, v[204:205]
	s_mov_b32 m0, s28
	s_nop 0
	global_load_lds_dwordx4 v[138:139], off
	v_lshl_add_u64 v[138:139], s[26:27], 0, v[132:133]
	s_add_i32 m0, s28, 0x2000
	s_nop 0
	global_load_lds_dwordx4 v[138:139], off
	v_lshl_add_u64 v[138:139], v[210:211], 0, s[70:71]
	s_mov_b32 m0, s43
	s_nop 0
	global_load_lds_dwordx4 v[138:139], off
	v_lshl_add_u64 v[138:139], v[212:213], 0, s[70:71]
	s_mov_b32 m0, s44
	s_nop 0
	global_load_lds_dwordx4 v[138:139], off
	s_waitcnt vmcnt(8)
	s_waitcnt lgkmcnt(0)
	s_setprio 1
	s_barrier
	v_mfma_f32_16x16x32_bf16 v[60:63], v[142:145], v[174:177], v[60:63]
	v_mfma_f32_16x16x32_bf16 v[56:59], v[150:153], v[174:177], v[56:59]
	v_mfma_f32_16x16x32_bf16 v[52:55], v[142:145], v[182:185], v[52:55]
	v_mfma_f32_16x16x32_bf16 v[44:47], v[150:153], v[182:185], v[44:47]
	v_mfma_f32_16x16x32_bf16 v[36:39], v[142:145], v[190:193], v[36:39]
	v_mfma_f32_16x16x32_bf16 v[28:31], v[150:153], v[190:193], v[28:31]
	v_mfma_f32_16x16x32_bf16 v[20:23], v[142:145], v[198:201], v[20:23]
	v_mfma_f32_16x16x32_bf16 v[12:15], v[150:153], v[198:201], v[12:15]
	v_mfma_f32_16x16x32_bf16 v[60:63], v[146:149], v[178:181], v[60:63]
	v_mfma_f32_16x16x32_bf16 v[56:59], v[154:157], v[178:181], v[56:59]
	v_mfma_f32_16x16x32_bf16 v[52:55], v[146:149], v[186:189], v[52:55]
	v_mfma_f32_16x16x32_bf16 v[44:47], v[154:157], v[186:189], v[44:47]
	v_mfma_f32_16x16x32_bf16 v[36:39], v[146:149], v[194:197], v[36:39]
	v_mfma_f32_16x16x32_bf16 v[28:31], v[154:157], v[194:197], v[28:31]
	v_mfma_f32_16x16x32_bf16 v[20:23], v[146:149], v[206:209], v[20:23]
	v_mfma_f32_16x16x32_bf16 v[12:15], v[154:157], v[206:209], v[12:15]
	s_setprio 0
	s_setprio 1
	v_mfma_f32_16x16x32_bf16 v[48:51], v[158:161], v[174:177], v[48:51]
	v_mfma_f32_16x16x32_bf16 v[40:43], v[166:169], v[174:177], v[40:43]
	v_mfma_f32_16x16x32_bf16 v[32:35], v[158:161], v[182:185], v[32:35]
	v_mfma_f32_16x16x32_bf16 v[24:27], v[166:169], v[182:185], v[24:27]
	v_mfma_f32_16x16x32_bf16 v[16:19], v[158:161], v[190:193], v[16:19]
	v_mfma_f32_16x16x32_bf16 v[8:11], v[166:169], v[190:193], v[8:11]
	v_mfma_f32_16x16x32_bf16 v[4:7], v[158:161], v[198:201], v[4:7]
	v_mfma_f32_16x16x32_bf16 v[0:3], v[166:169], v[198:201], v[0:3]
	v_mfma_f32_16x16x32_bf16 v[48:51], v[162:165], v[178:181], v[48:51]
	v_mfma_f32_16x16x32_bf16 v[40:43], v[170:173], v[178:181], v[40:43]
	v_mfma_f32_16x16x32_bf16 v[32:35], v[162:165], v[186:189], v[32:35]
	v_mfma_f32_16x16x32_bf16 v[24:27], v[170:173], v[186:189], v[24:27]
	v_mfma_f32_16x16x32_bf16 v[16:19], v[162:165], v[194:197], v[16:19]
	v_mfma_f32_16x16x32_bf16 v[8:11], v[170:173], v[194:197], v[8:11]
	v_mfma_f32_16x16x32_bf16 v[4:7], v[162:165], v[206:209], v[4:7]
	v_mfma_f32_16x16x32_bf16 v[0:3], v[170:173], v[206:209], v[0:3]
	s_barrier
	s_setprio 0
	s_add_i32 s52, s52, 2
	s_add_u32 s24, s24, 0x100
	s_addc_u32 s25, s25, 0
	s_add_u32 s50, s50, 0x100
	s_addc_u32 s51, s51, 0
.LBB0_1573:
	s_add_u32 s26, s24, 0xfffe0080
	s_addc_u32 s27, s25, -1
	s_add_i32 s53, 0, 0x10000
	s_cmp_eq_u32 s52, 4
	s_cselect_b32 s29, s17, s27
	s_cselect_b32 s28, s48, s26
	v_add_u32_e32 v138, s53, v140
	s_cselect_b32 s27, s15, s51
	s_cselect_b32 s26, s49, s50
	s_add_i32 s62, 0, 0x14000
	ds_read_b128 v[142:145], v138
	ds_read_b128 v[146:149], v138 offset:1024
	ds_read_b128 v[150:153], v138 offset:2048
	ds_read_b128 v[154:157], v138 offset:3072
	v_add_u32_e32 v138, s62, v140
	ds_read_b128 v[158:161], v138
	ds_read_b128 v[162:165], v138 offset:1024
	ds_read_b128 v[166:169], v138 offset:2048
	ds_read_b128 v[170:173], v138 offset:3072
	v_lshl_add_u64 v[138:139], s[24:25], 0, v[134:135]
	s_add_i32 m0, s23, 0xc000
	ds_read_b128 v[174:177], v141
	ds_read_b128 v[178:181], v141 offset:1024
	ds_read_b128 v[182:185], v141 offset:2048
	ds_read_b128 v[186:189], v141 offset:3072
	ds_read_b128 v[190:193], v141 offset:4096
	ds_read_b128 v[194:197], v141 offset:5120
	ds_read_b128 v[198:201], v141 offset:6144
	ds_read_b128 v[206:209], v141 offset:7168
	global_load_lds_dwordx4 v[138:139], off
	v_lshl_add_u64 v[138:139], s[24:25], 0, v[136:137]
	s_add_i32 m0, s23, 0xe000
	s_nop 0
	global_load_lds_dwordx4 v[138:139], off
	s_waitcnt vmcnt(8)
	s_waitcnt lgkmcnt(0)
	s_setprio 1
	s_barrier
; #define PG8_STAGE(bufoff, gbase, voff) do { _Pragma("unroll") for (int _i = 0; _i < 2; ++_i) \
;         __builtin_amdgcn_global_load_lds((const unsigned*)((const char*)(gbase) + (voff)[_i]), (PG8_LAS unsigned*)(lds + (bufoff) + ldsw + _i * 8192), 16, 0, 0); } while (0)
; #define PG8_LDA(dst, b, h) do { _Pragma("unroll") for (int m = 0; m < 4; ++m) _Pragma("unroll") for (int k = 0; k < 2; ++k) dst[m][k] = *(const PG8_LAS bf16x8*)(lds + PG8_SA(b, h) + aoff + m * 2048 + k * 1024); } while (0)
; #define PG8_MMA(ai, bj, At, Bt) do { __builtin_amdgcn_s_setprio(1); _Pragma("unroll") for (int m = 0; m < 4; ++m) _Pragma("unroll") for (int n = 0; n < 2; ++n) _Pragma("unroll") for (int k = 0; k < 2; ++k) \
;         acc[ai][bj][m][n] = __builtin_amdgcn_mfma_f32_16x16x32_bf16(Bt[n][k], At[m][k], acc[ai][bj][m][n], 0, 0, 0); __builtin_amdgcn_s_setprio(0); } while (0)
; #define PG8_WAIT_V(n) asm volatile("s_waitcnt vmcnt(" #n ")" ::: "memory")
; #define PG8_WAIT_L(n) asm volatile("s_waitcnt lgkmcnt(" #n ")" ::: "memory")
; #define PG8_BAR __builtin_amdgcn_s_barrier()
; #define PG8_SCHED __builtin_amdgcn_sched_barrier(0)
; template <class Epi, class Sched, bool ALIGN_EPI = false, bool SP2 = false>
; __device__ __forceinline__ void gemm_phase(PG8_LAS unsigned char* lds, const Gemm g, const Sched& S, const Epi& E, const int tid) {
;     ...
;             PG8_WAIT_V(8); PG8_WAIT_L(0); PG8_BAR; PG8_MMA(0, 0, At, B0); PG8_MMA(0, 1, At, B1); PG8_BAR; PG8_SCHED;
;             PG8_LDA(At, 0, 1); PG8_STAGE(PG8_SB(0, 0), b2, voffB); PG8_STAGE(PG8_SB(0, 1), b2 + hstep, voffB); PG8_STAGE(PG8_SA(0, 0), a2, voffA);
;             PG8_WAIT_V(8); PG8_WAIT_L(0); PG8_BAR; PG8_MMA(1, 0, At, B0); PG8_MMA(1, 1, At, B1); PG8_BAR; PG8_SCHED;
	v_mfma_f32_16x16x32_bf16 v[124:127], v[142:145], v[174:177], v[124:127]
	v_mfma_f32_16x16x32_bf16 v[120:123], v[150:153], v[174:177], v[120:123]
	v_mfma_f32_16x16x32_bf16 v[116:119], v[142:145], v[182:185], v[116:119]
	v_mfma_f32_16x16x32_bf16 v[108:111], v[150:153], v[182:185], v[108:111]
	v_mfma_f32_16x16x32_bf16 v[100:103], v[142:145], v[190:193], v[100:103]
	v_mfma_f32_16x16x32_bf16 v[92:95], v[150:153], v[190:193], v[92:95]
	v_mfma_f32_16x16x32_bf16 v[84:87], v[142:145], v[198:201], v[84:87]
	v_mfma_f32_16x16x32_bf16 v[76:79], v[150:153], v[198:201], v[76:79]
	v_mfma_f32_16x16x32_bf16 v[124:127], v[146:149], v[178:181], v[124:127]
	v_mfma_f32_16x16x32_bf16 v[120:123], v[154:157], v[178:181], v[120:123]
	v_mfma_f32_16x16x32_bf16 v[116:119], v[146:149], v[186:189], v[116:119]
	v_mfma_f32_16x16x32_bf16 v[108:111], v[154:157], v[186:189], v[108:111]
	v_mfma_f32_16x16x32_bf16 v[100:103], v[146:149], v[194:197], v[100:103]
	v_mfma_f32_16x16x32_bf16 v[92:95], v[154:157], v[194:197], v[92:95]
	v_mfma_f32_16x16x32_bf16 v[84:87], v[146:149], v[206:209], v[84:87]
	v_mfma_f32_16x16x32_bf16 v[76:79], v[154:157], v[206:209], v[76:79]
	s_setprio 0
	s_setprio 1
	v_mfma_f32_16x16x32_bf16 v[112:115], v[158:161], v[174:177], v[112:115]
	v_mfma_f32_16x16x32_bf16 v[104:107], v[166:169], v[174:177], v[104:107]
	v_mfma_f32_16x16x32_bf16 v[96:99], v[158:161], v[182:185], v[96:99]
	v_mfma_f32_16x16x32_bf16 v[88:91], v[166:169], v[182:185], v[88:91]
	v_mfma_f32_16x16x32_bf16 v[80:83], v[158:161], v[190:193], v[80:83]
	v_mfma_f32_16x16x32_bf16 v[72:75], v[166:169], v[190:193], v[72:75]
	v_mfma_f32_16x16x32_bf16 v[68:71], v[158:161], v[198:201], v[68:71]
	v_mfma_f32_16x16x32_bf16 v[64:67], v[166:169], v[198:201], v[64:67]
	v_mfma_f32_16x16x32_bf16 v[112:115], v[162:165], v[178:181], v[112:115]
	v_mfma_f32_16x16x32_bf16 v[104:107], v[170:173], v[178:181], v[104:107]
	v_mfma_f32_16x16x32_bf16 v[96:99], v[162:165], v[186:189], v[96:99]
	v_mfma_f32_16x16x32_bf16 v[88:91], v[170:173], v[186:189], v[88:91]
	v_mfma_f32_16x16x32_bf16 v[80:83], v[162:165], v[194:197], v[80:83]
	v_mfma_f32_16x16x32_bf16 v[72:75], v[170:173], v[194:197], v[72:75]
	v_mfma_f32_16x16x32_bf16 v[68:71], v[162:165], v[206:209], v[68:71]
	v_mfma_f32_16x16x32_bf16 v[64:67], v[170:173], v[206:209], v[64:67]
	s_barrier
	s_setprio 0
	s_add_i32 s53, s53, s34
	v_lshl_add_u64 v[138:139], s[26:27], 0, v[204:205]
	s_mov_b32 m0, s53
	ds_read_b128 v[174:177], v141 offset:16384
	ds_read_b128 v[178:181], v141 offset:17408
	ds_read_b128 v[182:185], v141 offset:18432
	ds_read_b128 v[186:189], v141 offset:19456
	ds_read_b128 v[190:193], v141 offset:20480
	ds_read_b128 v[194:197], v141 offset:21504
	ds_read_b128 v[198:201], v141 offset:22528
	ds_read_b128 v[206:209], v141 offset:23552
	global_load_lds_dwordx4 v[138:139], off
	s_add_i32 m0, s53, 0x2000
	s_add_u32 s54, s26, 0x20000
	v_lshl_add_u64 v[202:203], s[26:27], 0, v[132:133]
	s_addc_u32 s55, s27, 0
	s_add_i32 s53, s62, s34
	global_load_lds_dwordx4 v[202:203], off
	v_lshl_add_u64 v[210:211], s[54:55], 0, v[204:205]
	s_mov_b32 m0, s53
	v_lshl_add_u64 v[212:213], s[28:29], 0, v[130:131]
	global_load_lds_dwordx4 v[210:211], off
	v_lshl_add_u64 v[210:211], s[54:55], 0, v[132:133]
	s_add_i32 m0, s53, 0x2000
	s_nop 0
	global_load_lds_dwordx4 v[210:211], off
	v_lshl_add_u64 v[210:211], s[28:29], 0, v[128:129]
	s_mov_b32 m0, s23
	s_nop 0
	global_load_lds_dwordx4 v[210:211], off
	s_mov_b32 m0, s35
	s_nop 0
	global_load_lds_dwordx4 v[212:213], off
	s_waitcnt vmcnt(8)
	s_waitcnt lgkmcnt(0)
	s_setprio 1
	s_barrier
	v_mfma_f32_16x16x32_bf16 v[60:63], v[142:145], v[174:177], v[60:63]
	v_mfma_f32_16x16x32_bf16 v[56:59], v[150:153], v[174:177], v[56:59]
	v_mfma_f32_16x16x32_bf16 v[52:55], v[142:145], v[182:185], v[52:55]
	v_mfma_f32_16x16x32_bf16 v[44:47], v[150:153], v[182:185], v[44:47]
	v_mfma_f32_16x16x32_bf16 v[36:39], v[142:145], v[190:193], v[36:39]
	v_mfma_f32_16x16x32_bf16 v[28:31], v[150:153], v[190:193], v[28:31]
	v_mfma_f32_16x16x32_bf16 v[20:23], v[142:145], v[198:201], v[20:23]
	v_mfma_f32_16x16x32_bf16 v[12:15], v[150:153], v[198:201], v[12:15]
	v_mfma_f32_16x16x32_bf16 v[60:63], v[146:149], v[178:181], v[60:63]
	v_mfma_f32_16x16x32_bf16 v[56:59], v[154:157], v[178:181], v[56:59]
	v_mfma_f32_16x16x32_bf16 v[52:55], v[146:149], v[186:189], v[52:55]
	v_mfma_f32_16x16x32_bf16 v[44:47], v[154:157], v[186:189], v[44:47]
	v_mfma_f32_16x16x32_bf16 v[36:39], v[146:149], v[194:197], v[36:39]
	v_mfma_f32_16x16x32_bf16 v[28:31], v[154:157], v[194:197], v[28:31]
	v_mfma_f32_16x16x32_bf16 v[20:23], v[146:149], v[206:209], v[20:23]
	v_mfma_f32_16x16x32_bf16 v[12:15], v[154:157], v[206:209], v[12:15]
	s_setprio 0
	s_setprio 1
	v_mfma_f32_16x16x32_bf16 v[48:51], v[158:161], v[174:177], v[48:51]
	v_mfma_f32_16x16x32_bf16 v[40:43], v[166:169], v[174:177], v[40:43]
	v_mfma_f32_16x16x32_bf16 v[32:35], v[158:161], v[182:185], v[32:35]
	v_mfma_f32_16x16x32_bf16 v[24:27], v[166:169], v[182:185], v[24:27]
	v_mfma_f32_16x16x32_bf16 v[16:19], v[158:161], v[190:193], v[16:19]
	v_mfma_f32_16x16x32_bf16 v[8:11], v[166:169], v[190:193], v[8:11]
	v_mfma_f32_16x16x32_bf16 v[4:7], v[158:161], v[198:201], v[4:7]
	v_mfma_f32_16x16x32_bf16 v[0:3], v[166:169], v[198:201], v[0:3]
	v_mfma_f32_16x16x32_bf16 v[48:51], v[162:165], v[178:181], v[48:51]
	v_mfma_f32_16x16x32_bf16 v[40:43], v[170:173], v[178:181], v[40:43]
	v_mfma_f32_16x16x32_bf16 v[32:35], v[162:165], v[186:189], v[32:35]
	v_mfma_f32_16x16x32_bf16 v[24:27], v[170:173], v[186:189], v[24:27]
	v_mfma_f32_16x16x32_bf16 v[16:19], v[162:165], v[194:197], v[16:19]
	v_mfma_f32_16x16x32_bf16 v[8:11], v[170:173], v[194:197], v[8:11]
	v_mfma_f32_16x16x32_bf16 v[4:7], v[162:165], v[206:209], v[4:7]
	v_mfma_f32_16x16x32_bf16 v[0:3], v[170:173], v[206:209], v[0:3]
	s_barrier
; #define PG8_STAGE(bufoff, gbase, voff) do { _Pragma("unroll") for (int _i = 0; _i < 2; ++_i) \
;         __builtin_amdgcn_global_load_lds((const unsigned*)((const char*)(gbase) + (voff)[_i]), (PG8_LAS unsigned*)(lds + (bufoff) + ldsw + _i * 8192), 16, 0, 0); } while (0)
; #define PG8_LDA(dst, b, h) do { _Pragma("unroll") for (int m = 0; m < 4; ++m) _Pragma("unroll") for (int k = 0; k < 2; ++k) dst[m][k] = *(const PG8_LAS bf16x8*)(lds + PG8_SA(b, h) + aoff + m * 2048 + k * 1024); } while (0)
; #define PG8_LDB(dst, b, h) do { _Pragma("unroll") for (int n = 0; n < 2; ++n) _Pragma("unroll") for (int k = 0; k < 2; ++k) dst[n][k] = *(const PG8_LAS bf16x8*)(lds + PG8_SB(b, h) + boff + n * 2048 + k * 1024); } while (0)
; #define PG8_MMA(ai, bj, At, Bt) do { __builtin_amdgcn_s_setprio(1); _Pragma("unroll") for (int m = 0; m < 4; ++m) _Pragma("unroll") for (int n = 0; n < 2; ++n) _Pragma("unroll") for (int k = 0; k < 2; ++k) \
;         acc[ai][bj][m][n] = __builtin_amdgcn_mfma_f32_16x16x32_bf16(Bt[n][k], At[m][k], acc[ai][bj][m][n], 0, 0, 0); __builtin_amdgcn_s_setprio(0); } while (0)
; #define PG8_WAIT_V(n) asm volatile("s_waitcnt vmcnt(" #n ")" ::: "memory")
; #define PG8_WAIT_L(n) asm volatile("s_waitcnt lgkmcnt(" #n ")" ::: "memory")
; #define PG8_BAR __builtin_amdgcn_s_barrier()
; #define PG8_SCHED __builtin_amdgcn_sched_barrier(0)
; template <class Epi, class Sched, bool ALIGN_EPI = false, bool SP2 = false>
; __device__ __forceinline__ void gemm_phase(PG8_LAS unsigned char* lds, const Gemm g, const Sched& S, const Epi& E, const int tid) {
;     ...
;             PG8_LDB(B0, 1, 0); PG8_LDB(B1, 1, 1); PG8_SCHED; PG8_LDA(At, 1, 0); PG8_STAGE(PG8_SA(0, 1), a2 + hstep, voffA);
;             PG8_WAIT_V(8); PG8_WAIT_L(0); PG8_BAR; PG8_MMA(0, 0, At, B0); PG8_MMA(0, 1, At, B1); PG8_BAR; PG8_SCHED;
	s_setprio 0
	s_add_i32 s53, 0, 0x18000
	s_add_i32 s54, 0, 0x1c000
	v_add_u32_e32 v154, s53, v140
	v_add_u32_e32 v170, s54, v140
	ds_read_b128 v[142:145], v154
	ds_read_b128 v[146:149], v154 offset:1024
	ds_read_b128 v[150:153], v154 offset:2048
	ds_read_b128 v[154:157], v154 offset:3072
	ds_read_b128 v[158:161], v170
	ds_read_b128 v[162:165], v170 offset:1024
	ds_read_b128 v[166:169], v170 offset:2048
	ds_read_b128 v[170:173], v170 offset:3072
	s_add_u32 s28, s28, 0x20000
	s_addc_u32 s29, s29, 0
	s_mov_b32 m0, s36
	v_lshl_add_u64 v[214:215], s[28:29], 0, v[128:129]
	ds_read_b128 v[174:177], v141 offset:32768
	ds_read_b128 v[178:181], v141 offset:33792
	ds_read_b128 v[182:185], v141 offset:34816
	ds_read_b128 v[186:189], v141 offset:35840
	ds_read_b128 v[190:193], v141 offset:36864
	ds_read_b128 v[194:197], v141 offset:37888
	ds_read_b128 v[198:201], v141 offset:38912
	ds_read_b128 v[206:209], v141 offset:39936
	global_load_lds_dwordx4 v[214:215], off
	v_lshl_add_u64 v[214:215], s[28:29], 0, v[130:131]
	s_mov_b32 m0, s37
	s_nop 0
	global_load_lds_dwordx4 v[214:215], off
	s_waitcnt vmcnt(8)
	s_waitcnt lgkmcnt(0)
	s_setprio 1
	s_barrier
	v_mfma_f32_16x16x32_bf16 v[124:127], v[142:145], v[174:177], v[124:127]
	v_mfma_f32_16x16x32_bf16 v[120:123], v[150:153], v[174:177], v[120:123]
	v_mfma_f32_16x16x32_bf16 v[116:119], v[142:145], v[182:185], v[116:119]
	v_mfma_f32_16x16x32_bf16 v[108:111], v[150:153], v[182:185], v[108:111]
	v_mfma_f32_16x16x32_bf16 v[100:103], v[142:145], v[190:193], v[100:103]
	v_mfma_f32_16x16x32_bf16 v[92:95], v[150:153], v[190:193], v[92:95]
	v_mfma_f32_16x16x32_bf16 v[84:87], v[142:145], v[198:201], v[84:87]
	v_mfma_f32_16x16x32_bf16 v[76:79], v[150:153], v[198:201], v[76:79]
	v_mfma_f32_16x16x32_bf16 v[124:127], v[146:149], v[178:181], v[124:127]
	v_mfma_f32_16x16x32_bf16 v[120:123], v[154:157], v[178:181], v[120:123]
	v_mfma_f32_16x16x32_bf16 v[116:119], v[146:149], v[186:189], v[116:119]
	v_mfma_f32_16x16x32_bf16 v[108:111], v[154:157], v[186:189], v[108:111]
	v_mfma_f32_16x16x32_bf16 v[100:103], v[146:149], v[194:197], v[100:103]
	v_mfma_f32_16x16x32_bf16 v[92:95], v[154:157], v[194:197], v[92:95]
	v_mfma_f32_16x16x32_bf16 v[84:87], v[146:149], v[206:209], v[84:87]
	v_mfma_f32_16x16x32_bf16 v[76:79], v[154:157], v[206:209], v[76:79]
	s_setprio 0
	s_setprio 1
	v_mfma_f32_16x16x32_bf16 v[112:115], v[158:161], v[174:177], v[112:115]
	v_mfma_f32_16x16x32_bf16 v[104:107], v[166:169], v[174:177], v[104:107]
	v_mfma_f32_16x16x32_bf16 v[96:99], v[158:161], v[182:185], v[96:99]
	v_mfma_f32_16x16x32_bf16 v[88:91], v[166:169], v[182:185], v[88:91]
	v_mfma_f32_16x16x32_bf16 v[80:83], v[158:161], v[190:193], v[80:83]
	v_mfma_f32_16x16x32_bf16 v[72:75], v[166:169], v[190:193], v[72:75]
	v_mfma_f32_16x16x32_bf16 v[68:71], v[158:161], v[198:201], v[68:71]
	v_mfma_f32_16x16x32_bf16 v[64:67], v[166:169], v[198:201], v[64:67]
	v_mfma_f32_16x16x32_bf16 v[112:115], v[162:165], v[178:181], v[112:115]
	v_mfma_f32_16x16x32_bf16 v[104:107], v[170:173], v[178:181], v[104:107]
	v_mfma_f32_16x16x32_bf16 v[96:99], v[162:165], v[186:189], v[96:99]
	v_mfma_f32_16x16x32_bf16 v[88:91], v[170:173], v[186:189], v[88:91]
	v_mfma_f32_16x16x32_bf16 v[80:83], v[162:165], v[194:197], v[80:83]
	v_mfma_f32_16x16x32_bf16 v[72:75], v[170:173], v[194:197], v[72:75]
	v_mfma_f32_16x16x32_bf16 v[68:71], v[162:165], v[206:209], v[68:71]
	v_mfma_f32_16x16x32_bf16 v[64:67], v[170:173], v[206:209], v[64:67]
	s_barrier
; #define PG8_STAGE(bufoff, gbase, voff) do { _Pragma("unroll") for (int _i = 0; _i < 2; ++_i) \
;         __builtin_amdgcn_global_load_lds((const unsigned*)((const char*)(gbase) + (voff)[_i]), (PG8_LAS unsigned*)(lds + (bufoff) + ldsw + _i * 8192), 16, 0, 0); } while (0)
; #define PG8_LDA(dst, b, h) do { _Pragma("unroll") for (int m = 0; m < 4; ++m) _Pragma("unroll") for (int k = 0; k < 2; ++k) dst[m][k] = *(const PG8_LAS bf16x8*)(lds + PG8_SA(b, h) + aoff + m * 2048 + k * 1024); } while (0)
; #define PG8_MMA(ai, bj, At, Bt) do { __builtin_amdgcn_s_setprio(1); _Pragma("unroll") for (int m = 0; m < 4; ++m) _Pragma("unroll") for (int n = 0; n < 2; ++n) _Pragma("unroll") for (int k = 0; k < 2; ++k) \
;         acc[ai][bj][m][n] = __builtin_amdgcn_mfma_f32_16x16x32_bf16(Bt[n][k], At[m][k], acc[ai][bj][m][n], 0, 0, 0); __builtin_amdgcn_s_setprio(0); } while (0)
; #define PG8_WAIT_V(n) asm volatile("s_waitcnt vmcnt(" #n ")" ::: "memory")
; #define PG8_WAIT_L(n) asm volatile("s_waitcnt lgkmcnt(" #n ")" ::: "memory")
; #define PG8_BAR __builtin_amdgcn_s_barrier()
; #define PG8_SCHED __builtin_amdgcn_sched_barrier(0)
; template <class Epi, class Sched, bool ALIGN_EPI = false, bool SP2 = false>
; __device__ __forceinline__ void gemm_phase(PG8_LAS unsigned char* lds, const Gemm g, const Sched& S, const Epi& E, const int tid) {
;     ...
;             PG8_LDA(At, 1, 1); PG8_STAGE(PG8_SB(1, 0), b3, voffB); PG8_STAGE(PG8_SB(1, 1), b3 + hstep, voffB); PG8_STAGE(PG8_SA(1, 0), a3, voffA);
;             PG8_WAIT_V(8); PG8_WAIT_L(0); PG8_BAR; PG8_MMA(1, 0, At, B0); PG8_MMA(1, 1, At, B1); PG8_BAR; PG8_SCHED;
;     ...
;         if constexpr (ALIGN_EPI) { if (wr == 0) PG8_BAR; }
	s_setprio 0
	s_add_i32 s28, s53, s34
	v_lshl_add_u64 v[138:139], v[138:139], 0, s[70:71]
	s_mov_b32 m0, s28
	ds_read_b128 v[174:177], v141 offset:49152
	ds_read_b128 v[178:181], v141 offset:50176
	ds_read_b128 v[182:185], v141 offset:51200
	ds_read_b128 v[186:189], v141 offset:52224
	ds_read_b128 v[190:193], v141 offset:53248
	ds_read_b128 v[194:197], v141 offset:54272
	ds_read_b128 v[198:201], v141 offset:55296
	ds_read_b128 v[206:209], v141 offset:56320
	global_load_lds_dwordx4 v[138:139], off
	s_add_i32 m0, s28, 0x2000
	s_add_u32 s26, s26, 0x20080
	v_lshl_add_u64 v[138:139], v[202:203], 0, s[70:71]
	s_addc_u32 s27, s27, 0
	s_add_i32 s28, s54, s34
	global_load_lds_dwordx4 v[138:139], off
	v_lshl_add_u64 v[138:139], s[26:27], 0, v[204:205]
	s_mov_b32 m0, s28
	s_nop 0
	global_load_lds_dwordx4 v[138:139], off
	v_lshl_add_u64 v[138:139], s[26:27], 0, v[132:133]
	s_add_i32 m0, s28, 0x2000
	s_nop 0
	global_load_lds_dwordx4 v[138:139], off
	v_lshl_add_u64 v[138:139], v[210:211], 0, s[70:71]
	s_mov_b32 m0, s43
	s_nop 0
	global_load_lds_dwordx4 v[138:139], off
	v_lshl_add_u64 v[138:139], v[212:213], 0, s[70:71]
	s_mov_b32 m0, s44
	s_nop 0
	global_load_lds_dwordx4 v[138:139], off
	s_waitcnt vmcnt(8)
	s_waitcnt lgkmcnt(0)
	s_setprio 1
	s_barrier
	v_mfma_f32_16x16x32_bf16 v[60:63], v[142:145], v[174:177], v[60:63]
	v_mfma_f32_16x16x32_bf16 v[56:59], v[150:153], v[174:177], v[56:59]
	v_mfma_f32_16x16x32_bf16 v[52:55], v[142:145], v[182:185], v[52:55]
	v_mfma_f32_16x16x32_bf16 v[44:47], v[150:153], v[182:185], v[44:47]
	v_mfma_f32_16x16x32_bf16 v[36:39], v[142:145], v[190:193], v[36:39]
	v_mfma_f32_16x16x32_bf16 v[28:31], v[150:153], v[190:193], v[28:31]
	v_mfma_f32_16x16x32_bf16 v[20:23], v[142:145], v[198:201], v[20:23]
	v_mfma_f32_16x16x32_bf16 v[12:15], v[150:153], v[198:201], v[12:15]
	v_mfma_f32_16x16x32_bf16 v[60:63], v[146:149], v[178:181], v[60:63]
	v_mfma_f32_16x16x32_bf16 v[56:59], v[154:157], v[178:181], v[56:59]
	v_mfma_f32_16x16x32_bf16 v[52:55], v[146:149], v[186:189], v[52:55]
	v_mfma_f32_16x16x32_bf16 v[44:47], v[154:157], v[186:189], v[44:47]
	v_mfma_f32_16x16x32_bf16 v[36:39], v[146:149], v[194:197], v[36:39]
	v_mfma_f32_16x16x32_bf16 v[28:31], v[154:157], v[194:197], v[28:31]
	v_mfma_f32_16x16x32_bf16 v[20:23], v[146:149], v[206:209], v[20:23]
	v_mfma_f32_16x16x32_bf16 v[12:15], v[154:157], v[206:209], v[12:15]
	s_setprio 0
	s_setprio 1
	v_mfma_f32_16x16x32_bf16 v[48:51], v[158:161], v[174:177], v[48:51]
	v_mfma_f32_16x16x32_bf16 v[40:43], v[166:169], v[174:177], v[40:43]
	v_mfma_f32_16x16x32_bf16 v[32:35], v[158:161], v[182:185], v[32:35]
	v_mfma_f32_16x16x32_bf16 v[24:27], v[166:169], v[182:185], v[24:27]
	v_mfma_f32_16x16x32_bf16 v[16:19], v[158:161], v[190:193], v[16:19]
	v_mfma_f32_16x16x32_bf16 v[8:11], v[166:169], v[190:193], v[8:11]
	v_mfma_f32_16x16x32_bf16 v[4:7], v[158:161], v[198:201], v[4:7]
	v_mfma_f32_16x16x32_bf16 v[0:3], v[166:169], v[198:201], v[0:3]
	v_mfma_f32_16x16x32_bf16 v[48:51], v[162:165], v[178:181], v[48:51]
	v_mfma_f32_16x16x32_bf16 v[40:43], v[170:173], v[178:181], v[40:43]
	v_mfma_f32_16x16x32_bf16 v[32:35], v[162:165], v[186:189], v[32:35]
	v_mfma_f32_16x16x32_bf16 v[24:27], v[170:173], v[186:189], v[24:27]
	v_mfma_f32_16x16x32_bf16 v[16:19], v[162:165], v[194:197], v[16:19]
	v_mfma_f32_16x16x32_bf16 v[8:11], v[170:173], v[194:197], v[8:11]
	v_mfma_f32_16x16x32_bf16 v[4:7], v[162:165], v[206:209], v[4:7]
	v_mfma_f32_16x16x32_bf16 v[0:3], v[170:173], v[206:209], v[0:3]
	s_barrier
	s_setprio 0
	s_add_i32 s52, s52, 2
	s_add_u32 s24, s24, 0x100
	s_addc_u32 s25, s25, 0
	s_add_u32 s50, s50, 0x100
	s_addc_u32 s51, s51, 0
	s_cmp_gt_u32 s52, 5
	s_cbranch_scc0 .LBB0_1573
	s_and_b64 vcc, exec, s[12:13]
	s_cbranch_vccz .LBB0_1576
	s_barrier
